# speedup vs baseline: 1.0045x; 1.0045x over previous
.LBB0_109:
	s_lshl_b32 s62, s86, 3
	v_cvt_f32_u32_e32 v2, s62
	s_sub_i32 s65, 0, s62
	s_abs_i32 s63, s85
	s_ashr_i32 s64, s85, 31
	v_rcp_iflag_f32_e32 v2, v2
	v_bfe_i32 v5, v171, 27, 1
	v_lshlrev_b32_e32 v169, 4, v171
	v_lshrrev_b32_e32 v5, 22, v5
	v_mul_f32_e32 v2, 0x4f7ffffe, v2
	v_cvt_u32_f32_e32 v2, v2
	v_add_u32_e32 v5, v169, v5
	v_and_b32_e32 v5, 0xfffffc00, v5
	v_sub_u32_e32 v5, v169, v5
	v_readfirstlane_b32 s68, v2
	s_mul_i32 s65, s65, s68
	s_mul_hi_u32 s65, s68, s65
	s_add_i32 s68, s68, s65
	s_mul_hi_u32 s65, s63, s68
	s_mul_i32 s68, s65, s62
	s_sub_i32 s63, s63, s68
	s_add_i32 s69, s65, 1
	s_sub_i32 s68, s63, s62
	s_cmp_ge_u32 s63, s62
	s_cselect_b32 s65, s69, s65
	s_cselect_b32 s63, s68, s63
	s_add_i32 s68, s65, 1
	s_cmp_ge_u32 s63, s62
	s_cselect_b32 s63, s68, s65
	s_xor_b32 s65, s63, s64
	s_sub_i32 s70, s65, s64
	v_lshrrev_b32_e32 v6, 4, v5
	s_mul_i32 s62, s70, s62
	v_bitop3_b32 v5, v6, v5, 32 bitop3:0x6c
	s_sub_i32 s62, s85, s62
	v_ashrrev_i32_e32 v6, 31, v5
	s_ashr_i32 s89, s62, 3
	s_lshl_b32 s62, s62, 8
	v_lshrrev_b32_e32 v6, 26, v6
	s_and_b32 s71, s62, 0x700
	s_lshl_b32 s62, s89, 8
	v_ashrrev_i32_e32 v2, 31, v171
	v_add_u32_e32 v6, v5, v6
	v_lshrrev_b32_e32 v2, 26, v2
	v_ashrrev_i32_e32 v133, 6, v6
	v_and_b32_e32 v6, 0xc0, v6
	s_ashr_i32 s63, s62, 31
	v_and_b32_e32 v3, 15, v0
	v_and_b32_e32 v4, 48, v0
	v_add_u32_e32 v2, v171, v2
	v_sub_u32_e32 v5, v5, v6
	v_and_b32_e32 v6, 32, v0
	v_lshlrev_b32_e32 v10, 2, v0
	s_lshl_b64 s[72:73], s[62:63], 6
	v_lshlrev_b32_e32 v0, 6, v0
	s_lshl_b32 s63, s65, 11
	v_ashrrev_i32_e32 v131, 6, v2
	v_lshlrev_b32_e32 v3, 6, v3
	v_and_b32_e32 v10, 32, v10
	v_and_b32_e32 v0, 0x3c0, v0
	s_or_b32 s63, s63, s71
	s_lshl_b32 s64, s64, 11
	v_or_b32_e32 v9, v3, v4
	v_bitop3_b32 v3, v3, v10, v4 bitop3:0x36
	v_bitop3_b32 v4, v0, v10, v4 bitop3:0x36
	s_sub_i32 s64, s63, s64
	v_lshlrev_b32_e32 v0, 15, v131
	s_ashr_i32 s65, s64, 31
	v_and_b32_e32 v0, 0xffff0000, v0
	v_ashrrev_i16_sdwa v5, v167, sext(v5) dst_sel:DWORD dst_unused:UNUSED_PAD src0_sel:DWORD src1_sel:BYTE_0
	s_lshl_b64 s[64:65], s[64:65], 12
	v_lshl_add_u32 v0, v133, 12, v0
	v_bfe_i32 v134, v5, 0, 16
	v_and_or_b32 v0, v2, 64, v0
	s_add_u32 s64, s54, s64
	s_waitcnt vmcnt(0)
	v_lshl_add_u32 v164, v134, 1, v0
	s_addc_u32 s65, s55, s65
	v_lshlrev_b32_e32 v14, 13, v1
	v_lshl_add_u64 v[0:1], s[64:65], 0, v[164:165]
	s_mul_i32 s64, s4, 0x1800
	s_mul_hi_u32 s63, s4, 0x1800
	s_add_u32 s64, s64, s72
	s_addc_u32 s63, s63, s73
	s_add_u32 s64, s66, s64
	v_bfe_i32 v7, v171, 6, 1
	s_addc_u32 s65, s67, s63
	s_lshl_b64 s[68:69], s[4:5], 12
	v_and_b32_e32 v7, s4, v7
	v_lshrrev_b32_e32 v8, 7, v171
	s_add_u32 s4, s68, s72
	v_add_lshl_u32 v7, v7, v8, 10
	v_lshlrev_b32_e32 v8, 6, v171
	s_addc_u32 s63, s69, s73
	v_and_b32_e32 v5, 0x3f0, v169
	v_and_b32_e32 v8, 0x3000, v8
	v_bitop3_b32 v11, v9, s77, v10 bitop3:0xde
	v_bitop3_b32 v12, v9, s78, v10 bitop3:0xde
	v_bitop3_b32 v13, v9, s79, v10 bitop3:0xde
	v_bitop3_b32 v9, v9, s80, v10 bitop3:0xde
	v_or_b32_e32 v10, 0x800, v14
	v_or_b32_e32 v15, 0x1000, v14
	s_waitcnt vmcnt(0)
	v_or_b32_e32 v16, 0x1800, v14
	v_lshl_add_u64 v[128:129], v[0:1], 0, s[20:21]
	s_add_u32 s66, s66, s4
	v_mov_b32_e32 v0, 0
	v_bitop3_b32 v164, v5, v7, v6 bitop3:0xde
	s_addc_u32 s67, s67, s63
	s_mov_b32 s4, -2
	v_add_u32_e32 v138, v11, v8
	v_add_u32_e32 v192, v3, v14
	v_add_u32_e32 v191, v4, v10
	v_add_u32_e32 v190, v4, v15
	v_add_u32_e32 v189, v4, v16
	v_add_u32_e32 v137, 0xc000, v169
	v_add_u32_e32 v136, 0xe000, v169
	v_add_u32_e32 v135, v12, v8
	v_add_u32_e32 v188, 0x10000, v169
	v_add_u32_e32 v187, 0x12000, v169
	v_add_u32_e32 v186, 0x2000, v169
	v_add_u32_e32 v185, 0x14000, v169
	v_add_u32_e32 v184, 0x16000, v169
	v_add_u32_e32 v130, v13, v8
	v_add_u32_e32 v183, 0x4000, v169
	v_add_u32_e32 v182, 0x6000, v169
	v_add_u32_e32 v132, v9, v8
	v_add_u32_e32 v181, 0x18000, v169
	v_add_u32_e32 v180, 0x1a000, v169
	v_add_u32_e32 v179, 0x8000, v169
	v_add_u32_e32 v177, 0xa000, v169
	v_add_u32_e32 v175, 0x1c000, v169
	v_add_u32_e32 v173, 0x1e000, v169
	v_mov_b32_e32 v1, v0
	v_mov_b32_e32 v2, v0
	v_mov_b32_e32 v3, v0
	v_mov_b32_e32 v4, v0
	v_mov_b32_e32 v5, v0
	v_mov_b32_e32 v6, v0
	v_mov_b32_e32 v7, v0
	v_mov_b32_e32 v8, v0
	v_mov_b32_e32 v9, v0
	v_mov_b32_e32 v10, v0
	v_mov_b32_e32 v11, v0
	v_mov_b32_e32 v12, v0
	v_mov_b32_e32 v13, v0
	v_mov_b32_e32 v14, v0
	v_mov_b32_e32 v15, v0
	v_mov_b32_e32 v16, v0
	v_mov_b32_e32 v17, v0
	v_mov_b32_e32 v18, v0
	v_mov_b32_e32 v19, v0
	v_mov_b32_e32 v20, v0
	v_mov_b32_e32 v21, v0
	v_mov_b32_e32 v22, v0
	v_mov_b32_e32 v23, v0
	v_mov_b32_e32 v24, v0
	v_mov_b32_e32 v25, v0
	v_mov_b32_e32 v26, v0
	v_mov_b32_e32 v27, v0
	v_mov_b32_e32 v28, v0
	v_mov_b32_e32 v29, v0
	v_mov_b32_e32 v30, v0
	v_mov_b32_e32 v31, v0
	v_mov_b32_e32 v32, v0
	v_mov_b32_e32 v33, v0
	v_mov_b32_e32 v34, v0
	v_mov_b32_e32 v35, v0
	v_mov_b32_e32 v36, v0
	v_mov_b32_e32 v37, v0
	v_mov_b32_e32 v38, v0
	v_mov_b32_e32 v39, v0
	v_mov_b32_e32 v40, v0
	v_mov_b32_e32 v41, v0
	v_mov_b32_e32 v42, v0
	v_mov_b32_e32 v43, v0
	v_mov_b32_e32 v44, v0
	v_mov_b32_e32 v45, v0
	v_mov_b32_e32 v46, v0
	v_mov_b32_e32 v47, v0
	v_mov_b32_e32 v48, v0
	v_mov_b32_e32 v49, v0
	v_mov_b32_e32 v50, v0
	v_mov_b32_e32 v51, v0
	v_mov_b32_e32 v52, v0
	v_mov_b32_e32 v53, v0
	v_mov_b32_e32 v54, v0
	v_mov_b32_e32 v55, v0
	v_mov_b32_e32 v56, v0
	v_mov_b32_e32 v57, v0
	v_mov_b32_e32 v58, v0
	v_mov_b32_e32 v59, v0
	v_mov_b32_e32 v60, v0
	v_mov_b32_e32 v61, v0
	v_mov_b32_e32 v62, v0
	v_mov_b32_e32 v63, v0
	v_mov_b32_e32 v64, v0
	v_mov_b32_e32 v65, v0
	v_mov_b32_e32 v66, v0
	v_mov_b32_e32 v67, v0
	v_mov_b32_e32 v68, v0
	v_mov_b32_e32 v69, v0
	v_mov_b32_e32 v70, v0
	v_mov_b32_e32 v71, v0
	v_mov_b32_e32 v72, v0
	v_mov_b32_e32 v73, v0
	v_mov_b32_e32 v74, v0
	v_mov_b32_e32 v75, v0
	v_mov_b32_e32 v76, v0
	v_mov_b32_e32 v77, v0
	v_mov_b32_e32 v78, v0
	v_mov_b32_e32 v79, v0
	v_mov_b32_e32 v80, v0
	v_mov_b32_e32 v81, v0
	v_mov_b32_e32 v82, v0
	v_mov_b32_e32 v83, v0
	v_mov_b32_e32 v84, v0
	v_mov_b32_e32 v85, v0
	v_mov_b32_e32 v86, v0
	v_mov_b32_e32 v87, v0
	v_mov_b32_e32 v88, v0
	v_mov_b32_e32 v89, v0
	v_mov_b32_e32 v90, v0
	v_mov_b32_e32 v91, v0
	v_mov_b32_e32 v92, v0
	v_mov_b32_e32 v93, v0
	v_mov_b32_e32 v94, v0
	v_mov_b32_e32 v95, v0
	v_mov_b32_e32 v96, v0
	v_mov_b32_e32 v97, v0
	v_mov_b32_e32 v98, v0
	v_mov_b32_e32 v99, v0
	v_mov_b32_e32 v100, v0
	v_mov_b32_e32 v101, v0
	v_mov_b32_e32 v102, v0
	v_mov_b32_e32 v103, v0
	v_mov_b32_e32 v104, v0
	v_mov_b32_e32 v105, v0
	v_mov_b32_e32 v106, v0
	v_mov_b32_e32 v107, v0
	v_mov_b32_e32 v108, v0
	v_mov_b32_e32 v109, v0
	v_mov_b32_e32 v110, v0
	v_mov_b32_e32 v111, v0
	v_mov_b32_e32 v112, v0
	v_mov_b32_e32 v113, v0
	v_mov_b32_e32 v114, v0
	v_mov_b32_e32 v115, v0
	v_mov_b32_e32 v116, v0
	v_mov_b32_e32 v117, v0
	v_mov_b32_e32 v118, v0
	v_mov_b32_e32 v119, v0
	v_mov_b32_e32 v120, v0
	v_mov_b32_e32 v121, v0
	v_mov_b32_e32 v122, v0
	v_mov_b32_e32 v123, v0
	v_mov_b32_e32 v124, v0
	v_mov_b32_e32 v125, v0
	v_mov_b32_e32 v126, v0
	v_mov_b32_e32 v127, v0
	s_barrier
	v_readlane_b32 s98, v242, 1
	s_lshl_b32 s98, s98, 10
	s_add_i32 s63, s98, 0xc000
	v_lshl_add_u64 v[142:143], v[128:129], 0, s[22:23]
	s_mov_b32 m0, s63
	s_add_i32 s63, s98, 0xe000
	global_load_lds_dwordx4 v[142:143], off
	v_lshl_add_u64 v[142:143], v[128:129], 0, s[24:25]
	s_mov_b32 m0, s63
	s_nop 0
	global_load_lds_dwordx4 v[142:143], off
.LBB0_110:
	ds_read_b128 v[140:143], v138
	ds_read_b128 v[144:147], v138 offset:1024
	ds_read_b128 v[148:151], v138 offset:2048
	ds_read_b128 v[152:155], v138 offset:3072
	ds_read_b128 v[156:159], v192
	ds_read_b128 v[160:163], v192 offset:1024
	ds_read_b128 v[194:197], v191
	ds_read_b128 v[198:201], v191 offset:1024
	ds_read_b128 v[202:205], v190
	ds_read_b128 v[206:209], v190 offset:1024
	ds_read_b128 v[210:213], v189
	ds_read_b128 v[214:217], v189 offset:1024
	s_waitcnt lgkmcnt(8)
	s_waitcnt vmcnt(10)
	s_barrier
	s_waitcnt lgkmcnt(0)
	s_waitcnt lgkmcnt(0)
	v_mfma_f32_16x16x32_bf16 v[124:127], v[140:143], v[156:159], v[124:127]
	v_mfma_f32_16x16x32_bf16 v[120:123], v[148:151], v[156:159], v[120:123]
	v_mfma_f32_16x16x32_bf16 v[116:119], v[140:143], v[194:197], v[116:119]
	v_mfma_f32_16x16x32_bf16 v[112:115], v[148:151], v[194:197], v[112:115]
	v_mfma_f32_16x16x32_bf16 v[108:111], v[140:143], v[202:205], v[108:111]
	v_mfma_f32_16x16x32_bf16 v[104:107], v[148:151], v[202:205], v[104:107]
	v_mfma_f32_16x16x32_bf16 v[100:103], v[140:143], v[210:213], v[100:103]
	v_mfma_f32_16x16x32_bf16 v[96:99], v[148:151], v[210:213], v[96:99]
	v_mfma_f32_16x16x32_bf16 v[124:127], v[144:147], v[160:163], v[124:127]
	v_mfma_f32_16x16x32_bf16 v[120:123], v[152:155], v[160:163], v[120:123]
	v_mfma_f32_16x16x32_bf16 v[116:119], v[144:147], v[198:201], v[116:119]
	v_mfma_f32_16x16x32_bf16 v[112:115], v[152:155], v[198:201], v[112:115]
	v_mfma_f32_16x16x32_bf16 v[108:111], v[144:147], v[206:209], v[108:111]
	v_mfma_f32_16x16x32_bf16 v[104:107], v[152:155], v[206:209], v[104:107]
	v_mfma_f32_16x16x32_bf16 v[100:103], v[144:147], v[214:217], v[100:103]
	v_mfma_f32_16x16x32_bf16 v[96:99], v[152:155], v[214:217], v[96:99]
	s_barrier
	s_add_i32 s63, s98, 0x10000
	v_lshl_add_u64 v[234:235], s[66:67], 0, v[164:165]
	s_mov_b32 m0, s63
	s_add_i32 s63, s98, 0x12000
	ds_read_b128 v[218:221], v135
	ds_read_b128 v[222:225], v135 offset:1024
	ds_read_b128 v[226:229], v135 offset:2048
	ds_read_b128 v[230:233], v135 offset:3072
	global_load_lds_dwordx4 v[234:235], off
	v_lshl_add_u64 v[236:237], v[234:235], 0, s[10:11]
	s_mov_b32 m0, s63
	s_nop 0
	global_load_lds_dwordx4 v[236:237], off
	s_mov_b32 s63, s98
	v_lshl_add_u64 v[236:237], v[128:129], 0, s[26:27]
	s_mov_b32 m0, s63
	s_add_i32 s63, s98, 0x2000
	global_load_lds_dwordx4 v[236:237], off
	v_lshl_add_u64 v[236:237], v[128:129], 0, s[28:29]
	s_mov_b32 m0, s63
	s_nop 0
	global_load_lds_dwordx4 v[236:237], off
	s_waitcnt vmcnt(12)
	s_barrier
	s_waitcnt lgkmcnt(0)
	s_waitcnt lgkmcnt(0)
	v_mfma_f32_16x16x32_bf16 v[92:95], v[218:221], v[156:159], v[92:95]
	v_mfma_f32_16x16x32_bf16 v[88:91], v[226:229], v[156:159], v[88:91]
	v_mfma_f32_16x16x32_bf16 v[84:87], v[218:221], v[194:197], v[84:87]
	v_mfma_f32_16x16x32_bf16 v[80:83], v[226:229], v[194:197], v[80:83]
	v_mfma_f32_16x16x32_bf16 v[76:79], v[218:221], v[202:205], v[76:79]
	v_mfma_f32_16x16x32_bf16 v[72:75], v[226:229], v[202:205], v[72:75]
	v_mfma_f32_16x16x32_bf16 v[68:71], v[218:221], v[210:213], v[68:71]
	v_mfma_f32_16x16x32_bf16 v[64:67], v[226:229], v[210:213], v[64:67]
	v_mfma_f32_16x16x32_bf16 v[92:95], v[222:225], v[160:163], v[92:95]
	v_mfma_f32_16x16x32_bf16 v[88:91], v[230:233], v[160:163], v[88:91]
	v_mfma_f32_16x16x32_bf16 v[84:87], v[222:225], v[198:201], v[84:87]
	v_mfma_f32_16x16x32_bf16 v[80:83], v[230:233], v[198:201], v[80:83]
	v_mfma_f32_16x16x32_bf16 v[76:79], v[222:225], v[206:209], v[76:79]
	v_mfma_f32_16x16x32_bf16 v[72:75], v[230:233], v[206:209], v[72:75]
	v_mfma_f32_16x16x32_bf16 v[68:71], v[222:225], v[214:217], v[68:71]
	v_mfma_f32_16x16x32_bf16 v[64:67], v[230:233], v[214:217], v[64:67]
	s_barrier
	ds_read_b128 v[156:159], v192 offset:16384
	ds_read_b128 v[160:163], v192 offset:17408
	ds_read_b128 v[194:197], v191 offset:16384
	ds_read_b128 v[198:201], v191 offset:17408
	ds_read_b128 v[202:205], v190 offset:16384
	ds_read_b128 v[206:209], v190 offset:17408
	ds_read_b128 v[210:213], v189 offset:16384
	ds_read_b128 v[214:217], v189 offset:17408
	s_add_i32 s63, s98, 0x14000
	v_lshl_add_u64 v[236:237], v[234:235], 0, s[30:31]
	s_mov_b32 m0, s63
	s_add_i32 s63, s98, 0x16000
	global_load_lds_dwordx4 v[236:237], off
	v_lshl_add_u64 v[236:237], v[234:235], 0, s[34:35]
	s_mov_b32 m0, s63
	s_nop 0
	global_load_lds_dwordx4 v[236:237], off
	s_barrier
	s_waitcnt lgkmcnt(0)
	s_waitcnt lgkmcnt(0)
	v_mfma_f32_16x16x32_bf16 v[60:63], v[140:143], v[156:159], v[60:63]
	v_mfma_f32_16x16x32_bf16 v[56:59], v[148:151], v[156:159], v[56:59]
	v_mfma_f32_16x16x32_bf16 v[52:55], v[140:143], v[194:197], v[52:55]
	v_mfma_f32_16x16x32_bf16 v[48:51], v[148:151], v[194:197], v[48:51]
	v_mfma_f32_16x16x32_bf16 v[44:47], v[140:143], v[202:205], v[44:47]
	v_mfma_f32_16x16x32_bf16 v[40:43], v[148:151], v[202:205], v[40:43]
	v_mfma_f32_16x16x32_bf16 v[36:39], v[140:143], v[210:213], v[36:39]
	v_mfma_f32_16x16x32_bf16 v[32:35], v[148:151], v[210:213], v[32:35]
	v_mfma_f32_16x16x32_bf16 v[60:63], v[144:147], v[160:163], v[60:63]
	v_mfma_f32_16x16x32_bf16 v[56:59], v[152:155], v[160:163], v[56:59]
	v_mfma_f32_16x16x32_bf16 v[52:55], v[144:147], v[198:201], v[52:55]
	v_mfma_f32_16x16x32_bf16 v[48:51], v[152:155], v[198:201], v[48:51]
	v_mfma_f32_16x16x32_bf16 v[44:47], v[144:147], v[206:209], v[44:47]
	v_mfma_f32_16x16x32_bf16 v[40:43], v[152:155], v[206:209], v[40:43]
	v_mfma_f32_16x16x32_bf16 v[36:39], v[144:147], v[214:217], v[36:39]
	v_mfma_f32_16x16x32_bf16 v[32:35], v[152:155], v[214:217], v[32:35]
	s_barrier
	s_add_i32 s63, s98, 0x4000
	v_lshl_add_u64 v[142:143], v[128:129], 0, s[40:41]
	s_mov_b32 m0, s63
	s_add_i32 s63, s98, 0x6000
	global_load_lds_dwordx4 v[142:143], off
	s_mov_b32 m0, s63
	s_nop 0
	global_load_lds_dwordx4 v[128:129], off
	s_waitcnt vmcnt(12)
	s_barrier
	v_mfma_f32_16x16x32_bf16 v[28:31], v[218:221], v[156:159], v[28:31]
	v_mfma_f32_16x16x32_bf16 v[24:27], v[226:229], v[156:159], v[24:27]
	v_mfma_f32_16x16x32_bf16 v[20:23], v[218:221], v[194:197], v[20:23]
	v_mfma_f32_16x16x32_bf16 v[16:19], v[226:229], v[194:197], v[16:19]
	v_mfma_f32_16x16x32_bf16 v[12:15], v[218:221], v[202:205], v[12:15]
	v_mfma_f32_16x16x32_bf16 v[8:11], v[226:229], v[202:205], v[8:11]
	v_mfma_f32_16x16x32_bf16 v[4:7], v[218:221], v[210:213], v[4:7]
	v_mfma_f32_16x16x32_bf16 v[0:3], v[226:229], v[210:213], v[0:3]
	v_mfma_f32_16x16x32_bf16 v[28:31], v[222:225], v[160:163], v[28:31]
	v_mfma_f32_16x16x32_bf16 v[24:27], v[230:233], v[160:163], v[24:27]
	v_mfma_f32_16x16x32_bf16 v[20:23], v[222:225], v[198:201], v[20:23]
	v_mfma_f32_16x16x32_bf16 v[16:19], v[230:233], v[198:201], v[16:19]
	v_mfma_f32_16x16x32_bf16 v[12:15], v[222:225], v[206:209], v[12:15]
	v_mfma_f32_16x16x32_bf16 v[8:11], v[230:233], v[206:209], v[8:11]
	v_mfma_f32_16x16x32_bf16 v[4:7], v[222:225], v[214:217], v[4:7]
	v_mfma_f32_16x16x32_bf16 v[0:3], v[230:233], v[214:217], v[0:3]
	s_barrier
	ds_read_b128 v[140:143], v130
	ds_read_b128 v[144:147], v130 offset:1024
	ds_read_b128 v[148:151], v130 offset:2048
	ds_read_b128 v[152:155], v130 offset:3072
	ds_read_b128 v[156:159], v192 offset:32768
	ds_read_b128 v[160:163], v192 offset:33792
	ds_read_b128 v[194:197], v191 offset:32768
	ds_read_b128 v[198:201], v191 offset:33792
	ds_read_b128 v[202:205], v190 offset:32768
	ds_read_b128 v[206:209], v190 offset:33792
	ds_read_b128 v[210:213], v189 offset:32768
	ds_read_b128 v[214:217], v189 offset:33792
	s_waitcnt lgkmcnt(8)
	s_waitcnt vmcnt(10)
	s_barrier
	s_waitcnt lgkmcnt(0)
	s_waitcnt lgkmcnt(0)
	v_mfma_f32_16x16x32_bf16 v[124:127], v[140:143], v[156:159], v[124:127]
	v_mfma_f32_16x16x32_bf16 v[120:123], v[148:151], v[156:159], v[120:123]
	v_mfma_f32_16x16x32_bf16 v[116:119], v[140:143], v[194:197], v[116:119]
	v_mfma_f32_16x16x32_bf16 v[112:115], v[148:151], v[194:197], v[112:115]
	v_mfma_f32_16x16x32_bf16 v[108:111], v[140:143], v[202:205], v[108:111]
	v_mfma_f32_16x16x32_bf16 v[104:107], v[148:151], v[202:205], v[104:107]
	v_mfma_f32_16x16x32_bf16 v[100:103], v[140:143], v[210:213], v[100:103]
	v_mfma_f32_16x16x32_bf16 v[96:99], v[148:151], v[210:213], v[96:99]
	v_mfma_f32_16x16x32_bf16 v[124:127], v[144:147], v[160:163], v[124:127]
	v_mfma_f32_16x16x32_bf16 v[120:123], v[152:155], v[160:163], v[120:123]
	v_mfma_f32_16x16x32_bf16 v[116:119], v[144:147], v[198:201], v[116:119]
	v_mfma_f32_16x16x32_bf16 v[112:115], v[152:155], v[198:201], v[112:115]
	v_mfma_f32_16x16x32_bf16 v[108:111], v[144:147], v[206:209], v[108:111]
	v_mfma_f32_16x16x32_bf16 v[104:107], v[152:155], v[206:209], v[104:107]
	v_mfma_f32_16x16x32_bf16 v[100:103], v[144:147], v[214:217], v[100:103]
	v_mfma_f32_16x16x32_bf16 v[96:99], v[152:155], v[214:217], v[96:99]
	s_barrier
	s_add_i32 s63, s98, 0x18000
	v_lshl_add_u64 v[234:235], s[64:65], 0, v[164:165]
	s_mov_b32 m0, s63
	s_add_i32 s63, s98, 0x1a000
	ds_read_b128 v[218:221], v132
	ds_read_b128 v[222:225], v132 offset:1024
	ds_read_b128 v[226:229], v132 offset:2048
	ds_read_b128 v[230:233], v132 offset:3072
	global_load_lds_dwordx4 v[234:235], off
	v_lshl_add_u64 v[236:237], v[234:235], 0, s[10:11]
	s_mov_b32 m0, s63
	s_nop 0
	global_load_lds_dwordx4 v[236:237], off
	s_add_i32 s63, s98, 0x8000
	v_lshl_add_u64 v[236:237], v[128:129], 0, s[44:45]
	s_mov_b32 m0, s63
	s_add_i32 s63, s98, 0xa000
	global_load_lds_dwordx4 v[236:237], off
	v_lshl_add_u64 v[236:237], v[128:129], 0, s[46:47]
	s_mov_b32 m0, s63
	s_nop 0
	global_load_lds_dwordx4 v[236:237], off
	s_waitcnt vmcnt(12)
	s_barrier
	s_waitcnt lgkmcnt(0)
	s_waitcnt lgkmcnt(0)
	v_mfma_f32_16x16x32_bf16 v[92:95], v[218:221], v[156:159], v[92:95]
	v_mfma_f32_16x16x32_bf16 v[88:91], v[226:229], v[156:159], v[88:91]
	v_mfma_f32_16x16x32_bf16 v[84:87], v[218:221], v[194:197], v[84:87]
	v_mfma_f32_16x16x32_bf16 v[80:83], v[226:229], v[194:197], v[80:83]
	v_mfma_f32_16x16x32_bf16 v[76:79], v[218:221], v[202:205], v[76:79]
	v_mfma_f32_16x16x32_bf16 v[72:75], v[226:229], v[202:205], v[72:75]
	v_mfma_f32_16x16x32_bf16 v[68:71], v[218:221], v[210:213], v[68:71]
	v_mfma_f32_16x16x32_bf16 v[64:67], v[226:229], v[210:213], v[64:67]
	v_mfma_f32_16x16x32_bf16 v[92:95], v[222:225], v[160:163], v[92:95]
	v_mfma_f32_16x16x32_bf16 v[88:91], v[230:233], v[160:163], v[88:91]
	v_mfma_f32_16x16x32_bf16 v[84:87], v[222:225], v[198:201], v[84:87]
	v_mfma_f32_16x16x32_bf16 v[80:83], v[230:233], v[198:201], v[80:83]
	v_mfma_f32_16x16x32_bf16 v[76:79], v[222:225], v[206:209], v[76:79]
	v_mfma_f32_16x16x32_bf16 v[72:75], v[230:233], v[206:209], v[72:75]
	v_mfma_f32_16x16x32_bf16 v[68:71], v[222:225], v[214:217], v[68:71]
	v_mfma_f32_16x16x32_bf16 v[64:67], v[230:233], v[214:217], v[64:67]
	s_barrier
	ds_read_b128 v[156:159], v192 offset:49152
	ds_read_b128 v[160:163], v192 offset:50176
	ds_read_b128 v[194:197], v191 offset:49152
	ds_read_b128 v[198:201], v191 offset:50176
	ds_read_b128 v[202:205], v190 offset:49152
	ds_read_b128 v[206:209], v190 offset:50176
	ds_read_b128 v[210:213], v189 offset:49152
	ds_read_b128 v[214:217], v189 offset:50176
	s_add_i32 s63, s98, 0x1c000
	v_lshl_add_u64 v[236:237], v[234:235], 0, s[30:31]
	s_mov_b32 m0, s63
	s_add_i32 s63, s98, 0x1e000
	global_load_lds_dwordx4 v[236:237], off
	v_lshl_add_u64 v[236:237], v[234:235], 0, s[34:35]
	s_mov_b32 m0, s63
	s_nop 0
	global_load_lds_dwordx4 v[236:237], off
	s_barrier
	s_waitcnt lgkmcnt(0)
	s_waitcnt lgkmcnt(0)
	v_mfma_f32_16x16x32_bf16 v[60:63], v[140:143], v[156:159], v[60:63]
	v_mfma_f32_16x16x32_bf16 v[56:59], v[148:151], v[156:159], v[56:59]
	v_mfma_f32_16x16x32_bf16 v[52:55], v[140:143], v[194:197], v[52:55]
	v_mfma_f32_16x16x32_bf16 v[48:51], v[148:151], v[194:197], v[48:51]
	v_mfma_f32_16x16x32_bf16 v[44:47], v[140:143], v[202:205], v[44:47]
	v_mfma_f32_16x16x32_bf16 v[40:43], v[148:151], v[202:205], v[40:43]
	v_mfma_f32_16x16x32_bf16 v[36:39], v[140:143], v[210:213], v[36:39]
	v_mfma_f32_16x16x32_bf16 v[32:35], v[148:151], v[210:213], v[32:35]
	v_mfma_f32_16x16x32_bf16 v[60:63], v[144:147], v[160:163], v[60:63]
	v_mfma_f32_16x16x32_bf16 v[56:59], v[152:155], v[160:163], v[56:59]
	v_mfma_f32_16x16x32_bf16 v[52:55], v[144:147], v[198:201], v[52:55]
	v_mfma_f32_16x16x32_bf16 v[48:51], v[152:155], v[198:201], v[48:51]
	v_mfma_f32_16x16x32_bf16 v[44:47], v[144:147], v[206:209], v[44:47]
	v_mfma_f32_16x16x32_bf16 v[40:43], v[152:155], v[206:209], v[40:43]
	v_mfma_f32_16x16x32_bf16 v[36:39], v[144:147], v[214:217], v[36:39]
	v_mfma_f32_16x16x32_bf16 v[32:35], v[152:155], v[214:217], v[32:35]
	s_barrier
	v_lshl_add_u64 v[128:129], v[128:129], 0, s[56:57]
	s_add_i32 s63, s98, 0xc000
	v_lshl_add_u64 v[142:143], v[128:129], 0, s[22:23]
	s_mov_b32 m0, s63
	s_add_i32 s63, s98, 0xe000
	global_load_lds_dwordx4 v[142:143], off
	v_lshl_add_u64 v[142:143], v[128:129], 0, s[24:25]
	s_mov_b32 m0, s63
	s_nop 0
	global_load_lds_dwordx4 v[142:143], off
	s_waitcnt vmcnt(12)
	s_barrier
	v_mfma_f32_16x16x32_bf16 v[28:31], v[218:221], v[156:159], v[28:31]
	v_mfma_f32_16x16x32_bf16 v[24:27], v[226:229], v[156:159], v[24:27]
	v_mfma_f32_16x16x32_bf16 v[20:23], v[218:221], v[194:197], v[20:23]
	v_mfma_f32_16x16x32_bf16 v[16:19], v[226:229], v[194:197], v[16:19]
	v_mfma_f32_16x16x32_bf16 v[12:15], v[218:221], v[202:205], v[12:15]
	v_mfma_f32_16x16x32_bf16 v[8:11], v[226:229], v[202:205], v[8:11]
	v_mfma_f32_16x16x32_bf16 v[4:7], v[218:221], v[210:213], v[4:7]
	v_mfma_f32_16x16x32_bf16 v[0:3], v[226:229], v[210:213], v[0:3]
	v_mfma_f32_16x16x32_bf16 v[28:31], v[222:225], v[160:163], v[28:31]
	v_mfma_f32_16x16x32_bf16 v[24:27], v[230:233], v[160:163], v[24:27]
	v_mfma_f32_16x16x32_bf16 v[20:23], v[222:225], v[198:201], v[20:23]
	v_mfma_f32_16x16x32_bf16 v[16:19], v[230:233], v[198:201], v[16:19]
	v_mfma_f32_16x16x32_bf16 v[12:15], v[222:225], v[206:209], v[12:15]
	v_mfma_f32_16x16x32_bf16 v[8:11], v[230:233], v[206:209], v[8:11]
	v_mfma_f32_16x16x32_bf16 v[4:7], v[222:225], v[214:217], v[4:7]
	v_mfma_f32_16x16x32_bf16 v[0:3], v[230:233], v[214:217], v[0:3]
	s_add_i32 s4, s4, 2
	s_add_u32 s64, s64, s68
	s_addc_u32 s65, s65, s69
	s_add_u32 s66, s66, s68
	s_addc_u32 s67, s67, s69
	s_cmp_lt_u32 s4, 28
	s_barrier
	s_cbranch_scc1 .LBB0_110
	s_lshl_b32 s4, s70, 11
	s_or_b32 s64, s71, s4
	s_or_b32 s66, s64, 0x80
	v_lshlrev_b32_e32 v128, 3, v131
	v_lshlrev_b32_e32 v129, 5, v131
	s_ashr_i32 s67, s66, 31
	v_and_b32_e32 v128, 0xffff0, v128
	v_and_b32_e32 v129, 32, v129
	s_lshl_b64 s[66:67], s[66:67], 12
	v_add_u32_e32 v129, v129, v134
	v_add_lshl_u32 v128, v133, v128, 12
	s_add_u32 s66, s54, s66
	v_lshl_add_u32 v164, v129, 1, v128
	s_addc_u32 s67, s55, s67
	v_lshl_add_u64 v[128:129], s[66:67], 0, v[164:165]
	v_readfirstlane_b32 s4, v137
	ds_read_b128 v[140:143], v138
	ds_read_b128 v[144:147], v138 offset:1024
	ds_read_b128 v[148:151], v138 offset:2048
	ds_read_b128 v[152:155], v138 offset:3072
	ds_read_b128 v[156:159], v192
	ds_read_b128 v[160:163], v192 offset:1024
	ds_read_b128 v[194:197], v191
	ds_read_b128 v[198:201], v191 offset:1024
	ds_read_b128 v[202:205], v190
	ds_read_b128 v[206:209], v190 offset:1024
	ds_read_b128 v[210:213], v189
	ds_read_b128 v[214:217], v189 offset:1024
	v_lshl_add_u64 v[138:139], v[128:129], 0, s[58:59]
	s_mov_b32 m0, s4
	v_readfirstlane_b32 s4, v136
	global_load_lds_dwordx4 v[138:139], off
	v_lshl_add_u64 v[128:129], v[128:129], 0, s[60:61]
	s_mov_b32 m0, s4
	s_ashr_i32 s65, s64, 31
	global_load_lds_dwordx4 v[128:129], off
	s_waitcnt vmcnt(10)
	s_barrier
	s_waitcnt lgkmcnt(0)
	s_setprio 1
	s_waitcnt lgkmcnt(0)
	v_mfma_f32_16x16x32_bf16 v[124:127], v[140:143], v[156:159], v[124:127]
	v_mfma_f32_16x16x32_bf16 v[120:123], v[148:151], v[156:159], v[120:123]
	v_mfma_f32_16x16x32_bf16 v[116:119], v[140:143], v[194:197], v[116:119]
	v_mfma_f32_16x16x32_bf16 v[112:115], v[148:151], v[194:197], v[112:115]
	v_mfma_f32_16x16x32_bf16 v[108:111], v[140:143], v[202:205], v[108:111]
	v_mfma_f32_16x16x32_bf16 v[104:107], v[148:151], v[202:205], v[104:107]
	v_mfma_f32_16x16x32_bf16 v[100:103], v[140:143], v[210:213], v[100:103]
	v_mfma_f32_16x16x32_bf16 v[96:99], v[148:151], v[210:213], v[96:99]
	v_mfma_f32_16x16x32_bf16 v[124:127], v[144:147], v[160:163], v[124:127]
	v_mfma_f32_16x16x32_bf16 v[120:123], v[152:155], v[160:163], v[120:123]
	v_mfma_f32_16x16x32_bf16 v[116:119], v[144:147], v[198:201], v[116:119]
	v_mfma_f32_16x16x32_bf16 v[112:115], v[152:155], v[198:201], v[112:115]
	v_mfma_f32_16x16x32_bf16 v[108:111], v[144:147], v[206:209], v[108:111]
	v_mfma_f32_16x16x32_bf16 v[104:107], v[152:155], v[206:209], v[104:107]
	v_mfma_f32_16x16x32_bf16 v[100:103], v[144:147], v[214:217], v[100:103]
	v_mfma_f32_16x16x32_bf16 v[96:99], v[152:155], v[214:217], v[96:99]
	s_setprio 0
	s_barrier
	ds_read_b128 v[136:139], v135
	ds_read_b128 v[218:221], v135 offset:1024
	ds_read_b128 v[222:225], v135 offset:2048
	ds_read_b128 v[226:229], v135 offset:3072
	s_barrier
	s_waitcnt lgkmcnt(0)
	s_setprio 1
	s_waitcnt lgkmcnt(0)
	v_mfma_f32_16x16x32_bf16 v[92:95], v[136:139], v[156:159], v[92:95]
	v_mfma_f32_16x16x32_bf16 v[88:91], v[222:225], v[156:159], v[88:91]
	v_mfma_f32_16x16x32_bf16 v[84:87], v[136:139], v[194:197], v[84:87]
	v_mfma_f32_16x16x32_bf16 v[80:83], v[222:225], v[194:197], v[80:83]
	v_mfma_f32_16x16x32_bf16 v[76:79], v[136:139], v[202:205], v[76:79]
	v_mfma_f32_16x16x32_bf16 v[72:75], v[222:225], v[202:205], v[72:75]
	v_mfma_f32_16x16x32_bf16 v[68:71], v[136:139], v[210:213], v[68:71]
	v_mfma_f32_16x16x32_bf16 v[64:67], v[222:225], v[210:213], v[64:67]
	v_mfma_f32_16x16x32_bf16 v[156:159], v[218:221], v[160:163], v[92:95]
	v_mfma_f32_16x16x32_bf16 v[160:163], v[226:229], v[160:163], v[88:91]
	v_mfma_f32_16x16x32_bf16 v[194:197], v[218:221], v[198:201], v[84:87]
	v_mfma_f32_16x16x32_bf16 v[198:201], v[226:229], v[198:201], v[80:83]
	v_mfma_f32_16x16x32_bf16 v[202:205], v[218:221], v[206:209], v[76:79]
	v_mfma_f32_16x16x32_bf16 v[206:209], v[226:229], v[206:209], v[72:75]
	v_mfma_f32_16x16x32_bf16 v[210:213], v[218:221], v[214:217], v[68:71]
	v_mfma_f32_16x16x32_bf16 v[214:217], v[226:229], v[214:217], v[64:67]
	s_setprio 0
	s_barrier
	s_nop 0
	ds_read_b128 v[64:67], v192 offset:16384
	ds_read_b128 v[68:71], v192 offset:17408
	ds_read_b128 v[72:75], v191 offset:16384
	ds_read_b128 v[76:79], v191 offset:17408
	ds_read_b128 v[80:83], v190 offset:16384
	ds_read_b128 v[84:87], v190 offset:17408
	ds_read_b128 v[88:91], v189 offset:16384
	ds_read_b128 v[92:95], v189 offset:17408
	s_waitcnt vmcnt(4)
	s_barrier
	s_waitcnt lgkmcnt(0)
	s_setprio 1
	s_waitcnt lgkmcnt(0)
	v_mfma_f32_16x16x32_bf16 v[60:63], v[140:143], v[64:67], v[60:63]
	v_mfma_f32_16x16x32_bf16 v[56:59], v[148:151], v[64:67], v[56:59]
	v_mfma_f32_16x16x32_bf16 v[52:55], v[140:143], v[72:75], v[52:55]
	v_mfma_f32_16x16x32_bf16 v[48:51], v[148:151], v[72:75], v[48:51]
	v_mfma_f32_16x16x32_bf16 v[230:233], v[140:143], v[80:83], v[44:47]
	v_mfma_f32_16x16x32_bf16 v[234:237], v[148:151], v[80:83], v[40:43]
	v_mfma_f32_16x16x32_bf16 v[140:143], v[140:143], v[88:91], v[36:39]
	v_mfma_f32_16x16x32_bf16 v[148:151], v[148:151], v[88:91], v[32:35]
	v_mfma_f32_16x16x32_bf16 v[32:35], v[144:147], v[68:71], v[60:63]
	v_mfma_f32_16x16x32_bf16 v[36:39], v[152:155], v[68:71], v[56:59]
	v_mfma_f32_16x16x32_bf16 v[40:43], v[144:147], v[76:79], v[52:55]
	v_mfma_f32_16x16x32_bf16 v[44:47], v[152:155], v[76:79], v[48:51]
	v_mfma_f32_16x16x32_bf16 v[48:51], v[144:147], v[84:87], v[230:233]
	v_mfma_f32_16x16x32_bf16 v[52:55], v[152:155], v[84:87], v[234:237]
	v_mfma_f32_16x16x32_bf16 v[56:59], v[144:147], v[92:95], v[140:143]
	v_mfma_f32_16x16x32_bf16 v[60:63], v[152:155], v[92:95], v[148:151]
	s_setprio 0
	s_setprio 1
	v_mfma_f32_16x16x32_bf16 v[28:31], v[136:139], v[64:67], v[28:31]
	v_mfma_f32_16x16x32_bf16 v[24:27], v[222:225], v[64:67], v[24:27]
	v_mfma_f32_16x16x32_bf16 v[20:23], v[136:139], v[72:75], v[20:23]
	v_mfma_f32_16x16x32_bf16 v[64:67], v[222:225], v[72:75], v[16:19]
	v_mfma_f32_16x16x32_bf16 v[12:15], v[136:139], v[80:83], v[12:15]
	v_mfma_f32_16x16x32_bf16 v[8:11], v[222:225], v[80:83], v[8:11]
	v_mfma_f32_16x16x32_bf16 v[72:75], v[136:139], v[88:91], v[4:7]
	v_mfma_f32_16x16x32_bf16 v[80:83], v[222:225], v[88:91], v[0:3]
	v_mfma_f32_16x16x32_bf16 v[0:3], v[218:221], v[68:71], v[28:31]
	v_mfma_f32_16x16x32_bf16 v[4:7], v[226:229], v[68:71], v[24:27]
	v_mfma_f32_16x16x32_bf16 v[16:19], v[218:221], v[76:79], v[20:23]
	v_mfma_f32_16x16x32_bf16 v[20:23], v[226:229], v[76:79], v[64:67]
	v_mfma_f32_16x16x32_bf16 v[64:67], v[218:221], v[84:87], v[12:15]
	v_mfma_f32_16x16x32_bf16 v[68:71], v[226:229], v[84:87], v[8:11]
	v_mfma_f32_16x16x32_bf16 v[72:75], v[218:221], v[92:95], v[72:75]
	v_mfma_f32_16x16x32_bf16 v[76:79], v[226:229], v[92:95], v[80:83]
	s_setprio 0
	s_barrier
	ds_read_b128 v[12:15], v130
	ds_read_b128 v[8:11], v130 offset:1024
	ds_read_b128 v[24:27], v130 offset:2048
	ds_read_b128 v[80:83], v130 offset:3072
	ds_read_b128 v[140:143], v192 offset:32768
	ds_read_b128 v[148:151], v192 offset:33792
	ds_read_b128 v[218:221], v191 offset:32768
	ds_read_b128 v[222:225], v191 offset:33792
	ds_read_b128 v[226:229], v190 offset:32768
	ds_read_b128 v[230:233], v190 offset:33792
	ds_read_b128 v[234:237], v189 offset:32768
	ds_read_b128 v[238:241], v189 offset:33792
	s_waitcnt vmcnt(2)
	s_barrier
	s_waitcnt lgkmcnt(0)
	s_setprio 1
	s_waitcnt lgkmcnt(0)
	v_mfma_f32_16x16x32_bf16 v[28:31], v[12:15], v[140:143], v[124:127]
	v_mfma_f32_16x16x32_bf16 v[84:87], v[24:27], v[140:143], v[120:123]
	v_mfma_f32_16x16x32_bf16 v[88:91], v[12:15], v[218:221], v[116:119]
	v_mfma_f32_16x16x32_bf16 v[92:95], v[24:27], v[218:221], v[112:115]
	v_mfma_f32_16x16x32_bf16 v[108:111], v[12:15], v[226:229], v[108:111]
	v_mfma_f32_16x16x32_bf16 v[104:107], v[24:27], v[226:229], v[104:107]
	v_mfma_f32_16x16x32_bf16 v[100:103], v[12:15], v[234:237], v[100:103]
	v_mfma_f32_16x16x32_bf16 v[96:99], v[24:27], v[234:237], v[96:99]
	v_mfma_f32_16x16x32_bf16 v[152:155], v[8:11], v[148:151], v[28:31]
	v_mfma_f32_16x16x32_bf16 v[144:147], v[80:83], v[148:151], v[84:87]
	v_mfma_f32_16x16x32_bf16 v[136:139], v[8:11], v[222:225], v[88:91]
	v_mfma_f32_16x16x32_bf16 v[128:131], v[80:83], v[222:225], v[92:95]
	v_mfma_f32_16x16x32_bf16 v[120:123], v[8:11], v[230:233], v[108:111]
	v_mfma_f32_16x16x32_bf16 v[112:115], v[80:83], v[230:233], v[104:107]
	v_mfma_f32_16x16x32_bf16 v[104:107], v[8:11], v[238:241], v[100:103]
	v_mfma_f32_16x16x32_bf16 v[28:31], v[80:83], v[238:241], v[96:99]
	s_setprio 0
	s_barrier
	ds_read_b128 v[92:95], v132
	ds_read_b128 v[84:87], v132 offset:1024
	ds_read_b128 v[96:99], v132 offset:2048
	ds_read_b128 v[88:91], v132 offset:3072
	s_waitcnt vmcnt(0)
	s_barrier
	s_waitcnt lgkmcnt(0)
	s_setprio 1
	s_waitcnt lgkmcnt(0)
	v_mfma_f32_16x16x32_bf16 v[100:103], v[92:95], v[140:143], v[156:159]
	v_mfma_f32_16x16x32_bf16 v[108:111], v[96:99], v[140:143], v[160:163]
	v_mfma_f32_16x16x32_bf16 v[116:119], v[92:95], v[218:221], v[194:197]
	v_mfma_f32_16x16x32_bf16 v[124:127], v[96:99], v[218:221], v[198:201]
	v_mfma_f32_16x16x32_bf16 v[160:163], v[92:95], v[226:229], v[202:205]
	v_mfma_f32_16x16x32_bf16 v[194:197], v[96:99], v[226:229], v[206:209]
	v_mfma_f32_16x16x32_bf16 v[198:201], v[92:95], v[234:237], v[210:213]
	v_mfma_f32_16x16x32_bf16 v[202:205], v[96:99], v[234:237], v[214:217]
	v_mfma_f32_16x16x32_bf16 v[156:159], v[84:87], v[148:151], v[100:103]
	v_mfma_f32_16x16x32_bf16 v[148:151], v[88:91], v[148:151], v[108:111]
	v_mfma_f32_16x16x32_bf16 v[140:143], v[84:87], v[222:225], v[116:119]
	v_mfma_f32_16x16x32_bf16 v[132:135], v[88:91], v[222:225], v[124:127]
	v_mfma_f32_16x16x32_bf16 v[124:127], v[84:87], v[230:233], v[160:163]
	v_mfma_f32_16x16x32_bf16 v[116:119], v[88:91], v[230:233], v[194:197]
	v_mfma_f32_16x16x32_bf16 v[108:111], v[84:87], v[238:241], v[198:201]
	v_mfma_f32_16x16x32_bf16 v[100:103], v[88:91], v[238:241], v[202:205]
	s_setprio 0
	s_lshl_b64 s[66:67], s[64:65], 2
	s_barrier
	v_mbcnt_lo_u32_b32 v162, -1, 0
	v_mbcnt_hi_u32_b32 v162, -1, v162
	s_add_u32 s66, s87, s66
	v_add_u32_e32 v160, s76, v162
	s_addc_u32 s67, s88, s67
	v_and_b32_e32 v164, 0x100, v160
	v_and_b32_e32 v162, 15, v162
	v_lshl_add_u64 v[160:161], s[66:67], 0, v[164:165]
	v_lshlrev_b32_e32 v164, 2, v162
	v_lshl_add_u64 v[160:161], v[160:161], 0, v[164:165]
	global_load_dword v178, v[160:161], off
	global_load_dword v176, v[160:161], off offset:64
	global_load_dword v174, v[160:161], off offset:128
	global_load_dword v164, v[160:161], off offset:192
	global_load_dword v172, v[160:161], off offset:512
	global_load_dword v170, v[160:161], off offset:576
	global_load_dword v168, v[160:161], off offset:640
	global_load_dword v166, v[160:161], off offset:704
	v_mbcnt_lo_u32_b32 v194, -1, 0
	v_mbcnt_hi_u32_b32 v194, -1, v194
	s_mov_b64 s[66:67], -1
	v_add_u32_e32 v160, s76, v194
	v_bfe_u32 v161, v160, 8, 1
	v_ashrrev_i32_e32 v196, 6, v160
	v_bfe_u32 v160, v194, 4, 2
	v_and_b32_e32 v198, 3, v196
	v_and_b32_e32 v195, 15, v194
	s_cmp_gt_i32 s74, 1
	v_lshlrev_b32_e32 v193, 6, v161
	v_lshlrev_b32_e32 v197, 4, v160
	s_cbranch_scc0 .LBB0_113
	v_lshlrev_b32_e32 v161, 6, v198
	v_or3_b32 v160, v193, v195, s64
	v_or3_b32 v161, v161, v197, s62
	v_lshl_add_u32 v199, v160, 12, v161
	s_waitcnt vmcnt(0)
	v_mul_f32_e32 v160, v178, v178
	v_pk_mul_f32 v[200:201], v[152:153], v[160:161] op_sel_hi:[1,0]
	v_pk_mul_f32 v[162:163], v[154:155], v[160:161] op_sel_hi:[1,0]
	v_pk_mul_f32 v[202:203], v[158:159], v[160:161] op_sel_hi:[1,0]
	v_pk_mul_f32 v[204:205], v[156:157], v[160:161] op_sel_hi:[1,0]
	v_mul_f32_e32 v160, v144, v200
	v_mul_f32_e32 v161, v145, v201
	v_cvt_pk_bf16_f32 v160, v160, v161
	v_mul_f32_e32 v161, v146, v162
	v_mul_f32_e32 v162, v147, v163
	v_cvt_pk_bf16_f32 v161, v161, v162
	v_mul_f32_e32 v162, v148, v204
	v_mul_f32_e32 v163, v149, v205
	v_cvt_pk_bf16_f32 v162, v162, v163
	v_mul_f32_e32 v163, v150, v202
	v_mul_f32_e32 v200, v151, v203
	v_cvt_pk_bf16_f32 v163, v163, v200
	global_store_dwordx4 v199, v[160:163], s[6:7]
	v_add_u32_e32 v206, 0x10000, v199
	s_mov_b64 s[66:67], 0
	v_mul_f32_e32 v160, v176, v176
	v_pk_mul_f32 v[200:201], v[136:137], v[160:161] op_sel_hi:[1,0]
	v_pk_mul_f32 v[162:163], v[138:139], v[160:161] op_sel_hi:[1,0]
	v_pk_mul_f32 v[202:203], v[142:143], v[160:161] op_sel_hi:[1,0]
	v_pk_mul_f32 v[204:205], v[140:141], v[160:161] op_sel_hi:[1,0]
	v_mul_f32_e32 v160, v128, v200
	v_mul_f32_e32 v161, v129, v201
	v_cvt_pk_bf16_f32 v160, v160, v161
	v_mul_f32_e32 v161, v130, v162
	v_mul_f32_e32 v162, v131, v163
	v_cvt_pk_bf16_f32 v161, v161, v162
	v_mul_f32_e32 v162, v132, v204
	v_mul_f32_e32 v163, v133, v205
	v_cvt_pk_bf16_f32 v162, v162, v163
	v_mul_f32_e32 v163, v134, v202
	v_mul_f32_e32 v200, v135, v203
	v_cvt_pk_bf16_f32 v163, v163, v200
	global_store_dwordx4 v206, v[160:163], s[6:7]
	v_add_u32_e32 v206, 0x20000, v199
	v_add_u32_e32 v199, 0x30000, v199
	v_mul_f32_e32 v160, v174, v174
	v_pk_mul_f32 v[200:201], v[120:121], v[160:161] op_sel_hi:[1,0]
	v_pk_mul_f32 v[162:163], v[122:123], v[160:161] op_sel_hi:[1,0]
	v_pk_mul_f32 v[202:203], v[126:127], v[160:161] op_sel_hi:[1,0]
	v_pk_mul_f32 v[204:205], v[124:125], v[160:161] op_sel_hi:[1,0]
	v_mul_f32_e32 v160, v112, v200
	v_mul_f32_e32 v161, v113, v201
	v_cvt_pk_bf16_f32 v160, v160, v161
	v_mul_f32_e32 v161, v114, v162
	v_mul_f32_e32 v162, v115, v163
	v_cvt_pk_bf16_f32 v161, v161, v162
	v_mul_f32_e32 v162, v116, v204
	v_mul_f32_e32 v163, v117, v205
	v_cvt_pk_bf16_f32 v162, v162, v163
	v_mul_f32_e32 v163, v118, v202
	v_mul_f32_e32 v200, v119, v203
	v_cvt_pk_bf16_f32 v163, v163, v200
	global_store_dwordx4 v206, v[160:163], s[6:7]
	s_nop 1
	v_mul_f32_e32 v160, v164, v164
	v_pk_mul_f32 v[200:201], v[104:105], v[160:161] op_sel_hi:[1,0]
	v_pk_mul_f32 v[162:163], v[106:107], v[160:161] op_sel_hi:[1,0]
	v_pk_mul_f32 v[202:203], v[110:111], v[160:161] op_sel_hi:[1,0]
	v_pk_mul_f32 v[204:205], v[108:109], v[160:161] op_sel_hi:[1,0]
	v_mul_f32_e32 v160, v28, v200
	v_mul_f32_e32 v161, v29, v201
	v_cvt_pk_bf16_f32 v160, v160, v161
	v_mul_f32_e32 v161, v30, v162
	v_mul_f32_e32 v162, v31, v163
	v_cvt_pk_bf16_f32 v161, v161, v162
	v_mul_f32_e32 v162, v100, v204
	v_mul_f32_e32 v163, v101, v205
	v_cvt_pk_bf16_f32 v162, v162, v163
	v_mul_f32_e32 v163, v102, v202
	v_mul_f32_e32 v200, v103, v203
	v_cvt_pk_bf16_f32 v163, v163, v200

.LBB0_177:
	v_bfe_i32 v5, v136, 27, 1
	v_lshlrev_b32_e32 v135, 4, v136
	v_lshrrev_b32_e32 v5, 22, v5
	v_add_u32_e32 v5, v135, v5
	v_and_b32_e32 v5, 0xfffffc00, v5
	v_sub_u32_e32 v5, v135, v5
	v_lshrrev_b32_e32 v6, 4, v5
	v_bitop3_b32 v5, v6, v5, 32 bitop3:0x6c
	v_ashrrev_i32_e32 v6, 31, v5
	v_lshrrev_b32_e32 v6, 26, v6
	v_add_u32_e32 v6, v5, v6
	v_ashrrev_i32_e32 v157, 6, v6
	v_and_b32_e32 v6, 0xc0, v6
	v_sub_u32_e32 v5, v5, v6
	v_ashrrev_i16_sdwa v5, v134, sext(v5) dst_sel:DWORD dst_unused:UNUSED_PAD src0_sel:DWORD src1_sel:BYTE_0
	v_and_b32_e32 v2, 15, v0
	v_and_b32_e32 v3, 48, v0
	v_bfe_i32 v158, v5, 0, 16
	v_and_b32_e32 v5, 32, v0
	v_lshlrev_b32_e32 v8, 2, v0
	v_lshlrev_b32_e32 v0, 6, v0
	s_movk_i32 s65, 0x3f0
	v_lshlrev_b32_e32 v2, 6, v2
	v_and_b32_e32 v8, 32, v8
	v_and_b32_e32 v0, 0x3c0, v0
	v_ashrrev_i32_e32 v4, 31, v136
	v_bitop3_b32 v5, v135, v5, s65 bitop3:0x6c
	v_or_b32_e32 v7, v2, v3
	v_bitop3_b32 v2, v2, v8, v3 bitop3:0x36
	v_bitop3_b32 v3, v0, v8, v3 bitop3:0x36
	v_lshlrev_b32_e32 v0, 11, v136
	v_lshrrev_b32_e32 v4, 26, v4
	v_and_or_b32 v0, v0, s76, v5
	v_lshlrev_b32_e32 v5, 3, v136
	s_bfe_u32 s64, s85, 0x30003
	v_add_u32_e32 v4, v136, v4
	s_mov_b32 s65, 0x14000
	v_and_b32_e32 v5, 0xfffffc00, v5
	s_lshl_b32 s24, s64, 14
	v_ashrrev_i32_e32 v156, 6, v4
	v_bitop3_b32 v10, v7, s65, v8 bitop3:0xde
	s_mov_b32 s65, 0x1c000
	v_add_u32_e32 v128, v0, v5
	v_bitop3_b32 v9, v7, s74, v8 bitop3:0xde
	v_bitop3_b32 v11, v7, s75, v8 bitop3:0xde
	v_bitop3_b32 v7, v7, s65, v8 bitop3:0xde
	v_lshl_add_u64 v[130:131], s[24:25], 0, v[128:129]
	v_lshlrev_b32_e32 v0, 15, v156
	s_lshl_b32 s24, s85, 17
	s_and_b32 s65, s85, 7
	v_and_b32_e32 v0, 0xffff0000, v0
	s_and_b32 s24, s24, 0x1800000
	s_lshl_b32 s65, s65, 20
	v_lshl_add_u32 v0, v157, 12, v0
	s_or_b32 s24, s24, s65
	v_lshlrev_b32_e32 v6, 6, v136
	v_lshlrev_b32_e32 v1, 13, v1
	v_and_or_b32 v0, v4, 64, v0
	s_add_u32 s66, s24, s90
	v_and_b32_e32 v6, 0x3000, v6
	v_or_b32_e32 v8, 0x800, v1
	v_or_b32_e32 v12, 0x1000, v1
	v_or_b32_e32 v13, 0x1800, v1
	v_lshl_add_u32 v128, v158, 1, v0
	s_addc_u32 s67, 0, 0
	v_mov_b32_e32 v0, 0
	v_lshl_add_u64 v[132:133], s[66:67], 0, v[128:129]
	s_mov_b32 s24, -2
	v_add_u32_e32 v162, v9, v6
	v_add_u32_e32 v153, v2, v1
	v_add_u32_e32 v152, v3, v8
	v_add_u32_e32 v151, v3, v12
	v_add_u32_e32 v150, v3, v13
	v_add_u32_e32 v161, 0xc000, v135
	v_add_u32_e32 v160, 0xe000, v135
	v_add_u32_e32 v159, v10, v6
	v_add_u32_e32 v149, 0x10000, v135
	v_add_u32_e32 v148, 0x12000, v135
	v_add_u32_e32 v147, 0x2000, v135
	v_add_u32_e32 v146, 0x14000, v135
	v_add_u32_e32 v145, 0x16000, v135
	v_add_u32_e32 v155, v11, v6
	v_add_u32_e32 v144, 0x4000, v135
	v_add_u32_e32 v143, 0x6000, v135
	v_add_u32_e32 v154, v7, v6
	v_add_u32_e32 v142, 0x18000, v135
	v_add_u32_e32 v141, 0x1a000, v135
	v_add_u32_e32 v140, 0x8000, v135
	v_add_u32_e32 v139, 0xa000, v135
	v_add_u32_e32 v138, 0x1c000, v135
	v_add_u32_e32 v137, 0x1e000, v135
	v_mov_b32_e32 v1, v0
	v_mov_b32_e32 v2, v0
	v_mov_b32_e32 v3, v0
	v_mov_b32_e32 v4, v0
	v_mov_b32_e32 v5, v0
	v_mov_b32_e32 v6, v0
	v_mov_b32_e32 v7, v0
	v_mov_b32_e32 v8, v0
	v_mov_b32_e32 v9, v0
	v_mov_b32_e32 v10, v0
	v_mov_b32_e32 v11, v0
	v_mov_b32_e32 v12, v0
	v_mov_b32_e32 v13, v0
	v_mov_b32_e32 v14, v0
	v_mov_b32_e32 v15, v0
	v_mov_b32_e32 v16, v0
	v_mov_b32_e32 v17, v0
	v_mov_b32_e32 v18, v0
	v_mov_b32_e32 v19, v0
	v_mov_b32_e32 v20, v0
	v_mov_b32_e32 v21, v0
	v_mov_b32_e32 v22, v0
	v_mov_b32_e32 v23, v0
	v_mov_b32_e32 v24, v0
	v_mov_b32_e32 v25, v0
	v_mov_b32_e32 v26, v0
	v_mov_b32_e32 v27, v0
	v_mov_b32_e32 v28, v0
	v_mov_b32_e32 v29, v0
	v_mov_b32_e32 v30, v0
	v_mov_b32_e32 v31, v0
	v_mov_b32_e32 v32, v0
	v_mov_b32_e32 v33, v0
	v_mov_b32_e32 v34, v0
	v_mov_b32_e32 v35, v0
	v_mov_b32_e32 v36, v0
	v_mov_b32_e32 v37, v0
	v_mov_b32_e32 v38, v0
	v_mov_b32_e32 v39, v0
	v_mov_b32_e32 v40, v0
	v_mov_b32_e32 v41, v0
	v_mov_b32_e32 v42, v0
	v_mov_b32_e32 v43, v0
	v_mov_b32_e32 v44, v0
	v_mov_b32_e32 v45, v0
	v_mov_b32_e32 v46, v0
	v_mov_b32_e32 v47, v0
	v_mov_b32_e32 v48, v0
	v_mov_b32_e32 v49, v0
	v_mov_b32_e32 v50, v0
	v_mov_b32_e32 v51, v0
	v_mov_b32_e32 v52, v0
	v_mov_b32_e32 v53, v0
	v_mov_b32_e32 v54, v0
	v_mov_b32_e32 v55, v0
	v_mov_b32_e32 v56, v0
	v_mov_b32_e32 v57, v0
	v_mov_b32_e32 v58, v0
	v_mov_b32_e32 v59, v0
	v_mov_b32_e32 v60, v0
	v_mov_b32_e32 v61, v0
	v_mov_b32_e32 v62, v0
	v_mov_b32_e32 v63, v0
	v_mov_b32_e32 v64, v0
	v_mov_b32_e32 v65, v0
	v_mov_b32_e32 v66, v0
	v_mov_b32_e32 v67, v0
	v_mov_b32_e32 v68, v0
	v_mov_b32_e32 v69, v0
	v_mov_b32_e32 v70, v0
	v_mov_b32_e32 v71, v0
	v_mov_b32_e32 v72, v0
	v_mov_b32_e32 v73, v0
	v_mov_b32_e32 v74, v0
	v_mov_b32_e32 v75, v0
	v_mov_b32_e32 v76, v0
	v_mov_b32_e32 v77, v0
	v_mov_b32_e32 v78, v0
	v_mov_b32_e32 v79, v0
	v_mov_b32_e32 v80, v0
	v_mov_b32_e32 v81, v0
	v_mov_b32_e32 v82, v0
	v_mov_b32_e32 v83, v0
	v_mov_b32_e32 v84, v0
	v_mov_b32_e32 v85, v0
	v_mov_b32_e32 v86, v0
	v_mov_b32_e32 v87, v0
	v_mov_b32_e32 v88, v0
	v_mov_b32_e32 v89, v0
	v_mov_b32_e32 v90, v0
	v_mov_b32_e32 v91, v0
	v_mov_b32_e32 v92, v0
	v_mov_b32_e32 v93, v0
	v_mov_b32_e32 v94, v0
	v_mov_b32_e32 v95, v0
	v_mov_b32_e32 v96, v0
	v_mov_b32_e32 v97, v0
	v_mov_b32_e32 v98, v0
	v_mov_b32_e32 v99, v0
	v_mov_b32_e32 v100, v0
	v_mov_b32_e32 v101, v0
	v_mov_b32_e32 v102, v0
	v_mov_b32_e32 v103, v0
	v_mov_b32_e32 v104, v0
	v_mov_b32_e32 v105, v0
	v_mov_b32_e32 v106, v0
	v_mov_b32_e32 v107, v0
	v_mov_b32_e32 v108, v0
	v_mov_b32_e32 v109, v0
	v_mov_b32_e32 v110, v0
	v_mov_b32_e32 v111, v0
	v_mov_b32_e32 v112, v0
	v_mov_b32_e32 v113, v0
	v_mov_b32_e32 v114, v0
	v_mov_b32_e32 v115, v0
	v_mov_b32_e32 v116, v0
	v_mov_b32_e32 v117, v0
	v_mov_b32_e32 v118, v0
	v_mov_b32_e32 v119, v0
	v_mov_b32_e32 v120, v0
	v_mov_b32_e32 v121, v0
	v_mov_b32_e32 v122, v0
	v_mov_b32_e32 v123, v0
	v_mov_b32_e32 v124, v0
	v_mov_b32_e32 v125, v0
	v_mov_b32_e32 v126, v0
	v_mov_b32_e32 v127, v0
	s_barrier
	v_readlane_b32 s98, v242, 1
	s_lshl_b32 s98, s98, 10
	v_lshl_add_u64 v[228:229], s[50:51], 0, v[132:133]
	s_mov_b64 s[66:67], 0xe080080
	s_add_i32 s65, s98, 0xc000
	v_lshl_add_u64 v[166:167], v[228:229], 0, s[66:67]
	s_mov_b32 m0, s65
	s_mov_b64 s[66:67], 0xe0c0080
	s_add_i32 s65, s98, 0xe000
	global_load_lds_dwordx4 v[166:167], off
	v_lshl_add_u64 v[166:167], v[228:229], 0, s[66:67]
	s_mov_b32 m0, s65
	s_nop 0
	global_load_lds_dwordx4 v[166:167], off
.LBB0_178:
	ds_read_b128 v[164:167], v162
	ds_read_b128 v[168:171], v162 offset:1024
	ds_read_b128 v[172:175], v162 offset:2048
	ds_read_b128 v[176:179], v162 offset:3072
	ds_read_b128 v[180:183], v153
	ds_read_b128 v[184:187], v153 offset:1024
	ds_read_b128 v[188:191], v152
	ds_read_b128 v[192:195], v152 offset:1024
	ds_read_b128 v[196:199], v151
	ds_read_b128 v[200:203], v151 offset:1024
	ds_read_b128 v[204:207], v150
	ds_read_b128 v[208:211], v150 offset:1024
	s_waitcnt lgkmcnt(8)
	s_waitcnt vmcnt(10)
	s_barrier
	s_waitcnt lgkmcnt(0)
	s_waitcnt lgkmcnt(0)
	v_mfma_f32_16x16x32_bf16 v[124:127], v[164:167], v[180:183], v[124:127]
	v_mfma_f32_16x16x32_bf16 v[120:123], v[172:175], v[180:183], v[120:123]
	v_mfma_f32_16x16x32_bf16 v[116:119], v[164:167], v[188:191], v[116:119]
	v_mfma_f32_16x16x32_bf16 v[112:115], v[172:175], v[188:191], v[112:115]
	v_mfma_f32_16x16x32_bf16 v[108:111], v[164:167], v[196:199], v[108:111]
	v_mfma_f32_16x16x32_bf16 v[104:107], v[172:175], v[196:199], v[104:107]
	v_mfma_f32_16x16x32_bf16 v[100:103], v[164:167], v[204:207], v[100:103]
	v_mfma_f32_16x16x32_bf16 v[96:99], v[172:175], v[204:207], v[96:99]
	v_mfma_f32_16x16x32_bf16 v[124:127], v[168:171], v[184:187], v[124:127]
	v_mfma_f32_16x16x32_bf16 v[120:123], v[176:179], v[184:187], v[120:123]
	v_mfma_f32_16x16x32_bf16 v[116:119], v[168:171], v[192:195], v[116:119]
	v_mfma_f32_16x16x32_bf16 v[112:115], v[176:179], v[192:195], v[112:115]
	v_mfma_f32_16x16x32_bf16 v[108:111], v[168:171], v[200:203], v[108:111]
	v_mfma_f32_16x16x32_bf16 v[104:107], v[176:179], v[200:203], v[104:107]
	v_mfma_f32_16x16x32_bf16 v[100:103], v[168:171], v[208:211], v[100:103]
	v_mfma_f32_16x16x32_bf16 v[96:99], v[176:179], v[208:211], v[96:99]
	s_barrier
	v_lshl_add_u64 v[230:231], s[50:51], 0, v[130:131]
	s_mov_b64 s[66:67], 0x1880000
	s_add_i32 s65, s98, 0x10000
	v_lshl_add_u64 v[232:233], v[230:231], 0, s[66:67]
	s_mov_b32 m0, s65
	s_mov_b64 s[66:67], 0x1881000
	s_add_i32 s65, s98, 0x12000
	ds_read_b128 v[212:215], v159
	ds_read_b128 v[216:219], v159 offset:1024
	ds_read_b128 v[220:223], v159 offset:2048
	ds_read_b128 v[224:227], v159 offset:3072
	global_load_lds_dwordx4 v[232:233], off
	v_lshl_add_u64 v[232:233], v[230:231], 0, s[66:67]
	s_mov_b32 m0, s65
	s_nop 0
	global_load_lds_dwordx4 v[232:233], off
	s_mov_b64 s[66:67], 0xe000100
	s_mov_b32 s65, s98
	v_lshl_add_u64 v[232:233], v[228:229], 0, s[66:67]
	s_mov_b32 m0, s65
	s_mov_b64 s[66:67], 0xe040100
	s_add_i32 s65, s98, 0x2000
	global_load_lds_dwordx4 v[232:233], off
	v_lshl_add_u64 v[232:233], v[228:229], 0, s[66:67]
	s_mov_b32 m0, s65
	s_nop 0
	global_load_lds_dwordx4 v[232:233], off
	s_waitcnt vmcnt(12)
	s_barrier
	s_waitcnt lgkmcnt(0)
	s_waitcnt lgkmcnt(0)
	v_mfma_f32_16x16x32_bf16 v[92:95], v[212:215], v[180:183], v[92:95]
	v_mfma_f32_16x16x32_bf16 v[88:91], v[220:223], v[180:183], v[88:91]
	v_mfma_f32_16x16x32_bf16 v[84:87], v[212:215], v[188:191], v[84:87]
	v_mfma_f32_16x16x32_bf16 v[80:83], v[220:223], v[188:191], v[80:83]
	v_mfma_f32_16x16x32_bf16 v[76:79], v[212:215], v[196:199], v[76:79]
	v_mfma_f32_16x16x32_bf16 v[72:75], v[220:223], v[196:199], v[72:75]
	v_mfma_f32_16x16x32_bf16 v[68:71], v[212:215], v[204:207], v[68:71]
	v_mfma_f32_16x16x32_bf16 v[64:67], v[220:223], v[204:207], v[64:67]
	v_mfma_f32_16x16x32_bf16 v[92:95], v[216:219], v[184:187], v[92:95]
	v_mfma_f32_16x16x32_bf16 v[88:91], v[224:227], v[184:187], v[88:91]
	v_mfma_f32_16x16x32_bf16 v[84:87], v[216:219], v[192:195], v[84:87]
	v_mfma_f32_16x16x32_bf16 v[80:83], v[224:227], v[192:195], v[80:83]
	v_mfma_f32_16x16x32_bf16 v[76:79], v[216:219], v[200:203], v[76:79]
	v_mfma_f32_16x16x32_bf16 v[72:75], v[224:227], v[200:203], v[72:75]
	v_mfma_f32_16x16x32_bf16 v[68:71], v[216:219], v[208:211], v[68:71]
	v_mfma_f32_16x16x32_bf16 v[64:67], v[224:227], v[208:211], v[64:67]
	s_barrier
	ds_read_b128 v[180:183], v153 offset:16384
	ds_read_b128 v[184:187], v153 offset:17408
	ds_read_b128 v[188:191], v152 offset:16384
	ds_read_b128 v[192:195], v152 offset:17408
	ds_read_b128 v[196:199], v151 offset:16384
	ds_read_b128 v[200:203], v151 offset:17408
	ds_read_b128 v[204:207], v150 offset:16384
	ds_read_b128 v[208:211], v150 offset:17408
	s_mov_b64 s[66:67], 0x1882000
	s_add_i32 s65, s98, 0x14000
	v_lshl_add_u64 v[232:233], v[230:231], 0, s[66:67]
	s_mov_b32 m0, s65
	s_mov_b64 s[66:67], 0x1883000
	s_add_i32 s65, s98, 0x16000
	global_load_lds_dwordx4 v[232:233], off
	v_lshl_add_u64 v[232:233], v[230:231], 0, s[66:67]
	s_mov_b32 m0, s65
	s_nop 0
	global_load_lds_dwordx4 v[232:233], off
	s_barrier
	s_waitcnt lgkmcnt(0)
	s_waitcnt lgkmcnt(0)
	v_mfma_f32_16x16x32_bf16 v[60:63], v[164:167], v[180:183], v[60:63]
	v_mfma_f32_16x16x32_bf16 v[56:59], v[172:175], v[180:183], v[56:59]
	v_mfma_f32_16x16x32_bf16 v[52:55], v[164:167], v[188:191], v[52:55]
	v_mfma_f32_16x16x32_bf16 v[48:51], v[172:175], v[188:191], v[48:51]
	v_mfma_f32_16x16x32_bf16 v[44:47], v[164:167], v[196:199], v[44:47]
	v_mfma_f32_16x16x32_bf16 v[40:43], v[172:175], v[196:199], v[40:43]
	v_mfma_f32_16x16x32_bf16 v[36:39], v[164:167], v[204:207], v[36:39]
	v_mfma_f32_16x16x32_bf16 v[32:35], v[172:175], v[204:207], v[32:35]
	v_mfma_f32_16x16x32_bf16 v[60:63], v[168:171], v[184:187], v[60:63]
	v_mfma_f32_16x16x32_bf16 v[56:59], v[176:179], v[184:187], v[56:59]
	v_mfma_f32_16x16x32_bf16 v[52:55], v[168:171], v[192:195], v[52:55]
	v_mfma_f32_16x16x32_bf16 v[48:51], v[176:179], v[192:195], v[48:51]
	v_mfma_f32_16x16x32_bf16 v[44:47], v[168:171], v[200:203], v[44:47]
	v_mfma_f32_16x16x32_bf16 v[40:43], v[176:179], v[200:203], v[40:43]
	v_mfma_f32_16x16x32_bf16 v[36:39], v[168:171], v[208:211], v[36:39]
	v_mfma_f32_16x16x32_bf16 v[32:35], v[176:179], v[208:211], v[32:35]
	s_barrier
	s_add_i32 s65, s98, 0x4000
	v_lshl_add_u64 v[166:167], v[228:229], 0, s[26:27]
	s_mov_b32 m0, s65
	s_add_i32 s65, s98, 0x6000
	global_load_lds_dwordx4 v[166:167], off
	v_lshl_add_u64 v[166:167], v[228:229], 0, s[28:29]
	s_mov_b32 m0, s65
	s_nop 0
	global_load_lds_dwordx4 v[166:167], off
	s_waitcnt vmcnt(12)
	s_barrier
	v_mfma_f32_16x16x32_bf16 v[28:31], v[212:215], v[180:183], v[28:31]
	v_mfma_f32_16x16x32_bf16 v[24:27], v[220:223], v[180:183], v[24:27]
	v_mfma_f32_16x16x32_bf16 v[20:23], v[212:215], v[188:191], v[20:23]
	v_mfma_f32_16x16x32_bf16 v[16:19], v[220:223], v[188:191], v[16:19]
	v_mfma_f32_16x16x32_bf16 v[12:15], v[212:215], v[196:199], v[12:15]
	v_mfma_f32_16x16x32_bf16 v[8:11], v[220:223], v[196:199], v[8:11]
	v_mfma_f32_16x16x32_bf16 v[4:7], v[212:215], v[204:207], v[4:7]
	v_mfma_f32_16x16x32_bf16 v[0:3], v[220:223], v[204:207], v[0:3]
	v_mfma_f32_16x16x32_bf16 v[28:31], v[216:219], v[184:187], v[28:31]
	v_mfma_f32_16x16x32_bf16 v[24:27], v[224:227], v[184:187], v[24:27]
	v_mfma_f32_16x16x32_bf16 v[20:23], v[216:219], v[192:195], v[20:23]
	v_mfma_f32_16x16x32_bf16 v[16:19], v[224:227], v[192:195], v[16:19]
	v_mfma_f32_16x16x32_bf16 v[12:15], v[216:219], v[200:203], v[12:15]
	v_mfma_f32_16x16x32_bf16 v[8:11], v[224:227], v[200:203], v[8:11]
	v_mfma_f32_16x16x32_bf16 v[4:7], v[216:219], v[208:211], v[4:7]
	v_mfma_f32_16x16x32_bf16 v[0:3], v[224:227], v[208:211], v[0:3]
	s_barrier
	ds_read_b128 v[164:167], v155
	ds_read_b128 v[168:171], v155 offset:1024
	ds_read_b128 v[172:175], v155 offset:2048
	ds_read_b128 v[176:179], v155 offset:3072
	ds_read_b128 v[180:183], v153 offset:32768
	ds_read_b128 v[184:187], v153 offset:33792
	ds_read_b128 v[188:191], v152 offset:32768
	ds_read_b128 v[192:195], v152 offset:33792
	ds_read_b128 v[196:199], v151 offset:32768
	ds_read_b128 v[200:203], v151 offset:33792
	ds_read_b128 v[204:207], v150 offset:32768
	ds_read_b128 v[208:211], v150 offset:33792
	s_waitcnt lgkmcnt(8)
	s_waitcnt vmcnt(10)
	s_barrier
	s_waitcnt lgkmcnt(0)
	s_waitcnt lgkmcnt(0)
	v_mfma_f32_16x16x32_bf16 v[124:127], v[164:167], v[180:183], v[124:127]
	v_mfma_f32_16x16x32_bf16 v[120:123], v[172:175], v[180:183], v[120:123]
	v_mfma_f32_16x16x32_bf16 v[116:119], v[164:167], v[188:191], v[116:119]
	v_mfma_f32_16x16x32_bf16 v[112:115], v[172:175], v[188:191], v[112:115]
	v_mfma_f32_16x16x32_bf16 v[108:111], v[164:167], v[196:199], v[108:111]
	v_mfma_f32_16x16x32_bf16 v[104:107], v[172:175], v[196:199], v[104:107]
	v_mfma_f32_16x16x32_bf16 v[100:103], v[164:167], v[204:207], v[100:103]
	v_mfma_f32_16x16x32_bf16 v[96:99], v[172:175], v[204:207], v[96:99]
	v_mfma_f32_16x16x32_bf16 v[124:127], v[168:171], v[184:187], v[124:127]
	v_mfma_f32_16x16x32_bf16 v[120:123], v[176:179], v[184:187], v[120:123]
	v_mfma_f32_16x16x32_bf16 v[116:119], v[168:171], v[192:195], v[116:119]
	v_mfma_f32_16x16x32_bf16 v[112:115], v[176:179], v[192:195], v[112:115]
	v_mfma_f32_16x16x32_bf16 v[108:111], v[168:171], v[200:203], v[108:111]
	v_mfma_f32_16x16x32_bf16 v[104:107], v[176:179], v[200:203], v[104:107]
	v_mfma_f32_16x16x32_bf16 v[100:103], v[168:171], v[208:211], v[100:103]
	v_mfma_f32_16x16x32_bf16 v[96:99], v[176:179], v[208:211], v[96:99]
	s_barrier
	s_add_i32 s65, s98, 0x18000
	v_lshl_add_u64 v[232:233], v[230:231], 0, s[30:31]
	s_mov_b32 m0, s65
	s_add_i32 s65, s98, 0x1a000
	ds_read_b128 v[212:215], v154
	ds_read_b128 v[216:219], v154 offset:1024
	ds_read_b128 v[220:223], v154 offset:2048
	ds_read_b128 v[224:227], v154 offset:3072
	global_load_lds_dwordx4 v[232:233], off
	v_lshl_add_u64 v[232:233], v[230:231], 0, s[34:35]
	s_mov_b32 m0, s65
	s_nop 0
	global_load_lds_dwordx4 v[232:233], off
	s_add_i32 s65, s98, 0x8000
	v_lshl_add_u64 v[232:233], v[228:229], 0, s[40:41]
	s_mov_b32 m0, s65
	s_add_i32 s65, s98, 0xa000
	global_load_lds_dwordx4 v[232:233], off
	v_lshl_add_u64 v[228:229], v[228:229], 0, s[44:45]
	s_mov_b32 m0, s65
	s_nop 0
	global_load_lds_dwordx4 v[228:229], off
	s_waitcnt vmcnt(12)
	s_barrier
	s_waitcnt lgkmcnt(0)
	s_waitcnt lgkmcnt(0)
	v_mfma_f32_16x16x32_bf16 v[92:95], v[212:215], v[180:183], v[92:95]
	v_mfma_f32_16x16x32_bf16 v[88:91], v[220:223], v[180:183], v[88:91]
	v_mfma_f32_16x16x32_bf16 v[84:87], v[212:215], v[188:191], v[84:87]
	v_mfma_f32_16x16x32_bf16 v[80:83], v[220:223], v[188:191], v[80:83]
	v_mfma_f32_16x16x32_bf16 v[76:79], v[212:215], v[196:199], v[76:79]
	v_mfma_f32_16x16x32_bf16 v[72:75], v[220:223], v[196:199], v[72:75]
	v_mfma_f32_16x16x32_bf16 v[68:71], v[212:215], v[204:207], v[68:71]
	v_mfma_f32_16x16x32_bf16 v[64:67], v[220:223], v[204:207], v[64:67]
	v_mfma_f32_16x16x32_bf16 v[92:95], v[216:219], v[184:187], v[92:95]
	v_mfma_f32_16x16x32_bf16 v[88:91], v[224:227], v[184:187], v[88:91]
	v_mfma_f32_16x16x32_bf16 v[84:87], v[216:219], v[192:195], v[84:87]
	v_mfma_f32_16x16x32_bf16 v[80:83], v[224:227], v[192:195], v[80:83]
	v_mfma_f32_16x16x32_bf16 v[76:79], v[216:219], v[200:203], v[76:79]
	v_mfma_f32_16x16x32_bf16 v[72:75], v[224:227], v[200:203], v[72:75]
	v_mfma_f32_16x16x32_bf16 v[68:71], v[216:219], v[208:211], v[68:71]
	v_mfma_f32_16x16x32_bf16 v[64:67], v[224:227], v[208:211], v[64:67]
	s_barrier
	ds_read_b128 v[180:183], v153 offset:49152
	ds_read_b128 v[184:187], v153 offset:50176
	ds_read_b128 v[188:191], v152 offset:49152
	ds_read_b128 v[192:195], v152 offset:50176
	ds_read_b128 v[196:199], v151 offset:49152
	ds_read_b128 v[200:203], v151 offset:50176
	ds_read_b128 v[204:207], v150 offset:49152
	ds_read_b128 v[208:211], v150 offset:50176
	s_add_i32 s65, s98, 0x1c000
	v_lshl_add_u64 v[232:233], v[230:231], 0, s[46:47]
	s_mov_b32 m0, s65
	s_add_i32 s65, s98, 0x1e000
	global_load_lds_dwordx4 v[232:233], off
	v_lshl_add_u64 v[232:233], v[230:231], 0, s[56:57]
	s_mov_b32 m0, s65
	s_nop 0
	global_load_lds_dwordx4 v[232:233], off
	s_barrier
	s_waitcnt lgkmcnt(0)
	s_waitcnt lgkmcnt(0)
	v_mfma_f32_16x16x32_bf16 v[60:63], v[164:167], v[180:183], v[60:63]
	v_mfma_f32_16x16x32_bf16 v[56:59], v[172:175], v[180:183], v[56:59]
	v_mfma_f32_16x16x32_bf16 v[52:55], v[164:167], v[188:191], v[52:55]
	v_mfma_f32_16x16x32_bf16 v[48:51], v[172:175], v[188:191], v[48:51]
	v_mfma_f32_16x16x32_bf16 v[44:47], v[164:167], v[196:199], v[44:47]
	v_mfma_f32_16x16x32_bf16 v[40:43], v[172:175], v[196:199], v[40:43]
	v_mfma_f32_16x16x32_bf16 v[36:39], v[164:167], v[204:207], v[36:39]
	v_mfma_f32_16x16x32_bf16 v[32:35], v[172:175], v[204:207], v[32:35]
	v_mfma_f32_16x16x32_bf16 v[60:63], v[168:171], v[184:187], v[60:63]
	v_mfma_f32_16x16x32_bf16 v[56:59], v[176:179], v[184:187], v[56:59]
	v_mfma_f32_16x16x32_bf16 v[52:55], v[168:171], v[192:195], v[52:55]
	v_mfma_f32_16x16x32_bf16 v[48:51], v[176:179], v[192:195], v[48:51]
	v_mfma_f32_16x16x32_bf16 v[44:47], v[168:171], v[200:203], v[44:47]
	v_mfma_f32_16x16x32_bf16 v[40:43], v[176:179], v[200:203], v[40:43]
	v_mfma_f32_16x16x32_bf16 v[36:39], v[168:171], v[208:211], v[36:39]
	v_mfma_f32_16x16x32_bf16 v[32:35], v[176:179], v[208:211], v[32:35]
	s_barrier
	v_lshl_add_u64 v[132:133], v[132:133], 0, s[58:59]
	v_lshl_add_u64 v[228:229], s[50:51], 0, v[132:133]
	s_mov_b64 s[66:67], 0xe080080
	s_add_i32 s65, s98, 0xc000
	v_lshl_add_u64 v[166:167], v[228:229], 0, s[66:67]
	s_mov_b32 m0, s65
	s_mov_b64 s[66:67], 0xe0c0080
	s_add_i32 s65, s98, 0xe000
	global_load_lds_dwordx4 v[166:167], off
	v_lshl_add_u64 v[166:167], v[228:229], 0, s[66:67]
	s_mov_b32 m0, s65
	s_nop 0
	global_load_lds_dwordx4 v[166:167], off
	s_waitcnt vmcnt(12)
	s_barrier
	v_mfma_f32_16x16x32_bf16 v[28:31], v[212:215], v[180:183], v[28:31]
	v_mfma_f32_16x16x32_bf16 v[24:27], v[220:223], v[180:183], v[24:27]
	v_mfma_f32_16x16x32_bf16 v[20:23], v[212:215], v[188:191], v[20:23]
	v_mfma_f32_16x16x32_bf16 v[16:19], v[220:223], v[188:191], v[16:19]
	v_mfma_f32_16x16x32_bf16 v[12:15], v[212:215], v[196:199], v[12:15]
	v_mfma_f32_16x16x32_bf16 v[8:11], v[220:223], v[196:199], v[8:11]
	v_mfma_f32_16x16x32_bf16 v[4:7], v[212:215], v[204:207], v[4:7]
	v_mfma_f32_16x16x32_bf16 v[0:3], v[220:223], v[204:207], v[0:3]
	v_mfma_f32_16x16x32_bf16 v[28:31], v[216:219], v[184:187], v[28:31]
	v_mfma_f32_16x16x32_bf16 v[24:27], v[224:227], v[184:187], v[24:27]
	v_mfma_f32_16x16x32_bf16 v[20:23], v[216:219], v[192:195], v[20:23]
	v_mfma_f32_16x16x32_bf16 v[16:19], v[224:227], v[192:195], v[16:19]
	v_mfma_f32_16x16x32_bf16 v[12:15], v[216:219], v[200:203], v[12:15]
	v_mfma_f32_16x16x32_bf16 v[8:11], v[224:227], v[200:203], v[8:11]
	v_mfma_f32_16x16x32_bf16 v[4:7], v[216:219], v[208:211], v[4:7]
	v_mfma_f32_16x16x32_bf16 v[0:3], v[224:227], v[208:211], v[0:3]
	s_add_i32 s24, s24, 2
	v_lshl_add_u64 v[130:131], v[130:131], 0, s[10:11]
	s_cmp_lt_u32 s24, 28
	s_barrier
	s_cbranch_scc1 .LBB0_178
	s_lshl_b32 s24, s85, 5
	s_lshl_b32 s65, s85, 8
	s_and_b32 s24, s24, 0x1800
	s_and_b32 s65, s65, 0x700
	s_or_b32 s24, s65, s24
	v_lshlrev_b32_e32 v128, 3, v156
	v_lshlrev_b32_e32 v130, 5, v156
	v_and_b32_e32 v128, 0xffff0, v128
	v_and_b32_e32 v130, 32, v130
	s_lshl_b32 s65, s24, 12
	v_add_u32_e32 v130, v130, v158
	v_add_lshl_u32 v128, v157, v128, 12
	s_add_u32 s66, s68, s65
	v_lshl_add_u32 v128, v130, 1, v128
	s_addc_u32 s67, s69, 0
	v_lshl_add_u64 v[156:157], s[66:67], 0, v[128:129]
	v_readfirstlane_b32 s65, v161
	ds_read_b128 v[130:133], v162
	ds_read_b128 v[164:167], v162 offset:1024
	ds_read_b128 v[168:171], v162 offset:2048
	ds_read_b128 v[172:175], v162 offset:3072
	ds_read_b128 v[176:179], v153
	ds_read_b128 v[180:183], v153 offset:1024
	ds_read_b128 v[184:187], v152
	ds_read_b128 v[188:191], v152 offset:1024
	ds_read_b128 v[192:195], v151
	ds_read_b128 v[196:199], v151 offset:1024
	ds_read_b128 v[200:203], v150
	ds_read_b128 v[204:207], v150 offset:1024
	v_lshl_add_u64 v[162:163], v[156:157], 0, s[60:61]
	s_mov_b32 m0, s65
	v_readfirstlane_b32 s65, v160
	global_load_lds_dwordx4 v[162:163], off
	v_lshl_add_u64 v[156:157], v[156:157], 0, s[62:63]
	s_mov_b32 m0, s65
	s_nop 0
	global_load_lds_dwordx4 v[156:157], off
	s_waitcnt vmcnt(10)
	s_barrier
	s_waitcnt lgkmcnt(0)
	s_setprio 1
	s_waitcnt lgkmcnt(0)
	v_mfma_f32_16x16x32_bf16 v[124:127], v[130:133], v[176:179], v[124:127]
	v_mfma_f32_16x16x32_bf16 v[120:123], v[168:171], v[176:179], v[120:123]
	v_mfma_f32_16x16x32_bf16 v[116:119], v[130:133], v[184:187], v[116:119]
	v_mfma_f32_16x16x32_bf16 v[112:115], v[168:171], v[184:187], v[112:115]
	v_mfma_f32_16x16x32_bf16 v[108:111], v[130:133], v[192:195], v[108:111]
	v_mfma_f32_16x16x32_bf16 v[104:107], v[168:171], v[192:195], v[104:107]
	v_mfma_f32_16x16x32_bf16 v[100:103], v[130:133], v[200:203], v[100:103]
	v_mfma_f32_16x16x32_bf16 v[96:99], v[168:171], v[200:203], v[96:99]
	v_mfma_f32_16x16x32_bf16 v[124:127], v[164:167], v[180:183], v[124:127]
	v_mfma_f32_16x16x32_bf16 v[120:123], v[172:175], v[180:183], v[120:123]
	v_mfma_f32_16x16x32_bf16 v[116:119], v[164:167], v[188:191], v[116:119]
	v_mfma_f32_16x16x32_bf16 v[112:115], v[172:175], v[188:191], v[112:115]
	v_mfma_f32_16x16x32_bf16 v[108:111], v[164:167], v[196:199], v[108:111]
	v_mfma_f32_16x16x32_bf16 v[104:107], v[172:175], v[196:199], v[104:107]
	v_mfma_f32_16x16x32_bf16 v[100:103], v[164:167], v[204:207], v[100:103]
	v_mfma_f32_16x16x32_bf16 v[96:99], v[172:175], v[204:207], v[96:99]
	s_setprio 0
	s_barrier
	ds_read_b128 v[160:163], v159
	ds_read_b128 v[208:211], v159 offset:1024
	ds_read_b128 v[212:215], v159 offset:2048
	ds_read_b128 v[156:159], v159 offset:3072
	s_barrier
	s_waitcnt lgkmcnt(0)
	s_setprio 1
	s_waitcnt lgkmcnt(0)
	v_mfma_f32_16x16x32_bf16 v[92:95], v[160:163], v[176:179], v[92:95]
	v_mfma_f32_16x16x32_bf16 v[88:91], v[212:215], v[176:179], v[88:91]
	v_mfma_f32_16x16x32_bf16 v[84:87], v[160:163], v[184:187], v[84:87]
	v_mfma_f32_16x16x32_bf16 v[80:83], v[212:215], v[184:187], v[80:83]
	v_mfma_f32_16x16x32_bf16 v[76:79], v[160:163], v[192:195], v[76:79]
	v_mfma_f32_16x16x32_bf16 v[72:75], v[212:215], v[192:195], v[72:75]
	v_mfma_f32_16x16x32_bf16 v[68:71], v[160:163], v[200:203], v[68:71]
	v_mfma_f32_16x16x32_bf16 v[64:67], v[212:215], v[200:203], v[64:67]
	v_mfma_f32_16x16x32_bf16 v[176:179], v[208:211], v[180:183], v[92:95]
	v_mfma_f32_16x16x32_bf16 v[180:183], v[156:159], v[180:183], v[88:91]
	v_mfma_f32_16x16x32_bf16 v[184:187], v[208:211], v[188:191], v[84:87]
	v_mfma_f32_16x16x32_bf16 v[188:191], v[156:159], v[188:191], v[80:83]
	v_mfma_f32_16x16x32_bf16 v[192:195], v[208:211], v[196:199], v[76:79]
	v_mfma_f32_16x16x32_bf16 v[196:199], v[156:159], v[196:199], v[72:75]
	v_mfma_f32_16x16x32_bf16 v[200:203], v[208:211], v[204:207], v[68:71]
	v_mfma_f32_16x16x32_bf16 v[204:207], v[156:159], v[204:207], v[64:67]
	s_setprio 0
	s_barrier
	s_nop 0
	ds_read_b128 v[64:67], v153 offset:16384
	ds_read_b128 v[68:71], v153 offset:17408
	ds_read_b128 v[72:75], v152 offset:16384
	ds_read_b128 v[76:79], v152 offset:17408
	ds_read_b128 v[80:83], v151 offset:16384
	ds_read_b128 v[84:87], v151 offset:17408
	ds_read_b128 v[88:91], v150 offset:16384
	ds_read_b128 v[92:95], v150 offset:17408
	s_waitcnt vmcnt(4)
	s_barrier
	s_waitcnt lgkmcnt(0)
	s_setprio 1
	s_waitcnt lgkmcnt(0)
	v_mfma_f32_16x16x32_bf16 v[60:63], v[130:133], v[64:67], v[60:63]
	v_mfma_f32_16x16x32_bf16 v[56:59], v[168:171], v[64:67], v[56:59]
	v_mfma_f32_16x16x32_bf16 v[52:55], v[130:133], v[72:75], v[52:55]
	v_mfma_f32_16x16x32_bf16 v[48:51], v[168:171], v[72:75], v[48:51]
	v_mfma_f32_16x16x32_bf16 v[216:219], v[130:133], v[80:83], v[44:47]
	v_mfma_f32_16x16x32_bf16 v[220:223], v[168:171], v[80:83], v[40:43]
	v_mfma_f32_16x16x32_bf16 v[130:133], v[130:133], v[88:91], v[36:39]
	v_mfma_f32_16x16x32_bf16 v[168:171], v[168:171], v[88:91], v[32:35]
	v_mfma_f32_16x16x32_bf16 v[32:35], v[164:167], v[68:71], v[60:63]
	v_mfma_f32_16x16x32_bf16 v[36:39], v[172:175], v[68:71], v[56:59]
	v_mfma_f32_16x16x32_bf16 v[40:43], v[164:167], v[76:79], v[52:55]
	v_mfma_f32_16x16x32_bf16 v[44:47], v[172:175], v[76:79], v[48:51]
	v_mfma_f32_16x16x32_bf16 v[48:51], v[164:167], v[84:87], v[216:219]
	v_mfma_f32_16x16x32_bf16 v[52:55], v[172:175], v[84:87], v[220:223]
	v_mfma_f32_16x16x32_bf16 v[56:59], v[164:167], v[92:95], v[130:133]
	v_mfma_f32_16x16x32_bf16 v[60:63], v[172:175], v[92:95], v[168:171]
	s_setprio 0
	s_setprio 1
	v_mfma_f32_16x16x32_bf16 v[28:31], v[160:163], v[64:67], v[28:31]
	v_mfma_f32_16x16x32_bf16 v[24:27], v[212:215], v[64:67], v[24:27]
	v_mfma_f32_16x16x32_bf16 v[20:23], v[160:163], v[72:75], v[20:23]
	v_mfma_f32_16x16x32_bf16 v[64:67], v[212:215], v[72:75], v[16:19]
	v_mfma_f32_16x16x32_bf16 v[72:75], v[160:163], v[80:83], v[12:15]
	v_mfma_f32_16x16x32_bf16 v[8:11], v[212:215], v[80:83], v[8:11]
	v_mfma_f32_16x16x32_bf16 v[80:83], v[160:163], v[88:91], v[4:7]
	v_mfma_f32_16x16x32_bf16 v[0:3], v[212:215], v[88:91], v[0:3]
	v_mfma_f32_16x16x32_bf16 v[4:7], v[208:211], v[68:71], v[28:31]
	v_mfma_f32_16x16x32_bf16 v[12:15], v[156:159], v[68:71], v[24:27]
	v_mfma_f32_16x16x32_bf16 v[16:19], v[208:211], v[76:79], v[20:23]
	v_mfma_f32_16x16x32_bf16 v[20:23], v[156:159], v[76:79], v[64:67]
	v_mfma_f32_16x16x32_bf16 v[24:27], v[208:211], v[84:87], v[72:75]
	v_mfma_f32_16x16x32_bf16 v[28:31], v[156:159], v[84:87], v[8:11]
	v_mfma_f32_16x16x32_bf16 v[64:67], v[208:211], v[92:95], v[80:83]
	v_mfma_f32_16x16x32_bf16 v[68:71], v[156:159], v[92:95], v[0:3]
	s_setprio 0
	s_barrier
	ds_read_b128 v[8:11], v155
	ds_read_b128 v[0:3], v155 offset:1024
	ds_read_b128 v[76:79], v155 offset:2048
	ds_read_b128 v[72:75], v155 offset:3072
	ds_read_b128 v[130:133], v153 offset:32768
	ds_read_b128 v[156:159], v153 offset:33792
	ds_read_b128 v[160:163], v152 offset:32768
	ds_read_b128 v[164:167], v152 offset:33792
	ds_read_b128 v[168:171], v151 offset:32768
	ds_read_b128 v[172:175], v151 offset:33792
	ds_read_b128 v[208:211], v150 offset:32768
	ds_read_b128 v[212:215], v150 offset:33792
	s_waitcnt vmcnt(2)
	s_barrier
	s_waitcnt lgkmcnt(0)
	s_setprio 1
	s_waitcnt lgkmcnt(0)
	v_mfma_f32_16x16x32_bf16 v[80:83], v[8:11], v[130:133], v[124:127]
	v_mfma_f32_16x16x32_bf16 v[84:87], v[76:79], v[130:133], v[120:123]
	v_mfma_f32_16x16x32_bf16 v[88:91], v[8:11], v[160:163], v[116:119]
	v_mfma_f32_16x16x32_bf16 v[92:95], v[76:79], v[160:163], v[112:115]
	v_mfma_f32_16x16x32_bf16 v[108:111], v[8:11], v[168:171], v[108:111]
	v_mfma_f32_16x16x32_bf16 v[104:107], v[76:79], v[168:171], v[104:107]
	v_mfma_f32_16x16x32_bf16 v[100:103], v[8:11], v[208:211], v[100:103]
	v_mfma_f32_16x16x32_bf16 v[96:99], v[76:79], v[208:211], v[96:99]
	v_mfma_f32_16x16x32_bf16 v[112:115], v[0:3], v[156:159], v[80:83]
	v_mfma_f32_16x16x32_bf16 v[116:119], v[72:75], v[156:159], v[84:87]
	v_mfma_f32_16x16x32_bf16 v[120:123], v[0:3], v[164:167], v[88:91]
	v_mfma_f32_16x16x32_bf16 v[124:127], v[72:75], v[164:167], v[92:95]
	v_mfma_f32_16x16x32_bf16 v[108:111], v[0:3], v[172:175], v[108:111]
	v_mfma_f32_16x16x32_bf16 v[104:107], v[72:75], v[172:175], v[104:107]
	v_mfma_f32_16x16x32_bf16 v[100:103], v[0:3], v[212:215], v[100:103]
	v_mfma_f32_16x16x32_bf16 v[96:99], v[72:75], v[212:215], v[96:99]
	s_setprio 0
	s_barrier
	ds_read_b128 v[88:91], v154
	ds_read_b128 v[80:83], v154 offset:1024
	ds_read_b128 v[92:95], v154 offset:2048
	ds_read_b128 v[84:87], v154 offset:3072
	s_waitcnt vmcnt(0)
	s_barrier
	s_waitcnt lgkmcnt(0)
	s_setprio 1
	s_waitcnt lgkmcnt(0)
	v_mfma_f32_16x16x32_bf16 v[176:179], v[88:91], v[130:133], v[176:179]
	v_mfma_f32_16x16x32_bf16 v[130:133], v[92:95], v[130:133], v[180:183]
	v_mfma_f32_16x16x32_bf16 v[180:183], v[88:91], v[160:163], v[184:187]
	v_mfma_f32_16x16x32_bf16 v[160:163], v[92:95], v[160:163], v[188:191]
	v_mfma_f32_16x16x32_bf16 v[184:187], v[88:91], v[168:171], v[192:195]
	v_mfma_f32_16x16x32_bf16 v[168:171], v[92:95], v[168:171], v[196:199]
	v_mfma_f32_16x16x32_bf16 v[188:191], v[88:91], v[208:211], v[200:203]
	v_mfma_f32_16x16x32_bf16 v[192:195], v[92:95], v[208:211], v[204:207]
	v_mfma_f32_16x16x32_bf16 v[176:179], v[80:83], v[156:159], v[176:179]
	v_mfma_f32_16x16x32_bf16 v[130:133], v[84:87], v[156:159], v[130:133]
	v_mfma_f32_16x16x32_bf16 v[154:157], v[80:83], v[164:167], v[180:183]
	v_mfma_f32_16x16x32_bf16 v[158:161], v[84:87], v[164:167], v[160:163]
	v_mfma_f32_16x16x32_bf16 v[162:165], v[80:83], v[172:175], v[184:187]
	v_mfma_f32_16x16x32_bf16 v[166:169], v[84:87], v[172:175], v[168:171]
	v_mfma_f32_16x16x32_bf16 v[170:173], v[80:83], v[212:215], v[188:191]
	v_mfma_f32_16x16x32_bf16 v[180:183], v[84:87], v[212:215], v[192:195]
	s_setprio 0
	s_barrier
	v_mbcnt_lo_u32_b32 v128, -1, 0
	v_mbcnt_hi_u32_b32 v128, -1, v128
	v_cvt_pk_bf16_f32 v112, v112, v113
	v_cvt_pk_bf16_f32 v113, v114, v115
	v_cvt_pk_bf16_f32 v114, v116, v117
	v_cvt_pk_bf16_f32 v115, v118, v119
	s_lshl_b32 s66, s64, 9
	v_add_u32_e32 v174, s72, v128
	v_ashrrev_i32_e32 v175, 6, v174
	v_and_b32_e32 v184, 15, v128
	v_and_b32_e32 v185, 48, v128
	v_mul_lo_u32 v186, v175, s77
	v_bfe_u32 v187, v128, 3, 3
	v_lshlrev_b32_e32 v128, 4, v128
	v_add_u32_e32 v186, 0x20000, v186
	v_lshrrev_b32_e32 v174, 2, v174
	v_and_b32_e32 v128, 0x70, v128
	v_mul_u32_u24_e32 v184, 0x90, v184
	v_and_b32_e32 v174, 64, v174
	v_add3_u32 v184, v186, v184, v185
	v_or_b32_e32 v185, v186, v128
	v_or3_b32 v174, s24, v174, v187
	v_mad_u32_u24 v185, v187, s78, v185
	ds_write_b128 v184, v[112:115]
	v_cvt_pk_bf16_f32 v112, v176, v177
	v_cvt_pk_bf16_f32 v113, v178, v179
	v_cvt_pk_bf16_f32 v114, v130, v131
	v_cvt_pk_bf16_f32 v115, v132, v133
	ds_write_b128 v184, v[112:115] offset:64
	v_lshlrev_b32_e32 v175, 7, v175
	ds_read_b128 v[112:115], v185
	v_lshlrev_b32_e32 v116, 12, v174
	v_and_or_b32 v116, v175, s79, v116
	v_or3_b32 v128, v116, s66, v128
	ds_read_b128 v[116:119], v185 offset:1152
	v_lshl_add_u64 v[130:131], s[0:1], 0, v[128:129]
	s_mov_b32 s64, 0x8000
	s_waitcnt lgkmcnt(0)
	global_store_dwordx4 v128, v[112:115], s[0:1]
	v_cvt_pk_bf16_f32 v108, v108, v109
	v_cvt_pk_bf16_f32 v109, v110, v111
	v_cvt_pk_bf16_f32 v110, v104, v105
	v_cvt_pk_bf16_f32 v111, v106, v107
	v_cvt_pk_bf16_f32 v104, v162, v163
	s_nop 1
	v_add_co_u32_e32 v112, vcc, s64, v130
	v_cvt_pk_bf16_f32 v114, v124, v125
	v_cvt_pk_bf16_f32 v115, v126, v127
	v_cvt_pk_bf16_f32 v105, v164, v165
	v_cvt_pk_bf16_f32 v106, v166, v167
	s_nop 1
	v_addc_co_u32_e32 v113, vcc, 0, v131, vcc
	global_store_dwordx4 v[112:113], v[116:119], off
	v_cvt_pk_bf16_f32 v112, v120, v121
	v_cvt_pk_bf16_f32 v113, v122, v123
	ds_write_b128 v184, v[112:115]
	v_cvt_pk_bf16_f32 v112, v154, v155
	v_cvt_pk_bf16_f32 v113, v156, v157
	v_cvt_pk_bf16_f32 v114, v158, v159
	v_cvt_pk_bf16_f32 v115, v160, v161
	ds_write_b128 v184, v[112:115] offset:64
	ds_read_b128 v[112:115], v185
	ds_read_b128 v[116:119], v185 offset:1152
	v_add_co_u32_e32 v120, vcc, s74, v130
	ds_write_b128 v184, v[108:111]
	v_cvt_pk_bf16_f32 v107, v168, v169
	ds_write_b128 v184, v[104:107] offset:64
	v_addc_co_u32_e32 v121, vcc, 0, v131, vcc
	ds_read_b128 v[104:107], v185
	ds_read_b128 v[108:111], v185 offset:1152
	s_waitcnt lgkmcnt(0)
	global_store_dwordx4 v[120:121], v[112:115], off
	v_cvt_pk_bf16_f32 v100, v100, v101
	v_cvt_pk_bf16_f32 v101, v102, v103
	v_cvt_pk_bf16_f32 v102, v96, v97
	v_cvt_pk_bf16_f32 v103, v98, v99
	ds_write_b128 v184, v[100:103]
	s_nop 0
	v_add_co_u32_e32 v112, vcc, s75, v130
	v_cvt_pk_bf16_f32 v96, v170, v171
	v_cvt_pk_bf16_f32 v97, v172, v173
	v_cvt_pk_bf16_f32 v98, v180, v181
	v_cvt_pk_bf16_f32 v99, v182, v183
	s_nop 1
	v_addc_co_u32_e32 v113, vcc, 0, v131, vcc
	global_store_dwordx4 v[112:113], v[116:119], off
	v_add_co_u32_e32 v112, vcc, s76, v130
	ds_write_b128 v184, v[96:99] offset:64
	s_nop 0
	v_addc_co_u32_e32 v113, vcc, 0, v131, vcc
	ds_read_b128 v[96:99], v185
	ds_read_b128 v[100:103], v185 offset:1152
	global_store_dwordx4 v[112:113], v[104:107], off
	s_nop 1
	v_add_co_u32_e32 v104, vcc, s80, v130
	s_nop 1
	v_addc_co_u32_e32 v105, vcc, 0, v131, vcc
	global_store_dwordx4 v[104:105], v[108:111], off
	v_add_co_u32_e32 v104, vcc, s81, v130
	s_nop 1
	v_addc_co_u32_e32 v105, vcc, 0, v131, vcc
	s_waitcnt lgkmcnt(0)
	global_store_dwordx4 v[104:105], v[96:99], off
	s_nop 1
	v_add_co_u32_e32 v96, vcc, s82, v130
	s_nop 1
	v_addc_co_u32_e32 v97, vcc, 0, v131, vcc
	global_store_dwordx4 v[96:97], v[100:103], off
	ds_read_b128 v[96:99], v153 offset:49152
	ds_read_b128 v[100:103], v153 offset:50176
	ds_read_b128 v[104:107], v152 offset:49152
	ds_read_b128 v[108:111], v152 offset:50176
	ds_read_b128 v[112:115], v151 offset:49152
	ds_read_b128 v[116:119], v151 offset:50176
	ds_read_b128 v[120:123], v150 offset:49152
	ds_read_b128 v[124:127], v150 offset:50176
	s_barrier
	s_waitcnt lgkmcnt(0)
	s_setprio 1
	s_waitcnt lgkmcnt(0)
	v_mfma_f32_16x16x32_bf16 v[32:35], v[8:11], v[96:99], v[32:35]
	v_mfma_f32_16x16x32_bf16 v[36:39], v[76:79], v[96:99], v[36:39]
	v_mfma_f32_16x16x32_bf16 v[40:43], v[8:11], v[104:107], v[40:43]
	v_mfma_f32_16x16x32_bf16 v[130:133], v[76:79], v[104:107], v[44:47]
	v_mfma_f32_16x16x32_bf16 v[150:153], v[8:11], v[112:115], v[48:51]
	v_mfma_f32_16x16x32_bf16 v[52:55], v[76:79], v[112:115], v[52:55]
	v_mfma_f32_16x16x32_bf16 v[8:11], v[8:11], v[120:123], v[56:59]
	v_mfma_f32_16x16x32_bf16 v[60:63], v[76:79], v[120:123], v[60:63]
	v_mfma_f32_16x16x32_bf16 v[56:59], v[0:3], v[100:103], v[32:35]
	v_mfma_f32_16x16x32_bf16 v[48:51], v[72:75], v[100:103], v[36:39]
	v_mfma_f32_16x16x32_bf16 v[44:47], v[0:3], v[108:111], v[40:43]
	v_mfma_f32_16x16x32_bf16 v[40:43], v[72:75], v[108:111], v[130:133]
	v_mfma_f32_16x16x32_bf16 v[36:39], v[0:3], v[116:119], v[150:153]
	v_mfma_f32_16x16x32_bf16 v[32:35], v[72:75], v[116:119], v[52:55]
	v_mfma_f32_16x16x32_bf16 v[8:11], v[0:3], v[124:127], v[8:11]
	v_mfma_f32_16x16x32_bf16 v[0:3], v[72:75], v[124:127], v[60:63]
	s_setprio 0
	s_setprio 1
	v_mfma_f32_16x16x32_bf16 v[4:7], v[88:91], v[96:99], v[4:7]
	v_mfma_f32_16x16x32_bf16 v[12:15], v[92:95], v[96:99], v[12:15]
	v_mfma_f32_16x16x32_bf16 v[16:19], v[88:91], v[104:107], v[16:19]
	v_mfma_f32_16x16x32_bf16 v[20:23], v[92:95], v[104:107], v[20:23]
	v_mfma_f32_16x16x32_bf16 v[72:75], v[88:91], v[112:115], v[24:27]
	v_mfma_f32_16x16x32_bf16 v[76:79], v[92:95], v[112:115], v[28:31]
	v_mfma_f32_16x16x32_bf16 v[64:67], v[88:91], v[120:123], v[64:67]
	v_mfma_f32_16x16x32_bf16 v[68:71], v[92:95], v[120:123], v[68:71]
	v_mfma_f32_16x16x32_bf16 v[60:63], v[80:83], v[100:103], v[4:7]
	v_mfma_f32_16x16x32_bf16 v[52:55], v[84:87], v[100:103], v[12:15]
	v_mfma_f32_16x16x32_bf16 v[28:31], v[80:83], v[108:111], v[16:19]
	v_mfma_f32_16x16x32_bf16 v[24:27], v[84:87], v[108:111], v[20:23]
	v_mfma_f32_16x16x32_bf16 v[20:23], v[80:83], v[116:119], v[72:75]
	v_mfma_f32_16x16x32_bf16 v[16:19], v[84:87], v[116:119], v[76:79]
	v_mfma_f32_16x16x32_bf16 v[12:15], v[80:83], v[124:127], v[64:67]
	v_mfma_f32_16x16x32_bf16 v[4:7], v[84:87], v[124:127], v[68:71]
	s_setprio 0
	v_cmp_gt_u32_e32 vcc, s83, v136
	s_barrier
	s_and_saveexec_b64 s[64:65], vcc
	s_cbranch_execz .LBB0_181
	s_barrier

.LBB0_233:
	v_bfe_i32 v5, v179, 27, 1
	v_lshlrev_b32_e32 v169, 4, v179
	v_lshrrev_b32_e32 v5, 22, v5
	v_add_u32_e32 v5, v169, v5
	v_and_b32_e32 v5, 0xfffffc00, v5
	v_sub_u32_e32 v5, v169, v5
	v_lshrrev_b32_e32 v6, 4, v5
	v_bitop3_b32 v5, v6, v5, 32 bitop3:0x6c
	v_ashrrev_i32_e32 v6, 31, v5
	v_lshrrev_b32_e32 v6, 26, v6
	v_ashrrev_i32_e32 v4, 31, v179
	v_add_u32_e32 v6, v5, v6
	s_lshl_b32 s56, s83, 3
	v_lshrrev_b32_e32 v4, 26, v4
	v_ashrrev_i32_e32 v133, 6, v6
	v_and_b32_e32 v6, 0xc0, v6
	s_ff1_i32_b32 s57, s56
	s_add_i32 s56, s56, -1
	v_and_b32_e32 v2, 15, v0
	v_and_b32_e32 v3, 48, v0
	v_add_u32_e32 v4, v179, v4
	v_sub_u32_e32 v5, v5, v6
	v_and_b32_e32 v6, 32, v0
	v_lshlrev_b32_e32 v10, 2, v0
	v_lshlrev_b32_e32 v0, 6, v0
	s_lshr_b32 s62, s85, s57
	s_and_b32 s56, s85, s56
	s_and_b32 s63, s85, 7
	v_ashrrev_i32_e32 v131, 6, v4
	v_lshlrev_b32_e32 v2, 6, v2
	v_and_b32_e32 v10, 32, v10
	v_and_b32_e32 v0, 0x3c0, v0
	s_lshr_b32 s80, s56, 3
	v_or_b32_e32 v9, v2, v3
	v_bitop3_b32 v2, v2, v10, v3 bitop3:0x36
	v_bitop3_b32 v3, v0, v10, v3 bitop3:0x36
	s_lshl_b32 s56, s62, 11
	s_lshl_b32 s57, s63, 8
	v_lshlrev_b32_e32 v0, 16, v131
	s_or_b32 s56, s56, s57
	s_mov_b32 s57, s15
	v_and_b32_e32 v0, 0xfffe0000, v0
	s_lshl_b32 s60, s80, 14
	v_ashrrev_i16_sdwa v5, v167, sext(v5) dst_sel:DWORD dst_unused:UNUSED_PAD src0_sel:DWORD src1_sel:BYTE_0
	s_lshl_b64 s[56:57], s[56:57], 13
	v_lshl_add_u32 v0, v133, 13, v0
	v_bfe_i32 v134, v5, 0, 16
	v_and_or_b32 v0, v4, 64, v0
	s_add_u32 s56, s40, s56
	v_lshl_add_u32 v164, v134, 1, v0
	s_addc_u32 s57, s41, s57
	v_lshlrev_b32_e32 v14, 13, v1
	v_lshl_add_u64 v[0:1], s[56:57], 0, v[164:165]
	s_mul_i32 s57, s14, 0x1800
	s_mul_hi_u32 s56, s14, 0x1800
	s_add_u32 s57, s57, s60
	s_addc_u32 s58, s56, 0
	s_add_u32 s56, s65, s57
	v_bfe_i32 v7, v179, 6, 1
	s_addc_u32 s57, s66, s58
	s_lshl_b64 s[58:59], s[14:15], 12
	v_and_b32_e32 v7, s14, v7
	v_lshrrev_b32_e32 v8, 7, v179
	s_add_u32 s14, s58, s60
	v_add_lshl_u32 v7, v7, v8, 10
	v_lshlrev_b32_e32 v8, 6, v179
	s_addc_u32 s61, s59, 0
	v_and_b32_e32 v5, 0x3f0, v169
	v_and_b32_e32 v8, 0x3000, v8
	v_bitop3_b32 v11, v9, s67, v10 bitop3:0xde
	v_bitop3_b32 v12, v9, s69, v10 bitop3:0xde
	v_bitop3_b32 v13, v9, s70, v10 bitop3:0xde
	v_bitop3_b32 v9, v9, s71, v10 bitop3:0xde
	v_or_b32_e32 v10, 0x800, v14
	v_or_b32_e32 v15, 0x1000, v14
	v_or_b32_e32 v16, 0x1800, v14
	v_lshl_add_u64 v[128:129], v[0:1], 0, s[16:17]
	s_add_u32 s60, s65, s14
	v_mov_b32_e32 v0, 0
	v_bitop3_b32 v164, v5, v7, v6 bitop3:0xde
	s_addc_u32 s61, s66, s61
	s_mov_b32 s14, -2
	v_add_u32_e32 v138, v11, v8
	v_add_u32_e32 v193, v2, v14
	v_add_u32_e32 v192, v3, v10
	v_add_u32_e32 v191, v3, v15
	v_add_u32_e32 v190, v3, v16
	v_add_u32_e32 v137, 0xc000, v169
	v_add_u32_e32 v136, 0xe000, v169
	v_add_u32_e32 v135, v12, v8
	v_add_u32_e32 v189, 0x10000, v169
	v_add_u32_e32 v188, 0x12000, v169
	v_add_u32_e32 v187, 0x2000, v169
	v_add_u32_e32 v186, 0x14000, v169
	v_add_u32_e32 v185, 0x16000, v169
	v_add_u32_e32 v130, v13, v8
	v_add_u32_e32 v184, 0x4000, v169
	v_add_u32_e32 v183, 0x6000, v169
	v_add_u32_e32 v132, v9, v8
	v_add_u32_e32 v182, 0x18000, v169
	v_add_u32_e32 v181, 0x1a000, v169
	v_add_u32_e32 v177, 0x8000, v169
	v_add_u32_e32 v175, 0xa000, v169
	v_add_u32_e32 v173, 0x1c000, v169
	v_add_u32_e32 v171, 0x1e000, v169
	v_mov_b32_e32 v1, v0
	v_mov_b32_e32 v2, v0
	v_mov_b32_e32 v3, v0
	v_mov_b32_e32 v4, v0
	v_mov_b32_e32 v5, v0
	v_mov_b32_e32 v6, v0
	v_mov_b32_e32 v7, v0
	v_mov_b32_e32 v8, v0
	v_mov_b32_e32 v9, v0
	v_mov_b32_e32 v10, v0
	v_mov_b32_e32 v11, v0
	v_mov_b32_e32 v12, v0
	v_mov_b32_e32 v13, v0
	v_mov_b32_e32 v14, v0
	v_mov_b32_e32 v15, v0
	v_mov_b32_e32 v16, v0
	v_mov_b32_e32 v17, v0
	v_mov_b32_e32 v18, v0
	v_mov_b32_e32 v19, v0
	v_mov_b32_e32 v20, v0
	v_mov_b32_e32 v21, v0
	v_mov_b32_e32 v22, v0
	v_mov_b32_e32 v23, v0
	v_mov_b32_e32 v24, v0
	v_mov_b32_e32 v25, v0
	v_mov_b32_e32 v26, v0
	v_mov_b32_e32 v27, v0
	v_mov_b32_e32 v28, v0
	v_mov_b32_e32 v29, v0
	v_mov_b32_e32 v30, v0
	v_mov_b32_e32 v31, v0
	v_mov_b32_e32 v32, v0
	v_mov_b32_e32 v33, v0
	v_mov_b32_e32 v34, v0
	v_mov_b32_e32 v35, v0
	v_mov_b32_e32 v36, v0
	v_mov_b32_e32 v37, v0
	v_mov_b32_e32 v38, v0
	v_mov_b32_e32 v39, v0
	v_mov_b32_e32 v40, v0
	v_mov_b32_e32 v41, v0
	v_mov_b32_e32 v42, v0
	v_mov_b32_e32 v43, v0
	v_mov_b32_e32 v44, v0
	v_mov_b32_e32 v45, v0
	v_mov_b32_e32 v46, v0
	v_mov_b32_e32 v47, v0
	v_mov_b32_e32 v48, v0
	v_mov_b32_e32 v49, v0
	v_mov_b32_e32 v50, v0
	v_mov_b32_e32 v51, v0
	v_mov_b32_e32 v52, v0
	v_mov_b32_e32 v53, v0
	v_mov_b32_e32 v54, v0
	v_mov_b32_e32 v55, v0
	v_mov_b32_e32 v56, v0
	v_mov_b32_e32 v57, v0
	v_mov_b32_e32 v58, v0
	v_mov_b32_e32 v59, v0
	v_mov_b32_e32 v60, v0
	v_mov_b32_e32 v61, v0
	v_mov_b32_e32 v62, v0
	v_mov_b32_e32 v63, v0
	v_mov_b32_e32 v64, v0
	v_mov_b32_e32 v65, v0
	v_mov_b32_e32 v66, v0
	v_mov_b32_e32 v67, v0
	v_mov_b32_e32 v68, v0
	v_mov_b32_e32 v69, v0
	v_mov_b32_e32 v70, v0
	v_mov_b32_e32 v71, v0
	v_mov_b32_e32 v72, v0
	v_mov_b32_e32 v73, v0
	v_mov_b32_e32 v74, v0
	v_mov_b32_e32 v75, v0
	v_mov_b32_e32 v76, v0
	v_mov_b32_e32 v77, v0
	v_mov_b32_e32 v78, v0
	v_mov_b32_e32 v79, v0
	v_mov_b32_e32 v80, v0
	v_mov_b32_e32 v81, v0
	v_mov_b32_e32 v82, v0
	v_mov_b32_e32 v83, v0
	v_mov_b32_e32 v84, v0
	v_mov_b32_e32 v85, v0
	v_mov_b32_e32 v86, v0
	v_mov_b32_e32 v87, v0
	v_mov_b32_e32 v88, v0
	v_mov_b32_e32 v89, v0
	v_mov_b32_e32 v90, v0
	v_mov_b32_e32 v91, v0
	v_mov_b32_e32 v92, v0
	v_mov_b32_e32 v93, v0
	v_mov_b32_e32 v94, v0
	v_mov_b32_e32 v95, v0
	v_mov_b32_e32 v96, v0
	v_mov_b32_e32 v97, v0
	v_mov_b32_e32 v98, v0
	v_mov_b32_e32 v99, v0
	v_mov_b32_e32 v100, v0
	v_mov_b32_e32 v101, v0
	v_mov_b32_e32 v102, v0
	v_mov_b32_e32 v103, v0
	v_mov_b32_e32 v104, v0
	v_mov_b32_e32 v105, v0
	v_mov_b32_e32 v106, v0
	v_mov_b32_e32 v107, v0
	v_mov_b32_e32 v108, v0
	v_mov_b32_e32 v109, v0
	v_mov_b32_e32 v110, v0
	v_mov_b32_e32 v111, v0
	v_mov_b32_e32 v112, v0
	v_mov_b32_e32 v113, v0
	v_mov_b32_e32 v114, v0
	v_mov_b32_e32 v115, v0
	v_mov_b32_e32 v116, v0
	v_mov_b32_e32 v117, v0
	v_mov_b32_e32 v118, v0
	v_mov_b32_e32 v119, v0
	v_mov_b32_e32 v120, v0
	v_mov_b32_e32 v121, v0
	v_mov_b32_e32 v122, v0
	v_mov_b32_e32 v123, v0
	v_mov_b32_e32 v124, v0
	v_mov_b32_e32 v125, v0
	v_mov_b32_e32 v126, v0
	v_mov_b32_e32 v127, v0
	s_barrier
	v_readlane_b32 s98, v242, 1
	s_lshl_b32 s98, s98, 10
	s_add_i32 s82, s98, 0xc000
	v_lshl_add_u64 v[142:143], v[128:129], 0, s[18:19]
	s_mov_b32 m0, s82
	s_add_i32 s82, s98, 0xe000
	global_load_lds_dwordx4 v[142:143], off
	v_lshl_add_u64 v[142:143], v[128:129], 0, s[20:21]
	s_mov_b32 m0, s82
	s_nop 0
	global_load_lds_dwordx4 v[142:143], off
.LBB0_234:
	ds_read_b128 v[140:143], v138
	ds_read_b128 v[144:147], v138 offset:1024
	ds_read_b128 v[148:151], v138 offset:2048
	ds_read_b128 v[152:155], v138 offset:3072
	ds_read_b128 v[156:159], v193
	ds_read_b128 v[160:163], v193 offset:1024
	ds_read_b128 v[194:197], v192
	ds_read_b128 v[198:201], v192 offset:1024
	ds_read_b128 v[202:205], v191
	ds_read_b128 v[206:209], v191 offset:1024
	ds_read_b128 v[210:213], v190
	ds_read_b128 v[214:217], v190 offset:1024
	s_waitcnt lgkmcnt(8)
	s_waitcnt vmcnt(10)
	s_barrier
	s_waitcnt lgkmcnt(0)
	s_waitcnt lgkmcnt(0)
	v_mfma_f32_16x16x32_bf16 v[124:127], v[140:143], v[156:159], v[124:127]
	v_mfma_f32_16x16x32_bf16 v[120:123], v[148:151], v[156:159], v[120:123]
	v_mfma_f32_16x16x32_bf16 v[116:119], v[140:143], v[194:197], v[116:119]
	v_mfma_f32_16x16x32_bf16 v[112:115], v[148:151], v[194:197], v[112:115]
	v_mfma_f32_16x16x32_bf16 v[108:111], v[140:143], v[202:205], v[108:111]
	v_mfma_f32_16x16x32_bf16 v[104:107], v[148:151], v[202:205], v[104:107]
	v_mfma_f32_16x16x32_bf16 v[100:103], v[140:143], v[210:213], v[100:103]
	v_mfma_f32_16x16x32_bf16 v[96:99], v[148:151], v[210:213], v[96:99]
	v_mfma_f32_16x16x32_bf16 v[124:127], v[144:147], v[160:163], v[124:127]
	v_mfma_f32_16x16x32_bf16 v[120:123], v[152:155], v[160:163], v[120:123]
	v_mfma_f32_16x16x32_bf16 v[116:119], v[144:147], v[198:201], v[116:119]
	v_mfma_f32_16x16x32_bf16 v[112:115], v[152:155], v[198:201], v[112:115]
	v_mfma_f32_16x16x32_bf16 v[108:111], v[144:147], v[206:209], v[108:111]
	v_mfma_f32_16x16x32_bf16 v[104:107], v[152:155], v[206:209], v[104:107]
	v_mfma_f32_16x16x32_bf16 v[100:103], v[144:147], v[214:217], v[100:103]
	v_mfma_f32_16x16x32_bf16 v[96:99], v[152:155], v[214:217], v[96:99]
	s_barrier
	s_add_i32 s82, s98, 0x10000
	v_lshl_add_u64 v[234:235], s[60:61], 0, v[164:165]
	s_mov_b32 m0, s82
	s_add_i32 s82, s98, 0x12000
	ds_read_b128 v[218:221], v135
	ds_read_b128 v[222:225], v135 offset:1024
	ds_read_b128 v[226:229], v135 offset:2048
	ds_read_b128 v[230:233], v135 offset:3072
	global_load_lds_dwordx4 v[234:235], off
	v_lshl_add_u64 v[236:237], v[234:235], 0, s[2:3]
	s_mov_b32 m0, s82
	s_nop 0
	global_load_lds_dwordx4 v[236:237], off
	s_mov_b32 s82, s98
	v_lshl_add_u64 v[236:237], v[128:129], 0, s[22:23]
	s_mov_b32 m0, s82
	s_add_i32 s82, s98, 0x2000
	global_load_lds_dwordx4 v[236:237], off
	v_lshl_add_u64 v[236:237], v[128:129], 0, s[24:25]
	s_mov_b32 m0, s82
	s_nop 0
	global_load_lds_dwordx4 v[236:237], off
	s_waitcnt vmcnt(12)
	s_barrier
	s_waitcnt lgkmcnt(0)
	s_waitcnt lgkmcnt(0)
	v_mfma_f32_16x16x32_bf16 v[92:95], v[218:221], v[156:159], v[92:95]
	v_mfma_f32_16x16x32_bf16 v[88:91], v[226:229], v[156:159], v[88:91]
	v_mfma_f32_16x16x32_bf16 v[84:87], v[218:221], v[194:197], v[84:87]
	v_mfma_f32_16x16x32_bf16 v[80:83], v[226:229], v[194:197], v[80:83]
	v_mfma_f32_16x16x32_bf16 v[76:79], v[218:221], v[202:205], v[76:79]
	v_mfma_f32_16x16x32_bf16 v[72:75], v[226:229], v[202:205], v[72:75]
	v_mfma_f32_16x16x32_bf16 v[68:71], v[218:221], v[210:213], v[68:71]
	v_mfma_f32_16x16x32_bf16 v[64:67], v[226:229], v[210:213], v[64:67]
	v_mfma_f32_16x16x32_bf16 v[92:95], v[222:225], v[160:163], v[92:95]
	v_mfma_f32_16x16x32_bf16 v[88:91], v[230:233], v[160:163], v[88:91]
	v_mfma_f32_16x16x32_bf16 v[84:87], v[222:225], v[198:201], v[84:87]
	v_mfma_f32_16x16x32_bf16 v[80:83], v[230:233], v[198:201], v[80:83]
	v_mfma_f32_16x16x32_bf16 v[76:79], v[222:225], v[206:209], v[76:79]
	v_mfma_f32_16x16x32_bf16 v[72:75], v[230:233], v[206:209], v[72:75]
	v_mfma_f32_16x16x32_bf16 v[68:71], v[222:225], v[214:217], v[68:71]
	v_mfma_f32_16x16x32_bf16 v[64:67], v[230:233], v[214:217], v[64:67]
	s_barrier
	ds_read_b128 v[156:159], v193 offset:16384
	ds_read_b128 v[160:163], v193 offset:17408
	ds_read_b128 v[194:197], v192 offset:16384
	ds_read_b128 v[198:201], v192 offset:17408
	ds_read_b128 v[202:205], v191 offset:16384
	ds_read_b128 v[206:209], v191 offset:17408
	ds_read_b128 v[210:213], v190 offset:16384
	ds_read_b128 v[214:217], v190 offset:17408
	s_add_i32 s82, s98, 0x14000
	v_lshl_add_u64 v[236:237], v[234:235], 0, s[6:7]
	s_mov_b32 m0, s82
	s_add_i32 s82, s98, 0x16000
	global_load_lds_dwordx4 v[236:237], off
	v_lshl_add_u64 v[236:237], v[234:235], 0, s[8:9]
	s_mov_b32 m0, s82
	s_nop 0
	global_load_lds_dwordx4 v[236:237], off
	s_barrier
	s_waitcnt lgkmcnt(0)
	s_waitcnt lgkmcnt(0)
	v_mfma_f32_16x16x32_bf16 v[60:63], v[140:143], v[156:159], v[60:63]
	v_mfma_f32_16x16x32_bf16 v[56:59], v[148:151], v[156:159], v[56:59]
	v_mfma_f32_16x16x32_bf16 v[52:55], v[140:143], v[194:197], v[52:55]
	v_mfma_f32_16x16x32_bf16 v[48:51], v[148:151], v[194:197], v[48:51]
	v_mfma_f32_16x16x32_bf16 v[44:47], v[140:143], v[202:205], v[44:47]
	v_mfma_f32_16x16x32_bf16 v[40:43], v[148:151], v[202:205], v[40:43]
	v_mfma_f32_16x16x32_bf16 v[36:39], v[140:143], v[210:213], v[36:39]
	v_mfma_f32_16x16x32_bf16 v[32:35], v[148:151], v[210:213], v[32:35]
	v_mfma_f32_16x16x32_bf16 v[60:63], v[144:147], v[160:163], v[60:63]
	v_mfma_f32_16x16x32_bf16 v[56:59], v[152:155], v[160:163], v[56:59]
	v_mfma_f32_16x16x32_bf16 v[52:55], v[144:147], v[198:201], v[52:55]
	v_mfma_f32_16x16x32_bf16 v[48:51], v[152:155], v[198:201], v[48:51]
	v_mfma_f32_16x16x32_bf16 v[44:47], v[144:147], v[206:209], v[44:47]
	v_mfma_f32_16x16x32_bf16 v[40:43], v[152:155], v[206:209], v[40:43]
	v_mfma_f32_16x16x32_bf16 v[36:39], v[144:147], v[214:217], v[36:39]
	v_mfma_f32_16x16x32_bf16 v[32:35], v[152:155], v[214:217], v[32:35]
	s_barrier
	s_add_i32 s82, s98, 0x4000
	v_lshl_add_u64 v[142:143], v[128:129], 0, s[26:27]
	s_mov_b32 m0, s82
	s_add_i32 s82, s98, 0x6000
	global_load_lds_dwordx4 v[142:143], off
	s_mov_b32 m0, s82
	s_nop 0
	global_load_lds_dwordx4 v[128:129], off
	s_waitcnt vmcnt(12)
	s_barrier
	v_mfma_f32_16x16x32_bf16 v[28:31], v[218:221], v[156:159], v[28:31]
	v_mfma_f32_16x16x32_bf16 v[24:27], v[226:229], v[156:159], v[24:27]
	v_mfma_f32_16x16x32_bf16 v[20:23], v[218:221], v[194:197], v[20:23]
	v_mfma_f32_16x16x32_bf16 v[16:19], v[226:229], v[194:197], v[16:19]
	v_mfma_f32_16x16x32_bf16 v[12:15], v[218:221], v[202:205], v[12:15]
	v_mfma_f32_16x16x32_bf16 v[8:11], v[226:229], v[202:205], v[8:11]
	v_mfma_f32_16x16x32_bf16 v[4:7], v[218:221], v[210:213], v[4:7]
	v_mfma_f32_16x16x32_bf16 v[0:3], v[226:229], v[210:213], v[0:3]
	v_mfma_f32_16x16x32_bf16 v[28:31], v[222:225], v[160:163], v[28:31]
	v_mfma_f32_16x16x32_bf16 v[24:27], v[230:233], v[160:163], v[24:27]
	v_mfma_f32_16x16x32_bf16 v[20:23], v[222:225], v[198:201], v[20:23]
	v_mfma_f32_16x16x32_bf16 v[16:19], v[230:233], v[198:201], v[16:19]
	v_mfma_f32_16x16x32_bf16 v[12:15], v[222:225], v[206:209], v[12:15]
	v_mfma_f32_16x16x32_bf16 v[8:11], v[230:233], v[206:209], v[8:11]
	v_mfma_f32_16x16x32_bf16 v[4:7], v[222:225], v[214:217], v[4:7]
	v_mfma_f32_16x16x32_bf16 v[0:3], v[230:233], v[214:217], v[0:3]
	s_barrier
	ds_read_b128 v[140:143], v130
	ds_read_b128 v[144:147], v130 offset:1024
	ds_read_b128 v[148:151], v130 offset:2048
	ds_read_b128 v[152:155], v130 offset:3072
	ds_read_b128 v[156:159], v193 offset:32768
	ds_read_b128 v[160:163], v193 offset:33792
	ds_read_b128 v[194:197], v192 offset:32768
	ds_read_b128 v[198:201], v192 offset:33792
	ds_read_b128 v[202:205], v191 offset:32768
	ds_read_b128 v[206:209], v191 offset:33792
	ds_read_b128 v[210:213], v190 offset:32768
	ds_read_b128 v[214:217], v190 offset:33792
	s_waitcnt lgkmcnt(8)
	s_waitcnt vmcnt(10)
	s_barrier
	s_waitcnt lgkmcnt(0)
	s_waitcnt lgkmcnt(0)
	v_mfma_f32_16x16x32_bf16 v[124:127], v[140:143], v[156:159], v[124:127]
	v_mfma_f32_16x16x32_bf16 v[120:123], v[148:151], v[156:159], v[120:123]
	v_mfma_f32_16x16x32_bf16 v[116:119], v[140:143], v[194:197], v[116:119]
	v_mfma_f32_16x16x32_bf16 v[112:115], v[148:151], v[194:197], v[112:115]
	v_mfma_f32_16x16x32_bf16 v[108:111], v[140:143], v[202:205], v[108:111]
	v_mfma_f32_16x16x32_bf16 v[104:107], v[148:151], v[202:205], v[104:107]
	v_mfma_f32_16x16x32_bf16 v[100:103], v[140:143], v[210:213], v[100:103]
	v_mfma_f32_16x16x32_bf16 v[96:99], v[148:151], v[210:213], v[96:99]
	v_mfma_f32_16x16x32_bf16 v[124:127], v[144:147], v[160:163], v[124:127]
	v_mfma_f32_16x16x32_bf16 v[120:123], v[152:155], v[160:163], v[120:123]
	v_mfma_f32_16x16x32_bf16 v[116:119], v[144:147], v[198:201], v[116:119]
	v_mfma_f32_16x16x32_bf16 v[112:115], v[152:155], v[198:201], v[112:115]
	v_mfma_f32_16x16x32_bf16 v[108:111], v[144:147], v[206:209], v[108:111]
	v_mfma_f32_16x16x32_bf16 v[104:107], v[152:155], v[206:209], v[104:107]
	v_mfma_f32_16x16x32_bf16 v[100:103], v[144:147], v[214:217], v[100:103]
	v_mfma_f32_16x16x32_bf16 v[96:99], v[152:155], v[214:217], v[96:99]
	s_barrier
	s_add_i32 s82, s98, 0x18000
	v_lshl_add_u64 v[234:235], s[56:57], 0, v[164:165]
	s_mov_b32 m0, s82
	s_add_i32 s82, s98, 0x1a000
	ds_read_b128 v[218:221], v132
	ds_read_b128 v[222:225], v132 offset:1024
	ds_read_b128 v[226:229], v132 offset:2048
	ds_read_b128 v[230:233], v132 offset:3072
	global_load_lds_dwordx4 v[234:235], off
	v_lshl_add_u64 v[236:237], v[234:235], 0, s[2:3]
	s_mov_b32 m0, s82
	s_nop 0
	global_load_lds_dwordx4 v[236:237], off
	s_add_i32 s82, s98, 0x8000
	v_lshl_add_u64 v[236:237], v[128:129], 0, s[28:29]
	s_mov_b32 m0, s82
	s_add_i32 s82, s98, 0xa000
	global_load_lds_dwordx4 v[236:237], off
	v_lshl_add_u64 v[236:237], v[128:129], 0, s[30:31]
	s_mov_b32 m0, s82
	s_nop 0
	global_load_lds_dwordx4 v[236:237], off
	s_waitcnt vmcnt(12)
	s_barrier
	s_waitcnt lgkmcnt(0)
	s_waitcnt lgkmcnt(0)
	v_mfma_f32_16x16x32_bf16 v[92:95], v[218:221], v[156:159], v[92:95]
	v_mfma_f32_16x16x32_bf16 v[88:91], v[226:229], v[156:159], v[88:91]
	v_mfma_f32_16x16x32_bf16 v[84:87], v[218:221], v[194:197], v[84:87]
	v_mfma_f32_16x16x32_bf16 v[80:83], v[226:229], v[194:197], v[80:83]
	v_mfma_f32_16x16x32_bf16 v[76:79], v[218:221], v[202:205], v[76:79]
	v_mfma_f32_16x16x32_bf16 v[72:75], v[226:229], v[202:205], v[72:75]
	v_mfma_f32_16x16x32_bf16 v[68:71], v[218:221], v[210:213], v[68:71]
	v_mfma_f32_16x16x32_bf16 v[64:67], v[226:229], v[210:213], v[64:67]
	v_mfma_f32_16x16x32_bf16 v[92:95], v[222:225], v[160:163], v[92:95]
	v_mfma_f32_16x16x32_bf16 v[88:91], v[230:233], v[160:163], v[88:91]
	v_mfma_f32_16x16x32_bf16 v[84:87], v[222:225], v[198:201], v[84:87]
	v_mfma_f32_16x16x32_bf16 v[80:83], v[230:233], v[198:201], v[80:83]
	v_mfma_f32_16x16x32_bf16 v[76:79], v[222:225], v[206:209], v[76:79]
	v_mfma_f32_16x16x32_bf16 v[72:75], v[230:233], v[206:209], v[72:75]
	v_mfma_f32_16x16x32_bf16 v[68:71], v[222:225], v[214:217], v[68:71]
	v_mfma_f32_16x16x32_bf16 v[64:67], v[230:233], v[214:217], v[64:67]
	s_barrier
	ds_read_b128 v[156:159], v193 offset:49152
	ds_read_b128 v[160:163], v193 offset:50176
	ds_read_b128 v[194:197], v192 offset:49152
	ds_read_b128 v[198:201], v192 offset:50176
	ds_read_b128 v[202:205], v191 offset:49152
	ds_read_b128 v[206:209], v191 offset:50176
	ds_read_b128 v[210:213], v190 offset:49152
	ds_read_b128 v[214:217], v190 offset:50176
	s_add_i32 s82, s98, 0x1c000
	v_lshl_add_u64 v[236:237], v[234:235], 0, s[6:7]
	s_mov_b32 m0, s82
	s_add_i32 s82, s98, 0x1e000
	global_load_lds_dwordx4 v[236:237], off
	v_lshl_add_u64 v[236:237], v[234:235], 0, s[8:9]
	s_mov_b32 m0, s82
	s_nop 0
	global_load_lds_dwordx4 v[236:237], off
	s_barrier
	s_waitcnt lgkmcnt(0)
	s_waitcnt lgkmcnt(0)
	v_mfma_f32_16x16x32_bf16 v[60:63], v[140:143], v[156:159], v[60:63]
	v_mfma_f32_16x16x32_bf16 v[56:59], v[148:151], v[156:159], v[56:59]
	v_mfma_f32_16x16x32_bf16 v[52:55], v[140:143], v[194:197], v[52:55]
	v_mfma_f32_16x16x32_bf16 v[48:51], v[148:151], v[194:197], v[48:51]
	v_mfma_f32_16x16x32_bf16 v[44:47], v[140:143], v[202:205], v[44:47]
	v_mfma_f32_16x16x32_bf16 v[40:43], v[148:151], v[202:205], v[40:43]
	v_mfma_f32_16x16x32_bf16 v[36:39], v[140:143], v[210:213], v[36:39]
	v_mfma_f32_16x16x32_bf16 v[32:35], v[148:151], v[210:213], v[32:35]
	v_mfma_f32_16x16x32_bf16 v[60:63], v[144:147], v[160:163], v[60:63]
	v_mfma_f32_16x16x32_bf16 v[56:59], v[152:155], v[160:163], v[56:59]
	v_mfma_f32_16x16x32_bf16 v[52:55], v[144:147], v[198:201], v[52:55]
	v_mfma_f32_16x16x32_bf16 v[48:51], v[152:155], v[198:201], v[48:51]
	v_mfma_f32_16x16x32_bf16 v[44:47], v[144:147], v[206:209], v[44:47]
	v_mfma_f32_16x16x32_bf16 v[40:43], v[152:155], v[206:209], v[40:43]
	v_mfma_f32_16x16x32_bf16 v[36:39], v[144:147], v[214:217], v[36:39]
	v_mfma_f32_16x16x32_bf16 v[32:35], v[152:155], v[214:217], v[32:35]
	s_barrier
	v_lshl_add_u64 v[128:129], v[128:129], 0, s[34:35]
	s_add_i32 s82, s98, 0xc000
	v_lshl_add_u64 v[142:143], v[128:129], 0, s[18:19]
	s_mov_b32 m0, s82
	s_add_i32 s82, s98, 0xe000
	global_load_lds_dwordx4 v[142:143], off
	v_lshl_add_u64 v[142:143], v[128:129], 0, s[20:21]
	s_mov_b32 m0, s82
	s_nop 0
	global_load_lds_dwordx4 v[142:143], off
	s_waitcnt vmcnt(12)
	s_barrier
	v_mfma_f32_16x16x32_bf16 v[28:31], v[218:221], v[156:159], v[28:31]
	v_mfma_f32_16x16x32_bf16 v[24:27], v[226:229], v[156:159], v[24:27]
	v_mfma_f32_16x16x32_bf16 v[20:23], v[218:221], v[194:197], v[20:23]
	v_mfma_f32_16x16x32_bf16 v[16:19], v[226:229], v[194:197], v[16:19]
	v_mfma_f32_16x16x32_bf16 v[12:15], v[218:221], v[202:205], v[12:15]
	v_mfma_f32_16x16x32_bf16 v[8:11], v[226:229], v[202:205], v[8:11]
	v_mfma_f32_16x16x32_bf16 v[4:7], v[218:221], v[210:213], v[4:7]
	v_mfma_f32_16x16x32_bf16 v[0:3], v[226:229], v[210:213], v[0:3]
	v_mfma_f32_16x16x32_bf16 v[28:31], v[222:225], v[160:163], v[28:31]
	v_mfma_f32_16x16x32_bf16 v[24:27], v[230:233], v[160:163], v[24:27]
	v_mfma_f32_16x16x32_bf16 v[20:23], v[222:225], v[198:201], v[20:23]
	v_mfma_f32_16x16x32_bf16 v[16:19], v[230:233], v[198:201], v[16:19]
	v_mfma_f32_16x16x32_bf16 v[12:15], v[222:225], v[206:209], v[12:15]
	v_mfma_f32_16x16x32_bf16 v[8:11], v[230:233], v[206:209], v[8:11]
	v_mfma_f32_16x16x32_bf16 v[4:7], v[222:225], v[214:217], v[4:7]
	v_mfma_f32_16x16x32_bf16 v[0:3], v[230:233], v[214:217], v[0:3]
	s_add_i32 s14, s14, 2
	s_add_u32 s56, s56, s58
	s_addc_u32 s57, s57, s59
	s_add_u32 s60, s60, s58
	s_addc_u32 s61, s61, s59
	s_cmp_lt_u32 s14, 28
	s_barrier
	s_cbranch_scc1 .LBB0_234
	s_lshl_b32 s14, s62, 3
	s_or_b32 s82, s63, s14
	s_lshl_b32 s56, s82, 8
	v_lshlrev_b32_e32 v128, 3, v131
	v_lshlrev_b32_e32 v129, 5, v131
	s_or_b32 s14, s56, 0x80
	v_and_b32_e32 v128, 0x7fff0, v128
	v_and_b32_e32 v129, 32, v129
	s_lshl_b64 s[58:59], s[14:15], 13
	v_add_u32_e32 v129, v129, v134
	v_add_lshl_u32 v128, v133, v128, 13
	s_add_u32 s58, s40, s58
	v_lshl_add_u32 v164, v129, 1, v128
	s_addc_u32 s59, s41, s59
	v_lshl_add_u64 v[128:129], s[58:59], 0, v[164:165]
	v_readfirstlane_b32 s14, v137
	ds_read_b128 v[140:143], v138
	ds_read_b128 v[144:147], v138 offset:1024
	ds_read_b128 v[148:151], v138 offset:2048
	ds_read_b128 v[152:155], v138 offset:3072
	ds_read_b128 v[156:159], v193
	ds_read_b128 v[160:163], v193 offset:1024
	ds_read_b128 v[194:197], v192
	ds_read_b128 v[198:201], v192 offset:1024
	ds_read_b128 v[202:205], v191
	ds_read_b128 v[206:209], v191 offset:1024
	ds_read_b128 v[210:213], v190
	ds_read_b128 v[214:217], v190 offset:1024
	v_lshl_add_u64 v[138:139], v[128:129], 0, s[44:45]
	s_mov_b32 m0, s14
	v_readfirstlane_b32 s14, v136
	global_load_lds_dwordx4 v[138:139], off
	v_lshl_add_u64 v[128:129], v[128:129], 0, s[46:47]
	s_mov_b32 m0, s14
	s_mov_b32 s57, s15
	global_load_lds_dwordx4 v[128:129], off
	s_waitcnt vmcnt(10)
	s_barrier
	s_waitcnt lgkmcnt(0)
	s_setprio 1
	s_waitcnt lgkmcnt(0)
	v_mfma_f32_16x16x32_bf16 v[124:127], v[140:143], v[156:159], v[124:127]
	v_mfma_f32_16x16x32_bf16 v[120:123], v[148:151], v[156:159], v[120:123]
	v_mfma_f32_16x16x32_bf16 v[116:119], v[140:143], v[194:197], v[116:119]
	v_mfma_f32_16x16x32_bf16 v[112:115], v[148:151], v[194:197], v[112:115]
	v_mfma_f32_16x16x32_bf16 v[108:111], v[140:143], v[202:205], v[108:111]
	v_mfma_f32_16x16x32_bf16 v[104:107], v[148:151], v[202:205], v[104:107]
	v_mfma_f32_16x16x32_bf16 v[100:103], v[140:143], v[210:213], v[100:103]
	v_mfma_f32_16x16x32_bf16 v[96:99], v[148:151], v[210:213], v[96:99]
	v_mfma_f32_16x16x32_bf16 v[124:127], v[144:147], v[160:163], v[124:127]
	v_mfma_f32_16x16x32_bf16 v[120:123], v[152:155], v[160:163], v[120:123]
	v_mfma_f32_16x16x32_bf16 v[116:119], v[144:147], v[198:201], v[116:119]
	v_mfma_f32_16x16x32_bf16 v[112:115], v[152:155], v[198:201], v[112:115]
	v_mfma_f32_16x16x32_bf16 v[108:111], v[144:147], v[206:209], v[108:111]
	v_mfma_f32_16x16x32_bf16 v[104:107], v[152:155], v[206:209], v[104:107]
	v_mfma_f32_16x16x32_bf16 v[100:103], v[144:147], v[214:217], v[100:103]
	v_mfma_f32_16x16x32_bf16 v[96:99], v[152:155], v[214:217], v[96:99]
	s_setprio 0
	s_barrier
	ds_read_b128 v[136:139], v135
	ds_read_b128 v[218:221], v135 offset:1024
	ds_read_b128 v[222:225], v135 offset:2048
	ds_read_b128 v[226:229], v135 offset:3072
	s_barrier
	s_waitcnt lgkmcnt(0)
	s_setprio 1
	s_waitcnt lgkmcnt(0)
	v_mfma_f32_16x16x32_bf16 v[92:95], v[136:139], v[156:159], v[92:95]
	v_mfma_f32_16x16x32_bf16 v[84:87], v[136:139], v[194:197], v[84:87]
	v_mfma_f32_16x16x32_bf16 v[80:83], v[222:225], v[194:197], v[80:83]
	v_mfma_f32_16x16x32_bf16 v[88:91], v[222:225], v[156:159], v[88:91]
	v_mfma_f32_16x16x32_bf16 v[76:79], v[136:139], v[202:205], v[76:79]
	v_mfma_f32_16x16x32_bf16 v[72:75], v[222:225], v[202:205], v[72:75]
	v_mfma_f32_16x16x32_bf16 v[68:71], v[136:139], v[210:213], v[68:71]
	v_mfma_f32_16x16x32_bf16 v[64:67], v[222:225], v[210:213], v[64:67]
	v_mfma_f32_16x16x32_bf16 v[156:159], v[218:221], v[160:163], v[92:95]
	v_mfma_f32_16x16x32_bf16 v[194:197], v[218:221], v[198:201], v[84:87]
	v_mfma_f32_16x16x32_bf16 v[198:201], v[226:229], v[198:201], v[80:83]
	v_mfma_f32_16x16x32_bf16 v[160:163], v[226:229], v[160:163], v[88:91]
	v_mfma_f32_16x16x32_bf16 v[202:205], v[218:221], v[206:209], v[76:79]
	v_mfma_f32_16x16x32_bf16 v[206:209], v[226:229], v[206:209], v[72:75]
	v_mfma_f32_16x16x32_bf16 v[210:213], v[218:221], v[214:217], v[68:71]
	v_mfma_f32_16x16x32_bf16 v[214:217], v[226:229], v[214:217], v[64:67]
	s_setprio 0
	s_barrier
	s_nop 0
	ds_read_b128 v[64:67], v193 offset:16384
	ds_read_b128 v[68:71], v193 offset:17408
	ds_read_b128 v[72:75], v192 offset:16384
	ds_read_b128 v[76:79], v192 offset:17408
	ds_read_b128 v[80:83], v191 offset:16384
	ds_read_b128 v[84:87], v191 offset:17408
	ds_read_b128 v[88:91], v190 offset:16384
	ds_read_b128 v[92:95], v190 offset:17408
	s_waitcnt vmcnt(4)
	s_barrier
	s_waitcnt lgkmcnt(0)
	s_setprio 1
	s_waitcnt lgkmcnt(0)
	v_mfma_f32_16x16x32_bf16 v[60:63], v[140:143], v[64:67], v[60:63]
	v_mfma_f32_16x16x32_bf16 v[56:59], v[148:151], v[64:67], v[56:59]
	v_mfma_f32_16x16x32_bf16 v[52:55], v[140:143], v[72:75], v[52:55]
	v_mfma_f32_16x16x32_bf16 v[48:51], v[148:151], v[72:75], v[48:51]
	v_mfma_f32_16x16x32_bf16 v[230:233], v[140:143], v[80:83], v[44:47]
	v_mfma_f32_16x16x32_bf16 v[234:237], v[148:151], v[80:83], v[40:43]
	v_mfma_f32_16x16x32_bf16 v[140:143], v[140:143], v[88:91], v[36:39]
	v_mfma_f32_16x16x32_bf16 v[148:151], v[148:151], v[88:91], v[32:35]
	v_mfma_f32_16x16x32_bf16 v[32:35], v[144:147], v[68:71], v[60:63]
	v_mfma_f32_16x16x32_bf16 v[36:39], v[152:155], v[68:71], v[56:59]
	v_mfma_f32_16x16x32_bf16 v[40:43], v[144:147], v[76:79], v[52:55]
	v_mfma_f32_16x16x32_bf16 v[44:47], v[152:155], v[76:79], v[48:51]
	v_mfma_f32_16x16x32_bf16 v[48:51], v[144:147], v[84:87], v[230:233]
	v_mfma_f32_16x16x32_bf16 v[52:55], v[152:155], v[84:87], v[234:237]
	v_mfma_f32_16x16x32_bf16 v[56:59], v[144:147], v[92:95], v[140:143]
	v_mfma_f32_16x16x32_bf16 v[60:63], v[152:155], v[92:95], v[148:151]
	s_setprio 0
	s_setprio 1
	v_mfma_f32_16x16x32_bf16 v[28:31], v[136:139], v[64:67], v[28:31]
	v_mfma_f32_16x16x32_bf16 v[24:27], v[222:225], v[64:67], v[24:27]
	v_mfma_f32_16x16x32_bf16 v[20:23], v[136:139], v[72:75], v[20:23]
	v_mfma_f32_16x16x32_bf16 v[64:67], v[222:225], v[72:75], v[16:19]
	v_mfma_f32_16x16x32_bf16 v[12:15], v[136:139], v[80:83], v[12:15]
	v_mfma_f32_16x16x32_bf16 v[8:11], v[222:225], v[80:83], v[8:11]
	v_mfma_f32_16x16x32_bf16 v[72:75], v[136:139], v[88:91], v[4:7]
	v_mfma_f32_16x16x32_bf16 v[80:83], v[222:225], v[88:91], v[0:3]
	v_mfma_f32_16x16x32_bf16 v[0:3], v[218:221], v[68:71], v[28:31]
	v_mfma_f32_16x16x32_bf16 v[4:7], v[226:229], v[68:71], v[24:27]
	v_mfma_f32_16x16x32_bf16 v[16:19], v[218:221], v[76:79], v[20:23]
	v_mfma_f32_16x16x32_bf16 v[20:23], v[226:229], v[76:79], v[64:67]
	v_mfma_f32_16x16x32_bf16 v[24:27], v[218:221], v[84:87], v[12:15]
	v_mfma_f32_16x16x32_bf16 v[28:31], v[226:229], v[84:87], v[8:11]
	v_mfma_f32_16x16x32_bf16 v[64:67], v[218:221], v[92:95], v[72:75]
	v_mfma_f32_16x16x32_bf16 v[68:71], v[226:229], v[92:95], v[80:83]
	s_setprio 0
	s_barrier
	ds_read_b128 v[12:15], v130
	ds_read_b128 v[8:11], v130 offset:1024
	ds_read_b128 v[76:79], v130 offset:2048
	ds_read_b128 v[72:75], v130 offset:3072
	ds_read_b128 v[140:143], v193 offset:32768
	ds_read_b128 v[148:151], v193 offset:33792
	ds_read_b128 v[218:221], v192 offset:32768
	ds_read_b128 v[222:225], v192 offset:33792
	ds_read_b128 v[226:229], v191 offset:32768
	ds_read_b128 v[230:233], v191 offset:33792
	ds_read_b128 v[234:237], v190 offset:32768
	ds_read_b128 v[238:241], v190 offset:33792
	s_waitcnt vmcnt(2)
	s_barrier
	s_waitcnt lgkmcnt(0)
	s_setprio 1
	s_waitcnt lgkmcnt(0)
	v_mfma_f32_16x16x32_bf16 v[80:83], v[12:15], v[140:143], v[124:127]
	v_mfma_f32_16x16x32_bf16 v[84:87], v[76:79], v[140:143], v[120:123]
	v_mfma_f32_16x16x32_bf16 v[88:91], v[12:15], v[218:221], v[116:119]
	v_mfma_f32_16x16x32_bf16 v[92:95], v[76:79], v[218:221], v[112:115]
	v_mfma_f32_16x16x32_bf16 v[108:111], v[12:15], v[226:229], v[108:111]
	v_mfma_f32_16x16x32_bf16 v[104:107], v[76:79], v[226:229], v[104:107]
	v_mfma_f32_16x16x32_bf16 v[100:103], v[12:15], v[234:237], v[100:103]
	v_mfma_f32_16x16x32_bf16 v[96:99], v[76:79], v[234:237], v[96:99]
	v_mfma_f32_16x16x32_bf16 v[152:155], v[8:11], v[148:151], v[80:83]
	v_mfma_f32_16x16x32_bf16 v[144:147], v[72:75], v[148:151], v[84:87]
	v_mfma_f32_16x16x32_bf16 v[136:139], v[8:11], v[222:225], v[88:91]
	v_mfma_f32_16x16x32_bf16 v[128:131], v[72:75], v[222:225], v[92:95]
	v_mfma_f32_16x16x32_bf16 v[120:123], v[8:11], v[230:233], v[108:111]
	v_mfma_f32_16x16x32_bf16 v[112:115], v[72:75], v[230:233], v[104:107]
	v_mfma_f32_16x16x32_bf16 v[104:107], v[8:11], v[238:241], v[100:103]
	v_mfma_f32_16x16x32_bf16 v[96:99], v[72:75], v[238:241], v[96:99]
	s_setprio 0
	s_barrier
	ds_read_b128 v[88:91], v132
	ds_read_b128 v[80:83], v132 offset:1024
	ds_read_b128 v[92:95], v132 offset:2048
	ds_read_b128 v[84:87], v132 offset:3072
	s_waitcnt vmcnt(0)
	s_barrier
	s_waitcnt lgkmcnt(0)
	s_setprio 1
	s_waitcnt lgkmcnt(0)
	v_mfma_f32_16x16x32_bf16 v[100:103], v[88:91], v[140:143], v[156:159]
	v_mfma_f32_16x16x32_bf16 v[108:111], v[92:95], v[140:143], v[160:163]
	v_mfma_f32_16x16x32_bf16 v[116:119], v[88:91], v[218:221], v[194:197]
	v_mfma_f32_16x16x32_bf16 v[124:127], v[92:95], v[218:221], v[198:201]
	v_mfma_f32_16x16x32_bf16 v[160:163], v[88:91], v[226:229], v[202:205]
	v_mfma_f32_16x16x32_bf16 v[194:197], v[92:95], v[226:229], v[206:209]
	v_mfma_f32_16x16x32_bf16 v[198:201], v[88:91], v[234:237], v[210:213]
	v_mfma_f32_16x16x32_bf16 v[202:205], v[92:95], v[234:237], v[214:217]
	v_mfma_f32_16x16x32_bf16 v[156:159], v[80:83], v[148:151], v[100:103]
	v_mfma_f32_16x16x32_bf16 v[148:151], v[84:87], v[148:151], v[108:111]
	v_mfma_f32_16x16x32_bf16 v[140:143], v[80:83], v[222:225], v[116:119]
	v_mfma_f32_16x16x32_bf16 v[132:135], v[84:87], v[222:225], v[124:127]
	v_mfma_f32_16x16x32_bf16 v[124:127], v[80:83], v[230:233], v[160:163]
	v_mfma_f32_16x16x32_bf16 v[116:119], v[84:87], v[230:233], v[194:197]
	v_mfma_f32_16x16x32_bf16 v[108:111], v[80:83], v[238:241], v[198:201]
	v_mfma_f32_16x16x32_bf16 v[100:103], v[84:87], v[238:241], v[202:205]
	s_setprio 0
	s_lshl_b64 s[58:59], s[56:57], 2
	s_barrier
	v_mbcnt_lo_u32_b32 v162, -1, 0
	v_mbcnt_hi_u32_b32 v162, -1, v162
	s_add_u32 s58, s87, s58
	v_add_u32_e32 v160, s64, v162
	s_addc_u32 s59, s88, s59
	v_and_b32_e32 v164, 0x100, v160
	v_and_b32_e32 v162, 15, v162
	v_lshl_add_u64 v[160:161], s[58:59], 0, v[164:165]
	v_lshlrev_b32_e32 v164, 2, v162
	v_lshl_add_u64 v[160:161], v[160:161], 0, v[164:165]
	global_load_dword v180, v[160:161], off
	global_load_dword v178, v[160:161], off offset:64
	global_load_dword v176, v[160:161], off offset:128
	global_load_dword v174, v[160:161], off offset:192
	global_load_dword v172, v[160:161], off offset:512
	global_load_dword v170, v[160:161], off offset:576
	global_load_dword v168, v[160:161], off offset:640
	global_load_dword v166, v[160:161], off offset:704
	v_mbcnt_lo_u32_b32 v194, -1, 0
	v_mbcnt_hi_u32_b32 v194, -1, v194
	s_cmp_lg_u32 s81, 0
	v_add_u32_e32 v160, s64, v194
	v_bfe_u32 v196, v160, 8, 1
	v_ashrrev_i32_e32 v199, 6, v160
	v_bfe_u32 v160, v194, 4, 2
	s_cselect_b64 s[58:59], -1, 0
	v_and_b32_e32 v197, 3, v199
	v_and_b32_e32 v195, 15, v194
	s_and_b64 vcc, exec, s[58:59]
	v_lshlrev_b32_e32 v198, 4, v160
	s_cbranch_vccz .LBB0_246
	s_lshl_b32 s14, s80, 22
	s_lshl_b32 s57, s82, 14
	s_add_i32 s57, s57, s14
	v_lshlrev_b32_e32 v160, 6, v195
	v_or3_b32 v160, s57, v160, v198
	v_lshl_add_u32 v160, v197, 20, v160
	v_lshl_or_b32 v164, v196, 12, v160
	s_waitcnt vmcnt(0)
	v_pk_mul_f32 v[160:161], v[154:155], v[180:181] op_sel_hi:[1,0]
	v_pk_mul_f32 v[200:201], v[146:147], v[180:181] op_sel_hi:[1,0]
	v_max_f32_e32 v160, 0, v160
	v_mul_f32_e32 v204, v160, v160
	v_max_f32_e32 v160, 0, v200
	v_pk_mul_f32 v[162:163], v[152:153], v[180:181] op_sel_hi:[1,0]
	v_mul_f32_e32 v200, v160, v160
	v_max_f32_e32 v160, 0, v161
	v_pk_mul_f32 v[202:203], v[144:145], v[180:181] op_sel_hi:[1,0]
	v_max_f32_e32 v162, 0, v162
	v_max_f32_e32 v163, 0, v163
	v_mul_f32_e32 v161, v160, v160
	v_max_f32_e32 v160, 0, v201
	v_mul_f32_e32 v162, v162, v162
	v_max_f32_e32 v202, 0, v202
	v_mul_f32_e32 v163, v163, v163
	v_max_f32_e32 v203, 0, v203
	v_mul_f32_e32 v201, v160, v160
	v_cvt_pk_bf16_f32 v160, v162, v163
	v_cvt_pk_bf16_f32 v161, v204, v161
	v_mul_f32_e32 v202, v202, v202
	v_mul_f32_e32 v203, v203, v203
	v_cvt_pk_bf16_f32 v162, v202, v203
	v_cvt_pk_bf16_f32 v163, v200, v201
	global_store_dwordx4 v164, v[160:163], s[0:1]
	v_pk_mul_f32 v[202:203], v[150:151], v[180:181] op_sel_hi:[1,0]
	v_lshl_add_u64 v[200:201], s[0:1], 0, v[164:165]
	v_pk_mul_f32 v[160:161], v[158:159], v[180:181] op_sel_hi:[1,0]
	v_pk_mul_f32 v[162:163], v[156:157], v[180:181] op_sel_hi:[1,0]
	v_max_f32_e32 v160, 0, v160
	v_mul_f32_e32 v206, v160, v160
	v_max_f32_e32 v160, 0, v202
	v_mul_f32_e32 v202, v160, v160
	v_max_f32_e32 v160, 0, v161
	v_pk_mul_f32 v[204:205], v[148:149], v[180:181] op_sel_hi:[1,0]
	v_max_f32_e32 v162, 0, v162
	v_max_f32_e32 v163, 0, v163
	v_mul_f32_e32 v161, v160, v160
	v_max_f32_e32 v160, 0, v203
	v_add_co_u32_e32 v200, vcc, s74, v200
	v_mul_f32_e32 v162, v162, v162
	v_max_f32_e32 v204, 0, v204
	v_mul_f32_e32 v163, v163, v163
	v_max_f32_e32 v205, 0, v205
	v_mul_f32_e32 v203, v160, v160
	v_cvt_pk_bf16_f32 v160, v162, v163
	v_cvt_pk_bf16_f32 v161, v206, v161
	v_addc_co_u32_e32 v201, vcc, 0, v201, vcc
	v_mul_f32_e32 v204, v204, v204
	v_mul_f32_e32 v205, v205, v205
	v_cvt_pk_bf16_f32 v162, v204, v205
	v_cvt_pk_bf16_f32 v163, v202, v203
	global_store_dwordx4 v[200:201], v[160:163], off
	v_pk_mul_f32 v[202:203], v[130:131], v[178:179] op_sel_hi:[1,0]
	v_pk_mul_f32 v[204:205], v[128:129], v[178:179] op_sel_hi:[1,0]
	v_pk_mul_f32 v[160:161], v[138:139], v[178:179] op_sel_hi:[1,0]
	v_pk_mul_f32 v[162:163], v[136:137], v[178:179] op_sel_hi:[1,0]
	v_max_f32_e32 v160, 0, v160
	v_mul_f32_e32 v206, v160, v160
	v_max_f32_e32 v160, 0, v202
	v_mul_f32_e32 v202, v160, v160
	v_max_f32_e32 v160, 0, v161
	v_max_f32_e32 v162, 0, v162
	v_max_f32_e32 v163, 0, v163
	v_mul_f32_e32 v161, v160, v160
	v_max_f32_e32 v160, 0, v203
	v_mul_f32_e32 v162, v162, v162
	v_max_f32_e32 v204, 0, v204
	v_mul_f32_e32 v163, v163, v163
	v_max_f32_e32 v205, 0, v205
	v_mul_f32_e32 v203, v160, v160
	v_cvt_pk_bf16_f32 v160, v162, v163
	v_cvt_pk_bf16_f32 v161, v206, v161
	v_mul_f32_e32 v204, v204, v204
	v_mul_f32_e32 v205, v205, v205
	v_cvt_pk_bf16_f32 v162, v204, v205
	v_cvt_pk_bf16_f32 v163, v202, v203
	global_store_dwordx4 v164, v[160:163], s[0:1] offset:1024
	v_pk_mul_f32 v[202:203], v[134:135], v[178:179] op_sel_hi:[1,0]
	v_pk_mul_f32 v[204:205], v[132:133], v[178:179] op_sel_hi:[1,0]
	v_pk_mul_f32 v[160:161], v[142:143], v[178:179] op_sel_hi:[1,0]
	v_pk_mul_f32 v[162:163], v[140:141], v[178:179] op_sel_hi:[1,0]
	v_max_f32_e32 v160, 0, v160
	v_mul_f32_e32 v206, v160, v160
	v_max_f32_e32 v160, 0, v202
	v_mul_f32_e32 v202, v160, v160
	v_max_f32_e32 v160, 0, v161
	v_max_f32_e32 v162, 0, v162
	v_max_f32_e32 v163, 0, v163
	v_mul_f32_e32 v161, v160, v160
	v_max_f32_e32 v160, 0, v203
	v_mul_f32_e32 v162, v162, v162
	v_max_f32_e32 v204, 0, v204
	v_mul_f32_e32 v163, v163, v163
	v_max_f32_e32 v205, 0, v205
	v_mul_f32_e32 v203, v160, v160
	v_cvt_pk_bf16_f32 v160, v162, v163
	v_cvt_pk_bf16_f32 v161, v206, v161
	v_mul_f32_e32 v204, v204, v204
	v_mul_f32_e32 v205, v205, v205
	v_cvt_pk_bf16_f32 v162, v204, v205
	v_cvt_pk_bf16_f32 v163, v202, v203
	global_store_dwordx4 v[200:201], v[160:163], off offset:1024
	v_pk_mul_f32 v[202:203], v[114:115], v[176:177] op_sel_hi:[1,0]
	v_pk_mul_f32 v[204:205], v[112:113], v[176:177] op_sel_hi:[1,0]
	v_pk_mul_f32 v[160:161], v[122:123], v[176:177] op_sel_hi:[1,0]
	v_pk_mul_f32 v[162:163], v[120:121], v[176:177] op_sel_hi:[1,0]
	v_max_f32_e32 v160, 0, v160
	v_mul_f32_e32 v206, v160, v160
	v_max_f32_e32 v160, 0, v202
	v_mul_f32_e32 v202, v160, v160
	v_max_f32_e32 v160, 0, v161
	v_max_f32_e32 v162, 0, v162
	v_max_f32_e32 v163, 0, v163
	v_mul_f32_e32 v161, v160, v160
	v_max_f32_e32 v160, 0, v203
	v_mul_f32_e32 v162, v162, v162
	v_max_f32_e32 v204, 0, v204
	v_mul_f32_e32 v163, v163, v163
	v_max_f32_e32 v205, 0, v205
	v_mul_f32_e32 v203, v160, v160
	v_cvt_pk_bf16_f32 v160, v162, v163
	v_cvt_pk_bf16_f32 v161, v206, v161
	v_mul_f32_e32 v204, v204, v204
	v_mul_f32_e32 v205, v205, v205
	v_cvt_pk_bf16_f32 v162, v204, v205
	v_cvt_pk_bf16_f32 v163, v202, v203
	global_store_dwordx4 v164, v[160:163], s[0:1] offset:2048
	v_pk_mul_f32 v[202:203], v[118:119], v[176:177] op_sel_hi:[1,0]
	v_pk_mul_f32 v[204:205], v[116:117], v[176:177] op_sel_hi:[1,0]
	v_pk_mul_f32 v[160:161], v[126:127], v[176:177] op_sel_hi:[1,0]
	v_pk_mul_f32 v[162:163], v[124:125], v[176:177] op_sel_hi:[1,0]
	v_max_f32_e32 v160, 0, v160
	v_mul_f32_e32 v206, v160, v160
	v_max_f32_e32 v160, 0, v202
	v_mul_f32_e32 v202, v160, v160
	v_max_f32_e32 v160, 0, v161
	v_max_f32_e32 v162, 0, v162
	v_max_f32_e32 v163, 0, v163
	v_mul_f32_e32 v161, v160, v160
	v_max_f32_e32 v160, 0, v203
	v_mul_f32_e32 v162, v162, v162
	v_max_f32_e32 v204, 0, v204
	v_mul_f32_e32 v163, v163, v163
	v_max_f32_e32 v205, 0, v205
	v_mul_f32_e32 v203, v160, v160
	v_cvt_pk_bf16_f32 v160, v162, v163
	v_cvt_pk_bf16_f32 v161, v206, v161
	v_mul_f32_e32 v204, v204, v204
	v_mul_f32_e32 v205, v205, v205
	v_cvt_pk_bf16_f32 v162, v204, v205
	v_cvt_pk_bf16_f32 v163, v202, v203
	global_store_dwordx4 v[200:201], v[160:163], off offset:2048
	v_pk_mul_f32 v[200:201], v[98:99], v[174:175] op_sel_hi:[1,0]
	v_pk_mul_f32 v[202:203], v[96:97], v[174:175] op_sel_hi:[1,0]
	v_pk_mul_f32 v[160:161], v[106:107], v[174:175] op_sel_hi:[1,0]
	v_pk_mul_f32 v[162:163], v[104:105], v[174:175] op_sel_hi:[1,0]
	v_max_f32_e32 v160, 0, v160
	v_mul_f32_e32 v204, v160, v160
	v_max_f32_e32 v160, 0, v200
	v_mul_f32_e32 v200, v160, v160
	v_max_f32_e32 v160, 0, v161
	v_max_f32_e32 v162, 0, v162
	v_max_f32_e32 v163, 0, v163
	v_mul_f32_e32 v161, v160, v160
	v_max_f32_e32 v160, 0, v201
	v_mul_f32_e32 v162, v162, v162
	v_max_f32_e32 v202, 0, v202
	v_mul_f32_e32 v163, v163, v163
	v_max_f32_e32 v203, 0, v203
	v_mul_f32_e32 v201, v160, v160
	v_cvt_pk_bf16_f32 v160, v162, v163
	v_cvt_pk_bf16_f32 v161, v204, v161
	v_mul_f32_e32 v202, v202, v202
	v_mul_f32_e32 v203, v203, v203
	v_cvt_pk_bf16_f32 v162, v202, v203
	v_cvt_pk_bf16_f32 v163, v200, v201
	global_store_dwordx4 v164, v[160:163], s[0:1] offset:3072
	v_pk_mul_f32 v[200:201], v[102:103], v[174:175] op_sel_hi:[1,0]
	v_pk_mul_f32 v[202:203], v[100:101], v[174:175] op_sel_hi:[1,0]
	v_pk_mul_f32 v[160:161], v[110:111], v[174:175] op_sel_hi:[1,0]
	v_pk_mul_f32 v[162:163], v[108:109], v[174:175] op_sel_hi:[1,0]
	v_max_f32_e32 v160, 0, v160
	v_mul_f32_e32 v204, v160, v160
	v_max_f32_e32 v160, 0, v200
	v_max_f32_e32 v162, 0, v162
	v_max_f32_e32 v163, 0, v163
	v_mul_f32_e32 v200, v160, v160
	v_max_f32_e32 v160, 0, v161
	v_mul_f32_e32 v162, v162, v162
	v_max_f32_e32 v202, 0, v202
	v_mul_f32_e32 v163, v163, v163
	v_max_f32_e32 v203, 0, v203
	v_mul_f32_e32 v161, v160, v160
	v_max_f32_e32 v160, 0, v201
	v_mul_f32_e32 v202, v202, v202
	v_mul_f32_e32 v203, v203, v203
	v_mul_f32_e32 v201, v160, v160
	v_cvt_pk_bf16_f32 v160, v162, v163
	v_cvt_pk_bf16_f32 v161, v204, v161
	v_cvt_pk_bf16_f32 v162, v202, v203
	v_cvt_pk_bf16_f32 v163, v200, v201
	v_add_u32_e32 v164, 0x80c00, v164
	s_cbranch_execnz .LBB0_238

.LBB0_273:
	v_and_b32_e32 v2, 15, v0
	s_bfe_u32 s64, s86, 0x30003
	v_and_b32_e32 v3, 48, v0
	v_lshlrev_b32_e32 v134, 4, v135
	v_and_b32_e32 v5, 32, v0
	s_movk_i32 s65, 0x3f0
	v_and_b32_e32 v6, 64, v135
	v_lshlrev_b32_e32 v2, 6, v2
	v_lshlrev_b32_e32 v9, 2, v0
	v_lshlrev_b32_e32 v0, 6, v0
	s_lshl_b32 s66, s64, 14
	v_and_b32_e32 v4, 0x3f0, v134
	v_bitop3_b32 v155, v134, v5, s65 bitop3:0x6c
	v_lshlrev_b32_e32 v156, 13, v6
	v_lshlrev_b32_e32 v7, 3, v135
	v_mul_i32_i24_e32 v6, 0xffffe800, v6
	s_add_i32 s65, s20, -2
	v_or_b32_e32 v8, v2, v3
	v_and_b32_e32 v9, 32, v9
	s_mov_b32 s67, 0x14000
	v_and_b32_e32 v0, 0x3c0, v0
	v_and_b32_e32 v157, 0xfffffc00, v7
	v_bitop3_b32 v2, v2, v9, v3 bitop3:0x36
	v_bitop3_b32 v11, v8, s67, v9 bitop3:0xde
	s_mov_b32 s67, 0x1c000
	v_bitop3_b32 v3, v0, v9, v3 bitop3:0x36
	v_bitop3_b32 v0, v6, v4, v5 bitop3:0xf6
	s_add_u32 s66, s70, s66
	v_bitop3_b32 v10, v8, s74, v9 bitop3:0xde
	v_bitop3_b32 v12, v8, s75, v9 bitop3:0xde
	v_bitop3_b32 v8, v8, s67, v9 bitop3:0xde
	v_add3_u32 v128, v0, v156, v157
	s_addc_u32 s67, s71, 0
	v_lshlrev_b32_e32 v13, 13, v1
	v_lshl_add_u64 v[0:1], s[66:67], 0, v[128:129]
	s_mov_b64 s[66:67], 0xc3000
	v_lshl_add_u64 v[130:131], v[0:1], 0, s[66:67]
	s_lshl_b32 s66, s86, 11
	s_and_b32 s67, s86, 7
	s_and_b32 s66, s66, 0x60000
	s_lshl_b32 s67, s67, 14
	s_or_b32 s66, s66, s67
	v_bitop3_b32 v0, v4, v156, v5 bitop3:0xde
	s_add_u32 s66, s68, s66
	v_add_u32_e32 v128, v0, v157
	s_addc_u32 s67, s69, 0
	v_lshlrev_b32_e32 v7, 6, v135
	v_lshl_add_u64 v[0:1], s[66:67], 0, v[128:129]
	s_mov_b64 s[66:67], 0x301000
	v_and_b32_e32 v7, 0x3000, v7
	v_or_b32_e32 v9, 0x800, v13
	v_or_b32_e32 v14, 0x1000, v13
	v_or_b32_e32 v15, 0x1800, v13
	v_lshl_add_u64 v[132:133], v[0:1], 0, s[66:67]
	v_mov_b32_e32 v0, 0
	s_mov_b32 s66, 0
	v_add_u32_e32 v161, v10, v7
	v_add_u32_e32 v152, v2, v13
	v_add_u32_e32 v151, v3, v9
	v_add_u32_e32 v150, v3, v14
	v_add_u32_e32 v149, v3, v15
	v_add_u32_e32 v160, 0xc000, v134
	v_add_u32_e32 v159, 0xe000, v134
	v_add_u32_e32 v158, v11, v7
	v_add_u32_e32 v148, 0x10000, v134
	v_add_u32_e32 v147, 0x12000, v134
	v_add_u32_e32 v146, 0x2000, v134
	v_add_u32_e32 v145, 0x14000, v134
	v_add_u32_e32 v144, 0x16000, v134
	v_add_u32_e32 v154, v12, v7
	v_add_u32_e32 v143, 0x4000, v134
	v_add_u32_e32 v142, 0x6000, v134
	v_add_u32_e32 v153, v8, v7
	v_add_u32_e32 v141, 0x18000, v134
	v_add_u32_e32 v140, 0x1a000, v134
	v_add_u32_e32 v139, 0x8000, v134
	v_add_u32_e32 v138, 0xa000, v134
	v_add_u32_e32 v137, 0x1c000, v134
	v_add_u32_e32 v136, 0x1e000, v134
	v_mov_b32_e32 v1, v0
	v_mov_b32_e32 v2, v0
	v_mov_b32_e32 v3, v0
	v_mov_b32_e32 v4, v0
	v_mov_b32_e32 v5, v0
	v_mov_b32_e32 v6, v0
	v_mov_b32_e32 v7, v0
	v_mov_b32_e32 v8, v0
	v_mov_b32_e32 v9, v0
	v_mov_b32_e32 v10, v0
	v_mov_b32_e32 v11, v0
	v_mov_b32_e32 v12, v0
	v_mov_b32_e32 v13, v0
	v_mov_b32_e32 v14, v0
	v_mov_b32_e32 v15, v0
	v_mov_b32_e32 v16, v0
	v_mov_b32_e32 v17, v0
	v_mov_b32_e32 v18, v0
	v_mov_b32_e32 v19, v0
	v_mov_b32_e32 v20, v0
	v_mov_b32_e32 v21, v0
	v_mov_b32_e32 v22, v0
	v_mov_b32_e32 v23, v0
	v_mov_b32_e32 v24, v0
	v_mov_b32_e32 v25, v0
	v_mov_b32_e32 v26, v0
	v_mov_b32_e32 v27, v0
	v_mov_b32_e32 v28, v0
	v_mov_b32_e32 v29, v0
	v_mov_b32_e32 v30, v0
	v_mov_b32_e32 v31, v0
	v_mov_b32_e32 v32, v0
	v_mov_b32_e32 v33, v0
	v_mov_b32_e32 v34, v0
	v_mov_b32_e32 v35, v0
	v_mov_b32_e32 v36, v0
	v_mov_b32_e32 v37, v0
	v_mov_b32_e32 v38, v0
	v_mov_b32_e32 v39, v0
	v_mov_b32_e32 v40, v0
	v_mov_b32_e32 v41, v0
	v_mov_b32_e32 v42, v0
	v_mov_b32_e32 v43, v0
	v_mov_b32_e32 v44, v0
	v_mov_b32_e32 v45, v0
	v_mov_b32_e32 v46, v0
	v_mov_b32_e32 v47, v0
	v_mov_b32_e32 v48, v0
	v_mov_b32_e32 v49, v0
	v_mov_b32_e32 v50, v0
	v_mov_b32_e32 v51, v0
	v_mov_b32_e32 v52, v0
	v_mov_b32_e32 v53, v0
	v_mov_b32_e32 v54, v0
	v_mov_b32_e32 v55, v0
	v_mov_b32_e32 v56, v0
	v_mov_b32_e32 v57, v0
	v_mov_b32_e32 v58, v0
	v_mov_b32_e32 v59, v0
	v_mov_b32_e32 v60, v0
	v_mov_b32_e32 v61, v0
	v_mov_b32_e32 v62, v0
	v_mov_b32_e32 v63, v0
	v_mov_b32_e32 v64, v0
	v_mov_b32_e32 v65, v0
	v_mov_b32_e32 v66, v0
	v_mov_b32_e32 v67, v0
	v_mov_b32_e32 v68, v0
	v_mov_b32_e32 v69, v0
	v_mov_b32_e32 v70, v0
	v_mov_b32_e32 v71, v0
	v_mov_b32_e32 v72, v0
	v_mov_b32_e32 v73, v0
	v_mov_b32_e32 v74, v0
	v_mov_b32_e32 v75, v0
	v_mov_b32_e32 v76, v0
	v_mov_b32_e32 v77, v0
	v_mov_b32_e32 v78, v0
	v_mov_b32_e32 v79, v0
	v_mov_b32_e32 v80, v0
	v_mov_b32_e32 v81, v0
	v_mov_b32_e32 v82, v0
	v_mov_b32_e32 v83, v0
	v_mov_b32_e32 v84, v0
	v_mov_b32_e32 v85, v0
	v_mov_b32_e32 v86, v0
	v_mov_b32_e32 v87, v0
	v_mov_b32_e32 v88, v0
	v_mov_b32_e32 v89, v0
	v_mov_b32_e32 v90, v0
	v_mov_b32_e32 v91, v0
	v_mov_b32_e32 v92, v0
	v_mov_b32_e32 v93, v0
	v_mov_b32_e32 v94, v0
	v_mov_b32_e32 v95, v0
	v_mov_b32_e32 v96, v0
	v_mov_b32_e32 v97, v0
	v_mov_b32_e32 v98, v0
	v_mov_b32_e32 v99, v0
	v_mov_b32_e32 v100, v0
	v_mov_b32_e32 v101, v0
	v_mov_b32_e32 v102, v0
	v_mov_b32_e32 v103, v0
	v_mov_b32_e32 v104, v0
	v_mov_b32_e32 v105, v0
	v_mov_b32_e32 v106, v0
	v_mov_b32_e32 v107, v0
	v_mov_b32_e32 v108, v0
	v_mov_b32_e32 v109, v0
	v_mov_b32_e32 v110, v0
	v_mov_b32_e32 v111, v0
	v_mov_b32_e32 v112, v0
	v_mov_b32_e32 v113, v0
	v_mov_b32_e32 v114, v0
	v_mov_b32_e32 v115, v0
	v_mov_b32_e32 v116, v0
	v_mov_b32_e32 v117, v0
	v_mov_b32_e32 v118, v0
	v_mov_b32_e32 v119, v0
	v_mov_b32_e32 v120, v0
	v_mov_b32_e32 v121, v0
	v_mov_b32_e32 v122, v0
	v_mov_b32_e32 v123, v0
	v_mov_b32_e32 v124, v0
	v_mov_b32_e32 v125, v0
	v_mov_b32_e32 v126, v0
	v_mov_b32_e32 v127, v0
	s_barrier
	v_readlane_b32 s98, v242, 1
	s_lshl_b32 s98, s98, 10
	s_mov_b32 vcc_lo, 0xffe01000
	s_mov_b32 vcc_hi, -1
	v_lshl_add_u64 v[164:165], v[132:133], 0, vcc
	s_add_i32 s67, s98, 0xc000
	s_mov_b32 vcc_lo, 0xffe02000
	s_mov_b32 m0, s67
	s_mov_b32 vcc_hi, -1
	s_add_i32 s67, s98, 0xe000
	global_load_lds_dwordx4 v[164:165], off
	v_lshl_add_u64 v[164:165], v[132:133], 0, vcc
	s_mov_b32 m0, s67
	s_nop 0
	global_load_lds_dwordx4 v[164:165], off
.LBB0_274:
	ds_read_b128 v[162:165], v161
	ds_read_b128 v[166:169], v161 offset:1024
	ds_read_b128 v[170:173], v161 offset:2048
	ds_read_b128 v[174:177], v161 offset:3072
	ds_read_b128 v[178:181], v152
	ds_read_b128 v[182:185], v152 offset:1024
	ds_read_b128 v[186:189], v151
	ds_read_b128 v[190:193], v151 offset:1024
	ds_read_b128 v[194:197], v150
	ds_read_b128 v[198:201], v150 offset:1024
	ds_read_b128 v[202:205], v149
	ds_read_b128 v[206:209], v149 offset:1024
	s_waitcnt lgkmcnt(8)
	s_waitcnt vmcnt(10)
	s_barrier
	s_waitcnt lgkmcnt(0)
	s_waitcnt lgkmcnt(0)
	v_mfma_f32_16x16x32_bf16 v[124:127], v[162:165], v[178:181], v[124:127]
	v_mfma_f32_16x16x32_bf16 v[120:123], v[170:173], v[178:181], v[120:123]
	v_mfma_f32_16x16x32_bf16 v[116:119], v[162:165], v[186:189], v[116:119]
	v_mfma_f32_16x16x32_bf16 v[112:115], v[170:173], v[186:189], v[112:115]
	v_mfma_f32_16x16x32_bf16 v[108:111], v[162:165], v[194:197], v[108:111]
	v_mfma_f32_16x16x32_bf16 v[104:107], v[170:173], v[194:197], v[104:107]
	v_mfma_f32_16x16x32_bf16 v[100:103], v[162:165], v[202:205], v[100:103]
	v_mfma_f32_16x16x32_bf16 v[96:99], v[170:173], v[202:205], v[96:99]
	v_mfma_f32_16x16x32_bf16 v[124:127], v[166:169], v[182:185], v[124:127]
	v_mfma_f32_16x16x32_bf16 v[120:123], v[174:177], v[182:185], v[120:123]
	v_mfma_f32_16x16x32_bf16 v[116:119], v[166:169], v[190:193], v[116:119]
	v_mfma_f32_16x16x32_bf16 v[112:115], v[174:177], v[190:193], v[112:115]
	v_mfma_f32_16x16x32_bf16 v[108:111], v[166:169], v[198:201], v[108:111]
	v_mfma_f32_16x16x32_bf16 v[104:107], v[174:177], v[198:201], v[104:107]
	v_mfma_f32_16x16x32_bf16 v[100:103], v[166:169], v[206:209], v[100:103]
	v_mfma_f32_16x16x32_bf16 v[96:99], v[174:177], v[206:209], v[96:99]
	s_barrier
	s_mov_b32 vcc_lo, 0xfffbd000
	s_mov_b32 vcc_hi, -1
	s_add_i32 s67, s98, 0x10000
	v_lshl_add_u64 v[226:227], v[130:131], 0, vcc
	s_mov_b32 m0, s67
	s_add_i32 s67, s98, 0x12000
	ds_read_b128 v[210:213], v158
	ds_read_b128 v[214:217], v158 offset:1024
	ds_read_b128 v[218:221], v158 offset:2048
	ds_read_b128 v[222:225], v158 offset:3072
	global_load_lds_dwordx4 v[226:227], off
	v_lshl_add_u64 v[226:227], v[130:131], 0, s[22:23]
	s_mov_b32 m0, s67
	s_add_i32 s66, s66, 2
	global_load_lds_dwordx4 v[226:227], off
	s_mov_b32 s67, s98
	v_lshl_add_u64 v[226:227], v[132:133], 0, s[24:25]
	s_mov_b32 m0, s67
	s_add_i32 s67, s98, 0x2000
	global_load_lds_dwordx4 v[226:227], off
	v_lshl_add_u64 v[226:227], v[132:133], 0, s[26:27]
	s_mov_b32 m0, s67
	s_nop 0
	global_load_lds_dwordx4 v[226:227], off
	s_waitcnt vmcnt(12)
	s_barrier
	s_waitcnt lgkmcnt(0)
	s_waitcnt lgkmcnt(0)
	v_mfma_f32_16x16x32_bf16 v[92:95], v[210:213], v[178:181], v[92:95]
	v_mfma_f32_16x16x32_bf16 v[88:91], v[218:221], v[178:181], v[88:91]
	v_mfma_f32_16x16x32_bf16 v[84:87], v[210:213], v[186:189], v[84:87]
	v_mfma_f32_16x16x32_bf16 v[80:83], v[218:221], v[186:189], v[80:83]
	v_mfma_f32_16x16x32_bf16 v[76:79], v[210:213], v[194:197], v[76:79]
	v_mfma_f32_16x16x32_bf16 v[72:75], v[218:221], v[194:197], v[72:75]
	v_mfma_f32_16x16x32_bf16 v[68:71], v[210:213], v[202:205], v[68:71]
	v_mfma_f32_16x16x32_bf16 v[64:67], v[218:221], v[202:205], v[64:67]
	v_mfma_f32_16x16x32_bf16 v[92:95], v[214:217], v[182:185], v[92:95]
	v_mfma_f32_16x16x32_bf16 v[88:91], v[222:225], v[182:185], v[88:91]
	v_mfma_f32_16x16x32_bf16 v[84:87], v[214:217], v[190:193], v[84:87]
	v_mfma_f32_16x16x32_bf16 v[80:83], v[222:225], v[190:193], v[80:83]
	v_mfma_f32_16x16x32_bf16 v[76:79], v[214:217], v[198:201], v[76:79]
	v_mfma_f32_16x16x32_bf16 v[72:75], v[222:225], v[198:201], v[72:75]
	v_mfma_f32_16x16x32_bf16 v[68:71], v[214:217], v[206:209], v[68:71]
	v_mfma_f32_16x16x32_bf16 v[64:67], v[222:225], v[206:209], v[64:67]
	s_barrier
	ds_read_b128 v[178:181], v152 offset:16384
	ds_read_b128 v[182:185], v152 offset:17408
	ds_read_b128 v[186:189], v151 offset:16384
	ds_read_b128 v[190:193], v151 offset:17408
	ds_read_b128 v[194:197], v150 offset:16384
	ds_read_b128 v[198:201], v150 offset:17408
	ds_read_b128 v[202:205], v149 offset:16384
	ds_read_b128 v[206:209], v149 offset:17408
	s_add_i32 s67, s98, 0x14000
	v_lshl_add_u64 v[226:227], v[130:131], 0, s[28:29]
	s_mov_b32 m0, s67
	s_add_i32 s67, s98, 0x16000
	global_load_lds_dwordx4 v[226:227], off
	v_lshl_add_u64 v[226:227], v[130:131], 0, s[30:31]
	s_mov_b32 m0, s67
	s_nop 0
	global_load_lds_dwordx4 v[226:227], off
	s_barrier
	s_waitcnt lgkmcnt(0)
	s_waitcnt lgkmcnt(0)
	v_mfma_f32_16x16x32_bf16 v[60:63], v[162:165], v[178:181], v[60:63]
	v_mfma_f32_16x16x32_bf16 v[56:59], v[170:173], v[178:181], v[56:59]
	v_mfma_f32_16x16x32_bf16 v[52:55], v[162:165], v[186:189], v[52:55]
	v_mfma_f32_16x16x32_bf16 v[48:51], v[170:173], v[186:189], v[48:51]
	v_mfma_f32_16x16x32_bf16 v[44:47], v[162:165], v[194:197], v[44:47]
	v_mfma_f32_16x16x32_bf16 v[40:43], v[170:173], v[194:197], v[40:43]
	v_mfma_f32_16x16x32_bf16 v[36:39], v[162:165], v[202:205], v[36:39]
	v_mfma_f32_16x16x32_bf16 v[32:35], v[170:173], v[202:205], v[32:35]
	v_mfma_f32_16x16x32_bf16 v[60:63], v[166:169], v[182:185], v[60:63]
	v_mfma_f32_16x16x32_bf16 v[56:59], v[174:177], v[182:185], v[56:59]
	v_mfma_f32_16x16x32_bf16 v[52:55], v[166:169], v[190:193], v[52:55]
	v_mfma_f32_16x16x32_bf16 v[48:51], v[174:177], v[190:193], v[48:51]
	v_mfma_f32_16x16x32_bf16 v[44:47], v[166:169], v[198:201], v[44:47]
	v_mfma_f32_16x16x32_bf16 v[40:43], v[174:177], v[198:201], v[40:43]
	v_mfma_f32_16x16x32_bf16 v[36:39], v[166:169], v[206:209], v[36:39]
	v_mfma_f32_16x16x32_bf16 v[32:35], v[174:177], v[206:209], v[32:35]
	s_barrier
	s_add_i32 s67, s98, 0x4000
	v_lshl_add_u64 v[164:165], v[132:133], 0, s[34:35]
	s_mov_b32 m0, s67
	s_add_i32 s67, s98, 0x6000
	global_load_lds_dwordx4 v[164:165], off
	v_lshl_add_u64 v[164:165], v[132:133], 0, s[44:45]
	s_mov_b32 m0, s67
	s_nop 0
	global_load_lds_dwordx4 v[164:165], off
	s_waitcnt vmcnt(12)
	s_barrier
	v_mfma_f32_16x16x32_bf16 v[28:31], v[210:213], v[178:181], v[28:31]
	v_mfma_f32_16x16x32_bf16 v[24:27], v[218:221], v[178:181], v[24:27]
	v_mfma_f32_16x16x32_bf16 v[20:23], v[210:213], v[186:189], v[20:23]
	v_mfma_f32_16x16x32_bf16 v[16:19], v[218:221], v[186:189], v[16:19]
	v_mfma_f32_16x16x32_bf16 v[12:15], v[210:213], v[194:197], v[12:15]
	v_mfma_f32_16x16x32_bf16 v[8:11], v[218:221], v[194:197], v[8:11]
	v_mfma_f32_16x16x32_bf16 v[4:7], v[210:213], v[202:205], v[4:7]
	v_mfma_f32_16x16x32_bf16 v[0:3], v[218:221], v[202:205], v[0:3]
	v_mfma_f32_16x16x32_bf16 v[28:31], v[214:217], v[182:185], v[28:31]
	v_mfma_f32_16x16x32_bf16 v[24:27], v[222:225], v[182:185], v[24:27]
	v_mfma_f32_16x16x32_bf16 v[20:23], v[214:217], v[190:193], v[20:23]
	v_mfma_f32_16x16x32_bf16 v[16:19], v[222:225], v[190:193], v[16:19]
	v_mfma_f32_16x16x32_bf16 v[12:15], v[214:217], v[198:201], v[12:15]
	v_mfma_f32_16x16x32_bf16 v[8:11], v[222:225], v[198:201], v[8:11]
	v_mfma_f32_16x16x32_bf16 v[4:7], v[214:217], v[206:209], v[4:7]
	v_mfma_f32_16x16x32_bf16 v[0:3], v[222:225], v[206:209], v[0:3]
	s_barrier
	ds_read_b128 v[162:165], v154
	ds_read_b128 v[166:169], v154 offset:1024
	ds_read_b128 v[170:173], v154 offset:2048
	ds_read_b128 v[174:177], v154 offset:3072
	ds_read_b128 v[178:181], v152 offset:32768
	ds_read_b128 v[182:185], v152 offset:33792
	ds_read_b128 v[186:189], v151 offset:32768
	ds_read_b128 v[190:193], v151 offset:33792
	ds_read_b128 v[194:197], v150 offset:32768
	ds_read_b128 v[198:201], v150 offset:33792
	ds_read_b128 v[202:205], v149 offset:32768
	ds_read_b128 v[206:209], v149 offset:33792
	s_waitcnt lgkmcnt(8)
	s_waitcnt vmcnt(10)
	s_barrier
	s_waitcnt lgkmcnt(0)
	s_waitcnt lgkmcnt(0)
	v_mfma_f32_16x16x32_bf16 v[124:127], v[162:165], v[178:181], v[124:127]
	v_mfma_f32_16x16x32_bf16 v[120:123], v[170:173], v[178:181], v[120:123]
	v_mfma_f32_16x16x32_bf16 v[116:119], v[162:165], v[186:189], v[116:119]
	v_mfma_f32_16x16x32_bf16 v[112:115], v[170:173], v[186:189], v[112:115]
	v_mfma_f32_16x16x32_bf16 v[108:111], v[162:165], v[194:197], v[108:111]
	v_mfma_f32_16x16x32_bf16 v[104:107], v[170:173], v[194:197], v[104:107]
	v_mfma_f32_16x16x32_bf16 v[100:103], v[162:165], v[202:205], v[100:103]
	v_mfma_f32_16x16x32_bf16 v[96:99], v[170:173], v[202:205], v[96:99]
	v_mfma_f32_16x16x32_bf16 v[124:127], v[166:169], v[182:185], v[124:127]
	v_mfma_f32_16x16x32_bf16 v[120:123], v[174:177], v[182:185], v[120:123]
	v_mfma_f32_16x16x32_bf16 v[116:119], v[166:169], v[190:193], v[116:119]
	v_mfma_f32_16x16x32_bf16 v[112:115], v[174:177], v[190:193], v[112:115]
	v_mfma_f32_16x16x32_bf16 v[108:111], v[166:169], v[198:201], v[108:111]
	v_mfma_f32_16x16x32_bf16 v[104:107], v[174:177], v[198:201], v[104:107]
	v_mfma_f32_16x16x32_bf16 v[100:103], v[166:169], v[206:209], v[100:103]
	v_mfma_f32_16x16x32_bf16 v[96:99], v[174:177], v[206:209], v[96:99]
	s_barrier
	s_add_i32 s67, s98, 0x18000
	v_lshl_add_u64 v[226:227], v[130:131], 0, s[46:47]
	s_mov_b32 m0, s67
	s_add_i32 s67, s98, 0x1a000
	ds_read_b128 v[210:213], v153
	ds_read_b128 v[214:217], v153 offset:1024
	ds_read_b128 v[218:221], v153 offset:2048
	ds_read_b128 v[222:225], v153 offset:3072
	global_load_lds_dwordx4 v[226:227], off
	v_lshl_add_u64 v[226:227], v[130:131], 0, s[56:57]
	s_mov_b32 m0, s67
	s_nop 0
	global_load_lds_dwordx4 v[226:227], off
	s_add_i32 s67, s98, 0x8000
	v_lshl_add_u64 v[226:227], v[132:133], 0, s[58:59]
	s_mov_b32 m0, s67
	s_add_i32 s67, s98, 0xa000
	global_load_lds_dwordx4 v[226:227], off
	s_mov_b32 m0, s67
	s_nop 0
	global_load_lds_dwordx4 v[132:133], off
	s_waitcnt vmcnt(12)
	s_barrier
	s_waitcnt lgkmcnt(0)
	s_waitcnt lgkmcnt(0)
	v_mfma_f32_16x16x32_bf16 v[92:95], v[210:213], v[178:181], v[92:95]
	v_mfma_f32_16x16x32_bf16 v[88:91], v[218:221], v[178:181], v[88:91]
	v_mfma_f32_16x16x32_bf16 v[84:87], v[210:213], v[186:189], v[84:87]
	v_mfma_f32_16x16x32_bf16 v[80:83], v[218:221], v[186:189], v[80:83]
	v_mfma_f32_16x16x32_bf16 v[76:79], v[210:213], v[194:197], v[76:79]
	v_mfma_f32_16x16x32_bf16 v[72:75], v[218:221], v[194:197], v[72:75]
	v_mfma_f32_16x16x32_bf16 v[68:71], v[210:213], v[202:205], v[68:71]
	v_mfma_f32_16x16x32_bf16 v[64:67], v[218:221], v[202:205], v[64:67]
	v_mfma_f32_16x16x32_bf16 v[92:95], v[214:217], v[182:185], v[92:95]
	v_mfma_f32_16x16x32_bf16 v[88:91], v[222:225], v[182:185], v[88:91]
	v_mfma_f32_16x16x32_bf16 v[84:87], v[214:217], v[190:193], v[84:87]
	v_mfma_f32_16x16x32_bf16 v[80:83], v[222:225], v[190:193], v[80:83]
	v_mfma_f32_16x16x32_bf16 v[76:79], v[214:217], v[198:201], v[76:79]
	v_mfma_f32_16x16x32_bf16 v[72:75], v[222:225], v[198:201], v[72:75]
	v_mfma_f32_16x16x32_bf16 v[68:71], v[214:217], v[206:209], v[68:71]
	v_mfma_f32_16x16x32_bf16 v[64:67], v[222:225], v[206:209], v[64:67]
	s_barrier
	ds_read_b128 v[178:181], v152 offset:49152
	ds_read_b128 v[182:185], v152 offset:50176
	ds_read_b128 v[186:189], v151 offset:49152
	ds_read_b128 v[190:193], v151 offset:50176
	ds_read_b128 v[194:197], v150 offset:49152
	ds_read_b128 v[198:201], v150 offset:50176
	ds_read_b128 v[202:205], v149 offset:49152
	ds_read_b128 v[206:209], v149 offset:50176
	s_add_i32 s67, s98, 0x1c000
	v_lshl_add_u64 v[226:227], v[130:131], 0, s[58:59]
	s_mov_b32 m0, s67
	s_add_i32 s67, s98, 0x1e000
	global_load_lds_dwordx4 v[226:227], off
	s_mov_b32 m0, s67
	s_nop 0
	global_load_lds_dwordx4 v[130:131], off
	s_barrier
	s_waitcnt lgkmcnt(0)
	s_waitcnt lgkmcnt(0)
	v_mfma_f32_16x16x32_bf16 v[60:63], v[162:165], v[178:181], v[60:63]
	v_mfma_f32_16x16x32_bf16 v[56:59], v[170:173], v[178:181], v[56:59]
	v_mfma_f32_16x16x32_bf16 v[52:55], v[162:165], v[186:189], v[52:55]
	v_mfma_f32_16x16x32_bf16 v[48:51], v[170:173], v[186:189], v[48:51]
	v_mfma_f32_16x16x32_bf16 v[44:47], v[162:165], v[194:197], v[44:47]
	v_mfma_f32_16x16x32_bf16 v[40:43], v[170:173], v[194:197], v[40:43]
	v_mfma_f32_16x16x32_bf16 v[36:39], v[162:165], v[202:205], v[36:39]
	v_mfma_f32_16x16x32_bf16 v[32:35], v[170:173], v[202:205], v[32:35]
	v_mfma_f32_16x16x32_bf16 v[60:63], v[166:169], v[182:185], v[60:63]
	v_mfma_f32_16x16x32_bf16 v[56:59], v[174:177], v[182:185], v[56:59]
	v_mfma_f32_16x16x32_bf16 v[52:55], v[166:169], v[190:193], v[52:55]
	v_mfma_f32_16x16x32_bf16 v[48:51], v[174:177], v[190:193], v[48:51]
	v_mfma_f32_16x16x32_bf16 v[44:47], v[166:169], v[198:201], v[44:47]
	v_mfma_f32_16x16x32_bf16 v[40:43], v[174:177], v[198:201], v[40:43]
	v_mfma_f32_16x16x32_bf16 v[36:39], v[166:169], v[206:209], v[36:39]
	v_mfma_f32_16x16x32_bf16 v[32:35], v[174:177], v[206:209], v[32:35]
	s_barrier
	v_lshl_add_u64 v[132:133], v[132:133], 0, s[62:63]
	s_mov_b32 vcc_lo, 0xffe01000
	s_mov_b32 vcc_hi, -1
	v_lshl_add_u64 v[164:165], v[132:133], 0, vcc
	s_add_i32 s67, s98, 0xc000
	s_mov_b32 vcc_lo, 0xffe02000
	s_mov_b32 m0, s67
	s_mov_b32 vcc_hi, -1
	s_add_i32 s67, s98, 0xe000
	global_load_lds_dwordx4 v[164:165], off
	v_lshl_add_u64 v[164:165], v[132:133], 0, vcc
	s_mov_b32 m0, s67
	s_nop 0
	global_load_lds_dwordx4 v[164:165], off
	s_waitcnt vmcnt(12)
	s_barrier
	v_mfma_f32_16x16x32_bf16 v[28:31], v[210:213], v[178:181], v[28:31]
	v_mfma_f32_16x16x32_bf16 v[24:27], v[218:221], v[178:181], v[24:27]
	v_mfma_f32_16x16x32_bf16 v[20:23], v[210:213], v[186:189], v[20:23]
	v_mfma_f32_16x16x32_bf16 v[16:19], v[218:221], v[186:189], v[16:19]
	v_mfma_f32_16x16x32_bf16 v[12:15], v[210:213], v[194:197], v[12:15]
	v_mfma_f32_16x16x32_bf16 v[8:11], v[218:221], v[194:197], v[8:11]
	v_mfma_f32_16x16x32_bf16 v[4:7], v[210:213], v[202:205], v[4:7]
	v_mfma_f32_16x16x32_bf16 v[0:3], v[218:221], v[202:205], v[0:3]
	v_mfma_f32_16x16x32_bf16 v[28:31], v[214:217], v[182:185], v[28:31]
	v_mfma_f32_16x16x32_bf16 v[24:27], v[222:225], v[182:185], v[24:27]
	v_mfma_f32_16x16x32_bf16 v[20:23], v[214:217], v[190:193], v[20:23]
	v_mfma_f32_16x16x32_bf16 v[16:19], v[222:225], v[190:193], v[16:19]
	v_mfma_f32_16x16x32_bf16 v[12:15], v[214:217], v[198:201], v[12:15]
	v_mfma_f32_16x16x32_bf16 v[8:11], v[222:225], v[198:201], v[8:11]
	v_mfma_f32_16x16x32_bf16 v[4:7], v[214:217], v[206:209], v[4:7]
	v_mfma_f32_16x16x32_bf16 v[0:3], v[222:225], v[206:209], v[0:3]
	v_lshl_add_u64 v[130:131], v[130:131], 0, s[60:61]
	s_cmp_lt_u32 s66, s65
	s_barrier
	s_cbranch_scc1 .LBB0_274
	s_lshl_b32 s65, s86, 5
	s_lshl_b32 s66, s86, 8
	s_and_b32 s65, s65, 0x1800
	s_and_b32 s66, s66, 0x700
	s_or_b32 s97, s66, s65
	s_lshl_b32 s65, s97, 6
	s_add_u32 s65, s68, s65
	s_addc_u32 s86, s69, 0
	s_add_i32 s20, s20, -1
	s_lshl_b64 s[66:67], s[20:21], 20
	v_add_u32_e32 v128, v156, v157
	s_add_u32 s66, s65, s66
	v_or_b32_e32 v128, v128, v155
	s_addc_u32 s67, s86, s67
	v_lshl_add_u64 v[156:157], s[66:67], 0, v[128:129]
	v_readfirstlane_b32 s20, v160
	v_lshl_add_u64 v[206:207], v[156:157], 0, s[4:5]
	s_mov_b32 m0, s20
	v_readfirstlane_b32 s20, v159
	ds_read_b128 v[130:133], v161
	ds_read_b128 v[162:165], v161 offset:1024
	ds_read_b128 v[166:169], v161 offset:2048
	ds_read_b128 v[170:173], v161 offset:3072
	ds_read_b128 v[174:177], v152
	ds_read_b128 v[178:181], v152 offset:1024
	ds_read_b128 v[182:185], v151
	ds_read_b128 v[186:189], v151 offset:1024
	ds_read_b128 v[190:193], v150
	ds_read_b128 v[194:197], v150 offset:1024
	ds_read_b128 v[198:201], v149
	ds_read_b128 v[202:205], v149 offset:1024
	global_load_lds_dwordx4 v[206:207], off
	v_lshl_add_u64 v[156:157], v[156:157], 0, s[6:7]
	s_mov_b32 m0, s20
	s_nop 0
	global_load_lds_dwordx4 v[156:157], off
	s_waitcnt vmcnt(10)
	s_barrier
	s_waitcnt lgkmcnt(0)
	s_setprio 1
	s_waitcnt lgkmcnt(0)
	v_mfma_f32_16x16x32_bf16 v[124:127], v[130:133], v[174:177], v[124:127]
	v_mfma_f32_16x16x32_bf16 v[120:123], v[166:169], v[174:177], v[120:123]
	v_mfma_f32_16x16x32_bf16 v[116:119], v[130:133], v[182:185], v[116:119]
	v_mfma_f32_16x16x32_bf16 v[112:115], v[166:169], v[182:185], v[112:115]
	v_mfma_f32_16x16x32_bf16 v[108:111], v[130:133], v[190:193], v[108:111]
	v_mfma_f32_16x16x32_bf16 v[104:107], v[166:169], v[190:193], v[104:107]
	v_mfma_f32_16x16x32_bf16 v[100:103], v[130:133], v[198:201], v[100:103]
	v_mfma_f32_16x16x32_bf16 v[96:99], v[166:169], v[198:201], v[96:99]
	v_mfma_f32_16x16x32_bf16 v[124:127], v[162:165], v[178:181], v[124:127]
	v_mfma_f32_16x16x32_bf16 v[120:123], v[170:173], v[178:181], v[120:123]
	v_mfma_f32_16x16x32_bf16 v[116:119], v[162:165], v[186:189], v[116:119]
	v_mfma_f32_16x16x32_bf16 v[112:115], v[170:173], v[186:189], v[112:115]
	v_mfma_f32_16x16x32_bf16 v[108:111], v[162:165], v[194:197], v[108:111]
	v_mfma_f32_16x16x32_bf16 v[104:107], v[170:173], v[194:197], v[104:107]
	v_mfma_f32_16x16x32_bf16 v[100:103], v[162:165], v[202:205], v[100:103]
	v_mfma_f32_16x16x32_bf16 v[96:99], v[170:173], v[202:205], v[96:99]
	s_setprio 0
	s_barrier
	ds_read_b128 v[206:209], v158
	ds_read_b128 v[210:213], v158 offset:1024
	ds_read_b128 v[214:217], v158 offset:2048
	ds_read_b128 v[156:159], v158 offset:3072
	s_barrier
	s_waitcnt lgkmcnt(0)
	s_setprio 1
	s_waitcnt lgkmcnt(0)
	v_mfma_f32_16x16x32_bf16 v[92:95], v[206:209], v[174:177], v[92:95]
	v_mfma_f32_16x16x32_bf16 v[88:91], v[214:217], v[174:177], v[88:91]
	v_mfma_f32_16x16x32_bf16 v[84:87], v[206:209], v[182:185], v[84:87]
	v_mfma_f32_16x16x32_bf16 v[80:83], v[214:217], v[182:185], v[80:83]
	v_mfma_f32_16x16x32_bf16 v[76:79], v[206:209], v[190:193], v[76:79]
	v_mfma_f32_16x16x32_bf16 v[72:75], v[214:217], v[190:193], v[72:75]
	v_mfma_f32_16x16x32_bf16 v[68:71], v[206:209], v[198:201], v[68:71]
	v_mfma_f32_16x16x32_bf16 v[64:67], v[214:217], v[198:201], v[64:67]
	v_mfma_f32_16x16x32_bf16 v[174:177], v[210:213], v[178:181], v[92:95]
	v_mfma_f32_16x16x32_bf16 v[178:181], v[156:159], v[178:181], v[88:91]
	v_mfma_f32_16x16x32_bf16 v[182:185], v[210:213], v[186:189], v[84:87]
	v_mfma_f32_16x16x32_bf16 v[186:189], v[156:159], v[186:189], v[80:83]
	v_mfma_f32_16x16x32_bf16 v[190:193], v[210:213], v[194:197], v[76:79]
	v_mfma_f32_16x16x32_bf16 v[194:197], v[156:159], v[194:197], v[72:75]
	v_mfma_f32_16x16x32_bf16 v[198:201], v[210:213], v[202:205], v[68:71]
	v_mfma_f32_16x16x32_bf16 v[202:205], v[156:159], v[202:205], v[64:67]
	s_setprio 0
	s_barrier
	s_nop 0
	ds_read_b128 v[64:67], v152 offset:16384
	ds_read_b128 v[68:71], v152 offset:17408
	ds_read_b128 v[72:75], v151 offset:16384
	ds_read_b128 v[76:79], v151 offset:17408
	ds_read_b128 v[80:83], v150 offset:16384
	ds_read_b128 v[84:87], v150 offset:17408
	ds_read_b128 v[88:91], v149 offset:16384
	ds_read_b128 v[92:95], v149 offset:17408
	s_waitcnt vmcnt(4)
	s_barrier
	s_waitcnt lgkmcnt(0)
	s_setprio 1
	s_waitcnt lgkmcnt(0)
	v_mfma_f32_16x16x32_bf16 v[60:63], v[130:133], v[64:67], v[60:63]
	v_mfma_f32_16x16x32_bf16 v[56:59], v[166:169], v[64:67], v[56:59]
	v_mfma_f32_16x16x32_bf16 v[52:55], v[130:133], v[72:75], v[52:55]
	v_mfma_f32_16x16x32_bf16 v[48:51], v[166:169], v[72:75], v[48:51]
	v_mfma_f32_16x16x32_bf16 v[218:221], v[130:133], v[80:83], v[44:47]
	v_mfma_f32_16x16x32_bf16 v[222:225], v[166:169], v[80:83], v[40:43]
	v_mfma_f32_16x16x32_bf16 v[130:133], v[130:133], v[88:91], v[36:39]
	v_mfma_f32_16x16x32_bf16 v[166:169], v[166:169], v[88:91], v[32:35]
	v_mfma_f32_16x16x32_bf16 v[32:35], v[162:165], v[68:71], v[60:63]
	v_mfma_f32_16x16x32_bf16 v[36:39], v[170:173], v[68:71], v[56:59]
	v_mfma_f32_16x16x32_bf16 v[40:43], v[162:165], v[76:79], v[52:55]
	v_mfma_f32_16x16x32_bf16 v[44:47], v[170:173], v[76:79], v[48:51]
	v_mfma_f32_16x16x32_bf16 v[48:51], v[162:165], v[84:87], v[218:221]
	v_mfma_f32_16x16x32_bf16 v[52:55], v[170:173], v[84:87], v[222:225]
	v_mfma_f32_16x16x32_bf16 v[56:59], v[162:165], v[92:95], v[130:133]
	v_mfma_f32_16x16x32_bf16 v[60:63], v[170:173], v[92:95], v[166:169]
	s_setprio 0
	s_setprio 1
	v_mfma_f32_16x16x32_bf16 v[28:31], v[206:209], v[64:67], v[28:31]
	v_mfma_f32_16x16x32_bf16 v[24:27], v[214:217], v[64:67], v[24:27]
	v_mfma_f32_16x16x32_bf16 v[20:23], v[206:209], v[72:75], v[20:23]
	v_mfma_f32_16x16x32_bf16 v[64:67], v[214:217], v[72:75], v[16:19]
	v_mfma_f32_16x16x32_bf16 v[72:75], v[206:209], v[80:83], v[12:15]
	v_mfma_f32_16x16x32_bf16 v[8:11], v[214:217], v[80:83], v[8:11]
	v_mfma_f32_16x16x32_bf16 v[80:83], v[206:209], v[88:91], v[4:7]
	v_mfma_f32_16x16x32_bf16 v[0:3], v[214:217], v[88:91], v[0:3]
	v_mfma_f32_16x16x32_bf16 v[4:7], v[210:213], v[68:71], v[28:31]
	v_mfma_f32_16x16x32_bf16 v[12:15], v[156:159], v[68:71], v[24:27]
	v_mfma_f32_16x16x32_bf16 v[16:19], v[210:213], v[76:79], v[20:23]
	v_mfma_f32_16x16x32_bf16 v[20:23], v[156:159], v[76:79], v[64:67]
	v_mfma_f32_16x16x32_bf16 v[24:27], v[210:213], v[84:87], v[72:75]
	v_mfma_f32_16x16x32_bf16 v[28:31], v[156:159], v[84:87], v[8:11]
	v_mfma_f32_16x16x32_bf16 v[64:67], v[210:213], v[92:95], v[80:83]
	v_mfma_f32_16x16x32_bf16 v[68:71], v[156:159], v[92:95], v[0:3]
	s_setprio 0
	s_barrier
	ds_read_b128 v[8:11], v154
	ds_read_b128 v[0:3], v154 offset:1024
	ds_read_b128 v[76:79], v154 offset:2048
	ds_read_b128 v[72:75], v154 offset:3072
	ds_read_b128 v[130:133], v152 offset:32768
	ds_read_b128 v[154:157], v152 offset:33792
	ds_read_b128 v[158:161], v151 offset:32768
	ds_read_b128 v[162:165], v151 offset:33792
	ds_read_b128 v[166:169], v150 offset:32768
	ds_read_b128 v[170:173], v150 offset:33792
	ds_read_b128 v[206:209], v149 offset:32768
	ds_read_b128 v[210:213], v149 offset:33792
	s_waitcnt vmcnt(2)
	s_barrier
	s_waitcnt lgkmcnt(0)
	s_setprio 1
	s_waitcnt lgkmcnt(0)
	v_mfma_f32_16x16x32_bf16 v[80:83], v[8:11], v[130:133], v[124:127]
	v_mfma_f32_16x16x32_bf16 v[84:87], v[76:79], v[130:133], v[120:123]
	v_mfma_f32_16x16x32_bf16 v[88:91], v[8:11], v[158:161], v[116:119]
	v_mfma_f32_16x16x32_bf16 v[92:95], v[76:79], v[158:161], v[112:115]
	v_mfma_f32_16x16x32_bf16 v[108:111], v[8:11], v[166:169], v[108:111]
	v_mfma_f32_16x16x32_bf16 v[104:107], v[76:79], v[166:169], v[104:107]
	v_mfma_f32_16x16x32_bf16 v[100:103], v[8:11], v[206:209], v[100:103]
	v_mfma_f32_16x16x32_bf16 v[96:99], v[76:79], v[206:209], v[96:99]
	v_mfma_f32_16x16x32_bf16 v[112:115], v[0:3], v[154:157], v[80:83]
	v_mfma_f32_16x16x32_bf16 v[116:119], v[72:75], v[154:157], v[84:87]
	v_mfma_f32_16x16x32_bf16 v[120:123], v[0:3], v[162:165], v[88:91]
	v_mfma_f32_16x16x32_bf16 v[124:127], v[72:75], v[162:165], v[92:95]
	v_mfma_f32_16x16x32_bf16 v[108:111], v[0:3], v[170:173], v[108:111]
	v_mfma_f32_16x16x32_bf16 v[104:107], v[72:75], v[170:173], v[104:107]
	v_mfma_f32_16x16x32_bf16 v[100:103], v[0:3], v[210:213], v[100:103]
	v_mfma_f32_16x16x32_bf16 v[96:99], v[72:75], v[210:213], v[96:99]
	s_setprio 0
	s_barrier
	ds_read_b128 v[88:91], v153
	ds_read_b128 v[80:83], v153 offset:1024
	ds_read_b128 v[92:95], v153 offset:2048
	ds_read_b128 v[84:87], v153 offset:3072
	s_waitcnt vmcnt(0)
	s_barrier
	s_waitcnt lgkmcnt(0)
	s_setprio 1
	s_waitcnt lgkmcnt(0)
	v_mfma_f32_16x16x32_bf16 v[174:177], v[88:91], v[130:133], v[174:177]
	v_mfma_f32_16x16x32_bf16 v[130:133], v[92:95], v[130:133], v[178:181]
	v_mfma_f32_16x16x32_bf16 v[178:181], v[88:91], v[158:161], v[182:185]
	v_mfma_f32_16x16x32_bf16 v[158:161], v[92:95], v[158:161], v[186:189]
	v_mfma_f32_16x16x32_bf16 v[182:185], v[88:91], v[166:169], v[190:193]
	v_mfma_f32_16x16x32_bf16 v[166:169], v[92:95], v[166:169], v[194:197]
	v_mfma_f32_16x16x32_bf16 v[186:189], v[88:91], v[206:209], v[198:201]
	v_mfma_f32_16x16x32_bf16 v[190:193], v[92:95], v[206:209], v[202:205]
	v_mfma_f32_16x16x32_bf16 v[174:177], v[80:83], v[154:157], v[174:177]
	v_mfma_f32_16x16x32_bf16 v[130:133], v[84:87], v[154:157], v[130:133]
	v_mfma_f32_16x16x32_bf16 v[154:157], v[80:83], v[162:165], v[178:181]
	v_mfma_f32_16x16x32_bf16 v[158:161], v[84:87], v[162:165], v[158:161]
	v_mfma_f32_16x16x32_bf16 v[162:165], v[80:83], v[170:173], v[182:185]
	v_mfma_f32_16x16x32_bf16 v[166:169], v[84:87], v[170:173], v[166:169]
	v_mfma_f32_16x16x32_bf16 v[170:173], v[80:83], v[210:213], v[186:189]
	v_mfma_f32_16x16x32_bf16 v[178:181], v[84:87], v[210:213], v[190:193]
	s_setprio 0
	s_barrier
	v_mbcnt_lo_u32_b32 v128, -1, 0
	v_mbcnt_hi_u32_b32 v128, -1, v128
	v_cvt_pk_bf16_f32 v112, v112, v113
	v_cvt_pk_bf16_f32 v113, v114, v115
	v_cvt_pk_bf16_f32 v114, v116, v117
	v_cvt_pk_bf16_f32 v115, v118, v119
	s_lshl_b32 s89, s64, 9
	v_add_u32_e32 v153, s72, v128
	v_ashrrev_i32_e32 v182, 6, v153
	v_and_b32_e32 v183, 15, v128
	v_and_b32_e32 v184, 48, v128
	v_mul_lo_u32 v185, v182, s77
	v_bfe_u32 v186, v128, 3, 3
	v_lshlrev_b32_e32 v128, 4, v128
	v_add_u32_e32 v185, 0x20000, v185
	v_lshrrev_b32_e32 v153, 2, v153
	v_and_b32_e32 v128, 0x70, v128
	v_mul_u32_u24_e32 v183, 0x90, v183
	v_and_b32_e32 v153, 64, v153
	v_add3_u32 v183, v185, v183, v184
	v_or_b32_e32 v184, v185, v128
	v_or3_b32 v153, s97, v153, v186
	v_mad_u32_u24 v184, v186, s79, v184
	ds_write_b128 v183, v[112:115]
	v_cvt_pk_bf16_f32 v112, v174, v175
	v_cvt_pk_bf16_f32 v113, v176, v177
	v_cvt_pk_bf16_f32 v114, v130, v131
	v_cvt_pk_bf16_f32 v115, v132, v133
	ds_write_b128 v183, v[112:115] offset:64
	v_lshlrev_b32_e32 v182, 7, v182
	ds_read_b128 v[112:115], v184
	v_lshlrev_b32_e32 v116, 12, v153
	v_and_or_b32 v116, v182, s80, v116
	v_or3_b32 v128, v116, s89, v128
	ds_read_b128 v[116:119], v184 offset:1152
	v_lshl_add_u64 v[130:131], s[0:1], 0, v[128:129]
	s_mov_b32 s20, 0x8000
	s_waitcnt lgkmcnt(0)
	global_store_dwordx4 v128, v[112:115], s[0:1]
	v_cvt_pk_bf16_f32 v108, v108, v109
	v_cvt_pk_bf16_f32 v109, v110, v111
	v_cvt_pk_bf16_f32 v110, v104, v105
	v_cvt_pk_bf16_f32 v111, v106, v107
	v_cvt_pk_bf16_f32 v104, v162, v163
	s_nop 1
	v_add_co_u32_e32 v112, vcc, s20, v130
	v_cvt_pk_bf16_f32 v114, v124, v125
	v_cvt_pk_bf16_f32 v115, v126, v127
	v_cvt_pk_bf16_f32 v105, v164, v165
	v_cvt_pk_bf16_f32 v106, v166, v167
	s_nop 1
	v_addc_co_u32_e32 v113, vcc, 0, v131, vcc
	global_store_dwordx4 v[112:113], v[116:119], off
	v_cvt_pk_bf16_f32 v112, v120, v121
	v_cvt_pk_bf16_f32 v113, v122, v123
	ds_write_b128 v183, v[112:115]
	v_cvt_pk_bf16_f32 v112, v154, v155
	v_cvt_pk_bf16_f32 v113, v156, v157
	v_cvt_pk_bf16_f32 v114, v158, v159
	v_cvt_pk_bf16_f32 v115, v160, v161
	ds_write_b128 v183, v[112:115] offset:64
	ds_read_b128 v[112:115], v184
	ds_read_b128 v[116:119], v184 offset:1152
	v_add_co_u32_e32 v120, vcc, s74, v130
	ds_write_b128 v183, v[108:111]
	v_cvt_pk_bf16_f32 v107, v168, v169
	ds_write_b128 v183, v[104:107] offset:64
	v_addc_co_u32_e32 v121, vcc, 0, v131, vcc
	ds_read_b128 v[104:107], v184
	ds_read_b128 v[108:111], v184 offset:1152
	s_waitcnt lgkmcnt(0)
	global_store_dwordx4 v[120:121], v[112:115], off
	v_cvt_pk_bf16_f32 v100, v100, v101
	v_cvt_pk_bf16_f32 v101, v102, v103
	v_cvt_pk_bf16_f32 v102, v96, v97
	v_cvt_pk_bf16_f32 v103, v98, v99
	ds_write_b128 v183, v[100:103]
	s_nop 0
	v_add_co_u32_e32 v112, vcc, s75, v130
	v_cvt_pk_bf16_f32 v96, v170, v171
	v_cvt_pk_bf16_f32 v97, v172, v173
	v_cvt_pk_bf16_f32 v98, v178, v179
	v_cvt_pk_bf16_f32 v99, v180, v181
	s_nop 1
	v_addc_co_u32_e32 v113, vcc, 0, v131, vcc
	global_store_dwordx4 v[112:113], v[116:119], off
	v_add_co_u32_e32 v112, vcc, s78, v130
	ds_write_b128 v183, v[96:99] offset:64
	s_nop 0
	v_addc_co_u32_e32 v113, vcc, 0, v131, vcc
	ds_read_b128 v[96:99], v184
	ds_read_b128 v[100:103], v184 offset:1152
	global_store_dwordx4 v[112:113], v[104:107], off
	s_nop 1
	v_add_co_u32_e32 v104, vcc, s81, v130
	s_nop 1
	v_addc_co_u32_e32 v105, vcc, 0, v131, vcc
	global_store_dwordx4 v[104:105], v[108:111], off
	v_add_co_u32_e32 v104, vcc, s82, v130
	s_nop 1
	v_addc_co_u32_e32 v105, vcc, 0, v131, vcc
	s_waitcnt lgkmcnt(0)
	global_store_dwordx4 v[104:105], v[96:99], off
	s_nop 1
	v_add_co_u32_e32 v96, vcc, s83, v130
	s_nop 1
	v_addc_co_u32_e32 v97, vcc, 0, v131, vcc
	global_store_dwordx4 v[96:97], v[100:103], off
	ds_read_b128 v[96:99], v152 offset:49152
	ds_read_b128 v[100:103], v152 offset:50176
	ds_read_b128 v[104:107], v151 offset:49152
	ds_read_b128 v[108:111], v151 offset:50176
	ds_read_b128 v[112:115], v150 offset:49152
	ds_read_b128 v[116:119], v150 offset:50176
	ds_read_b128 v[120:123], v149 offset:49152
	ds_read_b128 v[124:127], v149 offset:50176
	s_barrier
	s_waitcnt lgkmcnt(0)
	s_setprio 1
	s_waitcnt lgkmcnt(0)
	v_mfma_f32_16x16x32_bf16 v[32:35], v[8:11], v[96:99], v[32:35]
	v_mfma_f32_16x16x32_bf16 v[36:39], v[76:79], v[96:99], v[36:39]
	v_mfma_f32_16x16x32_bf16 v[40:43], v[8:11], v[104:107], v[40:43]
	v_mfma_f32_16x16x32_bf16 v[130:133], v[76:79], v[104:107], v[44:47]
	v_mfma_f32_16x16x32_bf16 v[150:153], v[8:11], v[112:115], v[48:51]
	v_mfma_f32_16x16x32_bf16 v[52:55], v[76:79], v[112:115], v[52:55]
	v_mfma_f32_16x16x32_bf16 v[8:11], v[8:11], v[120:123], v[56:59]
	v_mfma_f32_16x16x32_bf16 v[60:63], v[76:79], v[120:123], v[60:63]
	v_mfma_f32_16x16x32_bf16 v[56:59], v[0:3], v[100:103], v[32:35]
	v_mfma_f32_16x16x32_bf16 v[48:51], v[72:75], v[100:103], v[36:39]
	v_mfma_f32_16x16x32_bf16 v[44:47], v[0:3], v[108:111], v[40:43]
	v_mfma_f32_16x16x32_bf16 v[40:43], v[72:75], v[108:111], v[130:133]
	v_mfma_f32_16x16x32_bf16 v[36:39], v[0:3], v[116:119], v[150:153]
	v_mfma_f32_16x16x32_bf16 v[32:35], v[72:75], v[116:119], v[52:55]
	v_mfma_f32_16x16x32_bf16 v[8:11], v[0:3], v[124:127], v[8:11]
	v_mfma_f32_16x16x32_bf16 v[0:3], v[72:75], v[124:127], v[60:63]
	s_setprio 0
	s_setprio 1
	v_mfma_f32_16x16x32_bf16 v[4:7], v[88:91], v[96:99], v[4:7]
	v_mfma_f32_16x16x32_bf16 v[12:15], v[92:95], v[96:99], v[12:15]
	v_mfma_f32_16x16x32_bf16 v[16:19], v[88:91], v[104:107], v[16:19]
	v_mfma_f32_16x16x32_bf16 v[20:23], v[92:95], v[104:107], v[20:23]
	v_mfma_f32_16x16x32_bf16 v[72:75], v[88:91], v[112:115], v[24:27]
	v_mfma_f32_16x16x32_bf16 v[76:79], v[92:95], v[112:115], v[28:31]
	v_mfma_f32_16x16x32_bf16 v[64:67], v[88:91], v[120:123], v[64:67]
	v_mfma_f32_16x16x32_bf16 v[68:71], v[92:95], v[120:123], v[68:71]
	v_mfma_f32_16x16x32_bf16 v[60:63], v[80:83], v[100:103], v[4:7]
	v_mfma_f32_16x16x32_bf16 v[52:55], v[84:87], v[100:103], v[12:15]
	v_mfma_f32_16x16x32_bf16 v[28:31], v[80:83], v[108:111], v[16:19]
	v_mfma_f32_16x16x32_bf16 v[24:27], v[84:87], v[108:111], v[20:23]
	v_mfma_f32_16x16x32_bf16 v[20:23], v[80:83], v[116:119], v[72:75]
	v_mfma_f32_16x16x32_bf16 v[16:19], v[84:87], v[116:119], v[76:79]
	v_mfma_f32_16x16x32_bf16 v[12:15], v[80:83], v[124:127], v[64:67]
	v_mfma_f32_16x16x32_bf16 v[4:7], v[84:87], v[124:127], v[68:71]
	s_setprio 0
	v_cmp_gt_u32_e32 vcc, s85, v135
	s_barrier
	s_and_saveexec_b64 s[64:65], vcc
	s_cbranch_execz .LBB0_277
	s_barrier

.LBB0_355:
	s_lshl_b32 s14, s70, 3
	v_cvt_f32_u32_e32 v2, s14
	s_sub_i32 s17, 0, s14
	s_abs_i32 s16, s69
	s_ashr_i32 s15, s69, 31
	v_rcp_iflag_f32_e32 v2, v2
	v_and_b32_e32 v3, 15, v0
	v_lshlrev_b32_e32 v3, 6, v3
	v_lshlrev_b32_e32 v6, 2, v0
	v_mul_f32_e32 v2, 0x4f7ffffe, v2
	v_cvt_u32_f32_e32 v2, v2
	v_lshlrev_b32_e32 v4, 6, v183
	v_and_b32_e32 v6, 32, v6
	v_lshlrev_b32_e32 v1, 13, v1
	v_readfirstlane_b32 s24, v2
	s_mul_i32 s17, s17, s24
	s_mul_hi_u32 s17, s24, s17
	s_add_i32 s24, s24, s17
	s_mul_hi_u32 s17, s16, s24
	s_mul_i32 s24, s17, s14
	s_sub_i32 s16, s16, s24
	s_add_i32 s25, s17, 1
	s_sub_i32 s24, s16, s14
	s_cmp_ge_u32 s16, s14
	s_cselect_b32 s17, s25, s17
	s_cselect_b32 s16, s24, s16
	s_add_i32 s24, s17, 1
	s_cmp_ge_u32 s16, s14
	s_cselect_b32 s16, s24, s17
	s_xor_b32 s16, s16, s15
	s_sub_i32 s67, s16, s15
	s_mul_i32 s14, s67, s14
	s_sub_i32 s14, s69, s14
	s_lshl_b32 s15, s67, 3
	s_and_b32 s16, s14, 7
	s_ashr_i32 s66, s14, 3
	s_or_b32 s68, s16, s15
	s_lshl_b32 s16, s66, 8
	s_lshl_b32 s14, s68, 8
	s_and_b64 s[24:25], s[22:23], exec
	s_cselect_b32 s24, s45, 0x40000
	s_cselect_b32 s36, 32, 0x80
	s_cselect_b32 s25, s46, 0x1000
	s_or_b32 s26, s14, 0x80
	s_ashr_i32 s27, s26, 31
	s_and_b64 s[28:29], s[22:23], exec
	s_cselect_b32 s37, 6, 12
	s_lshl_b64 s[26:27], s[26:27], s37
	s_add_u32 s26, s18, s26
	s_addc_u32 s27, s19, s27
	s_and_b64 s[28:29], s[22:23], exec
	s_cselect_b32 s28, 18, 7
	s_ashr_i32 s17, s16, 31
	s_and_b64 s[30:31], s[22:23], exec
	s_cselect_b32 s69, 12, 6
	s_lshl_b64 s[30:31], s[16:17], s69
	s_add_u32 s17, s20, s30
	s_addc_u32 s29, s21, s31
	s_ashr_i32 s15, s14, 31
	s_lshl_b64 s[30:31], s[14:15], s37
	s_add_u32 s15, s18, s30
	s_addc_u32 s30, s19, s31
	s_or_b32 s18, s16, s36
	s_ashr_i32 s19, s18, 31
	s_lshl_b64 s[18:19], s[18:19], s69
	v_and_b32_e32 v2, 48, v0
	s_add_u32 s20, s20, s18
	v_lshlrev_b32_e32 v0, 6, v0
	v_or_b32_e32 v5, v3, v2
	s_addc_u32 s21, s21, s19
	v_and_b32_e32 v0, 0x3c0, v0
	v_and_b32_e32 v4, 0x3000, v4
	v_bitop3_b32 v3, v3, v6, v2 bitop3:0x36
	v_bitop3_b32 v7, v5, s56, v6 bitop3:0xde
	v_bitop3_b32 v8, v5, s57, v6 bitop3:0xde
	v_bitop3_b32 v9, v5, s58, v6 bitop3:0xde
	v_bitop3_b32 v5, v5, s59, v6 bitop3:0xde
	v_bitop3_b32 v2, v0, v6, v2 bitop3:0x36
	v_or_b32_e32 v6, 0x800, v1
	v_or_b32_e32 v10, 0x1000, v1
	v_or_b32_e32 v11, 0x1800, v1
	s_and_b64 s[18:19], s[22:23], exec
	v_mov_b32_e32 v0, 0
	v_mov_b32_e32 v129, v165
	s_cselect_b32 s22, 7, 18
	s_mov_b64 s[18:19], 1
	v_add_u32_e32 v134, v7, v4
	v_add_u32_e32 v187, v3, v1
	v_add_u32_e32 v186, v2, v6
	v_add_u32_e32 v185, v2, v10
	v_add_u32_e32 v184, v2, v11
	v_add_u32_e32 v133, 0xc000, v169
	v_add_u32_e32 v132, 0xe000, v169
	v_add_u32_e32 v131, v8, v4
	v_add_u32_e32 v182, 0x10000, v169
	v_add_u32_e32 v181, 0x12000, v169
	v_add_u32_e32 v180, 0x2000, v169
	v_add_u32_e32 v179, 0x14000, v169
	v_add_u32_e32 v178, 0x16000, v169
	v_add_u32_e32 v130, v9, v4
	v_add_u32_e32 v177, 0x4000, v169
	v_add_u32_e32 v176, 0x6000, v169
	v_add_u32_e32 v136, v5, v4
	v_add_u32_e32 v175, 0x18000, v169
	v_add_u32_e32 v174, 0x1a000, v169
	v_add_u32_e32 v173, 0x8000, v169
	v_add_u32_e32 v172, 0xa000, v169
	v_add_u32_e32 v171, 0x1c000, v169
	v_add_u32_e32 v170, 0x1e000, v169
	v_mov_b32_e32 v1, v0
	v_mov_b32_e32 v2, v0
	v_mov_b32_e32 v3, v0
	v_mov_b32_e32 v4, v0
	v_mov_b32_e32 v5, v0
	v_mov_b32_e32 v6, v0
	v_mov_b32_e32 v7, v0
	v_mov_b32_e32 v8, v0
	v_mov_b32_e32 v9, v0
	v_mov_b32_e32 v10, v0
	v_mov_b32_e32 v11, v0
	v_mov_b32_e32 v12, v0
	v_mov_b32_e32 v13, v0
	v_mov_b32_e32 v14, v0
	v_mov_b32_e32 v15, v0
	v_mov_b32_e32 v16, v0
	v_mov_b32_e32 v17, v0
	v_mov_b32_e32 v18, v0
	v_mov_b32_e32 v19, v0
	v_mov_b32_e32 v20, v0
	v_mov_b32_e32 v21, v0
	v_mov_b32_e32 v22, v0
	v_mov_b32_e32 v23, v0
	v_mov_b32_e32 v24, v0
	v_mov_b32_e32 v25, v0
	v_mov_b32_e32 v26, v0
	v_mov_b32_e32 v27, v0
	v_mov_b32_e32 v28, v0
	v_mov_b32_e32 v29, v0
	v_mov_b32_e32 v30, v0
	v_mov_b32_e32 v31, v0
	v_mov_b32_e32 v32, v0
	v_mov_b32_e32 v33, v0
	v_mov_b32_e32 v34, v0
	v_mov_b32_e32 v35, v0
	v_mov_b32_e32 v36, v0
	v_mov_b32_e32 v37, v0
	v_mov_b32_e32 v38, v0
	v_mov_b32_e32 v39, v0
	v_mov_b32_e32 v40, v0
	v_mov_b32_e32 v41, v0
	v_mov_b32_e32 v42, v0
	v_mov_b32_e32 v43, v0
	v_mov_b32_e32 v44, v0
	v_mov_b32_e32 v45, v0
	v_mov_b32_e32 v46, v0
	v_mov_b32_e32 v47, v0
	v_mov_b32_e32 v48, v0
	v_mov_b32_e32 v49, v0
	v_mov_b32_e32 v50, v0
	v_mov_b32_e32 v51, v0
	v_mov_b32_e32 v52, v0
	v_mov_b32_e32 v53, v0
	v_mov_b32_e32 v54, v0
	v_mov_b32_e32 v55, v0
	v_mov_b32_e32 v56, v0
	v_mov_b32_e32 v57, v0
	v_mov_b32_e32 v58, v0
	v_mov_b32_e32 v59, v0
	v_mov_b32_e32 v60, v0
	v_mov_b32_e32 v61, v0
	v_mov_b32_e32 v62, v0
	v_mov_b32_e32 v63, v0
	v_mov_b32_e32 v64, v0
	v_mov_b32_e32 v65, v0
	v_mov_b32_e32 v66, v0
	v_mov_b32_e32 v67, v0
	v_mov_b32_e32 v68, v0
	v_mov_b32_e32 v69, v0
	v_mov_b32_e32 v70, v0
	v_mov_b32_e32 v71, v0
	v_mov_b32_e32 v72, v0
	v_mov_b32_e32 v73, v0
	v_mov_b32_e32 v74, v0
	v_mov_b32_e32 v75, v0
	v_mov_b32_e32 v76, v0
	v_mov_b32_e32 v77, v0
	v_mov_b32_e32 v78, v0
	v_mov_b32_e32 v79, v0
	v_mov_b32_e32 v80, v0
	v_mov_b32_e32 v81, v0
	v_mov_b32_e32 v82, v0
	v_mov_b32_e32 v83, v0
	v_mov_b32_e32 v84, v0
	v_mov_b32_e32 v85, v0
	v_mov_b32_e32 v86, v0
	v_mov_b32_e32 v87, v0
	v_mov_b32_e32 v88, v0
	v_mov_b32_e32 v89, v0
	v_mov_b32_e32 v90, v0
	v_mov_b32_e32 v91, v0
	v_mov_b32_e32 v92, v0
	v_mov_b32_e32 v93, v0
	v_mov_b32_e32 v94, v0
	v_mov_b32_e32 v95, v0
	v_mov_b32_e32 v96, v0
	v_mov_b32_e32 v97, v0
	v_mov_b32_e32 v98, v0
	v_mov_b32_e32 v99, v0
	v_mov_b32_e32 v100, v0
	v_mov_b32_e32 v101, v0
	v_mov_b32_e32 v102, v0
	v_mov_b32_e32 v103, v0
	v_mov_b32_e32 v104, v0
	v_mov_b32_e32 v105, v0
	v_mov_b32_e32 v106, v0
	v_mov_b32_e32 v107, v0
	v_mov_b32_e32 v108, v0
	v_mov_b32_e32 v109, v0
	v_mov_b32_e32 v110, v0
	v_mov_b32_e32 v111, v0
	v_mov_b32_e32 v112, v0
	v_mov_b32_e32 v113, v0
	v_mov_b32_e32 v114, v0
	v_mov_b32_e32 v115, v0
	v_mov_b32_e32 v116, v0
	v_mov_b32_e32 v117, v0
	v_mov_b32_e32 v118, v0
	v_mov_b32_e32 v119, v0
	v_mov_b32_e32 v120, v0
	v_mov_b32_e32 v121, v0
	v_mov_b32_e32 v122, v0
	v_mov_b32_e32 v123, v0
	v_mov_b32_e32 v124, v0
	v_mov_b32_e32 v125, v0
	v_mov_b32_e32 v126, v0
	v_mov_b32_e32 v127, v0
	s_barrier
	v_readlane_b32 s98, v242, 1
	s_lshl_b32 s98, s98, 10
	s_lshl_b64 s[70:71], s[18:19], s28
	s_add_u32 s70, s26, s70
	s_addc_u32 s71, s27, s71
	v_lshl_add_u64 v[162:163], s[70:71], 0, v[164:165]
	s_add_i32 s23, s98, 0xc000
	s_add_u32 s70, s70, s24
	s_mov_b32 m0, s23
	s_addc_u32 s71, s71, 0
	s_add_i32 s23, s98, 0xe000
	global_load_lds_dwordx4 v[162:163], off
	v_lshl_add_u64 v[162:163], s[70:71], 0, v[164:165]
	s_mov_b32 m0, s23
	s_nop 0
	global_load_lds_dwordx4 v[162:163], off
.LBB0_356:
	ds_read_b128 v[138:141], v134
	ds_read_b128 v[142:145], v134 offset:1024
	ds_read_b128 v[146:149], v134 offset:2048
	ds_read_b128 v[150:153], v134 offset:3072
	ds_read_b128 v[154:157], v187
	ds_read_b128 v[158:161], v187 offset:1024
	ds_read_b128 v[188:191], v186
	ds_read_b128 v[192:195], v186 offset:1024
	ds_read_b128 v[196:199], v185
	ds_read_b128 v[200:203], v185 offset:1024
	ds_read_b128 v[204:207], v184
	ds_read_b128 v[208:211], v184 offset:1024
	s_waitcnt lgkmcnt(8)
	s_waitcnt vmcnt(10)
	s_barrier
	s_waitcnt lgkmcnt(0)
	s_waitcnt lgkmcnt(0)
	v_mfma_f32_16x16x32_bf16 v[124:127], v[138:141], v[154:157], v[124:127]
	v_mfma_f32_16x16x32_bf16 v[120:123], v[146:149], v[154:157], v[120:123]
	v_mfma_f32_16x16x32_bf16 v[116:119], v[138:141], v[188:191], v[116:119]
	v_mfma_f32_16x16x32_bf16 v[112:115], v[146:149], v[188:191], v[112:115]
	v_mfma_f32_16x16x32_bf16 v[108:111], v[138:141], v[196:199], v[108:111]
	v_mfma_f32_16x16x32_bf16 v[104:107], v[146:149], v[196:199], v[104:107]
	v_mfma_f32_16x16x32_bf16 v[100:103], v[138:141], v[204:207], v[100:103]
	v_mfma_f32_16x16x32_bf16 v[96:99], v[146:149], v[204:207], v[96:99]
	v_mfma_f32_16x16x32_bf16 v[124:127], v[142:145], v[158:161], v[124:127]
	v_mfma_f32_16x16x32_bf16 v[120:123], v[150:153], v[158:161], v[120:123]
	v_mfma_f32_16x16x32_bf16 v[116:119], v[142:145], v[192:195], v[116:119]
	v_mfma_f32_16x16x32_bf16 v[112:115], v[150:153], v[192:195], v[112:115]
	v_mfma_f32_16x16x32_bf16 v[108:111], v[142:145], v[200:203], v[108:111]
	v_mfma_f32_16x16x32_bf16 v[104:107], v[150:153], v[200:203], v[104:107]
	v_mfma_f32_16x16x32_bf16 v[100:103], v[142:145], v[208:211], v[100:103]
	v_mfma_f32_16x16x32_bf16 v[96:99], v[150:153], v[208:211], v[96:99]
	s_barrier
	s_add_u32 s70, s18, 1
	s_addc_u32 s71, s19, 0
	s_lshl_b64 s[72:73], s[70:71], s22
	s_add_u32 s74, s17, s72
	s_addc_u32 s75, s29, s73
	v_lshl_add_u64 v[162:163], s[74:75], 0, v[128:129]
	s_add_i32 s23, s98, 0x10000
	s_add_u32 s74, s74, s25
	s_mov_b32 m0, s23
	s_addc_u32 s75, s75, 0
	s_add_i32 s23, s98, 0x12000
	ds_read_b128 v[212:215], v131
	ds_read_b128 v[216:219], v131 offset:1024
	ds_read_b128 v[220:223], v131 offset:2048
	ds_read_b128 v[224:227], v131 offset:3072
	global_load_lds_dwordx4 v[162:163], off
	v_lshl_add_u64 v[162:163], s[74:75], 0, v[128:129]
	s_mov_b32 m0, s23
	s_nop 0
	global_load_lds_dwordx4 v[162:163], off
	s_lshl_b64 s[70:71], s[70:71], s28
	s_add_u32 s74, s15, s70
	s_addc_u32 s75, s30, s71
	v_lshl_add_u64 v[162:163], s[74:75], 0, v[164:165]
	s_mov_b32 s23, s98
	s_add_u32 s74, s74, s24
	s_mov_b32 m0, s23
	s_addc_u32 s75, s75, 0
	s_add_i32 s23, s98, 0x2000
	global_load_lds_dwordx4 v[162:163], off
	v_lshl_add_u64 v[162:163], s[74:75], 0, v[164:165]
	s_mov_b32 m0, s23
	s_nop 0
	global_load_lds_dwordx4 v[162:163], off
	s_waitcnt vmcnt(12)
	s_barrier
	s_waitcnt lgkmcnt(0)
	s_waitcnt lgkmcnt(0)
	v_mfma_f32_16x16x32_bf16 v[92:95], v[212:215], v[154:157], v[92:95]
	v_mfma_f32_16x16x32_bf16 v[88:91], v[220:223], v[154:157], v[88:91]
	v_mfma_f32_16x16x32_bf16 v[84:87], v[212:215], v[188:191], v[84:87]
	v_mfma_f32_16x16x32_bf16 v[80:83], v[220:223], v[188:191], v[80:83]
	v_mfma_f32_16x16x32_bf16 v[76:79], v[212:215], v[196:199], v[76:79]
	v_mfma_f32_16x16x32_bf16 v[72:75], v[220:223], v[196:199], v[72:75]
	v_mfma_f32_16x16x32_bf16 v[68:71], v[212:215], v[204:207], v[68:71]
	v_mfma_f32_16x16x32_bf16 v[64:67], v[220:223], v[204:207], v[64:67]
	v_mfma_f32_16x16x32_bf16 v[92:95], v[216:219], v[158:161], v[92:95]
	v_mfma_f32_16x16x32_bf16 v[88:91], v[224:227], v[158:161], v[88:91]
	v_mfma_f32_16x16x32_bf16 v[84:87], v[216:219], v[192:195], v[84:87]
	v_mfma_f32_16x16x32_bf16 v[80:83], v[224:227], v[192:195], v[80:83]
	v_mfma_f32_16x16x32_bf16 v[76:79], v[216:219], v[200:203], v[76:79]
	v_mfma_f32_16x16x32_bf16 v[72:75], v[224:227], v[200:203], v[72:75]
	v_mfma_f32_16x16x32_bf16 v[68:71], v[216:219], v[208:211], v[68:71]
	v_mfma_f32_16x16x32_bf16 v[64:67], v[224:227], v[208:211], v[64:67]
	s_barrier
	ds_read_b128 v[154:157], v187 offset:16384
	ds_read_b128 v[158:161], v187 offset:17408
	ds_read_b128 v[188:191], v186 offset:16384
	ds_read_b128 v[192:195], v186 offset:17408
	ds_read_b128 v[196:199], v185 offset:16384
	ds_read_b128 v[200:203], v185 offset:17408
	ds_read_b128 v[204:207], v184 offset:16384
	ds_read_b128 v[208:211], v184 offset:17408
	s_add_u32 s72, s20, s72
	s_addc_u32 s73, s21, s73
	v_lshl_add_u64 v[162:163], s[72:73], 0, v[128:129]
	s_add_i32 s23, s98, 0x14000
	s_add_u32 s72, s72, s25
	s_mov_b32 m0, s23
	s_addc_u32 s73, s73, 0
	s_add_i32 s23, s98, 0x16000
	global_load_lds_dwordx4 v[162:163], off
	v_lshl_add_u64 v[162:163], s[72:73], 0, v[128:129]
	s_mov_b32 m0, s23
	s_nop 0
	global_load_lds_dwordx4 v[162:163], off
	s_barrier
	s_waitcnt lgkmcnt(0)
	s_waitcnt lgkmcnt(0)
	v_mfma_f32_16x16x32_bf16 v[60:63], v[138:141], v[154:157], v[60:63]
	v_mfma_f32_16x16x32_bf16 v[56:59], v[146:149], v[154:157], v[56:59]
	v_mfma_f32_16x16x32_bf16 v[52:55], v[138:141], v[188:191], v[52:55]
	v_mfma_f32_16x16x32_bf16 v[48:51], v[146:149], v[188:191], v[48:51]
	v_mfma_f32_16x16x32_bf16 v[44:47], v[138:141], v[196:199], v[44:47]
	v_mfma_f32_16x16x32_bf16 v[40:43], v[146:149], v[196:199], v[40:43]
	v_mfma_f32_16x16x32_bf16 v[36:39], v[138:141], v[204:207], v[36:39]
	v_mfma_f32_16x16x32_bf16 v[32:35], v[146:149], v[204:207], v[32:35]
	v_mfma_f32_16x16x32_bf16 v[60:63], v[142:145], v[158:161], v[60:63]
	v_mfma_f32_16x16x32_bf16 v[56:59], v[150:153], v[158:161], v[56:59]
	v_mfma_f32_16x16x32_bf16 v[52:55], v[142:145], v[192:195], v[52:55]
	v_mfma_f32_16x16x32_bf16 v[48:51], v[150:153], v[192:195], v[48:51]
	v_mfma_f32_16x16x32_bf16 v[44:47], v[142:145], v[200:203], v[44:47]
	v_mfma_f32_16x16x32_bf16 v[40:43], v[150:153], v[200:203], v[40:43]
	v_mfma_f32_16x16x32_bf16 v[36:39], v[142:145], v[208:211], v[36:39]
	v_mfma_f32_16x16x32_bf16 v[32:35], v[150:153], v[208:211], v[32:35]
	s_barrier
	s_add_u32 s70, s26, s70
	s_addc_u32 s71, s27, s71
	v_lshl_add_u64 v[162:163], s[70:71], 0, v[164:165]
	s_add_i32 s23, s98, 0x4000
	s_add_u32 s70, s70, s24
	s_mov_b32 m0, s23
	s_addc_u32 s71, s71, 0
	s_add_i32 s23, s98, 0x6000
	global_load_lds_dwordx4 v[162:163], off
	v_lshl_add_u64 v[162:163], s[70:71], 0, v[164:165]
	s_mov_b32 m0, s23
	s_nop 0
	global_load_lds_dwordx4 v[162:163], off
	s_waitcnt vmcnt(12)
	s_barrier
	v_mfma_f32_16x16x32_bf16 v[28:31], v[212:215], v[154:157], v[28:31]
	v_mfma_f32_16x16x32_bf16 v[24:27], v[220:223], v[154:157], v[24:27]
	v_mfma_f32_16x16x32_bf16 v[20:23], v[212:215], v[188:191], v[20:23]
	v_mfma_f32_16x16x32_bf16 v[16:19], v[220:223], v[188:191], v[16:19]
	v_mfma_f32_16x16x32_bf16 v[12:15], v[212:215], v[196:199], v[12:15]
	v_mfma_f32_16x16x32_bf16 v[8:11], v[220:223], v[196:199], v[8:11]
	v_mfma_f32_16x16x32_bf16 v[4:7], v[212:215], v[204:207], v[4:7]
	v_mfma_f32_16x16x32_bf16 v[0:3], v[220:223], v[204:207], v[0:3]
	v_mfma_f32_16x16x32_bf16 v[28:31], v[216:219], v[158:161], v[28:31]
	v_mfma_f32_16x16x32_bf16 v[24:27], v[224:227], v[158:161], v[24:27]
	v_mfma_f32_16x16x32_bf16 v[20:23], v[216:219], v[192:195], v[20:23]
	v_mfma_f32_16x16x32_bf16 v[16:19], v[224:227], v[192:195], v[16:19]
	v_mfma_f32_16x16x32_bf16 v[12:15], v[216:219], v[200:203], v[12:15]
	v_mfma_f32_16x16x32_bf16 v[8:11], v[224:227], v[200:203], v[8:11]
	v_mfma_f32_16x16x32_bf16 v[4:7], v[216:219], v[208:211], v[4:7]
	v_mfma_f32_16x16x32_bf16 v[0:3], v[224:227], v[208:211], v[0:3]
	s_barrier
	ds_read_b128 v[138:141], v130
	ds_read_b128 v[142:145], v130 offset:1024
	ds_read_b128 v[146:149], v130 offset:2048
	ds_read_b128 v[150:153], v130 offset:3072
	ds_read_b128 v[154:157], v187 offset:32768
	ds_read_b128 v[158:161], v187 offset:33792
	ds_read_b128 v[188:191], v186 offset:32768
	ds_read_b128 v[192:195], v186 offset:33792
	ds_read_b128 v[196:199], v185 offset:32768
	ds_read_b128 v[200:203], v185 offset:33792
	ds_read_b128 v[204:207], v184 offset:32768
	ds_read_b128 v[208:211], v184 offset:33792
	s_waitcnt lgkmcnt(8)
	s_waitcnt vmcnt(10)
	s_barrier
	s_waitcnt lgkmcnt(0)
	s_waitcnt lgkmcnt(0)
	v_mfma_f32_16x16x32_bf16 v[124:127], v[138:141], v[154:157], v[124:127]
	v_mfma_f32_16x16x32_bf16 v[120:123], v[146:149], v[154:157], v[120:123]
	v_mfma_f32_16x16x32_bf16 v[116:119], v[138:141], v[188:191], v[116:119]
	v_mfma_f32_16x16x32_bf16 v[112:115], v[146:149], v[188:191], v[112:115]
	v_mfma_f32_16x16x32_bf16 v[108:111], v[138:141], v[196:199], v[108:111]
	v_mfma_f32_16x16x32_bf16 v[104:107], v[146:149], v[196:199], v[104:107]
	v_mfma_f32_16x16x32_bf16 v[100:103], v[138:141], v[204:207], v[100:103]
	v_mfma_f32_16x16x32_bf16 v[96:99], v[146:149], v[204:207], v[96:99]
	v_mfma_f32_16x16x32_bf16 v[124:127], v[142:145], v[158:161], v[124:127]
	v_mfma_f32_16x16x32_bf16 v[120:123], v[150:153], v[158:161], v[120:123]
	v_mfma_f32_16x16x32_bf16 v[116:119], v[142:145], v[192:195], v[116:119]
	v_mfma_f32_16x16x32_bf16 v[112:115], v[150:153], v[192:195], v[112:115]
	v_mfma_f32_16x16x32_bf16 v[108:111], v[142:145], v[200:203], v[108:111]
	v_mfma_f32_16x16x32_bf16 v[104:107], v[150:153], v[200:203], v[104:107]
	v_mfma_f32_16x16x32_bf16 v[100:103], v[142:145], v[208:211], v[100:103]
	v_mfma_f32_16x16x32_bf16 v[96:99], v[150:153], v[208:211], v[96:99]
	s_barrier
	s_add_u32 s18, s18, 2
	s_addc_u32 s19, s19, 0
	s_lshl_b64 s[70:71], s[18:19], s22
	s_add_u32 s72, s17, s70
	s_addc_u32 s73, s29, s71
	v_lshl_add_u64 v[162:163], s[72:73], 0, v[128:129]
	s_add_i32 s23, s98, 0x18000
	s_add_u32 s72, s72, s25
	s_mov_b32 m0, s23
	s_addc_u32 s73, s73, 0
	s_add_i32 s23, s98, 0x1a000
	ds_read_b128 v[212:215], v136
	ds_read_b128 v[216:219], v136 offset:1024
	ds_read_b128 v[220:223], v136 offset:2048
	ds_read_b128 v[224:227], v136 offset:3072
	global_load_lds_dwordx4 v[162:163], off
	v_lshl_add_u64 v[162:163], s[72:73], 0, v[128:129]
	s_mov_b32 m0, s23
	s_nop 0
	global_load_lds_dwordx4 v[162:163], off
	s_lshl_b64 s[72:73], s[18:19], s28
	s_add_u32 s72, s15, s72
	s_addc_u32 s73, s30, s73
	v_lshl_add_u64 v[162:163], s[72:73], 0, v[164:165]
	s_add_i32 s23, s98, 0x8000
	s_add_u32 s72, s72, s24
	s_mov_b32 m0, s23
	s_addc_u32 s73, s73, 0
	s_add_i32 s23, s98, 0xa000
	global_load_lds_dwordx4 v[162:163], off
	v_lshl_add_u64 v[162:163], s[72:73], 0, v[164:165]
	s_mov_b32 m0, s23
	s_nop 0
	global_load_lds_dwordx4 v[162:163], off
	s_waitcnt vmcnt(12)
	s_barrier
	s_waitcnt lgkmcnt(0)
	s_waitcnt lgkmcnt(0)
	v_mfma_f32_16x16x32_bf16 v[92:95], v[212:215], v[154:157], v[92:95]
	v_mfma_f32_16x16x32_bf16 v[88:91], v[220:223], v[154:157], v[88:91]
	v_mfma_f32_16x16x32_bf16 v[84:87], v[212:215], v[188:191], v[84:87]
	v_mfma_f32_16x16x32_bf16 v[80:83], v[220:223], v[188:191], v[80:83]
	v_mfma_f32_16x16x32_bf16 v[76:79], v[212:215], v[196:199], v[76:79]
	v_mfma_f32_16x16x32_bf16 v[72:75], v[220:223], v[196:199], v[72:75]
	v_mfma_f32_16x16x32_bf16 v[68:71], v[212:215], v[204:207], v[68:71]
	v_mfma_f32_16x16x32_bf16 v[64:67], v[220:223], v[204:207], v[64:67]
	v_mfma_f32_16x16x32_bf16 v[92:95], v[216:219], v[158:161], v[92:95]
	v_mfma_f32_16x16x32_bf16 v[88:91], v[224:227], v[158:161], v[88:91]
	v_mfma_f32_16x16x32_bf16 v[84:87], v[216:219], v[192:195], v[84:87]
	v_mfma_f32_16x16x32_bf16 v[80:83], v[224:227], v[192:195], v[80:83]
	v_mfma_f32_16x16x32_bf16 v[76:79], v[216:219], v[200:203], v[76:79]
	v_mfma_f32_16x16x32_bf16 v[72:75], v[224:227], v[200:203], v[72:75]
	v_mfma_f32_16x16x32_bf16 v[68:71], v[216:219], v[208:211], v[68:71]
	v_mfma_f32_16x16x32_bf16 v[64:67], v[224:227], v[208:211], v[64:67]
	s_barrier
	ds_read_b128 v[154:157], v187 offset:49152
	ds_read_b128 v[158:161], v187 offset:50176
	ds_read_b128 v[188:191], v186 offset:49152
	ds_read_b128 v[192:195], v186 offset:50176
	ds_read_b128 v[196:199], v185 offset:49152
	ds_read_b128 v[200:203], v185 offset:50176
	ds_read_b128 v[204:207], v184 offset:49152
	ds_read_b128 v[208:211], v184 offset:50176
	s_add_u32 s70, s20, s70
	s_addc_u32 s71, s21, s71
	v_lshl_add_u64 v[162:163], s[70:71], 0, v[128:129]
	s_add_i32 s23, s98, 0x1c000
	s_add_u32 s70, s70, s25
	s_mov_b32 m0, s23
	s_addc_u32 s71, s71, 0
	s_add_i32 s23, s98, 0x1e000
	global_load_lds_dwordx4 v[162:163], off
	v_lshl_add_u64 v[162:163], s[70:71], 0, v[128:129]
	s_mov_b32 m0, s23
	s_nop 0
	global_load_lds_dwordx4 v[162:163], off
	s_barrier
	s_waitcnt lgkmcnt(0)
	s_waitcnt lgkmcnt(0)
	v_mfma_f32_16x16x32_bf16 v[60:63], v[138:141], v[154:157], v[60:63]
	v_mfma_f32_16x16x32_bf16 v[56:59], v[146:149], v[154:157], v[56:59]
	v_mfma_f32_16x16x32_bf16 v[52:55], v[138:141], v[188:191], v[52:55]
	v_mfma_f32_16x16x32_bf16 v[48:51], v[146:149], v[188:191], v[48:51]
	v_mfma_f32_16x16x32_bf16 v[44:47], v[138:141], v[196:199], v[44:47]
	v_mfma_f32_16x16x32_bf16 v[40:43], v[146:149], v[196:199], v[40:43]
	v_mfma_f32_16x16x32_bf16 v[36:39], v[138:141], v[204:207], v[36:39]
	v_mfma_f32_16x16x32_bf16 v[32:35], v[146:149], v[204:207], v[32:35]
	v_mfma_f32_16x16x32_bf16 v[60:63], v[142:145], v[158:161], v[60:63]
	v_mfma_f32_16x16x32_bf16 v[56:59], v[150:153], v[158:161], v[56:59]
	v_mfma_f32_16x16x32_bf16 v[52:55], v[142:145], v[192:195], v[52:55]
	v_mfma_f32_16x16x32_bf16 v[48:51], v[150:153], v[192:195], v[48:51]
	v_mfma_f32_16x16x32_bf16 v[44:47], v[142:145], v[200:203], v[44:47]
	v_mfma_f32_16x16x32_bf16 v[40:43], v[150:153], v[200:203], v[40:43]
	v_mfma_f32_16x16x32_bf16 v[36:39], v[142:145], v[208:211], v[36:39]
	v_mfma_f32_16x16x32_bf16 v[32:35], v[150:153], v[208:211], v[32:35]
	s_barrier
	s_lshl_b64 s[70:71], s[18:19], s28
	s_add_u32 s70, s26, s70
	s_addc_u32 s71, s27, s71
	v_lshl_add_u64 v[162:163], s[70:71], 0, v[164:165]
	s_add_i32 s23, s98, 0xc000
	s_add_u32 s70, s70, s24
	s_mov_b32 m0, s23
	s_addc_u32 s71, s71, 0
	s_add_i32 s23, s98, 0xe000
	global_load_lds_dwordx4 v[162:163], off
	v_lshl_add_u64 v[162:163], s[70:71], 0, v[164:165]
	s_mov_b32 m0, s23
	s_nop 0
	global_load_lds_dwordx4 v[162:163], off
	s_waitcnt vmcnt(12)
	s_barrier
	v_mfma_f32_16x16x32_bf16 v[28:31], v[212:215], v[154:157], v[28:31]
	v_mfma_f32_16x16x32_bf16 v[24:27], v[220:223], v[154:157], v[24:27]
	v_mfma_f32_16x16x32_bf16 v[20:23], v[212:215], v[188:191], v[20:23]
	v_mfma_f32_16x16x32_bf16 v[16:19], v[220:223], v[188:191], v[16:19]
	v_mfma_f32_16x16x32_bf16 v[12:15], v[212:215], v[196:199], v[12:15]
	v_mfma_f32_16x16x32_bf16 v[8:11], v[220:223], v[196:199], v[8:11]
	v_mfma_f32_16x16x32_bf16 v[4:7], v[212:215], v[204:207], v[4:7]
	v_mfma_f32_16x16x32_bf16 v[0:3], v[220:223], v[204:207], v[0:3]
	v_mfma_f32_16x16x32_bf16 v[28:31], v[216:219], v[158:161], v[28:31]
	v_mfma_f32_16x16x32_bf16 v[24:27], v[224:227], v[158:161], v[24:27]
	v_mfma_f32_16x16x32_bf16 v[20:23], v[216:219], v[192:195], v[20:23]
	v_mfma_f32_16x16x32_bf16 v[16:19], v[224:227], v[192:195], v[16:19]
	v_mfma_f32_16x16x32_bf16 v[12:15], v[216:219], v[200:203], v[12:15]
	v_mfma_f32_16x16x32_bf16 v[8:11], v[224:227], v[200:203], v[8:11]
	v_mfma_f32_16x16x32_bf16 v[4:7], v[216:219], v[208:211], v[4:7]
	v_mfma_f32_16x16x32_bf16 v[0:3], v[224:227], v[208:211], v[0:3]
	s_add_i32 s23, s18, -3
	s_cmp_lt_u32 s23, 28
	s_barrier
	s_cbranch_scc1 .LBB0_356
	s_lshl_b64 s[18:19], 31, s28
	s_add_u32 s18, s26, s18
	s_addc_u32 s19, s27, s19
	v_lshl_add_u64 v[128:129], s[18:19], 0, v[164:165]
	v_readfirstlane_b32 s15, v133
	s_add_u32 s18, s18, s24
	s_mov_b32 m0, s15
	s_addc_u32 s19, s19, 0
	v_readfirstlane_b32 s15, v132
	ds_read_b128 v[138:141], v134
	ds_read_b128 v[142:145], v134 offset:1024
	ds_read_b128 v[146:149], v134 offset:2048
	ds_read_b128 v[150:153], v134 offset:3072
	ds_read_b128 v[154:157], v187
	ds_read_b128 v[158:161], v187 offset:1024
	ds_read_b128 v[188:191], v186
	ds_read_b128 v[192:195], v186 offset:1024
	ds_read_b128 v[196:199], v185
	ds_read_b128 v[200:203], v185 offset:1024
	ds_read_b128 v[204:207], v184
	ds_read_b128 v[208:211], v184 offset:1024
	global_load_lds_dwordx4 v[128:129], off
	v_lshl_add_u64 v[128:129], s[18:19], 0, v[164:165]
	s_mov_b32 m0, s15
	s_nop 0
	global_load_lds_dwordx4 v[128:129], off
	s_waitcnt vmcnt(10)
	s_barrier
	s_waitcnt lgkmcnt(0)
	s_setprio 1
	s_waitcnt lgkmcnt(0)
	v_mfma_f32_16x16x32_bf16 v[124:127], v[138:141], v[154:157], v[124:127]
	v_mfma_f32_16x16x32_bf16 v[120:123], v[146:149], v[154:157], v[120:123]
	v_mfma_f32_16x16x32_bf16 v[116:119], v[138:141], v[188:191], v[116:119]
	v_mfma_f32_16x16x32_bf16 v[112:115], v[146:149], v[188:191], v[112:115]
	v_mfma_f32_16x16x32_bf16 v[108:111], v[138:141], v[196:199], v[108:111]
	v_mfma_f32_16x16x32_bf16 v[104:107], v[146:149], v[196:199], v[104:107]
	v_mfma_f32_16x16x32_bf16 v[100:103], v[138:141], v[204:207], v[100:103]
	v_mfma_f32_16x16x32_bf16 v[96:99], v[146:149], v[204:207], v[96:99]
	v_mfma_f32_16x16x32_bf16 v[124:127], v[142:145], v[158:161], v[124:127]
	v_mfma_f32_16x16x32_bf16 v[120:123], v[150:153], v[158:161], v[120:123]
	v_mfma_f32_16x16x32_bf16 v[116:119], v[142:145], v[192:195], v[116:119]
	v_mfma_f32_16x16x32_bf16 v[112:115], v[150:153], v[192:195], v[112:115]
	v_mfma_f32_16x16x32_bf16 v[108:111], v[142:145], v[200:203], v[108:111]
	v_mfma_f32_16x16x32_bf16 v[104:107], v[150:153], v[200:203], v[104:107]
	v_mfma_f32_16x16x32_bf16 v[100:103], v[142:145], v[208:211], v[100:103]
	v_mfma_f32_16x16x32_bf16 v[96:99], v[150:153], v[208:211], v[96:99]
	s_setprio 0
	s_barrier
	ds_read_b128 v[132:135], v131
	ds_read_b128 v[212:215], v131 offset:1024
	ds_read_b128 v[216:219], v131 offset:2048
	ds_read_b128 v[220:223], v131 offset:3072
	s_barrier
	s_waitcnt lgkmcnt(0)
	s_setprio 1
	s_waitcnt lgkmcnt(0)
	v_mfma_f32_16x16x32_bf16 v[92:95], v[132:135], v[154:157], v[92:95]
	v_mfma_f32_16x16x32_bf16 v[88:91], v[216:219], v[154:157], v[88:91]
	v_mfma_f32_16x16x32_bf16 v[84:87], v[132:135], v[188:191], v[84:87]
	v_mfma_f32_16x16x32_bf16 v[80:83], v[216:219], v[188:191], v[80:83]
	v_mfma_f32_16x16x32_bf16 v[76:79], v[132:135], v[196:199], v[76:79]
	v_mfma_f32_16x16x32_bf16 v[72:75], v[216:219], v[196:199], v[72:75]
	v_mfma_f32_16x16x32_bf16 v[68:71], v[132:135], v[204:207], v[68:71]
	v_mfma_f32_16x16x32_bf16 v[64:67], v[216:219], v[204:207], v[64:67]
	v_mfma_f32_16x16x32_bf16 v[154:157], v[212:215], v[158:161], v[92:95]
	v_mfma_f32_16x16x32_bf16 v[158:161], v[220:223], v[158:161], v[88:91]
	v_mfma_f32_16x16x32_bf16 v[188:191], v[212:215], v[192:195], v[84:87]
	v_mfma_f32_16x16x32_bf16 v[192:195], v[220:223], v[192:195], v[80:83]
	v_mfma_f32_16x16x32_bf16 v[196:199], v[212:215], v[200:203], v[76:79]
	v_mfma_f32_16x16x32_bf16 v[200:203], v[220:223], v[200:203], v[72:75]
	v_mfma_f32_16x16x32_bf16 v[204:207], v[212:215], v[208:211], v[68:71]
	v_mfma_f32_16x16x32_bf16 v[208:211], v[220:223], v[208:211], v[64:67]
	s_setprio 0
	s_barrier
	s_nop 0
	ds_read_b128 v[64:67], v187 offset:16384
	ds_read_b128 v[68:71], v187 offset:17408
	ds_read_b128 v[72:75], v186 offset:16384
	ds_read_b128 v[76:79], v186 offset:17408
	ds_read_b128 v[80:83], v185 offset:16384
	ds_read_b128 v[84:87], v185 offset:17408
	ds_read_b128 v[88:91], v184 offset:16384
	ds_read_b128 v[92:95], v184 offset:17408
	s_waitcnt vmcnt(4)
	s_barrier
	s_waitcnt lgkmcnt(0)
	s_setprio 1
	s_waitcnt lgkmcnt(0)
	v_mfma_f32_16x16x32_bf16 v[60:63], v[138:141], v[64:67], v[60:63]
	v_mfma_f32_16x16x32_bf16 v[56:59], v[146:149], v[64:67], v[56:59]
	v_mfma_f32_16x16x32_bf16 v[52:55], v[138:141], v[72:75], v[52:55]
	v_mfma_f32_16x16x32_bf16 v[48:51], v[146:149], v[72:75], v[48:51]
	v_mfma_f32_16x16x32_bf16 v[224:227], v[138:141], v[80:83], v[44:47]
	v_mfma_f32_16x16x32_bf16 v[228:231], v[146:149], v[80:83], v[40:43]
	v_mfma_f32_16x16x32_bf16 v[138:141], v[138:141], v[88:91], v[36:39]
	v_mfma_f32_16x16x32_bf16 v[146:149], v[146:149], v[88:91], v[32:35]
	v_mfma_f32_16x16x32_bf16 v[32:35], v[142:145], v[68:71], v[60:63]
	v_mfma_f32_16x16x32_bf16 v[36:39], v[150:153], v[68:71], v[56:59]
	v_mfma_f32_16x16x32_bf16 v[40:43], v[142:145], v[76:79], v[52:55]
	v_mfma_f32_16x16x32_bf16 v[44:47], v[150:153], v[76:79], v[48:51]
	v_mfma_f32_16x16x32_bf16 v[48:51], v[142:145], v[84:87], v[224:227]
	v_mfma_f32_16x16x32_bf16 v[52:55], v[150:153], v[84:87], v[228:231]
	v_mfma_f32_16x16x32_bf16 v[56:59], v[142:145], v[92:95], v[138:141]
	v_mfma_f32_16x16x32_bf16 v[60:63], v[150:153], v[92:95], v[146:149]
	s_setprio 0
	s_setprio 1
	v_mfma_f32_16x16x32_bf16 v[28:31], v[132:135], v[64:67], v[28:31]
	v_mfma_f32_16x16x32_bf16 v[24:27], v[216:219], v[64:67], v[24:27]
	v_mfma_f32_16x16x32_bf16 v[20:23], v[132:135], v[72:75], v[20:23]
	v_mfma_f32_16x16x32_bf16 v[16:19], v[216:219], v[72:75], v[16:19]
	v_mfma_f32_16x16x32_bf16 v[64:67], v[132:135], v[80:83], v[12:15]
	v_mfma_f32_16x16x32_bf16 v[8:11], v[216:219], v[80:83], v[8:11]
	v_mfma_f32_16x16x32_bf16 v[72:75], v[132:135], v[88:91], v[4:7]
	v_mfma_f32_16x16x32_bf16 v[0:3], v[216:219], v[88:91], v[0:3]
	v_mfma_f32_16x16x32_bf16 v[4:7], v[212:215], v[68:71], v[28:31]
	v_mfma_f32_16x16x32_bf16 v[12:15], v[220:223], v[68:71], v[24:27]
	v_mfma_f32_16x16x32_bf16 v[20:23], v[212:215], v[76:79], v[20:23]
	v_mfma_f32_16x16x32_bf16 v[28:31], v[220:223], v[76:79], v[16:19]
	v_mfma_f32_16x16x32_bf16 v[64:67], v[212:215], v[84:87], v[64:67]
	v_mfma_f32_16x16x32_bf16 v[68:71], v[220:223], v[84:87], v[8:11]
	v_mfma_f32_16x16x32_bf16 v[72:75], v[212:215], v[92:95], v[72:75]
	v_mfma_f32_16x16x32_bf16 v[76:79], v[220:223], v[92:95], v[0:3]
	s_setprio 0
	s_barrier
	ds_read_b128 v[8:11], v130
	ds_read_b128 v[0:3], v130 offset:1024
	ds_read_b128 v[16:19], v130 offset:2048
	ds_read_b128 v[80:83], v130 offset:3072
	ds_read_b128 v[138:141], v187 offset:32768
	ds_read_b128 v[212:215], v187 offset:33792
	ds_read_b128 v[216:219], v186 offset:32768
	ds_read_b128 v[220:223], v186 offset:33792
	ds_read_b128 v[224:227], v185 offset:32768
	ds_read_b128 v[228:231], v185 offset:33792
	ds_read_b128 v[232:235], v184 offset:32768
	ds_read_b128 v[236:239], v184 offset:33792
	s_waitcnt vmcnt(2)
	s_barrier
	s_waitcnt lgkmcnt(0)
	s_setprio 1
	s_waitcnt lgkmcnt(0)
	v_mfma_f32_16x16x32_bf16 v[24:27], v[8:11], v[138:141], v[124:127]
	v_mfma_f32_16x16x32_bf16 v[84:87], v[16:19], v[138:141], v[120:123]
	v_mfma_f32_16x16x32_bf16 v[88:91], v[8:11], v[216:219], v[116:119]
	v_mfma_f32_16x16x32_bf16 v[92:95], v[16:19], v[216:219], v[112:115]
	v_mfma_f32_16x16x32_bf16 v[108:111], v[8:11], v[224:227], v[108:111]
	v_mfma_f32_16x16x32_bf16 v[104:107], v[16:19], v[224:227], v[104:107]
	v_mfma_f32_16x16x32_bf16 v[100:103], v[8:11], v[232:235], v[100:103]
	v_mfma_f32_16x16x32_bf16 v[96:99], v[16:19], v[232:235], v[96:99]
	v_mfma_f32_16x16x32_bf16 v[148:151], v[0:3], v[212:215], v[24:27]
	v_mfma_f32_16x16x32_bf16 v[144:147], v[80:83], v[212:215], v[84:87]
	v_mfma_f32_16x16x32_bf16 v[132:135], v[0:3], v[220:223], v[88:91]
	v_mfma_f32_16x16x32_bf16 v[128:131], v[80:83], v[220:223], v[92:95]
	v_mfma_f32_16x16x32_bf16 v[116:119], v[0:3], v[228:231], v[108:111]
	v_mfma_f32_16x16x32_bf16 v[112:115], v[80:83], v[228:231], v[104:107]
	v_mfma_f32_16x16x32_bf16 v[100:103], v[0:3], v[236:239], v[100:103]
	v_mfma_f32_16x16x32_bf16 v[24:27], v[80:83], v[236:239], v[96:99]
	s_setprio 0
	s_barrier
	ds_read_b128 v[92:95], v136
	ds_read_b128 v[84:87], v136 offset:1024
	ds_read_b128 v[96:99], v136 offset:2048
	ds_read_b128 v[88:91], v136 offset:3072
	s_waitcnt vmcnt(0)
	s_barrier
	s_waitcnt lgkmcnt(0)
	s_setprio 1
	s_waitcnt lgkmcnt(0)
	v_mfma_f32_16x16x32_bf16 v[104:107], v[92:95], v[138:141], v[154:157]
	v_mfma_f32_16x16x32_bf16 v[108:111], v[96:99], v[138:141], v[158:161]
	v_mfma_f32_16x16x32_bf16 v[120:123], v[92:95], v[216:219], v[188:191]
	v_mfma_f32_16x16x32_bf16 v[124:127], v[96:99], v[216:219], v[192:195]
	v_mfma_f32_16x16x32_bf16 v[160:163], v[92:95], v[224:227], v[196:199]
	v_mfma_f32_16x16x32_bf16 v[188:191], v[96:99], v[224:227], v[200:203]
	v_mfma_f32_16x16x32_bf16 v[192:195], v[92:95], v[232:235], v[204:207]
	v_mfma_f32_16x16x32_bf16 v[196:199], v[96:99], v[232:235], v[208:211]
	v_mfma_f32_16x16x32_bf16 v[156:159], v[84:87], v[212:215], v[104:107]
	v_mfma_f32_16x16x32_bf16 v[152:155], v[88:91], v[212:215], v[108:111]
	v_mfma_f32_16x16x32_bf16 v[140:143], v[84:87], v[220:223], v[120:123]
	v_mfma_f32_16x16x32_bf16 v[136:139], v[88:91], v[220:223], v[124:127]
	v_mfma_f32_16x16x32_bf16 v[124:127], v[84:87], v[228:231], v[160:163]
	v_mfma_f32_16x16x32_bf16 v[120:123], v[88:91], v[228:231], v[188:191]
	v_mfma_f32_16x16x32_bf16 v[108:111], v[84:87], v[236:239], v[192:195]
	v_mfma_f32_16x16x32_bf16 v[104:107], v[88:91], v[236:239], v[196:199]
	s_setprio 0
	s_barrier
	v_mbcnt_lo_u32_b32 v164, -1, 0
	v_mbcnt_hi_u32_b32 v164, -1, v164
	s_cmp_lt_i32 s64, 3
	v_add_u32_e32 v160, s34, v164
	v_ashrrev_i32_e32 v192, 6, v160
	v_bfe_u32 v190, v160, 8, 1
	v_and_b32_e32 v191, 3, v192
	v_and_b32_e32 v188, 15, v164
	v_bfe_u32 v189, v160, 4, 2
	s_mov_b64 s[18:19], 0
	s_cbranch_scc1 .LBB0_362
	v_lshrrev_b32_e32 v160, 4, v160
	v_lshlrev_b32_e32 v162, 9, v189
	v_lshlrev_b32_e32 v163, 9, v160
	s_mov_b64 s[20:21], -1
	s_cmp_gt_i32 s64, 3
	v_lshlrev_b32_e32 v161, 4, v188
	v_and_b32_e32 v160, 0x400, v162
	v_and_b32_e32 v162, 0x200, v163
	s_cbranch_scc0 .LBB0_360
	s_lshl_b32 s15, s66, 20
	s_lshl_b32 s20, s66, 16
	s_and_b32 s15, s15, 0xff000000
	s_and_b32 s20, s20, 0xf0000
	s_lshl_b32 s17, s68, 21
	s_or_b32 s15, s20, s15
	v_lshlrev_b32_e32 v163, 14, v191
	s_add_i32 s15, s15, s17
	v_lshlrev_b32_e32 v166, 12, v190
	v_or3_b32 v163, s15, v161, v163
	v_or3_b32 v163, v163, v166, v162
	v_add_u32_e32 v166, v163, v160
	s_mov_b64 s[20:21], 0

.LBB0_464:
	v_bfe_i32 v5, v136, 27, 1
	v_lshlrev_b32_e32 v135, 4, v136
	v_lshrrev_b32_e32 v5, 22, v5
	v_add_u32_e32 v5, v135, v5
	v_and_b32_e32 v5, 0xfffffc00, v5
	v_sub_u32_e32 v5, v135, v5
	v_lshrrev_b32_e32 v6, 4, v5
	v_bitop3_b32 v5, v6, v5, 32 bitop3:0x6c
	v_ashrrev_i32_e32 v6, 31, v5
	v_lshrrev_b32_e32 v6, 26, v6
	v_add_u32_e32 v6, v5, v6
	v_ashrrev_i32_e32 v157, 6, v6
	v_and_b32_e32 v6, 0xc0, v6
	v_sub_u32_e32 v5, v5, v6
	v_ashrrev_i16_sdwa v5, v134, sext(v5) dst_sel:DWORD dst_unused:UNUSED_PAD src0_sel:DWORD src1_sel:BYTE_0
	v_and_b32_e32 v2, 15, v0
	v_and_b32_e32 v3, 48, v0
	v_bfe_i32 v158, v5, 0, 16
	v_and_b32_e32 v5, 32, v0
	v_lshlrev_b32_e32 v8, 2, v0
	v_lshlrev_b32_e32 v0, 6, v0
	s_movk_i32 s36, 0x3f0
	v_lshlrev_b32_e32 v2, 6, v2
	v_and_b32_e32 v8, 32, v8
	v_and_b32_e32 v0, 0x3c0, v0
	v_ashrrev_i32_e32 v4, 31, v136
	v_bitop3_b32 v5, v135, v5, s36 bitop3:0x6c
	v_or_b32_e32 v7, v2, v3
	v_bitop3_b32 v2, v2, v8, v3 bitop3:0x36
	v_bitop3_b32 v3, v0, v8, v3 bitop3:0x36
	v_lshlrev_b32_e32 v0, 11, v136
	v_lshrrev_b32_e32 v4, 26, v4
	v_and_or_b32 v0, v0, s78, v5
	v_lshlrev_b32_e32 v5, 3, v136
	s_bfe_u32 s66, s86, 0x30003
	v_add_u32_e32 v4, v136, v4
	s_mov_b32 s36, 0x14000
	v_and_b32_e32 v5, 0xfffffc00, v5
	s_lshl_b32 s24, s66, 14
	v_ashrrev_i32_e32 v156, 6, v4
	v_bitop3_b32 v10, v7, s36, v8 bitop3:0xde
	s_mov_b32 s36, 0x1c000
	v_add_u32_e32 v128, v0, v5
	v_bitop3_b32 v9, v7, s76, v8 bitop3:0xde
	v_bitop3_b32 v11, v7, s77, v8 bitop3:0xde
	v_bitop3_b32 v7, v7, s36, v8 bitop3:0xde
	v_lshl_add_u64 v[130:131], s[24:25], 0, v[128:129]
	v_lshlrev_b32_e32 v0, 15, v156
	s_lshl_b32 s24, s86, 17
	s_and_b32 s36, s86, 7
	v_and_b32_e32 v0, 0xffff0000, v0
	s_and_b32 s24, s24, 0x1800000
	s_lshl_b32 s36, s36, 20
	v_lshl_add_u32 v0, v157, 12, v0
	s_or_b32 s24, s24, s36
	v_lshlrev_b32_e32 v6, 6, v136
	v_lshlrev_b32_e32 v1, 13, v1
	v_and_or_b32 v0, v4, 64, v0
	s_add_u32 s68, s24, s90
	v_and_b32_e32 v6, 0x3000, v6
	v_or_b32_e32 v8, 0x800, v1
	v_or_b32_e32 v12, 0x1000, v1
	v_or_b32_e32 v13, 0x1800, v1
	v_lshl_add_u32 v128, v158, 1, v0
	s_addc_u32 s69, 0, 0
	v_mov_b32_e32 v0, 0
	v_lshl_add_u64 v[132:133], s[68:69], 0, v[128:129]
	s_mov_b32 s24, -2
	v_add_u32_e32 v162, v9, v6
	v_add_u32_e32 v153, v2, v1
	v_add_u32_e32 v152, v3, v8
	v_add_u32_e32 v151, v3, v12
	v_add_u32_e32 v150, v3, v13
	v_add_u32_e32 v161, 0xc000, v135
	v_add_u32_e32 v160, 0xe000, v135
	v_add_u32_e32 v159, v10, v6
	v_add_u32_e32 v149, 0x10000, v135
	v_add_u32_e32 v148, 0x12000, v135
	v_add_u32_e32 v147, 0x2000, v135
	v_add_u32_e32 v146, 0x14000, v135
	v_add_u32_e32 v145, 0x16000, v135
	v_add_u32_e32 v155, v11, v6
	v_add_u32_e32 v144, 0x4000, v135
	v_add_u32_e32 v143, 0x6000, v135
	v_add_u32_e32 v154, v7, v6
	v_add_u32_e32 v142, 0x18000, v135
	v_add_u32_e32 v141, 0x1a000, v135
	v_add_u32_e32 v140, 0x8000, v135
	v_add_u32_e32 v139, 0xa000, v135
	v_add_u32_e32 v138, 0x1c000, v135
	v_add_u32_e32 v137, 0x1e000, v135
	v_mov_b32_e32 v1, v0
	v_mov_b32_e32 v2, v0
	v_mov_b32_e32 v3, v0
	v_mov_b32_e32 v4, v0
	v_mov_b32_e32 v5, v0
	v_mov_b32_e32 v6, v0
	v_mov_b32_e32 v7, v0
	v_mov_b32_e32 v8, v0
	v_mov_b32_e32 v9, v0
	v_mov_b32_e32 v10, v0
	v_mov_b32_e32 v11, v0
	v_mov_b32_e32 v12, v0
	v_mov_b32_e32 v13, v0
	v_mov_b32_e32 v14, v0
	v_mov_b32_e32 v15, v0
	v_mov_b32_e32 v16, v0
	v_mov_b32_e32 v17, v0
	v_mov_b32_e32 v18, v0
	v_mov_b32_e32 v19, v0
	v_mov_b32_e32 v20, v0
	v_mov_b32_e32 v21, v0
	v_mov_b32_e32 v22, v0
	v_mov_b32_e32 v23, v0
	v_mov_b32_e32 v24, v0
	v_mov_b32_e32 v25, v0
	v_mov_b32_e32 v26, v0
	v_mov_b32_e32 v27, v0
	v_mov_b32_e32 v28, v0
	v_mov_b32_e32 v29, v0
	v_mov_b32_e32 v30, v0
	v_mov_b32_e32 v31, v0
	v_mov_b32_e32 v32, v0
	v_mov_b32_e32 v33, v0
	v_mov_b32_e32 v34, v0
	v_mov_b32_e32 v35, v0
	v_mov_b32_e32 v36, v0
	v_mov_b32_e32 v37, v0
	v_mov_b32_e32 v38, v0
	v_mov_b32_e32 v39, v0
	v_mov_b32_e32 v40, v0
	v_mov_b32_e32 v41, v0
	v_mov_b32_e32 v42, v0
	v_mov_b32_e32 v43, v0
	v_mov_b32_e32 v44, v0
	v_mov_b32_e32 v45, v0
	v_mov_b32_e32 v46, v0
	v_mov_b32_e32 v47, v0
	v_mov_b32_e32 v48, v0
	v_mov_b32_e32 v49, v0
	v_mov_b32_e32 v50, v0
	v_mov_b32_e32 v51, v0
	v_mov_b32_e32 v52, v0
	v_mov_b32_e32 v53, v0
	v_mov_b32_e32 v54, v0
	v_mov_b32_e32 v55, v0
	v_mov_b32_e32 v56, v0
	v_mov_b32_e32 v57, v0
	v_mov_b32_e32 v58, v0
	v_mov_b32_e32 v59, v0
	v_mov_b32_e32 v60, v0
	v_mov_b32_e32 v61, v0
	v_mov_b32_e32 v62, v0
	v_mov_b32_e32 v63, v0
	v_mov_b32_e32 v64, v0
	v_mov_b32_e32 v65, v0
	v_mov_b32_e32 v66, v0
	v_mov_b32_e32 v67, v0
	v_mov_b32_e32 v68, v0
	v_mov_b32_e32 v69, v0
	v_mov_b32_e32 v70, v0
	v_mov_b32_e32 v71, v0
	v_mov_b32_e32 v72, v0
	v_mov_b32_e32 v73, v0
	v_mov_b32_e32 v74, v0
	v_mov_b32_e32 v75, v0
	v_mov_b32_e32 v76, v0
	v_mov_b32_e32 v77, v0
	v_mov_b32_e32 v78, v0
	v_mov_b32_e32 v79, v0
	v_mov_b32_e32 v80, v0
	v_mov_b32_e32 v81, v0
	v_mov_b32_e32 v82, v0
	v_mov_b32_e32 v83, v0
	v_mov_b32_e32 v84, v0
	v_mov_b32_e32 v85, v0
	v_mov_b32_e32 v86, v0
	v_mov_b32_e32 v87, v0
	v_mov_b32_e32 v88, v0
	v_mov_b32_e32 v89, v0
	v_mov_b32_e32 v90, v0
	v_mov_b32_e32 v91, v0
	v_mov_b32_e32 v92, v0
	v_mov_b32_e32 v93, v0
	v_mov_b32_e32 v94, v0
	v_mov_b32_e32 v95, v0
	v_mov_b32_e32 v96, v0
	v_mov_b32_e32 v97, v0
	v_mov_b32_e32 v98, v0
	v_mov_b32_e32 v99, v0
	v_mov_b32_e32 v100, v0
	v_mov_b32_e32 v101, v0
	v_mov_b32_e32 v102, v0
	v_mov_b32_e32 v103, v0
	v_mov_b32_e32 v104, v0
	v_mov_b32_e32 v105, v0
	v_mov_b32_e32 v106, v0
	v_mov_b32_e32 v107, v0
	v_mov_b32_e32 v108, v0
	v_mov_b32_e32 v109, v0
	v_mov_b32_e32 v110, v0
	v_mov_b32_e32 v111, v0
	v_mov_b32_e32 v112, v0
	v_mov_b32_e32 v113, v0
	v_mov_b32_e32 v114, v0
	v_mov_b32_e32 v115, v0
	v_mov_b32_e32 v116, v0
	v_mov_b32_e32 v117, v0
	v_mov_b32_e32 v118, v0
	v_mov_b32_e32 v119, v0
	v_mov_b32_e32 v120, v0
	v_mov_b32_e32 v121, v0
	v_mov_b32_e32 v122, v0
	v_mov_b32_e32 v123, v0
	v_mov_b32_e32 v124, v0
	v_mov_b32_e32 v125, v0
	v_mov_b32_e32 v126, v0
	v_mov_b32_e32 v127, v0
	s_barrier
	v_readlane_b32 s98, v242, 1
	s_lshl_b32 s98, s98, 10
	v_lshl_add_u64 v[228:229], s[50:51], 0, v[132:133]
	s_mov_b64 s[68:69], 0xe080080
	s_add_i32 s36, s98, 0xc000
	v_lshl_add_u64 v[166:167], v[228:229], 0, s[68:69]
	s_mov_b32 m0, s36
	s_mov_b64 s[68:69], 0xe0c0080
	s_add_i32 s36, s98, 0xe000
	global_load_lds_dwordx4 v[166:167], off
	v_lshl_add_u64 v[166:167], v[228:229], 0, s[68:69]
	s_mov_b32 m0, s36
	s_nop 0
	global_load_lds_dwordx4 v[166:167], off
.LBB0_465:
	ds_read_b128 v[164:167], v162
	ds_read_b128 v[168:171], v162 offset:1024
	ds_read_b128 v[172:175], v162 offset:2048
	ds_read_b128 v[176:179], v162 offset:3072
	ds_read_b128 v[180:183], v153
	ds_read_b128 v[184:187], v153 offset:1024
	ds_read_b128 v[188:191], v152
	ds_read_b128 v[192:195], v152 offset:1024
	ds_read_b128 v[196:199], v151
	ds_read_b128 v[200:203], v151 offset:1024
	ds_read_b128 v[204:207], v150
	ds_read_b128 v[208:211], v150 offset:1024
	s_waitcnt lgkmcnt(8)
	s_waitcnt vmcnt(10)
	s_barrier
	s_waitcnt lgkmcnt(0)
	s_waitcnt lgkmcnt(0)
	v_mfma_f32_16x16x32_bf16 v[124:127], v[164:167], v[180:183], v[124:127]
	v_mfma_f32_16x16x32_bf16 v[120:123], v[172:175], v[180:183], v[120:123]
	v_mfma_f32_16x16x32_bf16 v[116:119], v[164:167], v[188:191], v[116:119]
	v_mfma_f32_16x16x32_bf16 v[112:115], v[172:175], v[188:191], v[112:115]
	v_mfma_f32_16x16x32_bf16 v[108:111], v[164:167], v[196:199], v[108:111]
	v_mfma_f32_16x16x32_bf16 v[104:107], v[172:175], v[196:199], v[104:107]
	v_mfma_f32_16x16x32_bf16 v[100:103], v[164:167], v[204:207], v[100:103]
	v_mfma_f32_16x16x32_bf16 v[96:99], v[172:175], v[204:207], v[96:99]
	v_mfma_f32_16x16x32_bf16 v[124:127], v[168:171], v[184:187], v[124:127]
	v_mfma_f32_16x16x32_bf16 v[120:123], v[176:179], v[184:187], v[120:123]
	v_mfma_f32_16x16x32_bf16 v[116:119], v[168:171], v[192:195], v[116:119]
	v_mfma_f32_16x16x32_bf16 v[112:115], v[176:179], v[192:195], v[112:115]
	v_mfma_f32_16x16x32_bf16 v[108:111], v[168:171], v[200:203], v[108:111]
	v_mfma_f32_16x16x32_bf16 v[104:107], v[176:179], v[200:203], v[104:107]
	v_mfma_f32_16x16x32_bf16 v[100:103], v[168:171], v[208:211], v[100:103]
	v_mfma_f32_16x16x32_bf16 v[96:99], v[176:179], v[208:211], v[96:99]
	s_barrier
	v_lshl_add_u64 v[230:231], s[50:51], 0, v[130:131]
	s_mov_b64 s[68:69], 0x3880000
	s_add_i32 s36, s98, 0x10000
	v_lshl_add_u64 v[232:233], v[230:231], 0, s[68:69]
	s_mov_b32 m0, s36
	s_mov_b64 s[68:69], 0x3881000
	s_add_i32 s36, s98, 0x12000
	ds_read_b128 v[212:215], v159
	ds_read_b128 v[216:219], v159 offset:1024
	ds_read_b128 v[220:223], v159 offset:2048
	ds_read_b128 v[224:227], v159 offset:3072
	global_load_lds_dwordx4 v[232:233], off
	v_lshl_add_u64 v[232:233], v[230:231], 0, s[68:69]
	s_mov_b32 m0, s36
	s_nop 0
	global_load_lds_dwordx4 v[232:233], off
	s_mov_b64 s[68:69], 0xe000100
	s_mov_b32 s36, s98
	v_lshl_add_u64 v[232:233], v[228:229], 0, s[68:69]
	s_mov_b32 m0, s36
	s_mov_b64 s[68:69], 0xe040100
	s_add_i32 s36, s98, 0x2000
	global_load_lds_dwordx4 v[232:233], off
	v_lshl_add_u64 v[232:233], v[228:229], 0, s[68:69]
	s_mov_b32 m0, s36
	s_nop 0
	global_load_lds_dwordx4 v[232:233], off
	s_waitcnt vmcnt(12)
	s_barrier
	s_waitcnt lgkmcnt(0)
	s_waitcnt lgkmcnt(0)
	v_mfma_f32_16x16x32_bf16 v[92:95], v[212:215], v[180:183], v[92:95]
	v_mfma_f32_16x16x32_bf16 v[88:91], v[220:223], v[180:183], v[88:91]
	v_mfma_f32_16x16x32_bf16 v[84:87], v[212:215], v[188:191], v[84:87]
	v_mfma_f32_16x16x32_bf16 v[80:83], v[220:223], v[188:191], v[80:83]
	v_mfma_f32_16x16x32_bf16 v[76:79], v[212:215], v[196:199], v[76:79]
	v_mfma_f32_16x16x32_bf16 v[72:75], v[220:223], v[196:199], v[72:75]
	v_mfma_f32_16x16x32_bf16 v[68:71], v[212:215], v[204:207], v[68:71]
	v_mfma_f32_16x16x32_bf16 v[64:67], v[220:223], v[204:207], v[64:67]
	v_mfma_f32_16x16x32_bf16 v[92:95], v[216:219], v[184:187], v[92:95]
	v_mfma_f32_16x16x32_bf16 v[88:91], v[224:227], v[184:187], v[88:91]
	v_mfma_f32_16x16x32_bf16 v[84:87], v[216:219], v[192:195], v[84:87]
	v_mfma_f32_16x16x32_bf16 v[80:83], v[224:227], v[192:195], v[80:83]
	v_mfma_f32_16x16x32_bf16 v[76:79], v[216:219], v[200:203], v[76:79]
	v_mfma_f32_16x16x32_bf16 v[72:75], v[224:227], v[200:203], v[72:75]
	v_mfma_f32_16x16x32_bf16 v[68:71], v[216:219], v[208:211], v[68:71]
	v_mfma_f32_16x16x32_bf16 v[64:67], v[224:227], v[208:211], v[64:67]
	s_barrier
	ds_read_b128 v[180:183], v153 offset:16384
	ds_read_b128 v[184:187], v153 offset:17408
	ds_read_b128 v[188:191], v152 offset:16384
	ds_read_b128 v[192:195], v152 offset:17408
	ds_read_b128 v[196:199], v151 offset:16384
	ds_read_b128 v[200:203], v151 offset:17408
	ds_read_b128 v[204:207], v150 offset:16384
	ds_read_b128 v[208:211], v150 offset:17408
	s_mov_b64 s[68:69], 0x3882000
	s_add_i32 s36, s98, 0x14000
	v_lshl_add_u64 v[232:233], v[230:231], 0, s[68:69]
	s_mov_b32 m0, s36
	s_mov_b64 s[68:69], 0x3883000
	s_add_i32 s36, s98, 0x16000
	global_load_lds_dwordx4 v[232:233], off
	v_lshl_add_u64 v[232:233], v[230:231], 0, s[68:69]
	s_mov_b32 m0, s36
	s_nop 0
	global_load_lds_dwordx4 v[232:233], off
	s_barrier
	s_waitcnt lgkmcnt(0)
	s_waitcnt lgkmcnt(0)
	v_mfma_f32_16x16x32_bf16 v[60:63], v[164:167], v[180:183], v[60:63]
	v_mfma_f32_16x16x32_bf16 v[56:59], v[172:175], v[180:183], v[56:59]
	v_mfma_f32_16x16x32_bf16 v[52:55], v[164:167], v[188:191], v[52:55]
	v_mfma_f32_16x16x32_bf16 v[48:51], v[172:175], v[188:191], v[48:51]
	v_mfma_f32_16x16x32_bf16 v[44:47], v[164:167], v[196:199], v[44:47]
	v_mfma_f32_16x16x32_bf16 v[40:43], v[172:175], v[196:199], v[40:43]
	v_mfma_f32_16x16x32_bf16 v[36:39], v[164:167], v[204:207], v[36:39]
	v_mfma_f32_16x16x32_bf16 v[32:35], v[172:175], v[204:207], v[32:35]
	v_mfma_f32_16x16x32_bf16 v[60:63], v[168:171], v[184:187], v[60:63]
	v_mfma_f32_16x16x32_bf16 v[56:59], v[176:179], v[184:187], v[56:59]
	v_mfma_f32_16x16x32_bf16 v[52:55], v[168:171], v[192:195], v[52:55]
	v_mfma_f32_16x16x32_bf16 v[48:51], v[176:179], v[192:195], v[48:51]
	v_mfma_f32_16x16x32_bf16 v[44:47], v[168:171], v[200:203], v[44:47]
	v_mfma_f32_16x16x32_bf16 v[40:43], v[176:179], v[200:203], v[40:43]
	v_mfma_f32_16x16x32_bf16 v[36:39], v[168:171], v[208:211], v[36:39]
	v_mfma_f32_16x16x32_bf16 v[32:35], v[176:179], v[208:211], v[32:35]
	s_barrier
	s_add_i32 s36, s98, 0x4000
	v_lshl_add_u64 v[166:167], v[228:229], 0, s[26:27]
	s_mov_b32 m0, s36
	s_add_i32 s36, s98, 0x6000
	global_load_lds_dwordx4 v[166:167], off
	v_lshl_add_u64 v[166:167], v[228:229], 0, s[28:29]
	s_mov_b32 m0, s36
	s_nop 0
	global_load_lds_dwordx4 v[166:167], off
	s_waitcnt vmcnt(12)
	s_barrier
	v_mfma_f32_16x16x32_bf16 v[28:31], v[212:215], v[180:183], v[28:31]
	v_mfma_f32_16x16x32_bf16 v[24:27], v[220:223], v[180:183], v[24:27]
	v_mfma_f32_16x16x32_bf16 v[20:23], v[212:215], v[188:191], v[20:23]
	v_mfma_f32_16x16x32_bf16 v[16:19], v[220:223], v[188:191], v[16:19]
	v_mfma_f32_16x16x32_bf16 v[12:15], v[212:215], v[196:199], v[12:15]
	v_mfma_f32_16x16x32_bf16 v[8:11], v[220:223], v[196:199], v[8:11]
	v_mfma_f32_16x16x32_bf16 v[4:7], v[212:215], v[204:207], v[4:7]
	v_mfma_f32_16x16x32_bf16 v[0:3], v[220:223], v[204:207], v[0:3]
	v_mfma_f32_16x16x32_bf16 v[28:31], v[216:219], v[184:187], v[28:31]
	v_mfma_f32_16x16x32_bf16 v[24:27], v[224:227], v[184:187], v[24:27]
	v_mfma_f32_16x16x32_bf16 v[20:23], v[216:219], v[192:195], v[20:23]
	v_mfma_f32_16x16x32_bf16 v[16:19], v[224:227], v[192:195], v[16:19]
	v_mfma_f32_16x16x32_bf16 v[12:15], v[216:219], v[200:203], v[12:15]
	v_mfma_f32_16x16x32_bf16 v[8:11], v[224:227], v[200:203], v[8:11]
	v_mfma_f32_16x16x32_bf16 v[4:7], v[216:219], v[208:211], v[4:7]
	v_mfma_f32_16x16x32_bf16 v[0:3], v[224:227], v[208:211], v[0:3]
	s_barrier
	ds_read_b128 v[164:167], v155
	ds_read_b128 v[168:171], v155 offset:1024
	ds_read_b128 v[172:175], v155 offset:2048
	ds_read_b128 v[176:179], v155 offset:3072
	ds_read_b128 v[180:183], v153 offset:32768
	ds_read_b128 v[184:187], v153 offset:33792
	ds_read_b128 v[188:191], v152 offset:32768
	ds_read_b128 v[192:195], v152 offset:33792
	ds_read_b128 v[196:199], v151 offset:32768
	ds_read_b128 v[200:203], v151 offset:33792
	ds_read_b128 v[204:207], v150 offset:32768
	ds_read_b128 v[208:211], v150 offset:33792
	s_waitcnt lgkmcnt(8)
	s_waitcnt vmcnt(10)
	s_barrier
	s_waitcnt lgkmcnt(0)
	s_waitcnt lgkmcnt(0)
	v_mfma_f32_16x16x32_bf16 v[124:127], v[164:167], v[180:183], v[124:127]
	v_mfma_f32_16x16x32_bf16 v[120:123], v[172:175], v[180:183], v[120:123]
	v_mfma_f32_16x16x32_bf16 v[116:119], v[164:167], v[188:191], v[116:119]
	v_mfma_f32_16x16x32_bf16 v[112:115], v[172:175], v[188:191], v[112:115]
	v_mfma_f32_16x16x32_bf16 v[108:111], v[164:167], v[196:199], v[108:111]
	v_mfma_f32_16x16x32_bf16 v[104:107], v[172:175], v[196:199], v[104:107]
	v_mfma_f32_16x16x32_bf16 v[100:103], v[164:167], v[204:207], v[100:103]
	v_mfma_f32_16x16x32_bf16 v[96:99], v[172:175], v[204:207], v[96:99]
	v_mfma_f32_16x16x32_bf16 v[124:127], v[168:171], v[184:187], v[124:127]
	v_mfma_f32_16x16x32_bf16 v[120:123], v[176:179], v[184:187], v[120:123]
	v_mfma_f32_16x16x32_bf16 v[116:119], v[168:171], v[192:195], v[116:119]
	v_mfma_f32_16x16x32_bf16 v[112:115], v[176:179], v[192:195], v[112:115]
	v_mfma_f32_16x16x32_bf16 v[108:111], v[168:171], v[200:203], v[108:111]
	v_mfma_f32_16x16x32_bf16 v[104:107], v[176:179], v[200:203], v[104:107]
	v_mfma_f32_16x16x32_bf16 v[100:103], v[168:171], v[208:211], v[100:103]
	v_mfma_f32_16x16x32_bf16 v[96:99], v[176:179], v[208:211], v[96:99]
	s_barrier
	s_add_i32 s36, s98, 0x18000
	v_lshl_add_u64 v[232:233], v[230:231], 0, s[30:31]
	s_mov_b32 m0, s36
	s_add_i32 s36, s98, 0x1a000
	ds_read_b128 v[212:215], v154
	ds_read_b128 v[216:219], v154 offset:1024
	ds_read_b128 v[220:223], v154 offset:2048
	ds_read_b128 v[224:227], v154 offset:3072
	global_load_lds_dwordx4 v[232:233], off
	v_lshl_add_u64 v[232:233], v[230:231], 0, s[34:35]
	s_mov_b32 m0, s36
	s_nop 0
	global_load_lds_dwordx4 v[232:233], off
	s_add_i32 s36, s98, 0x8000
	v_lshl_add_u64 v[232:233], v[228:229], 0, s[44:45]
	s_mov_b32 m0, s36
	s_add_i32 s36, s98, 0xa000
	global_load_lds_dwordx4 v[232:233], off
	v_lshl_add_u64 v[228:229], v[228:229], 0, s[46:47]
	s_mov_b32 m0, s36
	s_nop 0
	global_load_lds_dwordx4 v[228:229], off
	s_waitcnt vmcnt(12)
	s_barrier
	s_waitcnt lgkmcnt(0)
	s_waitcnt lgkmcnt(0)
	v_mfma_f32_16x16x32_bf16 v[92:95], v[212:215], v[180:183], v[92:95]
	v_mfma_f32_16x16x32_bf16 v[88:91], v[220:223], v[180:183], v[88:91]
	v_mfma_f32_16x16x32_bf16 v[84:87], v[212:215], v[188:191], v[84:87]
	v_mfma_f32_16x16x32_bf16 v[80:83], v[220:223], v[188:191], v[80:83]
	v_mfma_f32_16x16x32_bf16 v[76:79], v[212:215], v[196:199], v[76:79]
	v_mfma_f32_16x16x32_bf16 v[72:75], v[220:223], v[196:199], v[72:75]
	v_mfma_f32_16x16x32_bf16 v[68:71], v[212:215], v[204:207], v[68:71]
	v_mfma_f32_16x16x32_bf16 v[64:67], v[220:223], v[204:207], v[64:67]
	v_mfma_f32_16x16x32_bf16 v[92:95], v[216:219], v[184:187], v[92:95]
	v_mfma_f32_16x16x32_bf16 v[88:91], v[224:227], v[184:187], v[88:91]
	v_mfma_f32_16x16x32_bf16 v[84:87], v[216:219], v[192:195], v[84:87]
	v_mfma_f32_16x16x32_bf16 v[80:83], v[224:227], v[192:195], v[80:83]
	v_mfma_f32_16x16x32_bf16 v[76:79], v[216:219], v[200:203], v[76:79]
	v_mfma_f32_16x16x32_bf16 v[72:75], v[224:227], v[200:203], v[72:75]
	v_mfma_f32_16x16x32_bf16 v[68:71], v[216:219], v[208:211], v[68:71]
	v_mfma_f32_16x16x32_bf16 v[64:67], v[224:227], v[208:211], v[64:67]
	s_barrier
	ds_read_b128 v[180:183], v153 offset:49152
	ds_read_b128 v[184:187], v153 offset:50176
	ds_read_b128 v[188:191], v152 offset:49152
	ds_read_b128 v[192:195], v152 offset:50176
	ds_read_b128 v[196:199], v151 offset:49152
	ds_read_b128 v[200:203], v151 offset:50176
	ds_read_b128 v[204:207], v150 offset:49152
	ds_read_b128 v[208:211], v150 offset:50176
	s_add_i32 s36, s98, 0x1c000
	v_lshl_add_u64 v[232:233], v[230:231], 0, s[56:57]
	s_mov_b32 m0, s36
	s_add_i32 s36, s98, 0x1e000
	global_load_lds_dwordx4 v[232:233], off
	v_lshl_add_u64 v[232:233], v[230:231], 0, s[58:59]
	s_mov_b32 m0, s36
	s_nop 0
	global_load_lds_dwordx4 v[232:233], off
	s_barrier
	s_waitcnt lgkmcnt(0)
	s_waitcnt lgkmcnt(0)
	v_mfma_f32_16x16x32_bf16 v[60:63], v[164:167], v[180:183], v[60:63]
	v_mfma_f32_16x16x32_bf16 v[56:59], v[172:175], v[180:183], v[56:59]
	v_mfma_f32_16x16x32_bf16 v[52:55], v[164:167], v[188:191], v[52:55]
	v_mfma_f32_16x16x32_bf16 v[48:51], v[172:175], v[188:191], v[48:51]
	v_mfma_f32_16x16x32_bf16 v[44:47], v[164:167], v[196:199], v[44:47]
	v_mfma_f32_16x16x32_bf16 v[40:43], v[172:175], v[196:199], v[40:43]
	v_mfma_f32_16x16x32_bf16 v[36:39], v[164:167], v[204:207], v[36:39]
	v_mfma_f32_16x16x32_bf16 v[32:35], v[172:175], v[204:207], v[32:35]
	v_mfma_f32_16x16x32_bf16 v[60:63], v[168:171], v[184:187], v[60:63]
	v_mfma_f32_16x16x32_bf16 v[56:59], v[176:179], v[184:187], v[56:59]
	v_mfma_f32_16x16x32_bf16 v[52:55], v[168:171], v[192:195], v[52:55]
	v_mfma_f32_16x16x32_bf16 v[48:51], v[176:179], v[192:195], v[48:51]
	v_mfma_f32_16x16x32_bf16 v[44:47], v[168:171], v[200:203], v[44:47]
	v_mfma_f32_16x16x32_bf16 v[40:43], v[176:179], v[200:203], v[40:43]
	v_mfma_f32_16x16x32_bf16 v[36:39], v[168:171], v[208:211], v[36:39]
	v_mfma_f32_16x16x32_bf16 v[32:35], v[176:179], v[208:211], v[32:35]
	s_barrier
	v_lshl_add_u64 v[132:133], v[132:133], 0, s[60:61]
	v_lshl_add_u64 v[228:229], s[50:51], 0, v[132:133]
	s_mov_b64 s[68:69], 0xe080080
	s_add_i32 s36, s98, 0xc000
	v_lshl_add_u64 v[166:167], v[228:229], 0, s[68:69]
	s_mov_b32 m0, s36
	s_mov_b64 s[68:69], 0xe0c0080
	s_add_i32 s36, s98, 0xe000
	global_load_lds_dwordx4 v[166:167], off
	v_lshl_add_u64 v[166:167], v[228:229], 0, s[68:69]
	s_mov_b32 m0, s36
	s_nop 0
	global_load_lds_dwordx4 v[166:167], off
	s_waitcnt vmcnt(12)
	s_barrier
	v_mfma_f32_16x16x32_bf16 v[28:31], v[212:215], v[180:183], v[28:31]
	v_mfma_f32_16x16x32_bf16 v[24:27], v[220:223], v[180:183], v[24:27]
	v_mfma_f32_16x16x32_bf16 v[20:23], v[212:215], v[188:191], v[20:23]
	v_mfma_f32_16x16x32_bf16 v[16:19], v[220:223], v[188:191], v[16:19]
	v_mfma_f32_16x16x32_bf16 v[12:15], v[212:215], v[196:199], v[12:15]
	v_mfma_f32_16x16x32_bf16 v[8:11], v[220:223], v[196:199], v[8:11]
	v_mfma_f32_16x16x32_bf16 v[4:7], v[212:215], v[204:207], v[4:7]
	v_mfma_f32_16x16x32_bf16 v[0:3], v[220:223], v[204:207], v[0:3]
	v_mfma_f32_16x16x32_bf16 v[28:31], v[216:219], v[184:187], v[28:31]
	v_mfma_f32_16x16x32_bf16 v[24:27], v[224:227], v[184:187], v[24:27]
	v_mfma_f32_16x16x32_bf16 v[20:23], v[216:219], v[192:195], v[20:23]
	v_mfma_f32_16x16x32_bf16 v[16:19], v[224:227], v[192:195], v[16:19]
	v_mfma_f32_16x16x32_bf16 v[12:15], v[216:219], v[200:203], v[12:15]
	v_mfma_f32_16x16x32_bf16 v[8:11], v[224:227], v[200:203], v[8:11]
	v_mfma_f32_16x16x32_bf16 v[4:7], v[216:219], v[208:211], v[4:7]
	v_mfma_f32_16x16x32_bf16 v[0:3], v[224:227], v[208:211], v[0:3]
	s_add_i32 s24, s24, 2
	v_lshl_add_u64 v[130:131], v[130:131], 0, s[10:11]
	s_cmp_lt_u32 s24, 28
	s_barrier
	s_cbranch_scc1 .LBB0_465
	s_lshl_b32 s24, s86, 5
	s_lshl_b32 s36, s86, 8
	s_and_b32 s24, s24, 0x1800
	s_and_b32 s36, s36, 0x700
	s_or_b32 s24, s36, s24
	v_lshlrev_b32_e32 v128, 3, v156
	v_lshlrev_b32_e32 v130, 5, v156
	v_and_b32_e32 v128, 0xffff0, v128
	v_and_b32_e32 v130, 32, v130
	s_lshl_b32 s36, s24, 12
	v_add_u32_e32 v130, v130, v158
	v_add_lshl_u32 v128, v157, v128, 12
	s_add_u32 s68, s70, s36
	v_lshl_add_u32 v128, v130, 1, v128
	s_addc_u32 s69, s71, 0
	v_lshl_add_u64 v[156:157], s[68:69], 0, v[128:129]
	v_readfirstlane_b32 s36, v161
	ds_read_b128 v[130:133], v162
	ds_read_b128 v[164:167], v162 offset:1024
	ds_read_b128 v[168:171], v162 offset:2048
	ds_read_b128 v[172:175], v162 offset:3072
	ds_read_b128 v[176:179], v153
	ds_read_b128 v[180:183], v153 offset:1024
	ds_read_b128 v[184:187], v152
	ds_read_b128 v[188:191], v152 offset:1024
	ds_read_b128 v[192:195], v151
	ds_read_b128 v[196:199], v151 offset:1024
	ds_read_b128 v[200:203], v150
	ds_read_b128 v[204:207], v150 offset:1024
	v_lshl_add_u64 v[162:163], v[156:157], 0, s[62:63]
	s_mov_b32 m0, s36
	v_readfirstlane_b32 s36, v160
	global_load_lds_dwordx4 v[162:163], off
	v_lshl_add_u64 v[156:157], v[156:157], 0, s[64:65]
	s_mov_b32 m0, s36
	s_nop 0
	global_load_lds_dwordx4 v[156:157], off
	s_waitcnt vmcnt(10)
	s_barrier
	s_waitcnt lgkmcnt(0)
	s_setprio 1
	s_waitcnt lgkmcnt(0)
	v_mfma_f32_16x16x32_bf16 v[124:127], v[130:133], v[176:179], v[124:127]
	v_mfma_f32_16x16x32_bf16 v[120:123], v[168:171], v[176:179], v[120:123]
	v_mfma_f32_16x16x32_bf16 v[116:119], v[130:133], v[184:187], v[116:119]
	v_mfma_f32_16x16x32_bf16 v[112:115], v[168:171], v[184:187], v[112:115]
	v_mfma_f32_16x16x32_bf16 v[108:111], v[130:133], v[192:195], v[108:111]
	v_mfma_f32_16x16x32_bf16 v[104:107], v[168:171], v[192:195], v[104:107]
	v_mfma_f32_16x16x32_bf16 v[100:103], v[130:133], v[200:203], v[100:103]
	v_mfma_f32_16x16x32_bf16 v[96:99], v[168:171], v[200:203], v[96:99]
	v_mfma_f32_16x16x32_bf16 v[124:127], v[164:167], v[180:183], v[124:127]
	v_mfma_f32_16x16x32_bf16 v[120:123], v[172:175], v[180:183], v[120:123]
	v_mfma_f32_16x16x32_bf16 v[116:119], v[164:167], v[188:191], v[116:119]
	v_mfma_f32_16x16x32_bf16 v[112:115], v[172:175], v[188:191], v[112:115]
	v_mfma_f32_16x16x32_bf16 v[108:111], v[164:167], v[196:199], v[108:111]
	v_mfma_f32_16x16x32_bf16 v[104:107], v[172:175], v[196:199], v[104:107]
	v_mfma_f32_16x16x32_bf16 v[100:103], v[164:167], v[204:207], v[100:103]
	v_mfma_f32_16x16x32_bf16 v[96:99], v[172:175], v[204:207], v[96:99]
	s_setprio 0
	s_barrier
	ds_read_b128 v[160:163], v159
	ds_read_b128 v[208:211], v159 offset:1024
	ds_read_b128 v[212:215], v159 offset:2048
	ds_read_b128 v[156:159], v159 offset:3072
	s_barrier
	s_waitcnt lgkmcnt(0)
	s_setprio 1
	s_waitcnt lgkmcnt(0)
	v_mfma_f32_16x16x32_bf16 v[92:95], v[160:163], v[176:179], v[92:95]
	v_mfma_f32_16x16x32_bf16 v[88:91], v[212:215], v[176:179], v[88:91]
	v_mfma_f32_16x16x32_bf16 v[84:87], v[160:163], v[184:187], v[84:87]
	v_mfma_f32_16x16x32_bf16 v[80:83], v[212:215], v[184:187], v[80:83]
	v_mfma_f32_16x16x32_bf16 v[76:79], v[160:163], v[192:195], v[76:79]
	v_mfma_f32_16x16x32_bf16 v[72:75], v[212:215], v[192:195], v[72:75]
	v_mfma_f32_16x16x32_bf16 v[68:71], v[160:163], v[200:203], v[68:71]
	v_mfma_f32_16x16x32_bf16 v[64:67], v[212:215], v[200:203], v[64:67]
	v_mfma_f32_16x16x32_bf16 v[176:179], v[208:211], v[180:183], v[92:95]
	v_mfma_f32_16x16x32_bf16 v[180:183], v[156:159], v[180:183], v[88:91]
	v_mfma_f32_16x16x32_bf16 v[184:187], v[208:211], v[188:191], v[84:87]
	v_mfma_f32_16x16x32_bf16 v[188:191], v[156:159], v[188:191], v[80:83]
	v_mfma_f32_16x16x32_bf16 v[192:195], v[208:211], v[196:199], v[76:79]
	v_mfma_f32_16x16x32_bf16 v[196:199], v[156:159], v[196:199], v[72:75]
	v_mfma_f32_16x16x32_bf16 v[200:203], v[208:211], v[204:207], v[68:71]
	v_mfma_f32_16x16x32_bf16 v[204:207], v[156:159], v[204:207], v[64:67]
	s_setprio 0
	s_barrier
	s_nop 0
	ds_read_b128 v[64:67], v153 offset:16384
	ds_read_b128 v[68:71], v153 offset:17408
	ds_read_b128 v[72:75], v152 offset:16384
	ds_read_b128 v[76:79], v152 offset:17408
	ds_read_b128 v[80:83], v151 offset:16384
	ds_read_b128 v[84:87], v151 offset:17408
	ds_read_b128 v[88:91], v150 offset:16384
	ds_read_b128 v[92:95], v150 offset:17408
	s_waitcnt vmcnt(4)
	s_barrier
	s_waitcnt lgkmcnt(0)
	s_setprio 1
	s_waitcnt lgkmcnt(0)
	v_mfma_f32_16x16x32_bf16 v[60:63], v[130:133], v[64:67], v[60:63]
	v_mfma_f32_16x16x32_bf16 v[56:59], v[168:171], v[64:67], v[56:59]
	v_mfma_f32_16x16x32_bf16 v[52:55], v[130:133], v[72:75], v[52:55]
	v_mfma_f32_16x16x32_bf16 v[48:51], v[168:171], v[72:75], v[48:51]
	v_mfma_f32_16x16x32_bf16 v[216:219], v[130:133], v[80:83], v[44:47]
	v_mfma_f32_16x16x32_bf16 v[220:223], v[168:171], v[80:83], v[40:43]
	v_mfma_f32_16x16x32_bf16 v[130:133], v[130:133], v[88:91], v[36:39]
	v_mfma_f32_16x16x32_bf16 v[168:171], v[168:171], v[88:91], v[32:35]
	v_mfma_f32_16x16x32_bf16 v[32:35], v[164:167], v[68:71], v[60:63]
	v_mfma_f32_16x16x32_bf16 v[36:39], v[172:175], v[68:71], v[56:59]
	v_mfma_f32_16x16x32_bf16 v[40:43], v[164:167], v[76:79], v[52:55]
	v_mfma_f32_16x16x32_bf16 v[44:47], v[172:175], v[76:79], v[48:51]
	v_mfma_f32_16x16x32_bf16 v[48:51], v[164:167], v[84:87], v[216:219]
	v_mfma_f32_16x16x32_bf16 v[52:55], v[172:175], v[84:87], v[220:223]
	v_mfma_f32_16x16x32_bf16 v[56:59], v[164:167], v[92:95], v[130:133]
	v_mfma_f32_16x16x32_bf16 v[60:63], v[172:175], v[92:95], v[168:171]
	s_setprio 0
	s_setprio 1
	v_mfma_f32_16x16x32_bf16 v[28:31], v[160:163], v[64:67], v[28:31]
	v_mfma_f32_16x16x32_bf16 v[24:27], v[212:215], v[64:67], v[24:27]
	v_mfma_f32_16x16x32_bf16 v[20:23], v[160:163], v[72:75], v[20:23]
	v_mfma_f32_16x16x32_bf16 v[64:67], v[212:215], v[72:75], v[16:19]
	v_mfma_f32_16x16x32_bf16 v[72:75], v[160:163], v[80:83], v[12:15]
	v_mfma_f32_16x16x32_bf16 v[8:11], v[212:215], v[80:83], v[8:11]
	v_mfma_f32_16x16x32_bf16 v[80:83], v[160:163], v[88:91], v[4:7]
	v_mfma_f32_16x16x32_bf16 v[0:3], v[212:215], v[88:91], v[0:3]
	v_mfma_f32_16x16x32_bf16 v[4:7], v[208:211], v[68:71], v[28:31]
	v_mfma_f32_16x16x32_bf16 v[12:15], v[156:159], v[68:71], v[24:27]
	v_mfma_f32_16x16x32_bf16 v[16:19], v[208:211], v[76:79], v[20:23]
	v_mfma_f32_16x16x32_bf16 v[20:23], v[156:159], v[76:79], v[64:67]
	v_mfma_f32_16x16x32_bf16 v[24:27], v[208:211], v[84:87], v[72:75]
	v_mfma_f32_16x16x32_bf16 v[28:31], v[156:159], v[84:87], v[8:11]
	v_mfma_f32_16x16x32_bf16 v[64:67], v[208:211], v[92:95], v[80:83]
	v_mfma_f32_16x16x32_bf16 v[68:71], v[156:159], v[92:95], v[0:3]
	s_setprio 0
	s_barrier
	ds_read_b128 v[8:11], v155
	ds_read_b128 v[0:3], v155 offset:1024
	ds_read_b128 v[76:79], v155 offset:2048
	ds_read_b128 v[72:75], v155 offset:3072
	ds_read_b128 v[130:133], v153 offset:32768
	ds_read_b128 v[156:159], v153 offset:33792
	ds_read_b128 v[160:163], v152 offset:32768
	ds_read_b128 v[164:167], v152 offset:33792
	ds_read_b128 v[168:171], v151 offset:32768
	ds_read_b128 v[172:175], v151 offset:33792
	ds_read_b128 v[208:211], v150 offset:32768
	ds_read_b128 v[212:215], v150 offset:33792
	s_waitcnt vmcnt(2)
	s_barrier
	s_waitcnt lgkmcnt(0)
	s_setprio 1
	s_waitcnt lgkmcnt(0)
	v_mfma_f32_16x16x32_bf16 v[80:83], v[8:11], v[130:133], v[124:127]
	v_mfma_f32_16x16x32_bf16 v[84:87], v[76:79], v[130:133], v[120:123]
	v_mfma_f32_16x16x32_bf16 v[88:91], v[8:11], v[160:163], v[116:119]
	v_mfma_f32_16x16x32_bf16 v[92:95], v[76:79], v[160:163], v[112:115]
	v_mfma_f32_16x16x32_bf16 v[108:111], v[8:11], v[168:171], v[108:111]
	v_mfma_f32_16x16x32_bf16 v[104:107], v[76:79], v[168:171], v[104:107]
	v_mfma_f32_16x16x32_bf16 v[100:103], v[8:11], v[208:211], v[100:103]
	v_mfma_f32_16x16x32_bf16 v[96:99], v[76:79], v[208:211], v[96:99]
	v_mfma_f32_16x16x32_bf16 v[112:115], v[0:3], v[156:159], v[80:83]
	v_mfma_f32_16x16x32_bf16 v[116:119], v[72:75], v[156:159], v[84:87]
	v_mfma_f32_16x16x32_bf16 v[120:123], v[0:3], v[164:167], v[88:91]
	v_mfma_f32_16x16x32_bf16 v[124:127], v[72:75], v[164:167], v[92:95]
	v_mfma_f32_16x16x32_bf16 v[108:111], v[0:3], v[172:175], v[108:111]
	v_mfma_f32_16x16x32_bf16 v[104:107], v[72:75], v[172:175], v[104:107]
	v_mfma_f32_16x16x32_bf16 v[100:103], v[0:3], v[212:215], v[100:103]
	v_mfma_f32_16x16x32_bf16 v[96:99], v[72:75], v[212:215], v[96:99]
	s_setprio 0
	s_barrier
	ds_read_b128 v[88:91], v154
	ds_read_b128 v[80:83], v154 offset:1024
	ds_read_b128 v[92:95], v154 offset:2048
	ds_read_b128 v[84:87], v154 offset:3072
	s_waitcnt vmcnt(0)
	s_barrier
	s_waitcnt lgkmcnt(0)
	s_setprio 1
	s_waitcnt lgkmcnt(0)
	v_mfma_f32_16x16x32_bf16 v[176:179], v[88:91], v[130:133], v[176:179]
	v_mfma_f32_16x16x32_bf16 v[130:133], v[92:95], v[130:133], v[180:183]
	v_mfma_f32_16x16x32_bf16 v[180:183], v[88:91], v[160:163], v[184:187]
	v_mfma_f32_16x16x32_bf16 v[160:163], v[92:95], v[160:163], v[188:191]
	v_mfma_f32_16x16x32_bf16 v[184:187], v[88:91], v[168:171], v[192:195]
	v_mfma_f32_16x16x32_bf16 v[168:171], v[92:95], v[168:171], v[196:199]
	v_mfma_f32_16x16x32_bf16 v[188:191], v[88:91], v[208:211], v[200:203]
	v_mfma_f32_16x16x32_bf16 v[192:195], v[92:95], v[208:211], v[204:207]
	v_mfma_f32_16x16x32_bf16 v[176:179], v[80:83], v[156:159], v[176:179]
	v_mfma_f32_16x16x32_bf16 v[130:133], v[84:87], v[156:159], v[130:133]
	v_mfma_f32_16x16x32_bf16 v[154:157], v[80:83], v[164:167], v[180:183]
	v_mfma_f32_16x16x32_bf16 v[158:161], v[84:87], v[164:167], v[160:163]
	v_mfma_f32_16x16x32_bf16 v[162:165], v[80:83], v[172:175], v[184:187]
	v_mfma_f32_16x16x32_bf16 v[166:169], v[84:87], v[172:175], v[168:171]
	v_mfma_f32_16x16x32_bf16 v[170:173], v[80:83], v[212:215], v[188:191]
	v_mfma_f32_16x16x32_bf16 v[180:183], v[84:87], v[212:215], v[192:195]
	s_setprio 0
	s_barrier
	v_mbcnt_lo_u32_b32 v128, -1, 0
	v_mbcnt_hi_u32_b32 v128, -1, v128
	v_cvt_pk_bf16_f32 v112, v112, v113
	v_cvt_pk_bf16_f32 v113, v114, v115
	v_cvt_pk_bf16_f32 v114, v116, v117
	v_cvt_pk_bf16_f32 v115, v118, v119
	s_lshl_b32 s68, s66, 9
	v_add_u32_e32 v174, s74, v128
	v_ashrrev_i32_e32 v175, 6, v174
	v_and_b32_e32 v184, 15, v128
	v_and_b32_e32 v185, 48, v128
	v_mul_lo_u32 v186, v175, s79
	v_bfe_u32 v187, v128, 3, 3
	v_lshlrev_b32_e32 v128, 4, v128
	v_add_u32_e32 v186, 0x20000, v186
	v_lshrrev_b32_e32 v174, 2, v174
	v_and_b32_e32 v128, 0x70, v128
	v_mul_u32_u24_e32 v184, 0x90, v184
	v_and_b32_e32 v174, 64, v174
	v_add3_u32 v184, v186, v184, v185
	v_or_b32_e32 v185, v186, v128
	v_or3_b32 v174, s24, v174, v187
	v_mad_u32_u24 v185, v187, s80, v185
	ds_write_b128 v184, v[112:115]
	v_cvt_pk_bf16_f32 v112, v176, v177
	v_cvt_pk_bf16_f32 v113, v178, v179
	v_cvt_pk_bf16_f32 v114, v130, v131
	v_cvt_pk_bf16_f32 v115, v132, v133
	ds_write_b128 v184, v[112:115] offset:64
	v_lshlrev_b32_e32 v175, 7, v175
	ds_read_b128 v[112:115], v185
	v_lshlrev_b32_e32 v116, 12, v174
	v_and_or_b32 v116, v175, s81, v116
	v_or3_b32 v128, v116, s68, v128
	ds_read_b128 v[116:119], v185 offset:1152
	v_lshl_add_u64 v[130:131], s[0:1], 0, v[128:129]
	s_mov_b32 s36, 0x8000
	s_waitcnt lgkmcnt(0)
	global_store_dwordx4 v128, v[112:115], s[0:1]
	v_cvt_pk_bf16_f32 v108, v108, v109
	v_cvt_pk_bf16_f32 v109, v110, v111
	v_cvt_pk_bf16_f32 v110, v104, v105
	v_cvt_pk_bf16_f32 v111, v106, v107
	v_cvt_pk_bf16_f32 v104, v162, v163
	s_nop 1
	v_add_co_u32_e32 v112, vcc, s36, v130
	v_cvt_pk_bf16_f32 v114, v124, v125
	v_cvt_pk_bf16_f32 v115, v126, v127
	v_cvt_pk_bf16_f32 v105, v164, v165
	v_cvt_pk_bf16_f32 v106, v166, v167
	s_nop 1
	v_addc_co_u32_e32 v113, vcc, 0, v131, vcc
	global_store_dwordx4 v[112:113], v[116:119], off
	v_cvt_pk_bf16_f32 v112, v120, v121
	v_cvt_pk_bf16_f32 v113, v122, v123
	ds_write_b128 v184, v[112:115]
	v_cvt_pk_bf16_f32 v112, v154, v155
	v_cvt_pk_bf16_f32 v113, v156, v157
	v_cvt_pk_bf16_f32 v114, v158, v159
	v_cvt_pk_bf16_f32 v115, v160, v161
	ds_write_b128 v184, v[112:115] offset:64
	ds_read_b128 v[112:115], v185
	ds_read_b128 v[116:119], v185 offset:1152
	v_add_co_u32_e32 v120, vcc, s76, v130
	ds_write_b128 v184, v[108:111]
	v_cvt_pk_bf16_f32 v107, v168, v169
	ds_write_b128 v184, v[104:107] offset:64
	v_addc_co_u32_e32 v121, vcc, 0, v131, vcc
	ds_read_b128 v[104:107], v185
	ds_read_b128 v[108:111], v185 offset:1152
	s_waitcnt lgkmcnt(0)
	global_store_dwordx4 v[120:121], v[112:115], off
	v_cvt_pk_bf16_f32 v100, v100, v101
	v_cvt_pk_bf16_f32 v101, v102, v103
	v_cvt_pk_bf16_f32 v102, v96, v97
	v_cvt_pk_bf16_f32 v103, v98, v99
	ds_write_b128 v184, v[100:103]
	s_nop 0
	v_add_co_u32_e32 v112, vcc, s77, v130
	v_cvt_pk_bf16_f32 v96, v170, v171
	v_cvt_pk_bf16_f32 v97, v172, v173
	v_cvt_pk_bf16_f32 v98, v180, v181
	v_cvt_pk_bf16_f32 v99, v182, v183
	s_nop 1
	v_addc_co_u32_e32 v113, vcc, 0, v131, vcc
	global_store_dwordx4 v[112:113], v[116:119], off
	v_add_co_u32_e32 v112, vcc, s78, v130
	ds_write_b128 v184, v[96:99] offset:64
	s_nop 0
	v_addc_co_u32_e32 v113, vcc, 0, v131, vcc
	ds_read_b128 v[96:99], v185
	ds_read_b128 v[100:103], v185 offset:1152
	global_store_dwordx4 v[112:113], v[104:107], off
	s_nop 1
	v_add_co_u32_e32 v104, vcc, s82, v130
	s_nop 1
	v_addc_co_u32_e32 v105, vcc, 0, v131, vcc
	global_store_dwordx4 v[104:105], v[108:111], off
	v_add_co_u32_e32 v104, vcc, s83, v130
	s_nop 1
	v_addc_co_u32_e32 v105, vcc, 0, v131, vcc
	s_waitcnt lgkmcnt(0)
	global_store_dwordx4 v[104:105], v[96:99], off
	s_nop 1
	v_add_co_u32_e32 v96, vcc, s91, v130
	s_nop 1
	v_addc_co_u32_e32 v97, vcc, 0, v131, vcc
	global_store_dwordx4 v[96:97], v[100:103], off
	ds_read_b128 v[96:99], v153 offset:49152
	ds_read_b128 v[100:103], v153 offset:50176
	ds_read_b128 v[104:107], v152 offset:49152
	ds_read_b128 v[108:111], v152 offset:50176
	ds_read_b128 v[112:115], v151 offset:49152
	ds_read_b128 v[116:119], v151 offset:50176
	ds_read_b128 v[120:123], v150 offset:49152
	ds_read_b128 v[124:127], v150 offset:50176
	s_barrier
	s_waitcnt lgkmcnt(0)
	s_setprio 1
	s_waitcnt lgkmcnt(0)
	v_mfma_f32_16x16x32_bf16 v[32:35], v[8:11], v[96:99], v[32:35]
	v_mfma_f32_16x16x32_bf16 v[36:39], v[76:79], v[96:99], v[36:39]
	v_mfma_f32_16x16x32_bf16 v[40:43], v[8:11], v[104:107], v[40:43]
	v_mfma_f32_16x16x32_bf16 v[130:133], v[76:79], v[104:107], v[44:47]
	v_mfma_f32_16x16x32_bf16 v[150:153], v[8:11], v[112:115], v[48:51]
	v_mfma_f32_16x16x32_bf16 v[52:55], v[76:79], v[112:115], v[52:55]
	v_mfma_f32_16x16x32_bf16 v[8:11], v[8:11], v[120:123], v[56:59]
	v_mfma_f32_16x16x32_bf16 v[60:63], v[76:79], v[120:123], v[60:63]
	v_mfma_f32_16x16x32_bf16 v[56:59], v[0:3], v[100:103], v[32:35]
	v_mfma_f32_16x16x32_bf16 v[48:51], v[72:75], v[100:103], v[36:39]
	v_mfma_f32_16x16x32_bf16 v[44:47], v[0:3], v[108:111], v[40:43]
	v_mfma_f32_16x16x32_bf16 v[40:43], v[72:75], v[108:111], v[130:133]
	v_mfma_f32_16x16x32_bf16 v[36:39], v[0:3], v[116:119], v[150:153]
	v_mfma_f32_16x16x32_bf16 v[32:35], v[72:75], v[116:119], v[52:55]
	v_mfma_f32_16x16x32_bf16 v[8:11], v[0:3], v[124:127], v[8:11]
	v_mfma_f32_16x16x32_bf16 v[0:3], v[72:75], v[124:127], v[60:63]
	s_setprio 0
	s_setprio 1
	v_mfma_f32_16x16x32_bf16 v[4:7], v[88:91], v[96:99], v[4:7]
	v_mfma_f32_16x16x32_bf16 v[12:15], v[92:95], v[96:99], v[12:15]
	v_mfma_f32_16x16x32_bf16 v[16:19], v[88:91], v[104:107], v[16:19]
	v_mfma_f32_16x16x32_bf16 v[20:23], v[92:95], v[104:107], v[20:23]
	v_mfma_f32_16x16x32_bf16 v[72:75], v[88:91], v[112:115], v[24:27]
	v_mfma_f32_16x16x32_bf16 v[76:79], v[92:95], v[112:115], v[28:31]
	v_mfma_f32_16x16x32_bf16 v[64:67], v[88:91], v[120:123], v[64:67]
	v_mfma_f32_16x16x32_bf16 v[68:71], v[92:95], v[120:123], v[68:71]
	v_mfma_f32_16x16x32_bf16 v[60:63], v[80:83], v[100:103], v[4:7]
	v_mfma_f32_16x16x32_bf16 v[52:55], v[84:87], v[100:103], v[12:15]
	v_mfma_f32_16x16x32_bf16 v[28:31], v[80:83], v[108:111], v[16:19]
	v_mfma_f32_16x16x32_bf16 v[24:27], v[84:87], v[108:111], v[20:23]
	v_mfma_f32_16x16x32_bf16 v[20:23], v[80:83], v[116:119], v[72:75]
	v_mfma_f32_16x16x32_bf16 v[16:19], v[84:87], v[116:119], v[76:79]
	v_mfma_f32_16x16x32_bf16 v[12:15], v[80:83], v[124:127], v[64:67]
	v_mfma_f32_16x16x32_bf16 v[4:7], v[84:87], v[124:127], v[68:71]
	s_setprio 0
	v_cmp_gt_u32_e32 vcc, s92, v136
	s_barrier
	s_and_saveexec_b64 s[66:67], vcc
	s_cbranch_execz .LBB0_468
	s_barrier

.LBB0_520:
	v_bfe_i32 v5, v179, 27, 1
	v_lshlrev_b32_e32 v169, 4, v179
	v_lshrrev_b32_e32 v5, 22, v5
	v_add_u32_e32 v5, v169, v5
	v_and_b32_e32 v5, 0xfffffc00, v5
	v_sub_u32_e32 v5, v169, v5
	v_lshrrev_b32_e32 v6, 4, v5
	v_bitop3_b32 v5, v6, v5, 32 bitop3:0x6c
	v_ashrrev_i32_e32 v6, 31, v5
	v_lshrrev_b32_e32 v6, 26, v6
	v_ashrrev_i32_e32 v4, 31, v179
	v_add_u32_e32 v6, v5, v6
	s_lshl_b32 s36, s81, 3
	v_lshrrev_b32_e32 v4, 26, v4
	v_ashrrev_i32_e32 v133, 6, v6
	v_and_b32_e32 v6, 0xc0, v6
	s_ff1_i32_b32 s37, s36
	v_and_b32_e32 v2, 15, v0
	v_and_b32_e32 v3, 48, v0
	v_add_u32_e32 v4, v179, v4
	v_sub_u32_e32 v5, v5, v6
	v_and_b32_e32 v6, 32, v0
	v_lshlrev_b32_e32 v10, 2, v0
	v_lshlrev_b32_e32 v0, 6, v0
	s_lshr_b32 s60, s82, s37
	s_add_i32 s36, s36, -1
	s_and_b32 s61, s82, 7
	v_ashrrev_i32_e32 v131, 6, v4
	v_lshlrev_b32_e32 v2, 6, v2
	v_and_b32_e32 v10, 32, v10
	v_and_b32_e32 v0, 0x3c0, v0
	s_and_b32 s36, s82, s36
	v_or_b32_e32 v9, v2, v3
	v_bitop3_b32 v2, v2, v10, v3 bitop3:0x36
	v_bitop3_b32 v3, v0, v10, v3 bitop3:0x36
	s_lshl_b32 s37, s60, 11
	s_lshl_b32 s46, s61, 8
	v_lshlrev_b32_e32 v0, 16, v131
	s_lshr_b32 s78, s36, 3
	s_or_b32 s46, s37, s46
	s_mov_b32 s47, s15
	v_and_b32_e32 v0, 0xfffe0000, v0
	s_lshl_b32 s36, s78, 14
	v_ashrrev_i16_sdwa v5, v167, sext(v5) dst_sel:DWORD dst_unused:UNUSED_PAD src0_sel:DWORD src1_sel:BYTE_0
	s_lshl_b64 s[46:47], s[46:47], 13
	v_lshl_add_u32 v0, v133, 13, v0
	v_bfe_i32 v134, v5, 0, 16
	v_and_or_b32 v0, v4, 64, v0
	s_add_u32 s46, s40, s46
	v_lshl_add_u32 v164, v134, 1, v0
	s_addc_u32 s47, s41, s47
	v_lshlrev_b32_e32 v14, 13, v1
	v_lshl_add_u64 v[0:1], s[46:47], 0, v[164:165]
	s_mul_i32 s46, s14, 0x1800
	s_mul_hi_u32 s37, s14, 0x1800
	s_add_u32 s46, s46, s36
	s_addc_u32 s37, s37, 0
	s_add_u32 s46, s62, s46
	v_bfe_i32 v7, v179, 6, 1
	s_addc_u32 s47, s63, s37
	s_lshl_b64 s[56:57], s[14:15], 12
	v_and_b32_e32 v7, s14, v7
	v_lshrrev_b32_e32 v8, 7, v179
	s_add_u32 s14, s56, s36
	v_add_lshl_u32 v7, v7, v8, 10
	v_lshlrev_b32_e32 v8, 6, v179
	s_addc_u32 s36, s57, 0
	v_and_b32_e32 v5, 0x3f0, v169
	v_and_b32_e32 v8, 0x3000, v8
	v_bitop3_b32 v11, v9, s65, v10 bitop3:0xde
	v_bitop3_b32 v12, v9, s67, v10 bitop3:0xde
	v_bitop3_b32 v13, v9, s68, v10 bitop3:0xde
	v_bitop3_b32 v9, v9, s69, v10 bitop3:0xde
	v_or_b32_e32 v10, 0x800, v14
	v_or_b32_e32 v15, 0x1000, v14
	v_or_b32_e32 v16, 0x1800, v14
	v_lshl_add_u64 v[128:129], v[0:1], 0, s[16:17]
	s_add_u32 s58, s62, s14
	v_mov_b32_e32 v0, 0
	v_bitop3_b32 v164, v5, v7, v6 bitop3:0xde
	s_addc_u32 s59, s63, s36
	s_mov_b32 s14, -2
	v_add_u32_e32 v138, v11, v8
	v_add_u32_e32 v193, v2, v14
	v_add_u32_e32 v192, v3, v10
	v_add_u32_e32 v191, v3, v15
	v_add_u32_e32 v190, v3, v16
	v_add_u32_e32 v137, 0xc000, v169
	v_add_u32_e32 v136, 0xe000, v169
	v_add_u32_e32 v135, v12, v8
	v_add_u32_e32 v189, 0x10000, v169
	v_add_u32_e32 v188, 0x12000, v169
	v_add_u32_e32 v187, 0x2000, v169
	v_add_u32_e32 v186, 0x14000, v169
	v_add_u32_e32 v185, 0x16000, v169
	v_add_u32_e32 v130, v13, v8
	v_add_u32_e32 v184, 0x4000, v169
	v_add_u32_e32 v183, 0x6000, v169
	v_add_u32_e32 v132, v9, v8
	v_add_u32_e32 v182, 0x18000, v169
	v_add_u32_e32 v181, 0x1a000, v169
	v_add_u32_e32 v177, 0x8000, v169
	v_add_u32_e32 v175, 0xa000, v169
	v_add_u32_e32 v173, 0x1c000, v169
	v_add_u32_e32 v171, 0x1e000, v169
	v_mov_b32_e32 v1, v0
	v_mov_b32_e32 v2, v0
	v_mov_b32_e32 v3, v0
	v_mov_b32_e32 v4, v0
	v_mov_b32_e32 v5, v0
	v_mov_b32_e32 v6, v0
	v_mov_b32_e32 v7, v0
	v_mov_b32_e32 v8, v0
	v_mov_b32_e32 v9, v0
	v_mov_b32_e32 v10, v0
	v_mov_b32_e32 v11, v0
	v_mov_b32_e32 v12, v0
	v_mov_b32_e32 v13, v0
	v_mov_b32_e32 v14, v0
	v_mov_b32_e32 v15, v0
	v_mov_b32_e32 v16, v0
	v_mov_b32_e32 v17, v0
	v_mov_b32_e32 v18, v0
	v_mov_b32_e32 v19, v0
	v_mov_b32_e32 v20, v0
	v_mov_b32_e32 v21, v0
	v_mov_b32_e32 v22, v0
	v_mov_b32_e32 v23, v0
	v_mov_b32_e32 v24, v0
	v_mov_b32_e32 v25, v0
	v_mov_b32_e32 v26, v0
	v_mov_b32_e32 v27, v0
	v_mov_b32_e32 v28, v0
	v_mov_b32_e32 v29, v0
	v_mov_b32_e32 v30, v0
	v_mov_b32_e32 v31, v0
	v_mov_b32_e32 v32, v0
	v_mov_b32_e32 v33, v0
	v_mov_b32_e32 v34, v0
	v_mov_b32_e32 v35, v0
	v_mov_b32_e32 v36, v0
	v_mov_b32_e32 v37, v0
	v_mov_b32_e32 v38, v0
	v_mov_b32_e32 v39, v0
	v_mov_b32_e32 v40, v0
	v_mov_b32_e32 v41, v0
	v_mov_b32_e32 v42, v0
	v_mov_b32_e32 v43, v0
	v_mov_b32_e32 v44, v0
	v_mov_b32_e32 v45, v0
	v_mov_b32_e32 v46, v0
	v_mov_b32_e32 v47, v0
	v_mov_b32_e32 v48, v0
	v_mov_b32_e32 v49, v0
	v_mov_b32_e32 v50, v0
	v_mov_b32_e32 v51, v0
	v_mov_b32_e32 v52, v0
	v_mov_b32_e32 v53, v0
	v_mov_b32_e32 v54, v0
	v_mov_b32_e32 v55, v0
	v_mov_b32_e32 v56, v0
	v_mov_b32_e32 v57, v0
	v_mov_b32_e32 v58, v0
	v_mov_b32_e32 v59, v0
	v_mov_b32_e32 v60, v0
	v_mov_b32_e32 v61, v0
	v_mov_b32_e32 v62, v0
	v_mov_b32_e32 v63, v0
	v_mov_b32_e32 v64, v0
	v_mov_b32_e32 v65, v0
	v_mov_b32_e32 v66, v0
	v_mov_b32_e32 v67, v0
	v_mov_b32_e32 v68, v0
	v_mov_b32_e32 v69, v0
	v_mov_b32_e32 v70, v0
	v_mov_b32_e32 v71, v0
	v_mov_b32_e32 v72, v0
	v_mov_b32_e32 v73, v0
	v_mov_b32_e32 v74, v0
	v_mov_b32_e32 v75, v0
	v_mov_b32_e32 v76, v0
	v_mov_b32_e32 v77, v0
	v_mov_b32_e32 v78, v0
	v_mov_b32_e32 v79, v0
	v_mov_b32_e32 v80, v0
	v_mov_b32_e32 v81, v0
	v_mov_b32_e32 v82, v0
	v_mov_b32_e32 v83, v0
	v_mov_b32_e32 v84, v0
	v_mov_b32_e32 v85, v0
	v_mov_b32_e32 v86, v0
	v_mov_b32_e32 v87, v0
	v_mov_b32_e32 v88, v0
	v_mov_b32_e32 v89, v0
	v_mov_b32_e32 v90, v0
	v_mov_b32_e32 v91, v0
	v_mov_b32_e32 v92, v0
	v_mov_b32_e32 v93, v0
	v_mov_b32_e32 v94, v0
	v_mov_b32_e32 v95, v0
	v_mov_b32_e32 v96, v0
	v_mov_b32_e32 v97, v0
	v_mov_b32_e32 v98, v0
	v_mov_b32_e32 v99, v0
	v_mov_b32_e32 v100, v0
	v_mov_b32_e32 v101, v0
	v_mov_b32_e32 v102, v0
	v_mov_b32_e32 v103, v0
	v_mov_b32_e32 v104, v0
	v_mov_b32_e32 v105, v0
	v_mov_b32_e32 v106, v0
	v_mov_b32_e32 v107, v0
	v_mov_b32_e32 v108, v0
	v_mov_b32_e32 v109, v0
	v_mov_b32_e32 v110, v0
	v_mov_b32_e32 v111, v0
	v_mov_b32_e32 v112, v0
	v_mov_b32_e32 v113, v0
	v_mov_b32_e32 v114, v0
	v_mov_b32_e32 v115, v0
	v_mov_b32_e32 v116, v0
	v_mov_b32_e32 v117, v0
	v_mov_b32_e32 v118, v0
	v_mov_b32_e32 v119, v0
	v_mov_b32_e32 v120, v0
	v_mov_b32_e32 v121, v0
	v_mov_b32_e32 v122, v0
	v_mov_b32_e32 v123, v0
	v_mov_b32_e32 v124, v0
	v_mov_b32_e32 v125, v0
	v_mov_b32_e32 v126, v0
	v_mov_b32_e32 v127, v0
	s_barrier
	v_readlane_b32 s98, v242, 1
	s_lshl_b32 s98, s98, 10
	s_add_i32 s36, s98, 0xc000
	v_lshl_add_u64 v[142:143], v[128:129], 0, s[18:19]
	s_mov_b32 m0, s36
	s_add_i32 s36, s98, 0xe000
	global_load_lds_dwordx4 v[142:143], off
	v_lshl_add_u64 v[142:143], v[128:129], 0, s[20:21]
	s_mov_b32 m0, s36
	s_nop 0
	global_load_lds_dwordx4 v[142:143], off
.LBB0_521:
	ds_read_b128 v[140:143], v138
	ds_read_b128 v[144:147], v138 offset:1024
	ds_read_b128 v[148:151], v138 offset:2048
	ds_read_b128 v[152:155], v138 offset:3072
	ds_read_b128 v[156:159], v193
	ds_read_b128 v[160:163], v193 offset:1024
	ds_read_b128 v[194:197], v192
	ds_read_b128 v[198:201], v192 offset:1024
	ds_read_b128 v[202:205], v191
	ds_read_b128 v[206:209], v191 offset:1024
	ds_read_b128 v[210:213], v190
	ds_read_b128 v[214:217], v190 offset:1024
	s_waitcnt lgkmcnt(8)
	s_waitcnt vmcnt(10)
	s_barrier
	s_waitcnt lgkmcnt(0)
	s_waitcnt lgkmcnt(0)
	v_mfma_f32_16x16x32_bf16 v[124:127], v[140:143], v[156:159], v[124:127]
	v_mfma_f32_16x16x32_bf16 v[120:123], v[148:151], v[156:159], v[120:123]
	v_mfma_f32_16x16x32_bf16 v[116:119], v[140:143], v[194:197], v[116:119]
	v_mfma_f32_16x16x32_bf16 v[112:115], v[148:151], v[194:197], v[112:115]
	v_mfma_f32_16x16x32_bf16 v[108:111], v[140:143], v[202:205], v[108:111]
	v_mfma_f32_16x16x32_bf16 v[104:107], v[148:151], v[202:205], v[104:107]
	v_mfma_f32_16x16x32_bf16 v[100:103], v[140:143], v[210:213], v[100:103]
	v_mfma_f32_16x16x32_bf16 v[96:99], v[148:151], v[210:213], v[96:99]
	v_mfma_f32_16x16x32_bf16 v[124:127], v[144:147], v[160:163], v[124:127]
	v_mfma_f32_16x16x32_bf16 v[120:123], v[152:155], v[160:163], v[120:123]
	v_mfma_f32_16x16x32_bf16 v[116:119], v[144:147], v[198:201], v[116:119]
	v_mfma_f32_16x16x32_bf16 v[112:115], v[152:155], v[198:201], v[112:115]
	v_mfma_f32_16x16x32_bf16 v[108:111], v[144:147], v[206:209], v[108:111]
	v_mfma_f32_16x16x32_bf16 v[104:107], v[152:155], v[206:209], v[104:107]
	v_mfma_f32_16x16x32_bf16 v[100:103], v[144:147], v[214:217], v[100:103]
	v_mfma_f32_16x16x32_bf16 v[96:99], v[152:155], v[214:217], v[96:99]
	s_barrier
	s_add_i32 s36, s98, 0x10000
	v_lshl_add_u64 v[234:235], s[58:59], 0, v[164:165]
	s_mov_b32 m0, s36
	s_add_i32 s36, s98, 0x12000
	ds_read_b128 v[218:221], v135
	ds_read_b128 v[222:225], v135 offset:1024
	ds_read_b128 v[226:229], v135 offset:2048
	ds_read_b128 v[230:233], v135 offset:3072
	global_load_lds_dwordx4 v[234:235], off
	v_lshl_add_u64 v[236:237], v[234:235], 0, s[2:3]
	s_mov_b32 m0, s36
	s_nop 0
	global_load_lds_dwordx4 v[236:237], off
	s_mov_b32 s36, s98
	v_lshl_add_u64 v[236:237], v[128:129], 0, s[22:23]
	s_mov_b32 m0, s36
	s_add_i32 s36, s98, 0x2000
	global_load_lds_dwordx4 v[236:237], off
	v_lshl_add_u64 v[236:237], v[128:129], 0, s[24:25]
	s_mov_b32 m0, s36
	s_nop 0
	global_load_lds_dwordx4 v[236:237], off
	s_waitcnt vmcnt(12)
	s_barrier
	s_waitcnt lgkmcnt(0)
	s_waitcnt lgkmcnt(0)
	v_mfma_f32_16x16x32_bf16 v[92:95], v[218:221], v[156:159], v[92:95]
	v_mfma_f32_16x16x32_bf16 v[88:91], v[226:229], v[156:159], v[88:91]
	v_mfma_f32_16x16x32_bf16 v[84:87], v[218:221], v[194:197], v[84:87]
	v_mfma_f32_16x16x32_bf16 v[80:83], v[226:229], v[194:197], v[80:83]
	v_mfma_f32_16x16x32_bf16 v[76:79], v[218:221], v[202:205], v[76:79]
	v_mfma_f32_16x16x32_bf16 v[72:75], v[226:229], v[202:205], v[72:75]
	v_mfma_f32_16x16x32_bf16 v[68:71], v[218:221], v[210:213], v[68:71]
	v_mfma_f32_16x16x32_bf16 v[64:67], v[226:229], v[210:213], v[64:67]
	v_mfma_f32_16x16x32_bf16 v[92:95], v[222:225], v[160:163], v[92:95]
	v_mfma_f32_16x16x32_bf16 v[88:91], v[230:233], v[160:163], v[88:91]
	v_mfma_f32_16x16x32_bf16 v[84:87], v[222:225], v[198:201], v[84:87]
	v_mfma_f32_16x16x32_bf16 v[80:83], v[230:233], v[198:201], v[80:83]
	v_mfma_f32_16x16x32_bf16 v[76:79], v[222:225], v[206:209], v[76:79]
	v_mfma_f32_16x16x32_bf16 v[72:75], v[230:233], v[206:209], v[72:75]
	v_mfma_f32_16x16x32_bf16 v[68:71], v[222:225], v[214:217], v[68:71]
	v_mfma_f32_16x16x32_bf16 v[64:67], v[230:233], v[214:217], v[64:67]
	s_barrier
	ds_read_b128 v[156:159], v193 offset:16384
	ds_read_b128 v[160:163], v193 offset:17408
	ds_read_b128 v[194:197], v192 offset:16384
	ds_read_b128 v[198:201], v192 offset:17408
	ds_read_b128 v[202:205], v191 offset:16384
	ds_read_b128 v[206:209], v191 offset:17408
	ds_read_b128 v[210:213], v190 offset:16384
	ds_read_b128 v[214:217], v190 offset:17408
	s_add_i32 s36, s98, 0x14000
	v_lshl_add_u64 v[236:237], v[234:235], 0, s[6:7]
	s_mov_b32 m0, s36
	s_add_i32 s36, s98, 0x16000
	global_load_lds_dwordx4 v[236:237], off
	v_lshl_add_u64 v[236:237], v[234:235], 0, s[8:9]
	s_mov_b32 m0, s36
	s_nop 0
	global_load_lds_dwordx4 v[236:237], off
	s_barrier
	s_waitcnt lgkmcnt(0)
	s_waitcnt lgkmcnt(0)
	v_mfma_f32_16x16x32_bf16 v[60:63], v[140:143], v[156:159], v[60:63]
	v_mfma_f32_16x16x32_bf16 v[56:59], v[148:151], v[156:159], v[56:59]
	v_mfma_f32_16x16x32_bf16 v[52:55], v[140:143], v[194:197], v[52:55]
	v_mfma_f32_16x16x32_bf16 v[48:51], v[148:151], v[194:197], v[48:51]
	v_mfma_f32_16x16x32_bf16 v[44:47], v[140:143], v[202:205], v[44:47]
	v_mfma_f32_16x16x32_bf16 v[40:43], v[148:151], v[202:205], v[40:43]
	v_mfma_f32_16x16x32_bf16 v[36:39], v[140:143], v[210:213], v[36:39]
	v_mfma_f32_16x16x32_bf16 v[32:35], v[148:151], v[210:213], v[32:35]
	v_mfma_f32_16x16x32_bf16 v[60:63], v[144:147], v[160:163], v[60:63]
	v_mfma_f32_16x16x32_bf16 v[56:59], v[152:155], v[160:163], v[56:59]
	v_mfma_f32_16x16x32_bf16 v[52:55], v[144:147], v[198:201], v[52:55]
	v_mfma_f32_16x16x32_bf16 v[48:51], v[152:155], v[198:201], v[48:51]
	v_mfma_f32_16x16x32_bf16 v[44:47], v[144:147], v[206:209], v[44:47]
	v_mfma_f32_16x16x32_bf16 v[40:43], v[152:155], v[206:209], v[40:43]
	v_mfma_f32_16x16x32_bf16 v[36:39], v[144:147], v[214:217], v[36:39]
	v_mfma_f32_16x16x32_bf16 v[32:35], v[152:155], v[214:217], v[32:35]
	s_barrier
	s_add_i32 s36, s98, 0x4000
	v_lshl_add_u64 v[142:143], v[128:129], 0, s[26:27]
	s_mov_b32 m0, s36
	s_add_i32 s36, s98, 0x6000
	global_load_lds_dwordx4 v[142:143], off
	s_mov_b32 m0, s36
	s_nop 0
	global_load_lds_dwordx4 v[128:129], off
	s_waitcnt vmcnt(12)
	s_barrier
	v_mfma_f32_16x16x32_bf16 v[28:31], v[218:221], v[156:159], v[28:31]
	v_mfma_f32_16x16x32_bf16 v[24:27], v[226:229], v[156:159], v[24:27]
	v_mfma_f32_16x16x32_bf16 v[20:23], v[218:221], v[194:197], v[20:23]
	v_mfma_f32_16x16x32_bf16 v[16:19], v[226:229], v[194:197], v[16:19]
	v_mfma_f32_16x16x32_bf16 v[12:15], v[218:221], v[202:205], v[12:15]
	v_mfma_f32_16x16x32_bf16 v[8:11], v[226:229], v[202:205], v[8:11]
	v_mfma_f32_16x16x32_bf16 v[4:7], v[218:221], v[210:213], v[4:7]
	v_mfma_f32_16x16x32_bf16 v[0:3], v[226:229], v[210:213], v[0:3]
	v_mfma_f32_16x16x32_bf16 v[28:31], v[222:225], v[160:163], v[28:31]
	v_mfma_f32_16x16x32_bf16 v[24:27], v[230:233], v[160:163], v[24:27]
	v_mfma_f32_16x16x32_bf16 v[20:23], v[222:225], v[198:201], v[20:23]
	v_mfma_f32_16x16x32_bf16 v[16:19], v[230:233], v[198:201], v[16:19]
	v_mfma_f32_16x16x32_bf16 v[12:15], v[222:225], v[206:209], v[12:15]
	v_mfma_f32_16x16x32_bf16 v[8:11], v[230:233], v[206:209], v[8:11]
	v_mfma_f32_16x16x32_bf16 v[4:7], v[222:225], v[214:217], v[4:7]
	v_mfma_f32_16x16x32_bf16 v[0:3], v[230:233], v[214:217], v[0:3]
	s_barrier
	ds_read_b128 v[140:143], v130
	ds_read_b128 v[144:147], v130 offset:1024
	ds_read_b128 v[148:151], v130 offset:2048
	ds_read_b128 v[152:155], v130 offset:3072
	ds_read_b128 v[156:159], v193 offset:32768
	ds_read_b128 v[160:163], v193 offset:33792
	ds_read_b128 v[194:197], v192 offset:32768
	ds_read_b128 v[198:201], v192 offset:33792
	ds_read_b128 v[202:205], v191 offset:32768
	ds_read_b128 v[206:209], v191 offset:33792
	ds_read_b128 v[210:213], v190 offset:32768
	ds_read_b128 v[214:217], v190 offset:33792
	s_waitcnt lgkmcnt(8)
	s_waitcnt vmcnt(10)
	s_barrier
	s_waitcnt lgkmcnt(0)
	s_waitcnt lgkmcnt(0)
	v_mfma_f32_16x16x32_bf16 v[124:127], v[140:143], v[156:159], v[124:127]
	v_mfma_f32_16x16x32_bf16 v[120:123], v[148:151], v[156:159], v[120:123]
	v_mfma_f32_16x16x32_bf16 v[116:119], v[140:143], v[194:197], v[116:119]
	v_mfma_f32_16x16x32_bf16 v[112:115], v[148:151], v[194:197], v[112:115]
	v_mfma_f32_16x16x32_bf16 v[108:111], v[140:143], v[202:205], v[108:111]
	v_mfma_f32_16x16x32_bf16 v[104:107], v[148:151], v[202:205], v[104:107]
	v_mfma_f32_16x16x32_bf16 v[100:103], v[140:143], v[210:213], v[100:103]
	v_mfma_f32_16x16x32_bf16 v[96:99], v[148:151], v[210:213], v[96:99]
	v_mfma_f32_16x16x32_bf16 v[124:127], v[144:147], v[160:163], v[124:127]
	v_mfma_f32_16x16x32_bf16 v[120:123], v[152:155], v[160:163], v[120:123]
	v_mfma_f32_16x16x32_bf16 v[116:119], v[144:147], v[198:201], v[116:119]
	v_mfma_f32_16x16x32_bf16 v[112:115], v[152:155], v[198:201], v[112:115]
	v_mfma_f32_16x16x32_bf16 v[108:111], v[144:147], v[206:209], v[108:111]
	v_mfma_f32_16x16x32_bf16 v[104:107], v[152:155], v[206:209], v[104:107]
	v_mfma_f32_16x16x32_bf16 v[100:103], v[144:147], v[214:217], v[100:103]
	v_mfma_f32_16x16x32_bf16 v[96:99], v[152:155], v[214:217], v[96:99]
	s_barrier
	s_add_i32 s36, s98, 0x18000
	v_lshl_add_u64 v[234:235], s[46:47], 0, v[164:165]
	s_mov_b32 m0, s36
	s_add_i32 s36, s98, 0x1a000
	ds_read_b128 v[218:221], v132
	ds_read_b128 v[222:225], v132 offset:1024
	ds_read_b128 v[226:229], v132 offset:2048
	ds_read_b128 v[230:233], v132 offset:3072
	global_load_lds_dwordx4 v[234:235], off
	v_lshl_add_u64 v[236:237], v[234:235], 0, s[2:3]
	s_mov_b32 m0, s36
	s_nop 0
	global_load_lds_dwordx4 v[236:237], off
	s_add_i32 s36, s98, 0x8000
	v_lshl_add_u64 v[236:237], v[128:129], 0, s[28:29]
	s_mov_b32 m0, s36
	s_add_i32 s36, s98, 0xa000
	global_load_lds_dwordx4 v[236:237], off
	v_lshl_add_u64 v[236:237], v[128:129], 0, s[30:31]
	s_mov_b32 m0, s36
	s_nop 0
	global_load_lds_dwordx4 v[236:237], off
	s_waitcnt vmcnt(12)
	s_barrier
	s_waitcnt lgkmcnt(0)
	s_waitcnt lgkmcnt(0)
	v_mfma_f32_16x16x32_bf16 v[92:95], v[218:221], v[156:159], v[92:95]
	v_mfma_f32_16x16x32_bf16 v[88:91], v[226:229], v[156:159], v[88:91]
	v_mfma_f32_16x16x32_bf16 v[84:87], v[218:221], v[194:197], v[84:87]
	v_mfma_f32_16x16x32_bf16 v[80:83], v[226:229], v[194:197], v[80:83]
	v_mfma_f32_16x16x32_bf16 v[76:79], v[218:221], v[202:205], v[76:79]
	v_mfma_f32_16x16x32_bf16 v[72:75], v[226:229], v[202:205], v[72:75]
	v_mfma_f32_16x16x32_bf16 v[68:71], v[218:221], v[210:213], v[68:71]
	v_mfma_f32_16x16x32_bf16 v[64:67], v[226:229], v[210:213], v[64:67]
	v_mfma_f32_16x16x32_bf16 v[92:95], v[222:225], v[160:163], v[92:95]
	v_mfma_f32_16x16x32_bf16 v[88:91], v[230:233], v[160:163], v[88:91]
	v_mfma_f32_16x16x32_bf16 v[84:87], v[222:225], v[198:201], v[84:87]
	v_mfma_f32_16x16x32_bf16 v[80:83], v[230:233], v[198:201], v[80:83]
	v_mfma_f32_16x16x32_bf16 v[76:79], v[222:225], v[206:209], v[76:79]
	v_mfma_f32_16x16x32_bf16 v[72:75], v[230:233], v[206:209], v[72:75]
	v_mfma_f32_16x16x32_bf16 v[68:71], v[222:225], v[214:217], v[68:71]
	v_mfma_f32_16x16x32_bf16 v[64:67], v[230:233], v[214:217], v[64:67]
	s_barrier
	ds_read_b128 v[156:159], v193 offset:49152
	ds_read_b128 v[160:163], v193 offset:50176
	ds_read_b128 v[194:197], v192 offset:49152
	ds_read_b128 v[198:201], v192 offset:50176
	ds_read_b128 v[202:205], v191 offset:49152
	ds_read_b128 v[206:209], v191 offset:50176
	ds_read_b128 v[210:213], v190 offset:49152
	ds_read_b128 v[214:217], v190 offset:50176
	s_add_i32 s36, s98, 0x1c000
	v_lshl_add_u64 v[236:237], v[234:235], 0, s[6:7]
	s_mov_b32 m0, s36
	s_add_i32 s36, s98, 0x1e000
	global_load_lds_dwordx4 v[236:237], off
	v_lshl_add_u64 v[236:237], v[234:235], 0, s[8:9]
	s_mov_b32 m0, s36
	s_nop 0
	global_load_lds_dwordx4 v[236:237], off
	s_barrier
	s_waitcnt lgkmcnt(0)
	s_waitcnt lgkmcnt(0)
	v_mfma_f32_16x16x32_bf16 v[60:63], v[140:143], v[156:159], v[60:63]
	v_mfma_f32_16x16x32_bf16 v[56:59], v[148:151], v[156:159], v[56:59]
	v_mfma_f32_16x16x32_bf16 v[52:55], v[140:143], v[194:197], v[52:55]
	v_mfma_f32_16x16x32_bf16 v[48:51], v[148:151], v[194:197], v[48:51]
	v_mfma_f32_16x16x32_bf16 v[44:47], v[140:143], v[202:205], v[44:47]
	v_mfma_f32_16x16x32_bf16 v[40:43], v[148:151], v[202:205], v[40:43]
	v_mfma_f32_16x16x32_bf16 v[36:39], v[140:143], v[210:213], v[36:39]
	v_mfma_f32_16x16x32_bf16 v[32:35], v[148:151], v[210:213], v[32:35]
	v_mfma_f32_16x16x32_bf16 v[60:63], v[144:147], v[160:163], v[60:63]
	v_mfma_f32_16x16x32_bf16 v[56:59], v[152:155], v[160:163], v[56:59]
	v_mfma_f32_16x16x32_bf16 v[52:55], v[144:147], v[198:201], v[52:55]
	v_mfma_f32_16x16x32_bf16 v[48:51], v[152:155], v[198:201], v[48:51]
	v_mfma_f32_16x16x32_bf16 v[44:47], v[144:147], v[206:209], v[44:47]
	v_mfma_f32_16x16x32_bf16 v[40:43], v[152:155], v[206:209], v[40:43]
	v_mfma_f32_16x16x32_bf16 v[36:39], v[144:147], v[214:217], v[36:39]
	v_mfma_f32_16x16x32_bf16 v[32:35], v[152:155], v[214:217], v[32:35]
	s_barrier
	v_lshl_add_u64 v[128:129], v[128:129], 0, s[34:35]
	s_add_i32 s36, s98, 0xc000
	v_lshl_add_u64 v[142:143], v[128:129], 0, s[18:19]
	s_mov_b32 m0, s36
	s_add_i32 s36, s98, 0xe000
	global_load_lds_dwordx4 v[142:143], off
	v_lshl_add_u64 v[142:143], v[128:129], 0, s[20:21]
	s_mov_b32 m0, s36
	s_nop 0
	global_load_lds_dwordx4 v[142:143], off
	s_waitcnt vmcnt(12)
	s_barrier
	v_mfma_f32_16x16x32_bf16 v[28:31], v[218:221], v[156:159], v[28:31]
	v_mfma_f32_16x16x32_bf16 v[24:27], v[226:229], v[156:159], v[24:27]
	v_mfma_f32_16x16x32_bf16 v[20:23], v[218:221], v[194:197], v[20:23]
	v_mfma_f32_16x16x32_bf16 v[16:19], v[226:229], v[194:197], v[16:19]
	v_mfma_f32_16x16x32_bf16 v[12:15], v[218:221], v[202:205], v[12:15]
	v_mfma_f32_16x16x32_bf16 v[8:11], v[226:229], v[202:205], v[8:11]
	v_mfma_f32_16x16x32_bf16 v[4:7], v[218:221], v[210:213], v[4:7]
	v_mfma_f32_16x16x32_bf16 v[0:3], v[226:229], v[210:213], v[0:3]
	v_mfma_f32_16x16x32_bf16 v[28:31], v[222:225], v[160:163], v[28:31]
	v_mfma_f32_16x16x32_bf16 v[24:27], v[230:233], v[160:163], v[24:27]
	v_mfma_f32_16x16x32_bf16 v[20:23], v[222:225], v[198:201], v[20:23]
	v_mfma_f32_16x16x32_bf16 v[16:19], v[230:233], v[198:201], v[16:19]
	v_mfma_f32_16x16x32_bf16 v[12:15], v[222:225], v[206:209], v[12:15]
	v_mfma_f32_16x16x32_bf16 v[8:11], v[230:233], v[206:209], v[8:11]
	v_mfma_f32_16x16x32_bf16 v[4:7], v[222:225], v[214:217], v[4:7]
	v_mfma_f32_16x16x32_bf16 v[0:3], v[230:233], v[214:217], v[0:3]
	s_add_i32 s14, s14, 2
	s_add_u32 s46, s46, s56
	s_addc_u32 s47, s47, s57
	s_add_u32 s58, s58, s56
	s_addc_u32 s59, s59, s57
	s_cmp_lt_u32 s14, 28
	s_barrier
	s_cbranch_scc1 .LBB0_521
	s_lshl_b32 s14, s60, 3
	s_or_b32 s80, s61, s14
	s_lshl_b32 s46, s80, 8
	v_lshlrev_b32_e32 v128, 3, v131
	v_lshlrev_b32_e32 v129, 5, v131
	s_or_b32 s14, s46, 0x80
	v_and_b32_e32 v128, 0x7fff0, v128
	v_and_b32_e32 v129, 32, v129
	s_lshl_b64 s[56:57], s[14:15], 13
	v_add_u32_e32 v129, v129, v134
	v_add_lshl_u32 v128, v133, v128, 13
	s_add_u32 s56, s40, s56
	v_lshl_add_u32 v164, v129, 1, v128
	s_addc_u32 s57, s41, s57
	v_lshl_add_u64 v[128:129], s[56:57], 0, v[164:165]
	v_readfirstlane_b32 s14, v137
	ds_read_b128 v[140:143], v138
	ds_read_b128 v[144:147], v138 offset:1024
	ds_read_b128 v[148:151], v138 offset:2048
	ds_read_b128 v[152:155], v138 offset:3072
	ds_read_b128 v[156:159], v193
	ds_read_b128 v[160:163], v193 offset:1024
	ds_read_b128 v[194:197], v192
	ds_read_b128 v[198:201], v192 offset:1024
	ds_read_b128 v[202:205], v191
	ds_read_b128 v[206:209], v191 offset:1024
	ds_read_b128 v[210:213], v190
	ds_read_b128 v[214:217], v190 offset:1024
	v_lshl_add_u64 v[138:139], v[128:129], 0, s[38:39]
	s_mov_b32 m0, s14
	v_readfirstlane_b32 s14, v136
	global_load_lds_dwordx4 v[138:139], off
	v_lshl_add_u64 v[128:129], v[128:129], 0, s[44:45]
	s_mov_b32 m0, s14
	s_mov_b32 s47, s15
	global_load_lds_dwordx4 v[128:129], off
	s_waitcnt vmcnt(10)
	s_barrier
	s_waitcnt lgkmcnt(0)
	s_setprio 1
	s_waitcnt lgkmcnt(0)
	v_mfma_f32_16x16x32_bf16 v[124:127], v[140:143], v[156:159], v[124:127]
	v_mfma_f32_16x16x32_bf16 v[120:123], v[148:151], v[156:159], v[120:123]
	v_mfma_f32_16x16x32_bf16 v[116:119], v[140:143], v[194:197], v[116:119]
	v_mfma_f32_16x16x32_bf16 v[112:115], v[148:151], v[194:197], v[112:115]
	v_mfma_f32_16x16x32_bf16 v[108:111], v[140:143], v[202:205], v[108:111]
	v_mfma_f32_16x16x32_bf16 v[104:107], v[148:151], v[202:205], v[104:107]
	v_mfma_f32_16x16x32_bf16 v[100:103], v[140:143], v[210:213], v[100:103]
	v_mfma_f32_16x16x32_bf16 v[96:99], v[148:151], v[210:213], v[96:99]
	v_mfma_f32_16x16x32_bf16 v[124:127], v[144:147], v[160:163], v[124:127]
	v_mfma_f32_16x16x32_bf16 v[120:123], v[152:155], v[160:163], v[120:123]
	v_mfma_f32_16x16x32_bf16 v[116:119], v[144:147], v[198:201], v[116:119]
	v_mfma_f32_16x16x32_bf16 v[112:115], v[152:155], v[198:201], v[112:115]
	v_mfma_f32_16x16x32_bf16 v[108:111], v[144:147], v[206:209], v[108:111]
	v_mfma_f32_16x16x32_bf16 v[104:107], v[152:155], v[206:209], v[104:107]
	v_mfma_f32_16x16x32_bf16 v[100:103], v[144:147], v[214:217], v[100:103]
	v_mfma_f32_16x16x32_bf16 v[96:99], v[152:155], v[214:217], v[96:99]
	s_setprio 0
	s_barrier
	ds_read_b128 v[136:139], v135
	ds_read_b128 v[218:221], v135 offset:1024
	ds_read_b128 v[222:225], v135 offset:2048
	ds_read_b128 v[226:229], v135 offset:3072
	s_barrier
	s_waitcnt lgkmcnt(0)
	s_setprio 1
	s_waitcnt lgkmcnt(0)
	v_mfma_f32_16x16x32_bf16 v[92:95], v[136:139], v[156:159], v[92:95]
	v_mfma_f32_16x16x32_bf16 v[84:87], v[136:139], v[194:197], v[84:87]
	v_mfma_f32_16x16x32_bf16 v[80:83], v[222:225], v[194:197], v[80:83]
	v_mfma_f32_16x16x32_bf16 v[88:91], v[222:225], v[156:159], v[88:91]
	v_mfma_f32_16x16x32_bf16 v[76:79], v[136:139], v[202:205], v[76:79]
	v_mfma_f32_16x16x32_bf16 v[72:75], v[222:225], v[202:205], v[72:75]
	v_mfma_f32_16x16x32_bf16 v[68:71], v[136:139], v[210:213], v[68:71]
	v_mfma_f32_16x16x32_bf16 v[64:67], v[222:225], v[210:213], v[64:67]
	v_mfma_f32_16x16x32_bf16 v[156:159], v[218:221], v[160:163], v[92:95]
	v_mfma_f32_16x16x32_bf16 v[194:197], v[218:221], v[198:201], v[84:87]
	v_mfma_f32_16x16x32_bf16 v[198:201], v[226:229], v[198:201], v[80:83]
	v_mfma_f32_16x16x32_bf16 v[160:163], v[226:229], v[160:163], v[88:91]
	v_mfma_f32_16x16x32_bf16 v[202:205], v[218:221], v[206:209], v[76:79]
	v_mfma_f32_16x16x32_bf16 v[206:209], v[226:229], v[206:209], v[72:75]
	v_mfma_f32_16x16x32_bf16 v[210:213], v[218:221], v[214:217], v[68:71]
	v_mfma_f32_16x16x32_bf16 v[214:217], v[226:229], v[214:217], v[64:67]
	s_setprio 0
	s_barrier
	s_nop 0
	ds_read_b128 v[64:67], v193 offset:16384
	ds_read_b128 v[68:71], v193 offset:17408
	ds_read_b128 v[72:75], v192 offset:16384
	ds_read_b128 v[76:79], v192 offset:17408
	ds_read_b128 v[80:83], v191 offset:16384
	ds_read_b128 v[84:87], v191 offset:17408
	ds_read_b128 v[88:91], v190 offset:16384
	ds_read_b128 v[92:95], v190 offset:17408
	s_waitcnt vmcnt(4)
	s_barrier
	s_waitcnt lgkmcnt(0)
	s_setprio 1
	s_waitcnt lgkmcnt(0)
	v_mfma_f32_16x16x32_bf16 v[60:63], v[140:143], v[64:67], v[60:63]
	v_mfma_f32_16x16x32_bf16 v[56:59], v[148:151], v[64:67], v[56:59]
	v_mfma_f32_16x16x32_bf16 v[52:55], v[140:143], v[72:75], v[52:55]
	v_mfma_f32_16x16x32_bf16 v[48:51], v[148:151], v[72:75], v[48:51]
	v_mfma_f32_16x16x32_bf16 v[230:233], v[140:143], v[80:83], v[44:47]
	v_mfma_f32_16x16x32_bf16 v[234:237], v[148:151], v[80:83], v[40:43]
	v_mfma_f32_16x16x32_bf16 v[140:143], v[140:143], v[88:91], v[36:39]
	v_mfma_f32_16x16x32_bf16 v[148:151], v[148:151], v[88:91], v[32:35]
	v_mfma_f32_16x16x32_bf16 v[32:35], v[144:147], v[68:71], v[60:63]
	v_mfma_f32_16x16x32_bf16 v[36:39], v[152:155], v[68:71], v[56:59]
	v_mfma_f32_16x16x32_bf16 v[40:43], v[144:147], v[76:79], v[52:55]
	v_mfma_f32_16x16x32_bf16 v[44:47], v[152:155], v[76:79], v[48:51]
	v_mfma_f32_16x16x32_bf16 v[48:51], v[144:147], v[84:87], v[230:233]
	v_mfma_f32_16x16x32_bf16 v[52:55], v[152:155], v[84:87], v[234:237]
	v_mfma_f32_16x16x32_bf16 v[56:59], v[144:147], v[92:95], v[140:143]
	v_mfma_f32_16x16x32_bf16 v[60:63], v[152:155], v[92:95], v[148:151]
	s_setprio 0
	s_setprio 1
	v_mfma_f32_16x16x32_bf16 v[28:31], v[136:139], v[64:67], v[28:31]
	v_mfma_f32_16x16x32_bf16 v[24:27], v[222:225], v[64:67], v[24:27]
	v_mfma_f32_16x16x32_bf16 v[20:23], v[136:139], v[72:75], v[20:23]
	v_mfma_f32_16x16x32_bf16 v[64:67], v[222:225], v[72:75], v[16:19]
	v_mfma_f32_16x16x32_bf16 v[12:15], v[136:139], v[80:83], v[12:15]
	v_mfma_f32_16x16x32_bf16 v[8:11], v[222:225], v[80:83], v[8:11]
	v_mfma_f32_16x16x32_bf16 v[72:75], v[136:139], v[88:91], v[4:7]
	v_mfma_f32_16x16x32_bf16 v[80:83], v[222:225], v[88:91], v[0:3]
	v_mfma_f32_16x16x32_bf16 v[0:3], v[218:221], v[68:71], v[28:31]
	v_mfma_f32_16x16x32_bf16 v[4:7], v[226:229], v[68:71], v[24:27]
	v_mfma_f32_16x16x32_bf16 v[16:19], v[218:221], v[76:79], v[20:23]
	v_mfma_f32_16x16x32_bf16 v[20:23], v[226:229], v[76:79], v[64:67]
	v_mfma_f32_16x16x32_bf16 v[24:27], v[218:221], v[84:87], v[12:15]
	v_mfma_f32_16x16x32_bf16 v[28:31], v[226:229], v[84:87], v[8:11]
	v_mfma_f32_16x16x32_bf16 v[64:67], v[218:221], v[92:95], v[72:75]
	v_mfma_f32_16x16x32_bf16 v[68:71], v[226:229], v[92:95], v[80:83]
	s_setprio 0
	s_barrier
	ds_read_b128 v[12:15], v130
	ds_read_b128 v[8:11], v130 offset:1024
	ds_read_b128 v[76:79], v130 offset:2048
	ds_read_b128 v[72:75], v130 offset:3072
	ds_read_b128 v[140:143], v193 offset:32768
	ds_read_b128 v[148:151], v193 offset:33792
	ds_read_b128 v[218:221], v192 offset:32768
	ds_read_b128 v[222:225], v192 offset:33792
	ds_read_b128 v[226:229], v191 offset:32768
	ds_read_b128 v[230:233], v191 offset:33792
	ds_read_b128 v[234:237], v190 offset:32768
	ds_read_b128 v[238:241], v190 offset:33792
	s_waitcnt vmcnt(2)
	s_barrier
	s_waitcnt lgkmcnt(0)
	s_setprio 1
	s_waitcnt lgkmcnt(0)
	v_mfma_f32_16x16x32_bf16 v[80:83], v[12:15], v[140:143], v[124:127]
	v_mfma_f32_16x16x32_bf16 v[84:87], v[76:79], v[140:143], v[120:123]
	v_mfma_f32_16x16x32_bf16 v[88:91], v[12:15], v[218:221], v[116:119]
	v_mfma_f32_16x16x32_bf16 v[92:95], v[76:79], v[218:221], v[112:115]
	v_mfma_f32_16x16x32_bf16 v[108:111], v[12:15], v[226:229], v[108:111]
	v_mfma_f32_16x16x32_bf16 v[104:107], v[76:79], v[226:229], v[104:107]
	v_mfma_f32_16x16x32_bf16 v[100:103], v[12:15], v[234:237], v[100:103]
	v_mfma_f32_16x16x32_bf16 v[96:99], v[76:79], v[234:237], v[96:99]
	v_mfma_f32_16x16x32_bf16 v[152:155], v[8:11], v[148:151], v[80:83]
	v_mfma_f32_16x16x32_bf16 v[144:147], v[72:75], v[148:151], v[84:87]
	v_mfma_f32_16x16x32_bf16 v[136:139], v[8:11], v[222:225], v[88:91]
	v_mfma_f32_16x16x32_bf16 v[128:131], v[72:75], v[222:225], v[92:95]
	v_mfma_f32_16x16x32_bf16 v[120:123], v[8:11], v[230:233], v[108:111]
	v_mfma_f32_16x16x32_bf16 v[112:115], v[72:75], v[230:233], v[104:107]
	v_mfma_f32_16x16x32_bf16 v[104:107], v[8:11], v[238:241], v[100:103]
	v_mfma_f32_16x16x32_bf16 v[96:99], v[72:75], v[238:241], v[96:99]
	s_setprio 0
	s_barrier
	ds_read_b128 v[88:91], v132
	ds_read_b128 v[80:83], v132 offset:1024
	ds_read_b128 v[92:95], v132 offset:2048
	ds_read_b128 v[84:87], v132 offset:3072
	s_waitcnt vmcnt(0)
	s_barrier
	s_waitcnt lgkmcnt(0)
	s_setprio 1
	s_waitcnt lgkmcnt(0)
	v_mfma_f32_16x16x32_bf16 v[100:103], v[88:91], v[140:143], v[156:159]
	v_mfma_f32_16x16x32_bf16 v[108:111], v[92:95], v[140:143], v[160:163]
	v_mfma_f32_16x16x32_bf16 v[116:119], v[88:91], v[218:221], v[194:197]
	v_mfma_f32_16x16x32_bf16 v[124:127], v[92:95], v[218:221], v[198:201]
	v_mfma_f32_16x16x32_bf16 v[160:163], v[88:91], v[226:229], v[202:205]
	v_mfma_f32_16x16x32_bf16 v[194:197], v[92:95], v[226:229], v[206:209]
	v_mfma_f32_16x16x32_bf16 v[198:201], v[88:91], v[234:237], v[210:213]
	v_mfma_f32_16x16x32_bf16 v[202:205], v[92:95], v[234:237], v[214:217]
	v_mfma_f32_16x16x32_bf16 v[156:159], v[80:83], v[148:151], v[100:103]
	v_mfma_f32_16x16x32_bf16 v[148:151], v[84:87], v[148:151], v[108:111]
	v_mfma_f32_16x16x32_bf16 v[140:143], v[80:83], v[222:225], v[116:119]
	v_mfma_f32_16x16x32_bf16 v[132:135], v[84:87], v[222:225], v[124:127]
	v_mfma_f32_16x16x32_bf16 v[124:127], v[80:83], v[230:233], v[160:163]
	v_mfma_f32_16x16x32_bf16 v[116:119], v[84:87], v[230:233], v[194:197]
	v_mfma_f32_16x16x32_bf16 v[108:111], v[80:83], v[238:241], v[198:201]
	v_mfma_f32_16x16x32_bf16 v[100:103], v[84:87], v[238:241], v[202:205]
	s_setprio 0
	s_lshl_b64 s[56:57], s[46:47], 2
	s_barrier
	v_mbcnt_lo_u32_b32 v162, -1, 0
	v_mbcnt_hi_u32_b32 v162, -1, v162
	s_add_u32 s56, s87, s56
	v_add_u32_e32 v160, s64, v162
	s_addc_u32 s57, s88, s57
	v_and_b32_e32 v164, 0x100, v160
	v_and_b32_e32 v162, 15, v162
	v_lshl_add_u64 v[160:161], s[56:57], 0, v[164:165]
	v_lshlrev_b32_e32 v164, 2, v162
	v_lshl_add_u64 v[160:161], v[160:161], 0, v[164:165]
	global_load_dword v180, v[160:161], off
	global_load_dword v178, v[160:161], off offset:64
	global_load_dword v176, v[160:161], off offset:128
	global_load_dword v174, v[160:161], off offset:192
	global_load_dword v172, v[160:161], off offset:512
	global_load_dword v170, v[160:161], off offset:576
	global_load_dword v168, v[160:161], off offset:640
	global_load_dword v166, v[160:161], off offset:704
	v_mbcnt_lo_u32_b32 v194, -1, 0
	v_mbcnt_hi_u32_b32 v194, -1, v194
	s_cmp_lg_u32 s79, 0
	v_add_u32_e32 v160, s64, v194
	v_bfe_u32 v196, v160, 8, 1
	v_ashrrev_i32_e32 v199, 6, v160
	v_bfe_u32 v160, v194, 4, 2
	s_cselect_b64 s[56:57], -1, 0
	v_and_b32_e32 v197, 3, v199
	v_and_b32_e32 v195, 15, v194
	s_and_b64 vcc, exec, s[56:57]
	v_lshlrev_b32_e32 v198, 4, v160
	s_cbranch_vccz .LBB0_533
	s_lshl_b32 s14, s78, 22
	s_lshl_b32 s36, s80, 14
	s_add_i32 s36, s36, s14
	v_lshlrev_b32_e32 v160, 6, v195
	v_or3_b32 v160, s36, v160, v198
	v_lshl_add_u32 v160, v197, 20, v160
	v_lshl_or_b32 v164, v196, 12, v160
	s_waitcnt vmcnt(0)
	v_pk_mul_f32 v[160:161], v[154:155], v[180:181] op_sel_hi:[1,0]
	v_pk_mul_f32 v[200:201], v[146:147], v[180:181] op_sel_hi:[1,0]
	v_max_f32_e32 v160, 0, v160
	v_mul_f32_e32 v204, v160, v160
	v_max_f32_e32 v160, 0, v200
	v_pk_mul_f32 v[162:163], v[152:153], v[180:181] op_sel_hi:[1,0]
	v_mul_f32_e32 v200, v160, v160
	v_max_f32_e32 v160, 0, v161
	v_pk_mul_f32 v[202:203], v[144:145], v[180:181] op_sel_hi:[1,0]
	v_max_f32_e32 v162, 0, v162
	v_max_f32_e32 v163, 0, v163
	v_mul_f32_e32 v161, v160, v160
	v_max_f32_e32 v160, 0, v201
	v_mul_f32_e32 v162, v162, v162
	v_max_f32_e32 v202, 0, v202
	v_mul_f32_e32 v163, v163, v163
	v_max_f32_e32 v203, 0, v203
	v_mul_f32_e32 v201, v160, v160
	v_cvt_pk_bf16_f32 v160, v162, v163
	v_cvt_pk_bf16_f32 v161, v204, v161
	v_mul_f32_e32 v202, v202, v202
	v_mul_f32_e32 v203, v203, v203
	v_cvt_pk_bf16_f32 v162, v202, v203
	v_cvt_pk_bf16_f32 v163, v200, v201
	global_store_dwordx4 v164, v[160:163], s[0:1]
	v_pk_mul_f32 v[202:203], v[150:151], v[180:181] op_sel_hi:[1,0]
	v_lshl_add_u64 v[200:201], s[0:1], 0, v[164:165]
	v_pk_mul_f32 v[160:161], v[158:159], v[180:181] op_sel_hi:[1,0]
	v_pk_mul_f32 v[162:163], v[156:157], v[180:181] op_sel_hi:[1,0]
	v_max_f32_e32 v160, 0, v160
	v_mul_f32_e32 v206, v160, v160
	v_max_f32_e32 v160, 0, v202
	v_mul_f32_e32 v202, v160, v160
	v_max_f32_e32 v160, 0, v161
	v_pk_mul_f32 v[204:205], v[148:149], v[180:181] op_sel_hi:[1,0]
	v_max_f32_e32 v162, 0, v162
	v_max_f32_e32 v163, 0, v163
	v_mul_f32_e32 v161, v160, v160
	v_max_f32_e32 v160, 0, v203
	v_add_co_u32_e32 v200, vcc, s72, v200
	v_mul_f32_e32 v162, v162, v162
	v_max_f32_e32 v204, 0, v204
	v_mul_f32_e32 v163, v163, v163
	v_max_f32_e32 v205, 0, v205
	v_mul_f32_e32 v203, v160, v160
	v_cvt_pk_bf16_f32 v160, v162, v163
	v_cvt_pk_bf16_f32 v161, v206, v161
	v_addc_co_u32_e32 v201, vcc, 0, v201, vcc
	v_mul_f32_e32 v204, v204, v204
	v_mul_f32_e32 v205, v205, v205
	v_cvt_pk_bf16_f32 v162, v204, v205
	v_cvt_pk_bf16_f32 v163, v202, v203
	global_store_dwordx4 v[200:201], v[160:163], off
	v_pk_mul_f32 v[202:203], v[130:131], v[178:179] op_sel_hi:[1,0]
	v_pk_mul_f32 v[204:205], v[128:129], v[178:179] op_sel_hi:[1,0]
	v_pk_mul_f32 v[160:161], v[138:139], v[178:179] op_sel_hi:[1,0]
	v_pk_mul_f32 v[162:163], v[136:137], v[178:179] op_sel_hi:[1,0]
	v_max_f32_e32 v160, 0, v160
	v_mul_f32_e32 v206, v160, v160
	v_max_f32_e32 v160, 0, v202
	v_mul_f32_e32 v202, v160, v160
	v_max_f32_e32 v160, 0, v161
	v_max_f32_e32 v162, 0, v162
	v_max_f32_e32 v163, 0, v163
	v_mul_f32_e32 v161, v160, v160
	v_max_f32_e32 v160, 0, v203
	v_mul_f32_e32 v162, v162, v162
	v_max_f32_e32 v204, 0, v204
	v_mul_f32_e32 v163, v163, v163
	v_max_f32_e32 v205, 0, v205
	v_mul_f32_e32 v203, v160, v160
	v_cvt_pk_bf16_f32 v160, v162, v163
	v_cvt_pk_bf16_f32 v161, v206, v161
	v_mul_f32_e32 v204, v204, v204
	v_mul_f32_e32 v205, v205, v205
	v_cvt_pk_bf16_f32 v162, v204, v205
	v_cvt_pk_bf16_f32 v163, v202, v203
	global_store_dwordx4 v164, v[160:163], s[0:1] offset:1024
	v_pk_mul_f32 v[202:203], v[134:135], v[178:179] op_sel_hi:[1,0]
	v_pk_mul_f32 v[204:205], v[132:133], v[178:179] op_sel_hi:[1,0]
	v_pk_mul_f32 v[160:161], v[142:143], v[178:179] op_sel_hi:[1,0]
	v_pk_mul_f32 v[162:163], v[140:141], v[178:179] op_sel_hi:[1,0]
	v_max_f32_e32 v160, 0, v160
	v_mul_f32_e32 v206, v160, v160
	v_max_f32_e32 v160, 0, v202
	v_mul_f32_e32 v202, v160, v160
	v_max_f32_e32 v160, 0, v161
	v_max_f32_e32 v162, 0, v162
	v_max_f32_e32 v163, 0, v163
	v_mul_f32_e32 v161, v160, v160
	v_max_f32_e32 v160, 0, v203
	v_mul_f32_e32 v162, v162, v162
	v_max_f32_e32 v204, 0, v204
	v_mul_f32_e32 v163, v163, v163
	v_max_f32_e32 v205, 0, v205
	v_mul_f32_e32 v203, v160, v160
	v_cvt_pk_bf16_f32 v160, v162, v163
	v_cvt_pk_bf16_f32 v161, v206, v161
	v_mul_f32_e32 v204, v204, v204
	v_mul_f32_e32 v205, v205, v205
	v_cvt_pk_bf16_f32 v162, v204, v205
	v_cvt_pk_bf16_f32 v163, v202, v203
	global_store_dwordx4 v[200:201], v[160:163], off offset:1024
	v_pk_mul_f32 v[202:203], v[114:115], v[176:177] op_sel_hi:[1,0]
	v_pk_mul_f32 v[204:205], v[112:113], v[176:177] op_sel_hi:[1,0]
	v_pk_mul_f32 v[160:161], v[122:123], v[176:177] op_sel_hi:[1,0]
	v_pk_mul_f32 v[162:163], v[120:121], v[176:177] op_sel_hi:[1,0]
	v_max_f32_e32 v160, 0, v160
	v_mul_f32_e32 v206, v160, v160
	v_max_f32_e32 v160, 0, v202
	v_mul_f32_e32 v202, v160, v160
	v_max_f32_e32 v160, 0, v161
	v_max_f32_e32 v162, 0, v162
	v_max_f32_e32 v163, 0, v163
	v_mul_f32_e32 v161, v160, v160
	v_max_f32_e32 v160, 0, v203
	v_mul_f32_e32 v162, v162, v162
	v_max_f32_e32 v204, 0, v204
	v_mul_f32_e32 v163, v163, v163
	v_max_f32_e32 v205, 0, v205
	v_mul_f32_e32 v203, v160, v160
	v_cvt_pk_bf16_f32 v160, v162, v163
	v_cvt_pk_bf16_f32 v161, v206, v161
	v_mul_f32_e32 v204, v204, v204
	v_mul_f32_e32 v205, v205, v205
	v_cvt_pk_bf16_f32 v162, v204, v205
	v_cvt_pk_bf16_f32 v163, v202, v203
	global_store_dwordx4 v164, v[160:163], s[0:1] offset:2048
	v_pk_mul_f32 v[202:203], v[118:119], v[176:177] op_sel_hi:[1,0]
	v_pk_mul_f32 v[204:205], v[116:117], v[176:177] op_sel_hi:[1,0]
	v_pk_mul_f32 v[160:161], v[126:127], v[176:177] op_sel_hi:[1,0]
	v_pk_mul_f32 v[162:163], v[124:125], v[176:177] op_sel_hi:[1,0]
	v_max_f32_e32 v160, 0, v160
	v_mul_f32_e32 v206, v160, v160
	v_max_f32_e32 v160, 0, v202
	v_mul_f32_e32 v202, v160, v160
	v_max_f32_e32 v160, 0, v161
	v_max_f32_e32 v162, 0, v162
	v_max_f32_e32 v163, 0, v163
	v_mul_f32_e32 v161, v160, v160
	v_max_f32_e32 v160, 0, v203
	v_mul_f32_e32 v162, v162, v162
	v_max_f32_e32 v204, 0, v204
	v_mul_f32_e32 v163, v163, v163
	v_max_f32_e32 v205, 0, v205
	v_mul_f32_e32 v203, v160, v160
	v_cvt_pk_bf16_f32 v160, v162, v163
	v_cvt_pk_bf16_f32 v161, v206, v161
	v_mul_f32_e32 v204, v204, v204
	v_mul_f32_e32 v205, v205, v205
	v_cvt_pk_bf16_f32 v162, v204, v205
	v_cvt_pk_bf16_f32 v163, v202, v203
	global_store_dwordx4 v[200:201], v[160:163], off offset:2048
	v_pk_mul_f32 v[200:201], v[98:99], v[174:175] op_sel_hi:[1,0]
	v_pk_mul_f32 v[202:203], v[96:97], v[174:175] op_sel_hi:[1,0]
	v_pk_mul_f32 v[160:161], v[106:107], v[174:175] op_sel_hi:[1,0]
	v_pk_mul_f32 v[162:163], v[104:105], v[174:175] op_sel_hi:[1,0]
	v_max_f32_e32 v160, 0, v160
	v_mul_f32_e32 v204, v160, v160
	v_max_f32_e32 v160, 0, v200
	v_mul_f32_e32 v200, v160, v160
	v_max_f32_e32 v160, 0, v161
	v_max_f32_e32 v162, 0, v162
	v_max_f32_e32 v163, 0, v163
	v_mul_f32_e32 v161, v160, v160
	v_max_f32_e32 v160, 0, v201
	v_mul_f32_e32 v162, v162, v162
	v_max_f32_e32 v202, 0, v202
	v_mul_f32_e32 v163, v163, v163
	v_max_f32_e32 v203, 0, v203
	v_mul_f32_e32 v201, v160, v160
	v_cvt_pk_bf16_f32 v160, v162, v163
	v_cvt_pk_bf16_f32 v161, v204, v161
	v_mul_f32_e32 v202, v202, v202
	v_mul_f32_e32 v203, v203, v203
	v_cvt_pk_bf16_f32 v162, v202, v203
	v_cvt_pk_bf16_f32 v163, v200, v201
	global_store_dwordx4 v164, v[160:163], s[0:1] offset:3072
	v_pk_mul_f32 v[200:201], v[102:103], v[174:175] op_sel_hi:[1,0]
	v_pk_mul_f32 v[202:203], v[100:101], v[174:175] op_sel_hi:[1,0]
	v_pk_mul_f32 v[160:161], v[110:111], v[174:175] op_sel_hi:[1,0]
	v_pk_mul_f32 v[162:163], v[108:109], v[174:175] op_sel_hi:[1,0]
	v_max_f32_e32 v160, 0, v160
	v_mul_f32_e32 v204, v160, v160
	v_max_f32_e32 v160, 0, v200
	v_max_f32_e32 v162, 0, v162
	v_max_f32_e32 v163, 0, v163
	v_mul_f32_e32 v200, v160, v160
	v_max_f32_e32 v160, 0, v161
	v_mul_f32_e32 v162, v162, v162
	v_max_f32_e32 v202, 0, v202
	v_mul_f32_e32 v163, v163, v163
	v_max_f32_e32 v203, 0, v203
	v_mul_f32_e32 v161, v160, v160
	v_max_f32_e32 v160, 0, v201
	v_mul_f32_e32 v202, v202, v202
	v_mul_f32_e32 v203, v203, v203
	v_mul_f32_e32 v201, v160, v160
	v_cvt_pk_bf16_f32 v160, v162, v163
	v_cvt_pk_bf16_f32 v161, v204, v161
	v_cvt_pk_bf16_f32 v162, v202, v203
	v_cvt_pk_bf16_f32 v163, v200, v201
	v_add_u32_e32 v164, 0x80c00, v164
	s_cbranch_execnz .LBB0_525

.LBB0_560:
	v_and_b32_e32 v2, 15, v0
	s_bfe_u32 s66, s86, 0x30003
	v_and_b32_e32 v3, 48, v0
	v_lshlrev_b32_e32 v134, 4, v135
	v_and_b32_e32 v5, 32, v0
	s_movk_i32 s37, 0x3f0
	v_lshlrev_b32_e32 v2, 6, v2
	v_lshlrev_b32_e32 v9, 2, v0
	s_lshl_b32 s36, s66, 14
	v_bitop3_b32 v155, v134, v5, s37 bitop3:0x6c
	v_and_b32_e32 v6, 64, v135
	s_add_i32 s67, s20, -2
	v_or_b32_e32 v8, v2, v3
	v_and_b32_e32 v9, 32, v9
	s_mov_b32 s37, 0x14000
	v_lshlrev_b32_e32 v0, 6, v0
	v_and_b32_e32 v4, 0x3f0, v134
	v_lshlrev_b32_e32 v156, 13, v6
	v_lshlrev_b32_e32 v7, 3, v135
	v_mul_i32_i24_e32 v6, 0xffffe800, v6
	v_bitop3_b32 v11, v8, s37, v9 bitop3:0xde
	s_mov_b32 s37, 0x1c000
	v_and_b32_e32 v0, 0x3c0, v0
	s_add_u32 s68, s72, s36
	v_and_b32_e32 v157, 0xfffffc00, v7
	v_bitop3_b32 v2, v2, v9, v3 bitop3:0x36
	v_bitop3_b32 v10, v8, s76, v9 bitop3:0xde
	v_bitop3_b32 v12, v8, s77, v9 bitop3:0xde
	v_bitop3_b32 v8, v8, s37, v9 bitop3:0xde
	v_bitop3_b32 v3, v0, v9, v3 bitop3:0x36
	v_bitop3_b32 v0, v6, v4, v5 bitop3:0xf6
	s_addc_u32 s69, s73, 0
	s_lshl_b32 s36, s86, 11
	s_and_b32 s37, s86, 7
	v_add3_u32 v128, v0, v156, v157
	s_and_b32 s36, s36, 0x60000
	s_lshl_b32 s37, s37, 14
	v_lshlrev_b32_e32 v13, 13, v1
	v_lshl_add_u64 v[0:1], s[68:69], 0, v[128:129]
	s_mov_b64 s[68:69], 0xc3000
	s_or_b32 s36, s36, s37
	v_lshl_add_u64 v[130:131], v[0:1], 0, s[68:69]
	v_bitop3_b32 v0, v4, v156, v5 bitop3:0xde
	s_add_u32 s68, s70, s36
	v_add_u32_e32 v128, v0, v157
	s_addc_u32 s69, s71, 0
	v_lshlrev_b32_e32 v7, 6, v135
	v_lshl_add_u64 v[0:1], s[68:69], 0, v[128:129]
	s_mov_b64 s[68:69], 0x301000
	v_and_b32_e32 v7, 0x3000, v7
	v_or_b32_e32 v9, 0x800, v13
	v_or_b32_e32 v14, 0x1000, v13
	v_or_b32_e32 v15, 0x1800, v13
	v_lshl_add_u64 v[132:133], v[0:1], 0, s[68:69]
	v_mov_b32_e32 v0, 0
	s_mov_b32 s68, 0
	v_add_u32_e32 v161, v10, v7
	v_add_u32_e32 v152, v2, v13
	v_add_u32_e32 v151, v3, v9
	v_add_u32_e32 v150, v3, v14
	v_add_u32_e32 v149, v3, v15
	v_add_u32_e32 v160, 0xc000, v134
	v_add_u32_e32 v159, 0xe000, v134
	v_add_u32_e32 v158, v11, v7
	v_add_u32_e32 v148, 0x10000, v134
	v_add_u32_e32 v147, 0x12000, v134
	v_add_u32_e32 v146, 0x2000, v134
	v_add_u32_e32 v145, 0x14000, v134
	v_add_u32_e32 v144, 0x16000, v134
	v_add_u32_e32 v154, v12, v7
	v_add_u32_e32 v143, 0x4000, v134
	v_add_u32_e32 v142, 0x6000, v134
	v_add_u32_e32 v153, v8, v7
	v_add_u32_e32 v141, 0x18000, v134
	v_add_u32_e32 v140, 0x1a000, v134
	v_add_u32_e32 v139, 0x8000, v134
	v_add_u32_e32 v138, 0xa000, v134
	v_add_u32_e32 v137, 0x1c000, v134
	v_add_u32_e32 v136, 0x1e000, v134
	v_mov_b32_e32 v1, v0
	v_mov_b32_e32 v2, v0
	v_mov_b32_e32 v3, v0
	v_mov_b32_e32 v4, v0
	v_mov_b32_e32 v5, v0
	v_mov_b32_e32 v6, v0
	v_mov_b32_e32 v7, v0
	v_mov_b32_e32 v8, v0
	v_mov_b32_e32 v9, v0
	v_mov_b32_e32 v10, v0
	v_mov_b32_e32 v11, v0
	v_mov_b32_e32 v12, v0
	v_mov_b32_e32 v13, v0
	v_mov_b32_e32 v14, v0
	v_mov_b32_e32 v15, v0
	v_mov_b32_e32 v16, v0
	v_mov_b32_e32 v17, v0
	v_mov_b32_e32 v18, v0
	v_mov_b32_e32 v19, v0
	v_mov_b32_e32 v20, v0
	v_mov_b32_e32 v21, v0
	v_mov_b32_e32 v22, v0
	v_mov_b32_e32 v23, v0
	v_mov_b32_e32 v24, v0
	v_mov_b32_e32 v25, v0
	v_mov_b32_e32 v26, v0
	v_mov_b32_e32 v27, v0
	v_mov_b32_e32 v28, v0
	v_mov_b32_e32 v29, v0
	v_mov_b32_e32 v30, v0
	v_mov_b32_e32 v31, v0
	v_mov_b32_e32 v32, v0
	v_mov_b32_e32 v33, v0
	v_mov_b32_e32 v34, v0
	v_mov_b32_e32 v35, v0
	v_mov_b32_e32 v36, v0
	v_mov_b32_e32 v37, v0
	v_mov_b32_e32 v38, v0
	v_mov_b32_e32 v39, v0
	v_mov_b32_e32 v40, v0
	v_mov_b32_e32 v41, v0
	v_mov_b32_e32 v42, v0
	v_mov_b32_e32 v43, v0
	v_mov_b32_e32 v44, v0
	v_mov_b32_e32 v45, v0
	v_mov_b32_e32 v46, v0
	v_mov_b32_e32 v47, v0
	v_mov_b32_e32 v48, v0
	v_mov_b32_e32 v49, v0
	v_mov_b32_e32 v50, v0
	v_mov_b32_e32 v51, v0
	v_mov_b32_e32 v52, v0
	v_mov_b32_e32 v53, v0
	v_mov_b32_e32 v54, v0
	v_mov_b32_e32 v55, v0
	v_mov_b32_e32 v56, v0
	v_mov_b32_e32 v57, v0
	v_mov_b32_e32 v58, v0
	v_mov_b32_e32 v59, v0
	v_mov_b32_e32 v60, v0
	v_mov_b32_e32 v61, v0
	v_mov_b32_e32 v62, v0
	v_mov_b32_e32 v63, v0
	v_mov_b32_e32 v64, v0
	v_mov_b32_e32 v65, v0
	v_mov_b32_e32 v66, v0
	v_mov_b32_e32 v67, v0
	v_mov_b32_e32 v68, v0
	v_mov_b32_e32 v69, v0
	v_mov_b32_e32 v70, v0
	v_mov_b32_e32 v71, v0
	v_mov_b32_e32 v72, v0
	v_mov_b32_e32 v73, v0
	v_mov_b32_e32 v74, v0
	v_mov_b32_e32 v75, v0
	v_mov_b32_e32 v76, v0
	v_mov_b32_e32 v77, v0
	v_mov_b32_e32 v78, v0
	v_mov_b32_e32 v79, v0
	v_mov_b32_e32 v80, v0
	v_mov_b32_e32 v81, v0
	v_mov_b32_e32 v82, v0
	v_mov_b32_e32 v83, v0
	v_mov_b32_e32 v84, v0
	v_mov_b32_e32 v85, v0
	v_mov_b32_e32 v86, v0
	v_mov_b32_e32 v87, v0
	v_mov_b32_e32 v88, v0
	v_mov_b32_e32 v89, v0
	v_mov_b32_e32 v90, v0
	v_mov_b32_e32 v91, v0
	v_mov_b32_e32 v92, v0
	v_mov_b32_e32 v93, v0
	v_mov_b32_e32 v94, v0
	v_mov_b32_e32 v95, v0
	v_mov_b32_e32 v96, v0
	v_mov_b32_e32 v97, v0
	v_mov_b32_e32 v98, v0
	v_mov_b32_e32 v99, v0
	v_mov_b32_e32 v100, v0
	v_mov_b32_e32 v101, v0
	v_mov_b32_e32 v102, v0
	v_mov_b32_e32 v103, v0
	v_mov_b32_e32 v104, v0
	v_mov_b32_e32 v105, v0
	v_mov_b32_e32 v106, v0
	v_mov_b32_e32 v107, v0
	v_mov_b32_e32 v108, v0
	v_mov_b32_e32 v109, v0
	v_mov_b32_e32 v110, v0
	v_mov_b32_e32 v111, v0
	v_mov_b32_e32 v112, v0
	v_mov_b32_e32 v113, v0
	v_mov_b32_e32 v114, v0
	v_mov_b32_e32 v115, v0
	v_mov_b32_e32 v116, v0
	v_mov_b32_e32 v117, v0
	v_mov_b32_e32 v118, v0
	v_mov_b32_e32 v119, v0
	v_mov_b32_e32 v120, v0
	v_mov_b32_e32 v121, v0
	v_mov_b32_e32 v122, v0
	v_mov_b32_e32 v123, v0
	v_mov_b32_e32 v124, v0
	v_mov_b32_e32 v125, v0
	v_mov_b32_e32 v126, v0
	v_mov_b32_e32 v127, v0
	s_barrier
	v_readlane_b32 s98, v242, 1
	s_lshl_b32 s98, s98, 10
	s_add_i32 s36, s98, 0xc000
	v_lshl_add_u64 v[164:165], v[132:133], 0, s[22:23]
	s_mov_b32 m0, s36
	s_add_i32 s36, s98, 0xe000
	global_load_lds_dwordx4 v[164:165], off
	v_lshl_add_u64 v[164:165], v[132:133], 0, s[24:25]
	s_mov_b32 m0, s36
	s_nop 0
	global_load_lds_dwordx4 v[164:165], off
.LBB0_561:
	ds_read_b128 v[162:165], v161
	ds_read_b128 v[166:169], v161 offset:1024
	ds_read_b128 v[170:173], v161 offset:2048
	ds_read_b128 v[174:177], v161 offset:3072
	ds_read_b128 v[178:181], v152
	ds_read_b128 v[182:185], v152 offset:1024
	ds_read_b128 v[186:189], v151
	ds_read_b128 v[190:193], v151 offset:1024
	ds_read_b128 v[194:197], v150
	ds_read_b128 v[198:201], v150 offset:1024
	ds_read_b128 v[202:205], v149
	ds_read_b128 v[206:209], v149 offset:1024
	s_waitcnt lgkmcnt(8)
	s_waitcnt vmcnt(10)
	s_barrier
	s_waitcnt lgkmcnt(0)
	s_waitcnt lgkmcnt(0)
	v_mfma_f32_16x16x32_bf16 v[124:127], v[162:165], v[178:181], v[124:127]
	v_mfma_f32_16x16x32_bf16 v[120:123], v[170:173], v[178:181], v[120:123]
	v_mfma_f32_16x16x32_bf16 v[116:119], v[162:165], v[186:189], v[116:119]
	v_mfma_f32_16x16x32_bf16 v[112:115], v[170:173], v[186:189], v[112:115]
	v_mfma_f32_16x16x32_bf16 v[108:111], v[162:165], v[194:197], v[108:111]
	v_mfma_f32_16x16x32_bf16 v[104:107], v[170:173], v[194:197], v[104:107]
	v_mfma_f32_16x16x32_bf16 v[100:103], v[162:165], v[202:205], v[100:103]
	v_mfma_f32_16x16x32_bf16 v[96:99], v[170:173], v[202:205], v[96:99]
	v_mfma_f32_16x16x32_bf16 v[124:127], v[166:169], v[182:185], v[124:127]
	v_mfma_f32_16x16x32_bf16 v[120:123], v[174:177], v[182:185], v[120:123]
	v_mfma_f32_16x16x32_bf16 v[116:119], v[166:169], v[190:193], v[116:119]
	v_mfma_f32_16x16x32_bf16 v[112:115], v[174:177], v[190:193], v[112:115]
	v_mfma_f32_16x16x32_bf16 v[108:111], v[166:169], v[198:201], v[108:111]
	v_mfma_f32_16x16x32_bf16 v[104:107], v[174:177], v[198:201], v[104:107]
	v_mfma_f32_16x16x32_bf16 v[100:103], v[166:169], v[206:209], v[100:103]
	v_mfma_f32_16x16x32_bf16 v[96:99], v[174:177], v[206:209], v[96:99]
	s_barrier
	s_add_i32 s36, s98, 0x10000
	v_lshl_add_u64 v[226:227], v[130:131], 0, s[26:27]
	s_mov_b32 m0, s36
	s_add_i32 s36, s98, 0x12000
	ds_read_b128 v[210:213], v158
	ds_read_b128 v[214:217], v158 offset:1024
	ds_read_b128 v[218:221], v158 offset:2048
	ds_read_b128 v[222:225], v158 offset:3072
	global_load_lds_dwordx4 v[226:227], off
	v_lshl_add_u64 v[226:227], v[130:131], 0, s[28:29]
	s_mov_b32 m0, s36
	s_add_i32 s68, s68, 2
	global_load_lds_dwordx4 v[226:227], off
	s_mov_b32 s36, s98
	v_lshl_add_u64 v[226:227], v[132:133], 0, s[30:31]
	s_mov_b32 m0, s36
	s_add_i32 s36, s98, 0x2000
	global_load_lds_dwordx4 v[226:227], off
	v_lshl_add_u64 v[226:227], v[132:133], 0, s[34:35]
	s_mov_b32 m0, s36
	s_nop 0
	global_load_lds_dwordx4 v[226:227], off
	s_waitcnt vmcnt(12)
	s_barrier
	s_waitcnt lgkmcnt(0)
	s_waitcnt lgkmcnt(0)
	v_mfma_f32_16x16x32_bf16 v[92:95], v[210:213], v[178:181], v[92:95]
	v_mfma_f32_16x16x32_bf16 v[88:91], v[218:221], v[178:181], v[88:91]
	v_mfma_f32_16x16x32_bf16 v[84:87], v[210:213], v[186:189], v[84:87]
	v_mfma_f32_16x16x32_bf16 v[80:83], v[218:221], v[186:189], v[80:83]
	v_mfma_f32_16x16x32_bf16 v[76:79], v[210:213], v[194:197], v[76:79]
	v_mfma_f32_16x16x32_bf16 v[72:75], v[218:221], v[194:197], v[72:75]
	v_mfma_f32_16x16x32_bf16 v[68:71], v[210:213], v[202:205], v[68:71]
	v_mfma_f32_16x16x32_bf16 v[64:67], v[218:221], v[202:205], v[64:67]
	v_mfma_f32_16x16x32_bf16 v[92:95], v[214:217], v[182:185], v[92:95]
	v_mfma_f32_16x16x32_bf16 v[88:91], v[222:225], v[182:185], v[88:91]
	v_mfma_f32_16x16x32_bf16 v[84:87], v[214:217], v[190:193], v[84:87]
	v_mfma_f32_16x16x32_bf16 v[80:83], v[222:225], v[190:193], v[80:83]
	v_mfma_f32_16x16x32_bf16 v[76:79], v[214:217], v[198:201], v[76:79]
	v_mfma_f32_16x16x32_bf16 v[72:75], v[222:225], v[198:201], v[72:75]
	v_mfma_f32_16x16x32_bf16 v[68:71], v[214:217], v[206:209], v[68:71]
	v_mfma_f32_16x16x32_bf16 v[64:67], v[222:225], v[206:209], v[64:67]
	s_barrier
	ds_read_b128 v[178:181], v152 offset:16384
	ds_read_b128 v[182:185], v152 offset:17408
	ds_read_b128 v[186:189], v151 offset:16384
	ds_read_b128 v[190:193], v151 offset:17408
	ds_read_b128 v[194:197], v150 offset:16384
	ds_read_b128 v[198:201], v150 offset:17408
	ds_read_b128 v[202:205], v149 offset:16384
	ds_read_b128 v[206:209], v149 offset:17408
	s_add_i32 s36, s98, 0x14000
	v_lshl_add_u64 v[226:227], v[130:131], 0, s[38:39]
	s_mov_b32 m0, s36
	s_add_i32 s36, s98, 0x16000
	global_load_lds_dwordx4 v[226:227], off
	v_lshl_add_u64 v[226:227], v[130:131], 0, s[44:45]
	s_mov_b32 m0, s36
	s_nop 0
	global_load_lds_dwordx4 v[226:227], off
	s_barrier
	s_waitcnt lgkmcnt(0)
	s_waitcnt lgkmcnt(0)
	v_mfma_f32_16x16x32_bf16 v[60:63], v[162:165], v[178:181], v[60:63]
	v_mfma_f32_16x16x32_bf16 v[56:59], v[170:173], v[178:181], v[56:59]
	v_mfma_f32_16x16x32_bf16 v[52:55], v[162:165], v[186:189], v[52:55]
	v_mfma_f32_16x16x32_bf16 v[48:51], v[170:173], v[186:189], v[48:51]
	v_mfma_f32_16x16x32_bf16 v[44:47], v[162:165], v[194:197], v[44:47]
	v_mfma_f32_16x16x32_bf16 v[40:43], v[170:173], v[194:197], v[40:43]
	v_mfma_f32_16x16x32_bf16 v[36:39], v[162:165], v[202:205], v[36:39]
	v_mfma_f32_16x16x32_bf16 v[32:35], v[170:173], v[202:205], v[32:35]
	v_mfma_f32_16x16x32_bf16 v[60:63], v[166:169], v[182:185], v[60:63]
	v_mfma_f32_16x16x32_bf16 v[56:59], v[174:177], v[182:185], v[56:59]
	v_mfma_f32_16x16x32_bf16 v[52:55], v[166:169], v[190:193], v[52:55]
	v_mfma_f32_16x16x32_bf16 v[48:51], v[174:177], v[190:193], v[48:51]
	v_mfma_f32_16x16x32_bf16 v[44:47], v[166:169], v[198:201], v[44:47]
	v_mfma_f32_16x16x32_bf16 v[40:43], v[174:177], v[198:201], v[40:43]
	v_mfma_f32_16x16x32_bf16 v[36:39], v[166:169], v[206:209], v[36:39]
	v_mfma_f32_16x16x32_bf16 v[32:35], v[174:177], v[206:209], v[32:35]
	s_barrier
	s_add_i32 s36, s98, 0x4000
	v_lshl_add_u64 v[164:165], v[132:133], 0, s[46:47]
	s_mov_b32 m0, s36
	s_add_i32 s36, s98, 0x6000
	global_load_lds_dwordx4 v[164:165], off
	v_lshl_add_u64 v[164:165], v[132:133], 0, s[50:51]
	s_mov_b32 m0, s36
	s_nop 0
	global_load_lds_dwordx4 v[164:165], off
	s_waitcnt vmcnt(12)
	s_barrier
	v_mfma_f32_16x16x32_bf16 v[28:31], v[210:213], v[178:181], v[28:31]
	v_mfma_f32_16x16x32_bf16 v[24:27], v[218:221], v[178:181], v[24:27]
	v_mfma_f32_16x16x32_bf16 v[20:23], v[210:213], v[186:189], v[20:23]
	v_mfma_f32_16x16x32_bf16 v[16:19], v[218:221], v[186:189], v[16:19]
	v_mfma_f32_16x16x32_bf16 v[12:15], v[210:213], v[194:197], v[12:15]
	v_mfma_f32_16x16x32_bf16 v[8:11], v[218:221], v[194:197], v[8:11]
	v_mfma_f32_16x16x32_bf16 v[4:7], v[210:213], v[202:205], v[4:7]
	v_mfma_f32_16x16x32_bf16 v[0:3], v[218:221], v[202:205], v[0:3]
	v_mfma_f32_16x16x32_bf16 v[28:31], v[214:217], v[182:185], v[28:31]
	v_mfma_f32_16x16x32_bf16 v[24:27], v[222:225], v[182:185], v[24:27]
	v_mfma_f32_16x16x32_bf16 v[20:23], v[214:217], v[190:193], v[20:23]
	v_mfma_f32_16x16x32_bf16 v[16:19], v[222:225], v[190:193], v[16:19]
	v_mfma_f32_16x16x32_bf16 v[12:15], v[214:217], v[198:201], v[12:15]
	v_mfma_f32_16x16x32_bf16 v[8:11], v[222:225], v[198:201], v[8:11]
	v_mfma_f32_16x16x32_bf16 v[4:7], v[214:217], v[206:209], v[4:7]
	v_mfma_f32_16x16x32_bf16 v[0:3], v[222:225], v[206:209], v[0:3]
	s_barrier
	ds_read_b128 v[162:165], v154
	ds_read_b128 v[166:169], v154 offset:1024
	ds_read_b128 v[170:173], v154 offset:2048
	ds_read_b128 v[174:177], v154 offset:3072
	ds_read_b128 v[178:181], v152 offset:32768
	ds_read_b128 v[182:185], v152 offset:33792
	ds_read_b128 v[186:189], v151 offset:32768
	ds_read_b128 v[190:193], v151 offset:33792
	ds_read_b128 v[194:197], v150 offset:32768
	ds_read_b128 v[198:201], v150 offset:33792
	ds_read_b128 v[202:205], v149 offset:32768
	ds_read_b128 v[206:209], v149 offset:33792
	s_waitcnt lgkmcnt(8)
	s_waitcnt vmcnt(10)
	s_barrier
	s_waitcnt lgkmcnt(0)
	s_waitcnt lgkmcnt(0)
	v_mfma_f32_16x16x32_bf16 v[124:127], v[162:165], v[178:181], v[124:127]
	v_mfma_f32_16x16x32_bf16 v[120:123], v[170:173], v[178:181], v[120:123]
	v_mfma_f32_16x16x32_bf16 v[116:119], v[162:165], v[186:189], v[116:119]
	v_mfma_f32_16x16x32_bf16 v[112:115], v[170:173], v[186:189], v[112:115]
	v_mfma_f32_16x16x32_bf16 v[108:111], v[162:165], v[194:197], v[108:111]
	v_mfma_f32_16x16x32_bf16 v[104:107], v[170:173], v[194:197], v[104:107]
	v_mfma_f32_16x16x32_bf16 v[100:103], v[162:165], v[202:205], v[100:103]
	v_mfma_f32_16x16x32_bf16 v[96:99], v[170:173], v[202:205], v[96:99]
	v_mfma_f32_16x16x32_bf16 v[124:127], v[166:169], v[182:185], v[124:127]
	v_mfma_f32_16x16x32_bf16 v[120:123], v[174:177], v[182:185], v[120:123]
	v_mfma_f32_16x16x32_bf16 v[116:119], v[166:169], v[190:193], v[116:119]
	v_mfma_f32_16x16x32_bf16 v[112:115], v[174:177], v[190:193], v[112:115]
	v_mfma_f32_16x16x32_bf16 v[108:111], v[166:169], v[198:201], v[108:111]
	v_mfma_f32_16x16x32_bf16 v[104:107], v[174:177], v[198:201], v[104:107]
	v_mfma_f32_16x16x32_bf16 v[100:103], v[166:169], v[206:209], v[100:103]
	v_mfma_f32_16x16x32_bf16 v[96:99], v[174:177], v[206:209], v[96:99]
	s_barrier
	s_add_i32 s36, s98, 0x18000
	v_lshl_add_u64 v[226:227], v[130:131], 0, s[56:57]
	s_mov_b32 m0, s36
	s_add_i32 s36, s98, 0x1a000
	ds_read_b128 v[210:213], v153
	ds_read_b128 v[214:217], v153 offset:1024
	ds_read_b128 v[218:221], v153 offset:2048
	ds_read_b128 v[222:225], v153 offset:3072
	global_load_lds_dwordx4 v[226:227], off
	v_lshl_add_u64 v[226:227], v[130:131], 0, s[58:59]
	s_mov_b32 m0, s36
	s_nop 0
	global_load_lds_dwordx4 v[226:227], off
	s_add_i32 s36, s98, 0x8000
	v_lshl_add_u64 v[226:227], v[132:133], 0, s[60:61]
	s_mov_b32 m0, s36
	s_add_i32 s36, s98, 0xa000
	global_load_lds_dwordx4 v[226:227], off
	s_mov_b32 m0, s36
	s_nop 0
	global_load_lds_dwordx4 v[132:133], off
	s_waitcnt vmcnt(12)
	s_barrier
	s_waitcnt lgkmcnt(0)
	s_waitcnt lgkmcnt(0)
	v_mfma_f32_16x16x32_bf16 v[92:95], v[210:213], v[178:181], v[92:95]
	v_mfma_f32_16x16x32_bf16 v[88:91], v[218:221], v[178:181], v[88:91]
	v_mfma_f32_16x16x32_bf16 v[84:87], v[210:213], v[186:189], v[84:87]
	v_mfma_f32_16x16x32_bf16 v[80:83], v[218:221], v[186:189], v[80:83]
	v_mfma_f32_16x16x32_bf16 v[76:79], v[210:213], v[194:197], v[76:79]
	v_mfma_f32_16x16x32_bf16 v[72:75], v[218:221], v[194:197], v[72:75]
	v_mfma_f32_16x16x32_bf16 v[68:71], v[210:213], v[202:205], v[68:71]
	v_mfma_f32_16x16x32_bf16 v[64:67], v[218:221], v[202:205], v[64:67]
	v_mfma_f32_16x16x32_bf16 v[92:95], v[214:217], v[182:185], v[92:95]
	v_mfma_f32_16x16x32_bf16 v[88:91], v[222:225], v[182:185], v[88:91]
	v_mfma_f32_16x16x32_bf16 v[84:87], v[214:217], v[190:193], v[84:87]
	v_mfma_f32_16x16x32_bf16 v[80:83], v[222:225], v[190:193], v[80:83]
	v_mfma_f32_16x16x32_bf16 v[76:79], v[214:217], v[198:201], v[76:79]
	v_mfma_f32_16x16x32_bf16 v[72:75], v[222:225], v[198:201], v[72:75]
	v_mfma_f32_16x16x32_bf16 v[68:71], v[214:217], v[206:209], v[68:71]
	v_mfma_f32_16x16x32_bf16 v[64:67], v[222:225], v[206:209], v[64:67]
	s_barrier
	ds_read_b128 v[178:181], v152 offset:49152
	ds_read_b128 v[182:185], v152 offset:50176
	ds_read_b128 v[186:189], v151 offset:49152
	ds_read_b128 v[190:193], v151 offset:50176
	ds_read_b128 v[194:197], v150 offset:49152
	ds_read_b128 v[198:201], v150 offset:50176
	ds_read_b128 v[202:205], v149 offset:49152
	ds_read_b128 v[206:209], v149 offset:50176
	s_add_i32 s36, s98, 0x1c000
	v_lshl_add_u64 v[226:227], v[130:131], 0, s[60:61]
	s_mov_b32 m0, s36
	s_add_i32 s36, s98, 0x1e000
	global_load_lds_dwordx4 v[226:227], off
	s_mov_b32 m0, s36
	s_nop 0
	global_load_lds_dwordx4 v[130:131], off
	s_barrier
	s_waitcnt lgkmcnt(0)
	s_waitcnt lgkmcnt(0)
	v_mfma_f32_16x16x32_bf16 v[60:63], v[162:165], v[178:181], v[60:63]
	v_mfma_f32_16x16x32_bf16 v[56:59], v[170:173], v[178:181], v[56:59]
	v_mfma_f32_16x16x32_bf16 v[52:55], v[162:165], v[186:189], v[52:55]
	v_mfma_f32_16x16x32_bf16 v[48:51], v[170:173], v[186:189], v[48:51]
	v_mfma_f32_16x16x32_bf16 v[44:47], v[162:165], v[194:197], v[44:47]
	v_mfma_f32_16x16x32_bf16 v[40:43], v[170:173], v[194:197], v[40:43]
	v_mfma_f32_16x16x32_bf16 v[36:39], v[162:165], v[202:205], v[36:39]
	v_mfma_f32_16x16x32_bf16 v[32:35], v[170:173], v[202:205], v[32:35]
	v_mfma_f32_16x16x32_bf16 v[60:63], v[166:169], v[182:185], v[60:63]
	v_mfma_f32_16x16x32_bf16 v[56:59], v[174:177], v[182:185], v[56:59]
	v_mfma_f32_16x16x32_bf16 v[52:55], v[166:169], v[190:193], v[52:55]
	v_mfma_f32_16x16x32_bf16 v[48:51], v[174:177], v[190:193], v[48:51]
	v_mfma_f32_16x16x32_bf16 v[44:47], v[166:169], v[198:201], v[44:47]
	v_mfma_f32_16x16x32_bf16 v[40:43], v[174:177], v[198:201], v[40:43]
	v_mfma_f32_16x16x32_bf16 v[36:39], v[166:169], v[206:209], v[36:39]
	v_mfma_f32_16x16x32_bf16 v[32:35], v[174:177], v[206:209], v[32:35]
	s_barrier
	v_lshl_add_u64 v[132:133], v[132:133], 0, s[64:65]
	s_add_i32 s36, s98, 0xc000
	v_lshl_add_u64 v[164:165], v[132:133], 0, s[22:23]
	s_mov_b32 m0, s36
	s_add_i32 s36, s98, 0xe000
	global_load_lds_dwordx4 v[164:165], off
	v_lshl_add_u64 v[164:165], v[132:133], 0, s[24:25]
	s_mov_b32 m0, s36
	s_nop 0
	global_load_lds_dwordx4 v[164:165], off
	s_waitcnt vmcnt(12)
	s_barrier
	v_mfma_f32_16x16x32_bf16 v[28:31], v[210:213], v[178:181], v[28:31]
	v_mfma_f32_16x16x32_bf16 v[24:27], v[218:221], v[178:181], v[24:27]
	v_mfma_f32_16x16x32_bf16 v[20:23], v[210:213], v[186:189], v[20:23]
	v_mfma_f32_16x16x32_bf16 v[16:19], v[218:221], v[186:189], v[16:19]
	v_mfma_f32_16x16x32_bf16 v[12:15], v[210:213], v[194:197], v[12:15]
	v_mfma_f32_16x16x32_bf16 v[8:11], v[218:221], v[194:197], v[8:11]
	v_mfma_f32_16x16x32_bf16 v[4:7], v[210:213], v[202:205], v[4:7]
	v_mfma_f32_16x16x32_bf16 v[0:3], v[218:221], v[202:205], v[0:3]
	v_mfma_f32_16x16x32_bf16 v[28:31], v[214:217], v[182:185], v[28:31]
	v_mfma_f32_16x16x32_bf16 v[24:27], v[222:225], v[182:185], v[24:27]
	v_mfma_f32_16x16x32_bf16 v[20:23], v[214:217], v[190:193], v[20:23]
	v_mfma_f32_16x16x32_bf16 v[16:19], v[222:225], v[190:193], v[16:19]
	v_mfma_f32_16x16x32_bf16 v[12:15], v[214:217], v[198:201], v[12:15]
	v_mfma_f32_16x16x32_bf16 v[8:11], v[222:225], v[198:201], v[8:11]
	v_mfma_f32_16x16x32_bf16 v[4:7], v[214:217], v[206:209], v[4:7]
	v_mfma_f32_16x16x32_bf16 v[0:3], v[222:225], v[206:209], v[0:3]
	v_lshl_add_u64 v[130:131], v[130:131], 0, s[62:63]
	s_cmp_lt_u32 s68, s67
	s_barrier
	s_cbranch_scc1 .LBB0_561
	s_lshl_b32 s36, s86, 5
	s_lshl_b32 s37, s86, 8
	s_and_b32 s36, s36, 0x1800
	s_and_b32 s37, s37, 0x700
	s_or_b32 s96, s37, s36
	s_lshl_b32 s36, s96, 6
	s_add_u32 s36, s70, s36
	s_addc_u32 s37, s71, 0
	s_add_i32 s20, s20, -1
	s_lshl_b64 s[68:69], s[20:21], 20
	v_add_u32_e32 v128, v156, v157
	s_add_u32 s68, s36, s68
	v_or_b32_e32 v128, v128, v155
	s_addc_u32 s69, s37, s69
	v_lshl_add_u64 v[156:157], s[68:69], 0, v[128:129]
	v_readfirstlane_b32 s20, v160
	v_lshl_add_u64 v[206:207], v[156:157], 0, s[4:5]
	s_mov_b32 m0, s20
	v_readfirstlane_b32 s20, v159
	ds_read_b128 v[130:133], v161
	ds_read_b128 v[162:165], v161 offset:1024
	ds_read_b128 v[166:169], v161 offset:2048
	ds_read_b128 v[170:173], v161 offset:3072
	ds_read_b128 v[174:177], v152
	ds_read_b128 v[178:181], v152 offset:1024
	ds_read_b128 v[182:185], v151
	ds_read_b128 v[186:189], v151 offset:1024
	ds_read_b128 v[190:193], v150
	ds_read_b128 v[194:197], v150 offset:1024
	ds_read_b128 v[198:201], v149
	ds_read_b128 v[202:205], v149 offset:1024
	global_load_lds_dwordx4 v[206:207], off
	v_lshl_add_u64 v[156:157], v[156:157], 0, s[6:7]
	s_mov_b32 m0, s20
	s_nop 0
	global_load_lds_dwordx4 v[156:157], off
	s_waitcnt vmcnt(10)
	s_barrier
	s_waitcnt lgkmcnt(0)
	s_setprio 1
	s_waitcnt lgkmcnt(0)
	v_mfma_f32_16x16x32_bf16 v[124:127], v[130:133], v[174:177], v[124:127]
	v_mfma_f32_16x16x32_bf16 v[120:123], v[166:169], v[174:177], v[120:123]
	v_mfma_f32_16x16x32_bf16 v[116:119], v[130:133], v[182:185], v[116:119]
	v_mfma_f32_16x16x32_bf16 v[112:115], v[166:169], v[182:185], v[112:115]
	v_mfma_f32_16x16x32_bf16 v[108:111], v[130:133], v[190:193], v[108:111]
	v_mfma_f32_16x16x32_bf16 v[104:107], v[166:169], v[190:193], v[104:107]
	v_mfma_f32_16x16x32_bf16 v[100:103], v[130:133], v[198:201], v[100:103]
	v_mfma_f32_16x16x32_bf16 v[96:99], v[166:169], v[198:201], v[96:99]
	v_mfma_f32_16x16x32_bf16 v[124:127], v[162:165], v[178:181], v[124:127]
	v_mfma_f32_16x16x32_bf16 v[120:123], v[170:173], v[178:181], v[120:123]
	v_mfma_f32_16x16x32_bf16 v[116:119], v[162:165], v[186:189], v[116:119]
	v_mfma_f32_16x16x32_bf16 v[112:115], v[170:173], v[186:189], v[112:115]
	v_mfma_f32_16x16x32_bf16 v[108:111], v[162:165], v[194:197], v[108:111]
	v_mfma_f32_16x16x32_bf16 v[104:107], v[170:173], v[194:197], v[104:107]
	v_mfma_f32_16x16x32_bf16 v[100:103], v[162:165], v[202:205], v[100:103]
	v_mfma_f32_16x16x32_bf16 v[96:99], v[170:173], v[202:205], v[96:99]
	s_setprio 0
	s_barrier
	ds_read_b128 v[206:209], v158
	ds_read_b128 v[210:213], v158 offset:1024
	ds_read_b128 v[214:217], v158 offset:2048
	ds_read_b128 v[156:159], v158 offset:3072
	s_barrier
	s_waitcnt lgkmcnt(0)
	s_setprio 1
	s_waitcnt lgkmcnt(0)
	v_mfma_f32_16x16x32_bf16 v[92:95], v[206:209], v[174:177], v[92:95]
	v_mfma_f32_16x16x32_bf16 v[88:91], v[214:217], v[174:177], v[88:91]
	v_mfma_f32_16x16x32_bf16 v[84:87], v[206:209], v[182:185], v[84:87]
	v_mfma_f32_16x16x32_bf16 v[80:83], v[214:217], v[182:185], v[80:83]
	v_mfma_f32_16x16x32_bf16 v[76:79], v[206:209], v[190:193], v[76:79]
	v_mfma_f32_16x16x32_bf16 v[72:75], v[214:217], v[190:193], v[72:75]
	v_mfma_f32_16x16x32_bf16 v[68:71], v[206:209], v[198:201], v[68:71]
	v_mfma_f32_16x16x32_bf16 v[64:67], v[214:217], v[198:201], v[64:67]
	v_mfma_f32_16x16x32_bf16 v[174:177], v[210:213], v[178:181], v[92:95]
	v_mfma_f32_16x16x32_bf16 v[178:181], v[156:159], v[178:181], v[88:91]
	v_mfma_f32_16x16x32_bf16 v[182:185], v[210:213], v[186:189], v[84:87]
	v_mfma_f32_16x16x32_bf16 v[186:189], v[156:159], v[186:189], v[80:83]
	v_mfma_f32_16x16x32_bf16 v[190:193], v[210:213], v[194:197], v[76:79]
	v_mfma_f32_16x16x32_bf16 v[194:197], v[156:159], v[194:197], v[72:75]
	v_mfma_f32_16x16x32_bf16 v[198:201], v[210:213], v[202:205], v[68:71]
	v_mfma_f32_16x16x32_bf16 v[202:205], v[156:159], v[202:205], v[64:67]
	s_setprio 0
	s_barrier
	s_nop 0
	ds_read_b128 v[64:67], v152 offset:16384
	ds_read_b128 v[68:71], v152 offset:17408
	ds_read_b128 v[72:75], v151 offset:16384
	ds_read_b128 v[76:79], v151 offset:17408
	ds_read_b128 v[80:83], v150 offset:16384
	ds_read_b128 v[84:87], v150 offset:17408
	ds_read_b128 v[88:91], v149 offset:16384
	ds_read_b128 v[92:95], v149 offset:17408
	s_waitcnt vmcnt(4)
	s_barrier
	s_waitcnt lgkmcnt(0)
	s_setprio 1
	s_waitcnt lgkmcnt(0)
	v_mfma_f32_16x16x32_bf16 v[60:63], v[130:133], v[64:67], v[60:63]
	v_mfma_f32_16x16x32_bf16 v[56:59], v[166:169], v[64:67], v[56:59]
	v_mfma_f32_16x16x32_bf16 v[52:55], v[130:133], v[72:75], v[52:55]
	v_mfma_f32_16x16x32_bf16 v[48:51], v[166:169], v[72:75], v[48:51]
	v_mfma_f32_16x16x32_bf16 v[218:221], v[130:133], v[80:83], v[44:47]
	v_mfma_f32_16x16x32_bf16 v[222:225], v[166:169], v[80:83], v[40:43]
	v_mfma_f32_16x16x32_bf16 v[130:133], v[130:133], v[88:91], v[36:39]
	v_mfma_f32_16x16x32_bf16 v[166:169], v[166:169], v[88:91], v[32:35]
	v_mfma_f32_16x16x32_bf16 v[32:35], v[162:165], v[68:71], v[60:63]
	v_mfma_f32_16x16x32_bf16 v[36:39], v[170:173], v[68:71], v[56:59]
	v_mfma_f32_16x16x32_bf16 v[40:43], v[162:165], v[76:79], v[52:55]
	v_mfma_f32_16x16x32_bf16 v[44:47], v[170:173], v[76:79], v[48:51]
	v_mfma_f32_16x16x32_bf16 v[48:51], v[162:165], v[84:87], v[218:221]
	v_mfma_f32_16x16x32_bf16 v[52:55], v[170:173], v[84:87], v[222:225]
	v_mfma_f32_16x16x32_bf16 v[56:59], v[162:165], v[92:95], v[130:133]
	v_mfma_f32_16x16x32_bf16 v[60:63], v[170:173], v[92:95], v[166:169]
	s_setprio 0
	s_setprio 1
	v_mfma_f32_16x16x32_bf16 v[28:31], v[206:209], v[64:67], v[28:31]
	v_mfma_f32_16x16x32_bf16 v[24:27], v[214:217], v[64:67], v[24:27]
	v_mfma_f32_16x16x32_bf16 v[20:23], v[206:209], v[72:75], v[20:23]
	v_mfma_f32_16x16x32_bf16 v[64:67], v[214:217], v[72:75], v[16:19]
	v_mfma_f32_16x16x32_bf16 v[72:75], v[206:209], v[80:83], v[12:15]
	v_mfma_f32_16x16x32_bf16 v[8:11], v[214:217], v[80:83], v[8:11]
	v_mfma_f32_16x16x32_bf16 v[80:83], v[206:209], v[88:91], v[4:7]
	v_mfma_f32_16x16x32_bf16 v[0:3], v[214:217], v[88:91], v[0:3]
	v_mfma_f32_16x16x32_bf16 v[4:7], v[210:213], v[68:71], v[28:31]
	v_mfma_f32_16x16x32_bf16 v[12:15], v[156:159], v[68:71], v[24:27]
	v_mfma_f32_16x16x32_bf16 v[16:19], v[210:213], v[76:79], v[20:23]
	v_mfma_f32_16x16x32_bf16 v[20:23], v[156:159], v[76:79], v[64:67]
	v_mfma_f32_16x16x32_bf16 v[24:27], v[210:213], v[84:87], v[72:75]
	v_mfma_f32_16x16x32_bf16 v[28:31], v[156:159], v[84:87], v[8:11]
	v_mfma_f32_16x16x32_bf16 v[64:67], v[210:213], v[92:95], v[80:83]
	v_mfma_f32_16x16x32_bf16 v[68:71], v[156:159], v[92:95], v[0:3]
	s_setprio 0
	s_barrier
	ds_read_b128 v[8:11], v154
	ds_read_b128 v[0:3], v154 offset:1024
	ds_read_b128 v[76:79], v154 offset:2048
	ds_read_b128 v[72:75], v154 offset:3072
	ds_read_b128 v[130:133], v152 offset:32768
	ds_read_b128 v[154:157], v152 offset:33792
	ds_read_b128 v[158:161], v151 offset:32768
	ds_read_b128 v[162:165], v151 offset:33792
	ds_read_b128 v[166:169], v150 offset:32768
	ds_read_b128 v[170:173], v150 offset:33792
	ds_read_b128 v[206:209], v149 offset:32768
	ds_read_b128 v[210:213], v149 offset:33792
	s_waitcnt vmcnt(2)
	s_barrier
	s_waitcnt lgkmcnt(0)
	s_setprio 1
	s_waitcnt lgkmcnt(0)
	v_mfma_f32_16x16x32_bf16 v[80:83], v[8:11], v[130:133], v[124:127]
	v_mfma_f32_16x16x32_bf16 v[84:87], v[76:79], v[130:133], v[120:123]
	v_mfma_f32_16x16x32_bf16 v[88:91], v[8:11], v[158:161], v[116:119]
	v_mfma_f32_16x16x32_bf16 v[92:95], v[76:79], v[158:161], v[112:115]
	v_mfma_f32_16x16x32_bf16 v[108:111], v[8:11], v[166:169], v[108:111]
	v_mfma_f32_16x16x32_bf16 v[104:107], v[76:79], v[166:169], v[104:107]
	v_mfma_f32_16x16x32_bf16 v[100:103], v[8:11], v[206:209], v[100:103]
	v_mfma_f32_16x16x32_bf16 v[96:99], v[76:79], v[206:209], v[96:99]
	v_mfma_f32_16x16x32_bf16 v[112:115], v[0:3], v[154:157], v[80:83]
	v_mfma_f32_16x16x32_bf16 v[116:119], v[72:75], v[154:157], v[84:87]
	v_mfma_f32_16x16x32_bf16 v[120:123], v[0:3], v[162:165], v[88:91]
	v_mfma_f32_16x16x32_bf16 v[124:127], v[72:75], v[162:165], v[92:95]
	v_mfma_f32_16x16x32_bf16 v[108:111], v[0:3], v[170:173], v[108:111]
	v_mfma_f32_16x16x32_bf16 v[104:107], v[72:75], v[170:173], v[104:107]
	v_mfma_f32_16x16x32_bf16 v[100:103], v[0:3], v[210:213], v[100:103]
	v_mfma_f32_16x16x32_bf16 v[96:99], v[72:75], v[210:213], v[96:99]
	s_setprio 0
	s_barrier
	ds_read_b128 v[88:91], v153
	ds_read_b128 v[80:83], v153 offset:1024
	ds_read_b128 v[92:95], v153 offset:2048
	ds_read_b128 v[84:87], v153 offset:3072
	s_waitcnt vmcnt(0)
	s_barrier
	s_waitcnt lgkmcnt(0)
	s_setprio 1
	s_waitcnt lgkmcnt(0)
	v_mfma_f32_16x16x32_bf16 v[174:177], v[88:91], v[130:133], v[174:177]
	v_mfma_f32_16x16x32_bf16 v[130:133], v[92:95], v[130:133], v[178:181]
	v_mfma_f32_16x16x32_bf16 v[178:181], v[88:91], v[158:161], v[182:185]
	v_mfma_f32_16x16x32_bf16 v[158:161], v[92:95], v[158:161], v[186:189]
	v_mfma_f32_16x16x32_bf16 v[182:185], v[88:91], v[166:169], v[190:193]
	v_mfma_f32_16x16x32_bf16 v[166:169], v[92:95], v[166:169], v[194:197]
	v_mfma_f32_16x16x32_bf16 v[186:189], v[88:91], v[206:209], v[198:201]
	v_mfma_f32_16x16x32_bf16 v[190:193], v[92:95], v[206:209], v[202:205]
	v_mfma_f32_16x16x32_bf16 v[174:177], v[80:83], v[154:157], v[174:177]
	v_mfma_f32_16x16x32_bf16 v[130:133], v[84:87], v[154:157], v[130:133]
	v_mfma_f32_16x16x32_bf16 v[154:157], v[80:83], v[162:165], v[178:181]
	v_mfma_f32_16x16x32_bf16 v[158:161], v[84:87], v[162:165], v[158:161]
	v_mfma_f32_16x16x32_bf16 v[162:165], v[80:83], v[170:173], v[182:185]
	v_mfma_f32_16x16x32_bf16 v[166:169], v[84:87], v[170:173], v[166:169]
	v_mfma_f32_16x16x32_bf16 v[170:173], v[80:83], v[210:213], v[186:189]
	v_mfma_f32_16x16x32_bf16 v[178:181], v[84:87], v[210:213], v[190:193]
	s_setprio 0
	s_barrier
	v_mbcnt_lo_u32_b32 v128, -1, 0
	v_mbcnt_hi_u32_b32 v128, -1, v128
	v_cvt_pk_bf16_f32 v112, v112, v113
	v_cvt_pk_bf16_f32 v113, v114, v115
	v_cvt_pk_bf16_f32 v114, v116, v117
	v_cvt_pk_bf16_f32 v115, v118, v119
	s_lshl_b32 s89, s66, 9
	v_add_u32_e32 v153, s74, v128
	v_ashrrev_i32_e32 v182, 6, v153
	v_and_b32_e32 v183, 15, v128
	v_and_b32_e32 v184, 48, v128
	v_mul_lo_u32 v185, v182, s79
	v_bfe_u32 v186, v128, 3, 3
	v_lshlrev_b32_e32 v128, 4, v128
	v_add_u32_e32 v185, 0x20000, v185
	v_lshrrev_b32_e32 v153, 2, v153
	v_and_b32_e32 v128, 0x70, v128
	v_mul_u32_u24_e32 v183, 0x90, v183
	v_and_b32_e32 v153, 64, v153
	v_add3_u32 v183, v185, v183, v184
	v_or_b32_e32 v184, v185, v128
	v_or3_b32 v153, s96, v153, v186
	v_mad_u32_u24 v184, v186, s81, v184
	ds_write_b128 v183, v[112:115]
	v_cvt_pk_bf16_f32 v112, v174, v175
	v_cvt_pk_bf16_f32 v113, v176, v177
	v_cvt_pk_bf16_f32 v114, v130, v131
	v_cvt_pk_bf16_f32 v115, v132, v133
	ds_write_b128 v183, v[112:115] offset:64
	v_lshlrev_b32_e32 v182, 7, v182
	ds_read_b128 v[112:115], v184
	v_lshlrev_b32_e32 v116, 12, v153
	v_and_or_b32 v116, v182, s82, v116
	v_or3_b32 v128, v116, s89, v128
	ds_read_b128 v[116:119], v184 offset:1152
	v_lshl_add_u64 v[130:131], s[0:1], 0, v[128:129]
	s_mov_b32 s20, 0x8000
	s_waitcnt lgkmcnt(0)
	global_store_dwordx4 v128, v[112:115], s[0:1]
	v_cvt_pk_bf16_f32 v108, v108, v109
	v_cvt_pk_bf16_f32 v109, v110, v111
	v_cvt_pk_bf16_f32 v110, v104, v105
	v_cvt_pk_bf16_f32 v111, v106, v107
	v_cvt_pk_bf16_f32 v104, v162, v163
	s_nop 1
	v_add_co_u32_e32 v112, vcc, s20, v130
	v_cvt_pk_bf16_f32 v114, v124, v125
	v_cvt_pk_bf16_f32 v115, v126, v127
	v_cvt_pk_bf16_f32 v105, v164, v165
	v_cvt_pk_bf16_f32 v106, v166, v167
	s_nop 1
	v_addc_co_u32_e32 v113, vcc, 0, v131, vcc
	global_store_dwordx4 v[112:113], v[116:119], off
	v_cvt_pk_bf16_f32 v112, v120, v121
	v_cvt_pk_bf16_f32 v113, v122, v123
	ds_write_b128 v183, v[112:115]
	v_cvt_pk_bf16_f32 v112, v154, v155
	v_cvt_pk_bf16_f32 v113, v156, v157
	v_cvt_pk_bf16_f32 v114, v158, v159
	v_cvt_pk_bf16_f32 v115, v160, v161
	ds_write_b128 v183, v[112:115] offset:64
	ds_read_b128 v[112:115], v184
	ds_read_b128 v[116:119], v184 offset:1152
	v_add_co_u32_e32 v120, vcc, s76, v130
	ds_write_b128 v183, v[108:111]
	v_cvt_pk_bf16_f32 v107, v168, v169
	ds_write_b128 v183, v[104:107] offset:64
	v_addc_co_u32_e32 v121, vcc, 0, v131, vcc
	ds_read_b128 v[104:107], v184
	ds_read_b128 v[108:111], v184 offset:1152
	s_waitcnt lgkmcnt(0)
	global_store_dwordx4 v[120:121], v[112:115], off
	v_cvt_pk_bf16_f32 v100, v100, v101
	v_cvt_pk_bf16_f32 v101, v102, v103
	v_cvt_pk_bf16_f32 v102, v96, v97
	v_cvt_pk_bf16_f32 v103, v98, v99
	ds_write_b128 v183, v[100:103]
	s_nop 0
	v_add_co_u32_e32 v112, vcc, s77, v130
	v_cvt_pk_bf16_f32 v96, v170, v171
	v_cvt_pk_bf16_f32 v97, v172, v173
	v_cvt_pk_bf16_f32 v98, v178, v179
	v_cvt_pk_bf16_f32 v99, v180, v181
	s_nop 1
	v_addc_co_u32_e32 v113, vcc, 0, v131, vcc
	global_store_dwordx4 v[112:113], v[116:119], off
	v_add_co_u32_e32 v112, vcc, s80, v130
	ds_write_b128 v183, v[96:99] offset:64
	s_nop 0
	v_addc_co_u32_e32 v113, vcc, 0, v131, vcc
	ds_read_b128 v[96:99], v184
	ds_read_b128 v[100:103], v184 offset:1152
	global_store_dwordx4 v[112:113], v[104:107], off
	s_nop 1
	v_add_co_u32_e32 v104, vcc, s83, v130
	s_nop 1
	v_addc_co_u32_e32 v105, vcc, 0, v131, vcc
	global_store_dwordx4 v[104:105], v[108:111], off
	v_add_co_u32_e32 v104, vcc, s85, v130
	s_nop 1
	v_addc_co_u32_e32 v105, vcc, 0, v131, vcc
	s_waitcnt lgkmcnt(0)
	global_store_dwordx4 v[104:105], v[96:99], off
	s_nop 1
	v_add_co_u32_e32 v96, vcc, s87, v130
	s_nop 1
	v_addc_co_u32_e32 v97, vcc, 0, v131, vcc
	global_store_dwordx4 v[96:97], v[100:103], off
	ds_read_b128 v[96:99], v152 offset:49152
	ds_read_b128 v[100:103], v152 offset:50176
	ds_read_b128 v[104:107], v151 offset:49152
	ds_read_b128 v[108:111], v151 offset:50176
	ds_read_b128 v[112:115], v150 offset:49152
	ds_read_b128 v[116:119], v150 offset:50176
	ds_read_b128 v[120:123], v149 offset:49152
	ds_read_b128 v[124:127], v149 offset:50176
	s_barrier
	s_waitcnt lgkmcnt(0)
	s_setprio 1
	s_waitcnt lgkmcnt(0)
	v_mfma_f32_16x16x32_bf16 v[32:35], v[8:11], v[96:99], v[32:35]
	v_mfma_f32_16x16x32_bf16 v[36:39], v[76:79], v[96:99], v[36:39]
	v_mfma_f32_16x16x32_bf16 v[40:43], v[8:11], v[104:107], v[40:43]
	v_mfma_f32_16x16x32_bf16 v[130:133], v[76:79], v[104:107], v[44:47]
	v_mfma_f32_16x16x32_bf16 v[150:153], v[8:11], v[112:115], v[48:51]
	v_mfma_f32_16x16x32_bf16 v[52:55], v[76:79], v[112:115], v[52:55]
	v_mfma_f32_16x16x32_bf16 v[8:11], v[8:11], v[120:123], v[56:59]
	v_mfma_f32_16x16x32_bf16 v[60:63], v[76:79], v[120:123], v[60:63]
	v_mfma_f32_16x16x32_bf16 v[56:59], v[0:3], v[100:103], v[32:35]
	v_mfma_f32_16x16x32_bf16 v[48:51], v[72:75], v[100:103], v[36:39]
	v_mfma_f32_16x16x32_bf16 v[44:47], v[0:3], v[108:111], v[40:43]
	v_mfma_f32_16x16x32_bf16 v[40:43], v[72:75], v[108:111], v[130:133]
	v_mfma_f32_16x16x32_bf16 v[36:39], v[0:3], v[116:119], v[150:153]
	v_mfma_f32_16x16x32_bf16 v[32:35], v[72:75], v[116:119], v[52:55]
	v_mfma_f32_16x16x32_bf16 v[8:11], v[0:3], v[124:127], v[8:11]
	v_mfma_f32_16x16x32_bf16 v[0:3], v[72:75], v[124:127], v[60:63]
	s_setprio 0
	s_setprio 1
	v_mfma_f32_16x16x32_bf16 v[4:7], v[88:91], v[96:99], v[4:7]
	v_mfma_f32_16x16x32_bf16 v[12:15], v[92:95], v[96:99], v[12:15]
	v_mfma_f32_16x16x32_bf16 v[16:19], v[88:91], v[104:107], v[16:19]
	v_mfma_f32_16x16x32_bf16 v[20:23], v[92:95], v[104:107], v[20:23]
	v_mfma_f32_16x16x32_bf16 v[72:75], v[88:91], v[112:115], v[24:27]
	v_mfma_f32_16x16x32_bf16 v[76:79], v[92:95], v[112:115], v[28:31]
	v_mfma_f32_16x16x32_bf16 v[64:67], v[88:91], v[120:123], v[64:67]
	v_mfma_f32_16x16x32_bf16 v[68:71], v[92:95], v[120:123], v[68:71]
	v_mfma_f32_16x16x32_bf16 v[60:63], v[80:83], v[100:103], v[4:7]
	v_mfma_f32_16x16x32_bf16 v[52:55], v[84:87], v[100:103], v[12:15]
	v_mfma_f32_16x16x32_bf16 v[28:31], v[80:83], v[108:111], v[16:19]
	v_mfma_f32_16x16x32_bf16 v[24:27], v[84:87], v[108:111], v[20:23]
	v_mfma_f32_16x16x32_bf16 v[20:23], v[80:83], v[116:119], v[72:75]
	v_mfma_f32_16x16x32_bf16 v[16:19], v[84:87], v[116:119], v[76:79]
	v_mfma_f32_16x16x32_bf16 v[12:15], v[80:83], v[124:127], v[64:67]
	v_mfma_f32_16x16x32_bf16 v[4:7], v[84:87], v[124:127], v[68:71]
	s_setprio 0
	v_cmp_gt_u32_e32 vcc, s88, v135
	s_barrier
	s_and_saveexec_b64 s[66:67], vcc
	s_cbranch_execz .LBB0_564
	s_barrier
